# half-specific K-loop barriers: leading half takes only post-MFMA barriers, trailing half only pre-MFMA (4 instead of 8 per wave per iteration); rising s_setprio 1/2/3 through each MFMA block
# baseline (speedup 1.0000x reference)
; #define PG8_WAIT_V(n) asm volatile("s_waitcnt vmcnt(" #n ")" ::: "memory")
; #define PG8_BAR __builtin_amdgcn_s_barrier()
; template <class Epi, class Sched, bool ALIGN_EPI = false, bool SP2 = false>
; __device__ __forceinline__ void gemm_phase(PG8_LAS unsigned char* lds, const Gemm g, const Sched& S, const Epi& E) {
;     ...
;     const int tid = tid_l, wid = __builtin_amdgcn_readfirstlane(tid >> 6), lane = tid & 63, wr = wid >> 2, wc = wid & 3, fr = lane & 15, fq = lane >> 4;
;     const int K = g.K;
;     unsigned voffA[2], voffB[2];
; #pragma unroll
;     for (int i = 0; i < 2; ++i) { int R, C; stage_rc(tid * 16 + i * 8192, R, C); const int Rb = Epi::PERM ? ((R & ~31) + perm32(R & 31)) : R;
;         voffA[i] = (unsigned)(R * K + C) * 2u; voffB[i] = (unsigned)(Rb * K + C) * 2u; }
;     const size_t kstep = (size_t)(BK * 2);
;     const size_t hstep = (size_t)HALF * K * 2;
;     const size_t tstep = 2 * hstep;
;     const unsigned ldsw = (unsigned)wid * 1024u;
;     const int aoff = lds_byte(wr * 64 + fr, fq * 8), boff = lds_byte(wc * 32 + fr, fq * 8);
;     ...
;     Unit cur, nxt; int ui = 0;
;     if (!S.next(0, cur)) return;
;     f32x4 acc[2][2][4][2];
; #pragma unroll
;     for (int a = 0; a < 2; ++a)
; #pragma unroll
;         for (int b = 0; b < 2; ++b)
; #pragma unroll
;             for (int m = 0; m < 4; ++m)
; #pragma unroll
;                 for (int n = 0; n < 2; ++n) acc[a][b][m][n] = (f32x4){0.f, 0.f, 0.f, 0.f};
;     bf16x8 At[4][2], B0[2][2], B1[2][2];
;     const char* cA = (const char*)g.A + (size_t)cur.pm * tstep + (size_t)cur.kt0 * kstep; const char* cB = (const char*)g.Bt + (size_t)cur.pn * tstep + (size_t)cur.kt0 * kstep;
;     S.a_ready(cur);
;     ...
;     { const int rot0 = cur.krot, nt0 = cur.nkt; const char* sA0 = PG8_KP(cA, 0, rot0, nt0); const char* sA1 = PG8_KP(cA, 1, rot0, nt0); const char* sB0 = PG8_KP(cB, 0, rot0, nt0); const char* sB1 = PG8_KP(cB, 1, rot0, nt0);
;     if constexpr (SP2) {
;         PG8_STAGEB(PG8_SB(0, 0), sB0, voffB); PG8_STAGEB(PG8_SB(0, 1), sB0 + hstep, voffB); PG8_STAGE(PG8_SA(0, 0), sA0, voffA); PG8_STAGE(PG8_SA(0, 1), sA0 + hstep, voffA);
;         if (wr == 1) PG8_BAR;
;         PG8_WAIT_V(2); PG8_BAR;
;         PG8_STAGEB(PG8_SB(1, 0), sB1, voffB); PG8_STAGE(PG8_SA(1, 0), sA1, voffA); PG8_STAGEB(PG8_SB(1, 1), sB1 + hstep, voffB);
;         PG8_WAIT_V(6); PG8_BAR;
;     } else {
.LBB0_260:
	s_cmp_le_i32 s90, s30
	s_cselect_b64 s[0:1], -1, 0
	s_cmp_lt_i32 s30, s91
	s_cselect_b64 s[4:5], -1, 0
	s_and_b64 s[0:1], s[0:1], s[4:5]
	s_andn2_b64 vcc, exec, s[0:1]
	s_cbranch_vccnz .LBB0_741
	v_readlane_b32 s2, v254, 53
	v_readlane_b32 s3, v254, 54
	s_mov_b32 s3, s79
	s_mul_hi_u32 s0, s2, 0x1a00000
	v_writelane_b32 v254, s2, 53
	s_mul_i32 s1, s2, 0x1a00000
	s_mov_b64 s[82:83], s[66:67]
	s_add_u32 s1, s82, s1
	s_addc_u32 s0, s83, s0
	s_add_u32 s24, s1, 0x1000000
	s_addc_u32 s25, s0, 0
	v_readlane_b32 s0, v251, 53
	v_mov_b32_e32 v16, v0
	v_readlane_b32 s1, v251, 54
	v_writelane_b32 v254, s3, 54
	s_andn2_b64 vcc, exec, s[0:1]
	v_readfirstlane_b32 s16, v16
	s_cbranch_vccnz .LBB0_592
	v_lshlrev_b32_e32 v1, 4, v16
	v_add_u32_e32 v2, 0x2000, v1
	v_ashrrev_i32_e32 v3, 31, v2
	v_lshrrev_b32_e32 v3, 22, v3
	v_add_u32_e32 v3, v2, v3
	v_ashrrev_i32_e32 v10, 10, v3
	v_mul_i32_i24_e32 v3, 0x400, v10
	v_sub_u32_e32 v2, v2, v3
	v_lshrrev_b32_e32 v3, 4, v2
	v_bitop3_b32 v2, v3, v2, 32 bitop3:0x6c
	v_ashrrev_i32_e32 v3, 31, v2
	v_lshrrev_b32_e32 v3, 26, v3
	v_add_u32_e32 v3, v2, v3
	v_lshlrev_b32_e32 v4, 3, v10
	v_ashrrev_i32_e32 v11, 6, v3
	v_and_b32_e32 v4, -16, v4
	v_add_u32_e32 v4, v11, v4
	v_and_b32_e32 v5, 3, v11
	s_mov_b32 s2, 0xfffe0
	v_lshrrev_b32_e32 v6, 2, v4
	v_lshlrev_b32_e32 v7, 1, v4
	v_and_b32_e32 v3, 0xc0, v3
	v_and_or_b32 v5, v4, s2, v5
	v_and_b32_e32 v6, 4, v6
	v_and_b32_e32 v7, 24, v7
	v_sub_u32_e32 v2, v2, v3
	v_or3_b32 v5, v5, v6, v7
	v_lshlrev_b32_e32 v6, 5, v10
	v_ashrrev_i16_sdwa v2, v207, sext(v2) dst_sel:DWORD dst_unused:UNUSED_PAD src0_sel:DWORD src1_sel:BYTE_0
	v_and_b32_e32 v6, 32, v6
	v_bfe_i32 v12, v2, 0, 16
	v_add_lshl_u32 v2, v6, v12, 1
	v_lshl_add_u32 v180, v5, 12, v2
	v_lshl_add_u32 v182, v4, 12, v2
	v_bfe_i32 v2, v16, 27, 1
	v_lshrrev_b32_e32 v2, 22, v2
	v_add_u32_e32 v2, v1, v2
	v_and_b32_e32 v2, 0xfffffc00, v2
	v_sub_u32_e32 v1, v1, v2
	v_lshrrev_b32_e32 v2, 4, v1
	v_ashrrev_i32_e32 v3, 31, v16
	v_bitop3_b32 v1, v2, v1, 32 bitop3:0x6c
	v_lshrrev_b32_e32 v3, 26, v3
	v_ashrrev_i32_e32 v2, 31, v1
	v_add_u32_e32 v3, v16, v3
	v_lshrrev_b32_e32 v2, 26, v2
	v_ashrrev_i32_e32 v14, 6, v3
	v_add_u32_e32 v2, v1, v2
	v_lshlrev_b32_e32 v3, 3, v14
	v_ashrrev_i32_e32 v13, 6, v2
	v_and_b32_e32 v3, -16, v3
	v_add_u32_e32 v3, v13, v3
	s_add_u32 s88, s82, 0x1c800000
	v_and_b32_e32 v4, 3, v13
	v_lshrrev_b32_e32 v5, 2, v3
	v_lshlrev_b32_e32 v6, 1, v3
	v_and_b32_e32 v2, 0xc0, v2
	s_addc_u32 s8, s83, 0
	s_ashr_i32 s1, s16, 6
	v_and_or_b32 v4, v3, s2, v4
	v_and_b32_e32 v5, 4, v5
	v_and_b32_e32 v6, 24, v6
	v_sub_u32_e32 v1, v1, v2
	s_ashr_i32 s0, s16, 8
	s_lshl_b32 s70, s1, 10
	v_or3_b32 v4, v4, v5, v6
	v_lshlrev_b32_e32 v5, 5, v14
	v_ashrrev_i16_sdwa v1, v207, sext(v1) dst_sel:DWORD dst_unused:UNUSED_PAD src0_sel:DWORD src1_sel:BYTE_0
	v_readlane_b32 s2, v252, 47
	v_and_b32_e32 v5, 32, v5
	v_bfe_i32 v15, v1, 0, 16
	v_readlane_b32 s3, v252, 48
	s_add_u32 s38, s24, s2
	v_add_lshl_u32 v1, v5, v15, 1
	s_addc_u32 s39, s25, s3
	s_add_i32 s96, s70, 0
	v_lshl_add_u32 v184, v4, 12, v1
	s_add_i32 m0, s96, 0x10000
	v_readlane_b32 s2, v252, 51
	global_load_lds_dwordx4 v184, s[38:39]
	s_add_i32 m0, s96, 0x12000
	v_readlane_b32 s3, v252, 52
	s_add_u32 s40, s88, s2
	s_addc_u32 s41, s8, s3
	s_add_u32 s4, s38, 0x80000
	global_load_lds_dwordx4 v180, s[38:39]
	s_addc_u32 s5, s39, 0
	s_add_i32 m0, s96, 0x14000
	s_add_i32 s71, s96, 0x2000
	global_load_lds_dwordx4 v184, s[4:5]
	s_add_i32 m0, s96, 0x16000
	v_lshl_add_u32 v186, v3, 12, v1
	global_load_lds_dwordx4 v180, s[4:5]
	s_mov_b32 m0, s96
	s_add_u32 s4, s40, 0x80000
	global_load_lds_dwordx4 v186, s[40:41]
	s_mov_b32 m0, s71
	s_addc_u32 s5, s41, 0
	s_add_i32 s33, s96, 0x4000
	global_load_lds_dwordx4 v182, s[40:41]
	s_mov_b32 m0, s33
	s_add_i32 s30, s96, 0x6000
	global_load_lds_dwordx4 v186, s[4:5]
	s_mov_b32 m0, s30
	s_cmp_eq_u32 s0, 1
	global_load_lds_dwordx4 v182, s[4:5]
	s_cselect_b64 s[2:3], -1, 0
	v_mov_b32_e32 v185, v98
	v_mov_b32_e32 v181, v98
	v_mov_b32_e32 v187, v98
	v_mov_b32_e32 v183, v98
	v_writelane_b32 v254, s2, 58
	v_lshl_add_u64 v[6:7], s[38:39], 0, v[184:185]
	v_lshl_add_u64 v[4:5], s[38:39], 0, v[180:181]
	v_lshl_add_u64 v[2:3], s[40:41], 0, v[186:187]
	v_writelane_b32 v254, s3, 59
	s_cmp_lg_u32 s0, 1
	v_lshl_add_u64 v[8:9], s[40:41], 0, v[182:183]
	s_cbranch_scc1 .LBB0_264
; #define PG8_STAGE(bufoff, gbase, voff) do { _Pragma("unroll") for (int _i = 0; _i < 2; ++_i) \
;         __builtin_amdgcn_global_load_lds((const unsigned*)((const char*)(gbase) + (voff)[_i]), (PG8_LAS unsigned*)(lds + (bufoff) + ldsw + _i * 8192), 16, 0, AUX_A); } while (0)
; #define PG8_STAGEB(bufoff, gbase, voff) do { _Pragma("unroll") for (int _i = 0; _i < 2; ++_i) \
;         __builtin_amdgcn_global_load_lds((const unsigned*)((const char*)(gbase) + (voff)[_i]), (PG8_LAS unsigned*)(lds + (bufoff) + ldsw + _i * 8192), 16, 0, AUX_B); } while (0)
; template <class Epi, class Sched, bool ALIGN_EPI = false, bool SP2 = false>
; __device__ __forceinline__ void gemm_phase(PG8_LAS unsigned char* lds, const Gemm g, const Sched& S, const Epi& E) {
;     ...
;     const int tid = tid_l, wid = __builtin_amdgcn_readfirstlane(tid >> 6), lane = tid & 63, wr = wid >> 2, wc = wid & 3, fr = lane & 15, fq = lane >> 4;
;     const int K = g.K;
;     unsigned voffA[2], voffB[2];
; #pragma unroll
;     for (int i = 0; i < 2; ++i) { int R, C; stage_rc(tid * 16 + i * 8192, R, C); const int Rb = Epi::PERM ? ((R & ~31) + perm32(R & 31)) : R;
;         voffA[i] = (unsigned)(R * K + C) * 2u; voffB[i] = (unsigned)(Rb * K + C) * 2u; }
;     const size_t kstep = (size_t)(BK * 2);
;     const size_t hstep = (size_t)HALF * K * 2;
;     const size_t tstep = 2 * hstep;
;     const unsigned ldsw = (unsigned)wid * 1024u;
;     const int aoff = lds_byte(wr * 64 + fr, fq * 8), boff = lds_byte(wc * 32 + fr, fq * 8);
;     ...
;     const char* cA = (const char*)g.A + (size_t)cur.pm * tstep + (size_t)cur.kt0 * kstep; const char* cB = (const char*)g.Bt + (size_t)cur.pn * tstep + (size_t)cur.kt0 * kstep;
;     S.a_ready(cur);
;     ...
;     { const int rot0 = cur.krot, nt0 = cur.nkt; const char* sA0 = PG8_KP(cA, 0, rot0, nt0); const char* sA1 = PG8_KP(cA, 1, rot0, nt0); const char* sB0 = PG8_KP(cB, 0, rot0, nt0); const char* sB1 = PG8_KP(cB, 1, rot0, nt0);
;     if constexpr (SP2) {
;         PG8_STAGEB(PG8_SB(0, 0), sB0, voffB); PG8_STAGEB(PG8_SB(0, 1), sB0 + hstep, voffB); PG8_STAGE(PG8_SA(0, 0), sA0, voffA); PG8_STAGE(PG8_SA(0, 1), sA0 + hstep, voffA);
;         if (wr == 1) PG8_BAR;
;         PG8_WAIT_V(2); PG8_BAR;
;         PG8_STAGEB(PG8_SB(1, 0), sB1, voffB); PG8_STAGE(PG8_SA(1, 0), sA1, voffA); PG8_STAGEB(PG8_SB(1, 1), sB1 + hstep, voffB);
;         PG8_WAIT_V(6); PG8_BAR;
.LBB0_264:
	v_readlane_b32 s2, v254, 53
	v_readlane_b32 s3, v254, 54
	v_readlane_b32 s44, v249, 50
	s_lshl_b64 s[6:7], s[2:3], 14
	v_readlane_b32 s50, v249, 56
	v_readlane_b32 s51, v249, 57
	s_add_u32 s4, s50, s6
	s_addc_u32 s5, s51, s7
	s_lshl_b32 s78, s2, 6
	s_lshl_b32 s31, s2, 4
	s_lshl_b32 s75, s2, 2
	s_add_u32 s20, s82, 0x1ec00000
	s_addc_u32 s21, s83, 0
	v_writelane_b32 v254, s4, 60
	s_add_u32 s22, s82, 0x26100000
	s_addc_u32 s23, s83, 0
	v_writelane_b32 v254, s5, 61
	s_mov_b64 s[4:5], s[82:83]
	s_add_u32 s82, s4, 0x27300000
	s_addc_u32 s83, s5, 0
	v_bfe_u32 v99, v16, 4, 2
	s_add_u32 s2, s4, 0x800000
	v_and_b32_e32 v1, 15, v16
	v_lshlrev_b32_e32 v17, 4, v99
	v_lshlrev_b32_e32 v16, 2, v16
	v_writelane_b32 v254, s4, 62
	s_addc_u32 s3, s5, 0
	s_and_b32 s18, s1, 3
	s_lshl_b32 s6, s0, 6
	v_lshl_or_b32 v17, v1, 6, v17
	s_lshl_b32 s0, s0, 13
	v_and_b32_e32 v16, 32, v16
	v_bitop3_b32 v18, v17, s0, v16 bitop3:0xde
	s_lshl_b32 s0, s18, 5
	s_add_i32 m0, s96, 0x18000
	v_lshl_add_u64 v[6:7], v[6:7], 0, s[76:77]
	v_writelane_b32 v255, s0, 0
	s_lshl_b32 s0, s18, 12
	s_waitcnt vmcnt(2)
	s_barrier
	global_load_lds_dwordx4 v[6:7], off
	v_lshl_add_u64 v[4:5], v[4:5], 0, s[76:77]
	s_add_i32 m0, s96, 0x1a000
	s_add_i32 s90, s96, 0x8000
	s_add_i32 s91, s96, 0xa000
	v_bitop3_b32 v221, v17, s0, v16 bitop3:0xde
	global_load_lds_dwordx4 v[4:5], off
	v_lshl_add_u64 v[2:3], v[2:3], 0, s[76:77]
	s_mov_b32 m0, s90
	s_add_u32 s0, s38, 0x80080
	global_load_lds_dwordx4 v[2:3], off
	v_lshl_add_u64 v[2:3], v[8:9], 0, s[76:77]
	s_mov_b32 m0, s91
	s_addc_u32 s1, s39, 0
	global_load_lds_dwordx4 v[2:3], off
	s_add_i32 m0, s96, 0x1c000
	v_lshl_add_u64 v[2:3], s[0:1], 0, v[184:185]
	global_load_lds_dwordx4 v[2:3], off
	v_lshl_add_u64 v[2:3], s[0:1], 0, v[180:181]
	s_add_i32 m0, s96, 0x1e000
	s_cmpk_lt_u32 s16, 0x100
	global_load_lds_dwordx4 v[2:3], off
	v_lshlrev_b32_e32 v2, 15, v10
	v_and_b32_e32 v2, 0xffff0000, v2
	v_lshl_add_u32 v2, v11, 12, v2
	v_and_b32_e32 v3, 1, v10
	v_lshl_or_b32 v2, v3, 6, v2
	s_cselect_b64 s[10:11], -1, 0
	s_lshl_b32 s0, s18, 6
	v_lshl_add_u32 v188, v12, 1, v2
	v_lshlrev_b32_e32 v2, 15, v14
	v_writelane_b32 v255, s0, 1
	s_or_b32 s93, s0, 0xfffffc00
	v_and_b32_e32 v2, 0xffff0000, v2
	s_lshl_b64 s[0:1], s[78:79], 2
	s_waitcnt vmcnt(6)
	v_lshl_add_u32 v2, v13, 12, v2
	v_and_b32_e32 v3, 1, v14
	v_writelane_b32 v255, s0, 2
	v_lshl_or_b32 v2, v3, 6, v2
	v_writelane_b32 v254, s5, 63
	v_writelane_b32 v255, s1, 3
	v_readlane_b32 s0, v252, 49
	v_mov_b32_e32 v189, v98
	v_lshl_add_u32 v190, v15, 1, v2
	v_mov_b32_e32 v191, v98
	s_mov_b32 s94, 0
	v_add_u32_e32 v222, 0, v18
	v_readlane_b32 s95, v253, 5
	s_mov_b32 s78, s0
	v_readlane_b32 s45, v249, 51
	v_readlane_b32 s46, v249, 52
	v_readlane_b32 s47, v249, 53
	v_readlane_b32 s48, v249, 54
	v_readlane_b32 s49, v249, 55
	v_readlane_b32 s52, v249, 58
	v_readlane_b32 s53, v249, 59
	v_readlane_b32 s54, v249, 60
	v_readlane_b32 s55, v249, 61
	v_readlane_b32 s56, v249, 62
	v_readlane_b32 s57, v249, 63
	v_readlane_b32 s58, v250, 0
	v_readlane_b32 s59, v250, 1
	s_barrier
	v_readlane_b32 s1, v252, 50
	s_branch .LBB0_267

; #define PG8_STAGE(bufoff, gbase, voff) do { _Pragma("unroll") for (int _i = 0; _i < 2; ++_i) \
;         __builtin_amdgcn_global_load_lds((const unsigned*)((const char*)(gbase) + (voff)[_i]), (PG8_LAS unsigned*)(lds + (bufoff) + ldsw + _i * 8192), 16, 0, AUX_A); } while (0)
; #define PG8_LDA(dst, b, h) do { _Pragma("unroll") for (int m = 0; m < 4; ++m) _Pragma("unroll") for (int k = 0; k < 2; ++k) dst[m][k] = *(const PG8_LAS bf16x8*)(lds + PG8_SA(b, h) + aoff + m * 2048 + k * 1024); } while (0)
; #define PG8_LDB(dst, b, h) do { _Pragma("unroll") for (int n = 0; n < 2; ++n) _Pragma("unroll") for (int k = 0; k < 2; ++k) dst[n][k] = *(const PG8_LAS bf16x8*)(lds + PG8_SB(b, h) + boff + n * 2048 + k * 1024); } while (0)
; #define PG8_MMA(ai, bj, At, Bt) do { __builtin_amdgcn_s_setprio(1); _Pragma("unroll") for (int m = 0; m < 4; ++m) _Pragma("unroll") for (int n = 0; n < 2; ++n) _Pragma("unroll") for (int k = 0; k < 2; ++k) \
;         acc[ai][bj][m][n] = __builtin_amdgcn_mfma_f32_16x16x32_bf16(Bt[n][k], At[m][k], acc[ai][bj][m][n], 0, 0, 0); __builtin_amdgcn_s_setprio(0); } while (0)
; #define PG8_WAIT_V(n) asm volatile("s_waitcnt vmcnt(" #n ")" ::: "memory")
; #define PG8_WAIT_L(n) asm volatile("s_waitcnt lgkmcnt(" #n ")" ::: "memory")
; #define PG8_BAR __builtin_amdgcn_s_barrier()
; #define PG8_SCHED __builtin_amdgcn_sched_barrier(0)
; template <class Epi, class Sched, bool ALIGN_EPI = false, bool SP2 = false>
; __device__ __forceinline__ void gemm_phase(PG8_LAS unsigned char* lds, const Gemm g, const Sched& S, const Epi& E) {
;     ...
;             PG8_LDB(B0, 0, 0); PG8_LDB(B1, 0, 1); PG8_SCHED; PG8_LDA(At, 0, 0); PG8_STAGE(PG8_SA(1, 1), a1 + hstep, voffA);
;             PG8_WAIT_V(8); PG8_WAIT_L(0); PG8_BAR; PG8_MMA(0, 0, At, B0); PG8_MMA(0, 1, At, B1); PG8_BAR; PG8_SCHED;
.LBB0_270:
	s_add_i32 s81, s29, 2
	s_cmp_lt_u32 s29, 30
	s_cselect_b32 s0, 0, 0xffffffe0
	s_add_i32 s0, s81, s0
	s_ashr_i32 s1, s0, 31
	s_lshl_b64 s[0:1], s[0:1], 7
	s_add_u32 s42, s40, s0
	s_addc_u32 s43, s41, s1
	s_add_u32 s0, s38, s0
	s_addc_u32 s1, s39, s1
	s_cmp_eq_u32 s29, 30
	s_cselect_b32 s59, s49, s43
	s_cselect_b32 s58, s51, s42
	s_cselect_b32 s61, vcc_lo, s1
	s_cselect_b32 s60, vcc_hi, s0
	s_add_i32 s43, 0, 0x10000
	s_add_i32 s97, s43, s70
	s_add_i32 s46, 0, 0x14000
	s_add_i32 m0, s96, 0xc000
	s_add_i32 s69, s96, 0xe000
	s_add_i32 s84, s97, 0x2000
	s_add_u32 s62, s60, 0x80000
	s_addc_u32 s63, s61, 0
	s_add_i32 s4, s46, s70
	v_add_u32_e32 v148, s43, v221
	v_add_u32_e32 v164, s46, v221
	s_add_i32 s5, s4, 0x2000
	s_add_i32 s1, 0, 0x18000
	s_add_i32 s47, 0, 0x1c000
	ds_read_b128 v[136:139], v148
	ds_read_b128 v[140:143], v148 offset:1024
	ds_read_b128 v[144:147], v148 offset:2048
	ds_read_b128 v[148:151], v148 offset:3072
	ds_read_b128 v[152:155], v164
	ds_read_b128 v[156:159], v164 offset:1024
	ds_read_b128 v[160:163], v164 offset:2048
	ds_read_b128 v[164:167], v164 offset:3072
	s_add_u32 s56, s58, 0x80000
	s_addc_u32 s57, s59, 0
	s_add_i32 s0, s1, s70
	s_add_i32 s89, s0, 0x2000
	s_add_u32 s42, s60, 0x80080
	s_addc_u32 s43, s61, 0
	s_add_i32 s46, s47, s70
	s_add_i32 s92, s46, 0x2000
	ds_read_b128 v[192:195], v222
	ds_read_b128 v[196:199], v222 offset:1024
	ds_read_b128 v[200:203], v222 offset:2048
	ds_read_b128 v[224:227], v222 offset:3072
	ds_read_b128 v[228:231], v222 offset:4096
	ds_read_b128 v[232:235], v222 offset:5120
	ds_read_b128 v[236:239], v222 offset:6144
	ds_read_b128 v[240:243], v222 offset:7168
	global_load_lds_dwordx4 v[134:135], off
	s_mov_b32 m0, s69
	s_nop 0
	global_load_lds_dwordx4 v[132:133], off
	s_waitcnt vmcnt(8)
	s_waitcnt lgkmcnt(0)
	s_cmp_lg_u64 s[10:11], 0
	s_cbranch_scc1 .Lhb_1
	s_barrier
.Lhb_1:
	s_setprio 1
	s_waitcnt lgkmcnt(0)
	v_mfma_f32_16x16x32_bf16 v[128:131], v[136:139], v[192:195], v[128:131]
	v_mfma_f32_16x16x32_bf16 v[124:127], v[144:147], v[192:195], v[124:127]
	v_mfma_f32_16x16x32_bf16 v[112:115], v[136:139], v[200:203], v[112:115]
	v_mfma_f32_16x16x32_bf16 v[108:111], v[144:147], v[200:203], v[108:111]
	v_mfma_f32_16x16x32_bf16 v[94:97], v[136:139], v[228:231], v[94:97]
	v_mfma_f32_16x16x32_bf16 v[90:93], v[144:147], v[228:231], v[90:93]
	v_mfma_f32_16x16x32_bf16 v[78:81], v[136:139], v[236:239], v[78:81]
	v_mfma_f32_16x16x32_bf16 v[74:77], v[144:147], v[236:239], v[74:77]
	s_setprio 2
	v_mfma_f32_16x16x32_bf16 v[128:131], v[140:143], v[196:199], v[128:131]
	v_mfma_f32_16x16x32_bf16 v[124:127], v[148:151], v[196:199], v[124:127]
	v_mfma_f32_16x16x32_bf16 v[112:115], v[140:143], v[224:227], v[112:115]
	v_mfma_f32_16x16x32_bf16 v[108:111], v[148:151], v[224:227], v[108:111]
	v_mfma_f32_16x16x32_bf16 v[94:97], v[140:143], v[232:235], v[94:97]
	v_mfma_f32_16x16x32_bf16 v[90:93], v[148:151], v[232:235], v[90:93]
	v_mfma_f32_16x16x32_bf16 v[78:81], v[140:143], v[240:243], v[78:81]
	v_mfma_f32_16x16x32_bf16 v[74:77], v[148:151], v[240:243], v[74:77]
	v_mfma_f32_16x16x32_bf16 v[120:123], v[152:155], v[192:195], v[120:123]
	v_mfma_f32_16x16x32_bf16 v[116:119], v[160:163], v[192:195], v[116:119]
	v_mfma_f32_16x16x32_bf16 v[104:107], v[152:155], v[200:203], v[104:107]
	v_mfma_f32_16x16x32_bf16 v[100:103], v[160:163], v[200:203], v[100:103]
	s_setprio 3
	v_mfma_f32_16x16x32_bf16 v[86:89], v[152:155], v[228:231], v[86:89]
	v_mfma_f32_16x16x32_bf16 v[82:85], v[160:163], v[228:231], v[82:85]
	v_mfma_f32_16x16x32_bf16 v[70:73], v[152:155], v[236:239], v[70:73]
	v_mfma_f32_16x16x32_bf16 v[66:69], v[160:163], v[236:239], v[66:69]
	v_mfma_f32_16x16x32_bf16 v[120:123], v[156:159], v[196:199], v[120:123]
	v_mfma_f32_16x16x32_bf16 v[116:119], v[164:167], v[196:199], v[116:119]
	v_mfma_f32_16x16x32_bf16 v[104:107], v[156:159], v[224:227], v[104:107]
	v_mfma_f32_16x16x32_bf16 v[100:103], v[164:167], v[224:227], v[100:103]
	v_mfma_f32_16x16x32_bf16 v[86:89], v[156:159], v[232:235], v[86:89]
	v_mfma_f32_16x16x32_bf16 v[82:85], v[164:167], v[232:235], v[82:85]
	v_mfma_f32_16x16x32_bf16 v[70:73], v[156:159], v[240:243], v[70:73]
	v_mfma_f32_16x16x32_bf16 v[66:69], v[164:167], v[240:243], v[66:69]
	s_setprio 0
	s_cmp_eq_u64 s[10:11], 0
	s_cbranch_scc1 .Lhb_5
	s_barrier
; #define PG8_STAGE(bufoff, gbase, voff) do { _Pragma("unroll") for (int _i = 0; _i < 2; ++_i) \
;         __builtin_amdgcn_global_load_lds((const unsigned*)((const char*)(gbase) + (voff)[_i]), (PG8_LAS unsigned*)(lds + (bufoff) + ldsw + _i * 8192), 16, 0, AUX_A); } while (0)
; #define PG8_STAGEB(bufoff, gbase, voff) do { _Pragma("unroll") for (int _i = 0; _i < 2; ++_i) \
;         __builtin_amdgcn_global_load_lds((const unsigned*)((const char*)(gbase) + (voff)[_i]), (PG8_LAS unsigned*)(lds + (bufoff) + ldsw + _i * 8192), 16, 0, AUX_B); } while (0)
; #define PG8_LDA(dst, b, h) do { _Pragma("unroll") for (int m = 0; m < 4; ++m) _Pragma("unroll") for (int k = 0; k < 2; ++k) dst[m][k] = *(const PG8_LAS bf16x8*)(lds + PG8_SA(b, h) + aoff + m * 2048 + k * 1024); } while (0)
; #define PG8_LDB(dst, b, h) do { _Pragma("unroll") for (int n = 0; n < 2; ++n) _Pragma("unroll") for (int k = 0; k < 2; ++k) dst[n][k] = *(const PG8_LAS bf16x8*)(lds + PG8_SB(b, h) + boff + n * 2048 + k * 1024); } while (0)
; #define PG8_MMA(ai, bj, At, Bt) do { __builtin_amdgcn_s_setprio(1); _Pragma("unroll") for (int m = 0; m < 4; ++m) _Pragma("unroll") for (int n = 0; n < 2; ++n) _Pragma("unroll") for (int k = 0; k < 2; ++k) \
;         acc[ai][bj][m][n] = __builtin_amdgcn_mfma_f32_16x16x32_bf16(Bt[n][k], At[m][k], acc[ai][bj][m][n], 0, 0, 0); __builtin_amdgcn_s_setprio(0); } while (0)
; #define PG8_WAIT_V(n) asm volatile("s_waitcnt vmcnt(" #n ")" ::: "memory")
; #define PG8_WAIT_L(n) asm volatile("s_waitcnt lgkmcnt(" #n ")" ::: "memory")
; #define PG8_BAR __builtin_amdgcn_s_barrier()
; #define PG8_SCHED __builtin_amdgcn_sched_barrier(0)
; template <class Epi, class Sched, bool ALIGN_EPI = false, bool SP2 = false>
; __device__ __forceinline__ void gemm_phase(PG8_LAS unsigned char* lds, const Gemm g, const Sched& S, const Epi& E) {
;     ...
;             PG8_LDA(At, 0, 1); PG8_STAGEB(PG8_SB(0, 0), b2, voffB); PG8_STAGEB(PG8_SB(0, 1), b2 + hstep, voffB); PG8_STAGE(PG8_SA(0, 0), a2, voffA);
;             PG8_WAIT_V(8); PG8_WAIT_L(0); PG8_BAR; PG8_MMA(1, 0, At, B0); PG8_MMA(1, 1, At, B1); PG8_BAR; PG8_SCHED;
;             PG8_LDB(B0, 1, 0); PG8_LDB(B1, 1, 1); PG8_SCHED; PG8_LDA(At, 1, 0); PG8_STAGE(PG8_SA(0, 1), a2 + hstep, voffA);
;             PG8_WAIT_V(8); PG8_WAIT_L(0); PG8_BAR; PG8_MMA(0, 0, At, B0); PG8_MMA(0, 1, At, B1); PG8_BAR; PG8_SCHED;
.Lhb_5:
	s_mov_b32 m0, s97
	v_lshl_add_u64 v[244:245], s[60:61], 0, v[184:185]
	ds_read_b128 v[192:195], v222 offset:16384
	ds_read_b128 v[196:199], v222 offset:17408
	ds_read_b128 v[200:203], v222 offset:18432
	ds_read_b128 v[224:227], v222 offset:19456
	ds_read_b128 v[228:231], v222 offset:20480
	ds_read_b128 v[232:235], v222 offset:21504
	ds_read_b128 v[236:239], v222 offset:22528
	ds_read_b128 v[240:243], v222 offset:23552
	global_load_lds_dwordx4 v[244:245], off
	v_lshl_add_u64 v[246:247], s[60:61], 0, v[180:181]
	s_mov_b32 m0, s84
	v_lshl_add_u64 v[212:213], s[62:63], 0, v[184:185]
	global_load_lds_dwordx4 v[246:247], off
	s_mov_b32 m0, s4
	v_lshl_add_u64 v[172:173], s[58:59], 0, v[182:183]
	global_load_lds_dwordx4 v[212:213], off
	v_lshl_add_u64 v[212:213], s[62:63], 0, v[180:181]
	s_mov_b32 m0, s5
	s_nop 0
	global_load_lds_dwordx4 v[212:213], off
	v_lshl_add_u64 v[212:213], s[58:59], 0, v[186:187]
	s_mov_b32 m0, s96
	s_nop 0
	global_load_lds_dwordx4 v[212:213], off
	s_mov_b32 m0, s71
	s_nop 0
	global_load_lds_dwordx4 v[172:173], off
	s_waitcnt vmcnt(8)
	s_waitcnt lgkmcnt(0)
	s_cmp_lg_u64 s[10:11], 0
	s_cbranch_scc1 .Lhb_2
	s_barrier
.Lhb_2:
	s_setprio 1
	s_waitcnt lgkmcnt(0)
	v_mfma_f32_16x16x32_bf16 v[62:65], v[136:139], v[192:195], v[62:65]
	v_mfma_f32_16x16x32_bf16 v[58:61], v[144:147], v[192:195], v[58:61]
	v_mfma_f32_16x16x32_bf16 v[46:49], v[136:139], v[200:203], v[46:49]
	v_mfma_f32_16x16x32_bf16 v[42:45], v[144:147], v[200:203], v[42:45]
	v_mfma_f32_16x16x32_bf16 v[30:33], v[136:139], v[228:231], v[30:33]
	v_mfma_f32_16x16x32_bf16 v[26:29], v[144:147], v[228:231], v[26:29]
	v_mfma_f32_16x16x32_bf16 v[14:17], v[136:139], v[236:239], v[14:17]
	v_mfma_f32_16x16x32_bf16 v[10:13], v[144:147], v[236:239], v[10:13]
	s_setprio 2
	v_mfma_f32_16x16x32_bf16 v[62:65], v[140:143], v[196:199], v[62:65]
	v_mfma_f32_16x16x32_bf16 v[58:61], v[148:151], v[196:199], v[58:61]
	v_mfma_f32_16x16x32_bf16 v[46:49], v[140:143], v[224:227], v[46:49]
	v_mfma_f32_16x16x32_bf16 v[42:45], v[148:151], v[224:227], v[42:45]
	v_mfma_f32_16x16x32_bf16 v[30:33], v[140:143], v[232:235], v[30:33]
	v_mfma_f32_16x16x32_bf16 v[26:29], v[148:151], v[232:235], v[26:29]
	v_mfma_f32_16x16x32_bf16 v[14:17], v[140:143], v[240:243], v[14:17]
	v_mfma_f32_16x16x32_bf16 v[10:13], v[148:151], v[240:243], v[10:13]
	v_mfma_f32_16x16x32_bf16 v[54:57], v[152:155], v[192:195], v[54:57]
	v_mfma_f32_16x16x32_bf16 v[50:53], v[160:163], v[192:195], v[50:53]
	v_mfma_f32_16x16x32_bf16 v[38:41], v[152:155], v[200:203], v[38:41]
	v_mfma_f32_16x16x32_bf16 v[34:37], v[160:163], v[200:203], v[34:37]
	s_setprio 3
	v_mfma_f32_16x16x32_bf16 v[22:25], v[152:155], v[228:231], v[22:25]
	v_mfma_f32_16x16x32_bf16 v[18:21], v[160:163], v[228:231], v[18:21]
	v_mfma_f32_16x16x32_bf16 v[6:9], v[152:155], v[236:239], v[6:9]
	v_mfma_f32_16x16x32_bf16 v[2:5], v[160:163], v[236:239], v[2:5]
	v_mfma_f32_16x16x32_bf16 v[54:57], v[156:159], v[196:199], v[54:57]
	v_mfma_f32_16x16x32_bf16 v[50:53], v[164:167], v[196:199], v[50:53]
	v_mfma_f32_16x16x32_bf16 v[38:41], v[156:159], v[224:227], v[38:41]
	v_mfma_f32_16x16x32_bf16 v[34:37], v[164:167], v[224:227], v[34:37]
	v_mfma_f32_16x16x32_bf16 v[22:25], v[156:159], v[232:235], v[22:25]
	v_mfma_f32_16x16x32_bf16 v[18:21], v[164:167], v[232:235], v[18:21]
	v_mfma_f32_16x16x32_bf16 v[6:9], v[156:159], v[240:243], v[6:9]
	v_mfma_f32_16x16x32_bf16 v[2:5], v[164:167], v[240:243], v[2:5]
	s_setprio 0
	s_cmp_eq_u64 s[10:11], 0
	s_cbranch_scc1 .Lhb_6
	s_barrier
.Lhb_6:
	v_add_u32_e32 v148, s1, v221
	v_add_u32_e32 v164, s47, v221
	ds_read_b128 v[136:139], v148
	ds_read_b128 v[140:143], v148 offset:1024
	ds_read_b128 v[144:147], v148 offset:2048
	ds_read_b128 v[148:151], v148 offset:3072
	ds_read_b128 v[152:155], v164
	ds_read_b128 v[156:159], v164 offset:1024
	ds_read_b128 v[160:163], v164 offset:2048
	ds_read_b128 v[164:167], v164 offset:3072
	s_mov_b32 m0, s33
	v_lshl_add_u64 v[168:169], s[56:57], 0, v[186:187]
	ds_read_b128 v[192:195], v222 offset:32768
	ds_read_b128 v[196:199], v222 offset:33792
	ds_read_b128 v[200:203], v222 offset:34816
	ds_read_b128 v[224:227], v222 offset:35840
	ds_read_b128 v[228:231], v222 offset:36864
	ds_read_b128 v[232:235], v222 offset:37888
	ds_read_b128 v[236:239], v222 offset:38912
	ds_read_b128 v[240:243], v222 offset:39936
	global_load_lds_dwordx4 v[168:169], off
	v_lshl_add_u64 v[168:169], s[56:57], 0, v[182:183]
	s_mov_b32 m0, s30
	s_nop 0
	global_load_lds_dwordx4 v[168:169], off
	s_waitcnt vmcnt(8)
	s_waitcnt lgkmcnt(0)
	s_cmp_lg_u64 s[10:11], 0
	s_cbranch_scc1 .Lhb_3
	s_barrier

; #define PG8_STAGE(bufoff, gbase, voff) do { _Pragma("unroll") for (int _i = 0; _i < 2; ++_i) \
;         __builtin_amdgcn_global_load_lds((const unsigned*)((const char*)(gbase) + (voff)[_i]), (PG8_LAS unsigned*)(lds + (bufoff) + ldsw + _i * 8192), 16, 0, AUX_A); } while (0)
; #define PG8_STAGEB(bufoff, gbase, voff) do { _Pragma("unroll") for (int _i = 0; _i < 2; ++_i) \
;         __builtin_amdgcn_global_load_lds((const unsigned*)((const char*)(gbase) + (voff)[_i]), (PG8_LAS unsigned*)(lds + (bufoff) + ldsw + _i * 8192), 16, 0, AUX_B); } while (0)
; #define PG8_LDA(dst, b, h) do { _Pragma("unroll") for (int m = 0; m < 4; ++m) _Pragma("unroll") for (int k = 0; k < 2; ++k) dst[m][k] = *(const PG8_LAS bf16x8*)(lds + PG8_SA(b, h) + aoff + m * 2048 + k * 1024); } while (0)
; #define PG8_MMA(ai, bj, At, Bt) do { __builtin_amdgcn_s_setprio(1); _Pragma("unroll") for (int m = 0; m < 4; ++m) _Pragma("unroll") for (int n = 0; n < 2; ++n) _Pragma("unroll") for (int k = 0; k < 2; ++k) \
;         acc[ai][bj][m][n] = __builtin_amdgcn_mfma_f32_16x16x32_bf16(Bt[n][k], At[m][k], acc[ai][bj][m][n], 0, 0, 0); __builtin_amdgcn_s_setprio(0); } while (0)
; #define PG8_WAIT_V(n) asm volatile("s_waitcnt vmcnt(" #n ")" ::: "memory")
; #define PG8_WAIT_L(n) asm volatile("s_waitcnt lgkmcnt(" #n ")" ::: "memory")
; #define PG8_BAR __builtin_amdgcn_s_barrier()
; #define PG8_SCHED __builtin_amdgcn_sched_barrier(0)
; template <class Epi, class Sched, bool ALIGN_EPI = false, bool SP2 = false>
; __device__ __forceinline__ void gemm_phase(PG8_LAS unsigned char* lds, const Gemm g, const Sched& S, const Epi& E) {
;     ...
;             PG8_LDA(At, 1, 1); PG8_STAGEB(PG8_SB(1, 0), b3, voffB); PG8_STAGEB(PG8_SB(1, 1), b3 + hstep, voffB); PG8_STAGE(PG8_SA(1, 0), a3, voffA);
;             PG8_WAIT_V(8); PG8_WAIT_L(0); PG8_BAR; PG8_MMA(1, 0, At, B0); PG8_MMA(1, 1, At, B1); PG8_BAR; PG8_SCHED;
.Lhb_7:
	s_mov_b32 m0, s0
	v_lshl_add_u64 v[168:169], v[244:245], 0, s[76:77]
	ds_read_b128 v[192:195], v222 offset:49152
	ds_read_b128 v[196:199], v222 offset:50176
	ds_read_b128 v[200:203], v222 offset:51200
	ds_read_b128 v[224:227], v222 offset:52224
	ds_read_b128 v[228:231], v222 offset:53248
	ds_read_b128 v[232:235], v222 offset:54272
	ds_read_b128 v[236:239], v222 offset:55296
	ds_read_b128 v[240:243], v222 offset:56320
	global_load_lds_dwordx4 v[168:169], off
	v_lshl_add_u64 v[168:169], v[246:247], 0, s[76:77]
	s_mov_b32 m0, s89
	s_nop 0
	global_load_lds_dwordx4 v[168:169], off
	v_lshl_add_u64 v[168:169], s[42:43], 0, v[184:185]
	s_mov_b32 m0, s46
	s_nop 0
	global_load_lds_dwordx4 v[168:169], off
	v_lshl_add_u64 v[168:169], s[42:43], 0, v[180:181]
	s_mov_b32 m0, s92
	s_nop 0
	global_load_lds_dwordx4 v[168:169], off
	v_lshl_add_u64 v[168:169], v[212:213], 0, s[76:77]
	s_mov_b32 m0, s90
	s_nop 0
	global_load_lds_dwordx4 v[168:169], off
	v_lshl_add_u64 v[168:169], v[172:173], 0, s[76:77]
	s_mov_b32 m0, s91
	s_nop 0
	global_load_lds_dwordx4 v[168:169], off
	s_waitcnt vmcnt(8)
	s_waitcnt lgkmcnt(0)
	s_cmp_lg_u64 s[10:11], 0
	s_cbranch_scc1 .Lhb_4
	s_barrier

; #define PG8_BAR __builtin_amdgcn_s_barrier()
; template <class Epi, class Sched, bool ALIGN_EPI = false, bool SP2 = false>
; __device__ __forceinline__ void gemm_phase(PG8_LAS unsigned char* lds, const Gemm g, const Sched& S, const Epi& E) {
;     ...
;         for (int t = 0; t < nt; t += 2) {
;             const bool last = (t == nt - 2);
;     ...
;         if constexpr (ALIGN_EPI) { if (wr == 0) PG8_BAR; }
.Lhb_8:
	v_lshl_add_u64 v[132:133], v[132:133], 0, s[86:87]
	v_lshl_add_u64 v[134:135], v[134:135], 0, s[86:87]
	s_cmp_gt_u32 s81, 31
	s_mov_b32 s29, s81
	s_cbranch_scc0 .LBB0_270
	s_and_b64 vcc, exec, s[10:11]
	s_cbranch_vccz .LBB0_273

; #define PG8_BAR __builtin_amdgcn_s_barrier()
; template <class Epi, class Sched, bool ALIGN_EPI = false, bool SP2 = false>
; __device__ __forceinline__ void gemm_phase(PG8_LAS unsigned char* lds, const Gemm g, const Sched& S, const Epi& E) {
;     ...
;         cur = nxt; cA = nA; cB = nB; ++ui;
;         if constexpr (ALIGN_EPI) { if (wr == 1) PG8_BAR; }
.LBB0_588:
	s_andn2_b64 vcc, exec, s[26:27]
	s_mov_b64 s[36:37], -1
	s_cbranch_vccnz .LBB0_266
	v_readlane_b32 s0, v254, 58
	v_readlane_b32 s1, v254, 59
	s_andn2_b64 vcc, exec, s[0:1]
	s_cbranch_vccnz .LBB0_265
	s_branch .LBB0_265

;     __host__ __device__ void init(int M, int N, int K, int G_, int c_) { so.init(M, N, K, G_, c_); nN = N / BM; nkt = K / BK; G = G_; c = c_; }
;     __host__ __device__ void init(int M, int N, int K, int G_, int c_, int sj0_) { so.init(M, N, K, G_, c_); G = G_; c = c_; nkt = K / BK; sj0 = sj0_; }
; #define PG8_WAIT_V(n) asm volatile("s_waitcnt vmcnt(" #n ")" ::: "memory")
; #define PG8_BAR __builtin_amdgcn_s_barrier()
; template <class Epi, class Sched, bool ALIGN_EPI = false, bool SP2 = false>
; __device__ __forceinline__ void gemm_phase(PG8_LAS unsigned char* lds, const Gemm g, const Sched& S, const Epi& E) {
;     ...
;     const char* cA = (const char*)g.A + (size_t)cur.pm * tstep + (size_t)cur.kt0 * kstep; const char* cB = (const char*)g.Bt + (size_t)cur.pn * tstep + (size_t)cur.kt0 * kstep;
;     S.a_ready(cur);
;     ...
;     { const int rot0 = cur.krot, nt0 = cur.nkt; const char* sA0 = PG8_KP(cA, 0, rot0, nt0); const char* sA1 = PG8_KP(cA, 1, rot0, nt0); const char* sB0 = PG8_KP(cB, 0, rot0, nt0); const char* sB1 = PG8_KP(cB, 1, rot0, nt0);
;     if constexpr (SP2) {
;         PG8_STAGEB(PG8_SB(0, 0), sB0, voffB); PG8_STAGEB(PG8_SB(0, 1), sB0 + hstep, voffB); PG8_STAGE(PG8_SA(0, 0), sA0, voffA); PG8_STAGE(PG8_SA(0, 1), sA0 + hstep, voffA);
;         if (wr == 1) PG8_BAR;
;         PG8_WAIT_V(2); PG8_BAR;
;         PG8_STAGEB(PG8_SB(1, 0), sB1, voffB); PG8_STAGE(PG8_SA(1, 0), sA1, voffA); PG8_STAGEB(PG8_SB(1, 1), sB1 + hstep, voffB);
;         PG8_WAIT_V(6); PG8_BAR;
;     } else {
;         PG8_STAGEB(PG8_SB(0, 0), sB0, voffB); PG8_STAGE(PG8_SA(0, 0), sA0, voffA); PG8_STAGEB(PG8_SB(0, 1), sB0 + hstep, voffB); PG8_STAGE(PG8_SA(0, 1), sA0 + hstep, voffA);
;         if (wr == 1) PG8_BAR;
;         PG8_WAIT_V(4); PG8_BAR;
;         PG8_STAGEB(PG8_SB(1, 0), sB1, voffB); PG8_STAGE(PG8_SA(1, 0), sA1, voffA); PG8_STAGEB(PG8_SB(1, 1), sB1 + hstep, voffB);
;         PG8_WAIT_V(6); PG8_BAR;
;     }
; __global__ void __launch_bounds__(NWAVES * 64, 2) enc_fwd(Args args) {
;     ...
;         if (EN(5) && IN(pb + 4)) { for (int rep = 0; rep < NREP(5); ++rep) { FRESH_WS(); pg8::Gemm g{Z, (const bf16*)(ws + WS_WGLU + l * SZ_WGLU), NTOK, 1024, 1024}; pg8::PanelOrder S; S.init(NTOK, 1024, 1024, G, bx);
;             pg8::EpiGLU E{Z, SO, args.in[22] + (size_t)l * 1024};
;             pg8::gemm_phase<pg8::EpiGLU, pg8::PanelOrder, PG8_ALIGN, PG8_SP2>(lds + RING_OFF, g, S, E);
.LBB0_918:
	v_readlane_b32 s0, v254, 53
	v_readlane_b32 s1, v254, 54
	s_mov_b32 s1, s79
	v_writelane_b32 v254, s0, 53
	s_andn2_b64 vcc, exec, s[4:5]
	s_nop 0
	v_writelane_b32 v254, s1, 54
	s_cbranch_vccnz .LBB0_943
	v_ashrrev_i32_e32 v2, 31, v13
	v_lshrrev_b32_e32 v2, 26, v2
	v_add_u32_e32 v2, v13, v2
	v_ashrrev_i32_e32 v10, 6, v2
	v_bfe_i32 v2, v13, 27, 1
	v_lshlrev_b32_e32 v1, 4, v13
	v_lshrrev_b32_e32 v2, 22, v2
	v_add_u32_e32 v2, v1, v2
	v_and_b32_e32 v2, 0xfffffc00, v2
	v_sub_u32_e32 v2, v1, v2
	v_readlane_b32 s2, v254, 53
	v_lshrrev_b32_e32 v3, 4, v2
	v_readlane_b32 s3, v254, 54
	v_bitop3_b32 v2, v3, v2, 32 bitop3:0x6c
	s_lshl_b64 s[0:1], s[2:3], 21
	v_ashrrev_i32_e32 v4, 31, v2
	s_add_u32 s4, s34, 0x27780000
	v_lshrrev_b32_e32 v4, 26, v4
	s_addc_u32 s5, s35, 0
	v_add_u32_e32 v4, v2, v4
	s_add_u32 s0, s34, s0
	v_lshlrev_b32_e32 v3, 3, v10
	v_ashrrev_i32_e32 v11, 6, v4
	v_and_b32_e32 v4, 0xc0, v4
	s_addc_u32 s1, s35, s1
	v_and_b32_e32 v3, -16, v3
	v_sub_u32_e32 v2, v2, v4
	s_add_u32 s30, s0, 0x7800000
	v_add_u32_e32 v3, v11, v3
	v_ashrrev_i16_sdwa v2, v207, sext(v2) dst_sel:DWORD dst_unused:UNUSED_PAD src0_sel:DWORD src1_sel:BYTE_0
	s_addc_u32 s31, s1, 0
	v_lshlrev_b32_e32 v5, 5, v10
	v_bfe_i32 v12, v2, 0, 16
	v_lshlrev_b32_e32 v2, 1, v3
	v_lshrrev_b32_e32 v4, 2, v3
	v_and_b32_e32 v6, 3, v11
	s_mov_b32 s1, 0x1fffe0
	v_and_b32_e32 v5, 32, v5
	v_and_b32_e32 v2, 24, v2
	v_and_b32_e32 v4, 4, v4
	v_and_or_b32 v6, v3, s1, v6
	v_or3_b32 v2, v6, v4, v2
	v_add_lshl_u32 v4, v5, v12, 1
	v_add_u32_e32 v1, 0x2000, v1
	v_lshl_add_u32 v150, v2, 11, v4
	v_ashrrev_i32_e32 v2, 31, v1
	v_lshrrev_b32_e32 v2, 22, v2
	v_add_u32_e32 v2, v1, v2
	v_ashrrev_i32_e32 v14, 10, v2
	v_mul_i32_i24_e32 v2, 0x400, v14
	v_sub_u32_e32 v1, v1, v2
	v_lshrrev_b32_e32 v2, 4, v1
	v_bitop3_b32 v1, v2, v1, 32 bitop3:0x6c
	v_lshl_add_u32 v148, v3, 11, v4
	v_ashrrev_i32_e32 v3, 31, v1
	v_lshrrev_b32_e32 v3, 26, v3
	v_lshlrev_b32_e32 v2, 3, v14
	v_add_u32_e32 v3, v1, v3
	v_and_b32_e32 v2, -16, v2
	v_ashrrev_i32_e32 v15, 6, v3
	v_add_u32_e32 v2, v15, v2
	v_and_b32_e32 v5, 3, v15
	v_and_or_b32 v5, v2, s1, v5
	s_ashr_i32 s1, s12, 6
	s_ashr_i32 s43, s42, 31
	s_ashr_i32 s25, s24, 31
	s_ashr_i32 s0, s12, 8
	s_lshl_b32 s33, s1, 10
	s_lshl_b64 s[6:7], s[42:43], 19
	s_lshl_b64 s[8:9], s[24:25], 19
	v_and_b32_e32 v3, 0xc0, v3
	s_add_u32 s26, s30, s8
	v_sub_u32_e32 v1, v1, v3
	s_addc_u32 s27, s31, s9
	s_add_i32 s25, s33, 0
	v_ashrrev_i16_sdwa v1, v207, sext(v1) dst_sel:DWORD dst_unused:UNUSED_PAD src0_sel:DWORD src1_sel:BYTE_0
	s_add_i32 m0, s25, 0x10000
	v_lshlrev_b32_e32 v4, 5, v14
	v_bfe_i32 v16, v1, 0, 16
	v_lshlrev_b32_e32 v1, 1, v2
	v_lshrrev_b32_e32 v3, 2, v2
	global_load_lds_dwordx4 v150, s[26:27]
	s_add_i32 m0, s25, 0x12000
	v_and_b32_e32 v4, 32, v4
	v_and_b32_e32 v1, 24, v1
	v_and_b32_e32 v3, 4, v3
	s_add_u32 s64, s4, s6
	v_or3_b32 v1, v5, v3, v1
	v_add_lshl_u32 v3, v4, v16, 1
	s_addc_u32 s65, s5, s7
	v_lshl_add_u32 v154, v1, 11, v3
	s_add_u32 s6, s26, 0x40000
	global_load_lds_dwordx4 v154, s[26:27]
	s_addc_u32 s7, s27, 0
	s_add_i32 m0, s25, 0x14000
	s_add_i32 s62, s25, 0x2000
	global_load_lds_dwordx4 v150, s[6:7]
	s_add_i32 m0, s25, 0x16000
	v_lshl_add_u32 v152, v2, 11, v3
	global_load_lds_dwordx4 v154, s[6:7]
	s_mov_b32 m0, s25
	s_add_u32 s6, s64, 0x40000
	global_load_lds_dwordx4 v148, s[64:65]
	s_mov_b32 m0, s62
	s_addc_u32 s7, s65, 0
	s_add_i32 s63, s25, 0x4000
	global_load_lds_dwordx4 v152, s[64:65]
	s_mov_b32 m0, s63
	s_add_i32 s69, s25, 0x6000
	global_load_lds_dwordx4 v148, s[6:7]
	s_mov_b32 m0, s69
	v_mov_b32_e32 v151, v98
	global_load_lds_dwordx4 v152, s[6:7]
	v_mov_b32_e32 v155, v98
	v_mov_b32_e32 v149, v98
	v_mov_b32_e32 v153, v98
	s_cmp_eq_u32 s0, 1
	v_lshl_add_u64 v[8:9], s[26:27], 0, v[150:151]
	v_lshl_add_u64 v[6:7], s[26:27], 0, v[154:155]
	v_lshl_add_u64 v[2:3], s[64:65], 0, v[148:149]
	s_cselect_b64 s[6:7], -1, 0
	s_cmp_lg_u32 s0, 1
	v_lshl_add_u64 v[4:5], s[64:65], 0, v[152:153]
	s_cbranch_scc1 .LBB0_921
.LBB0_921:
	v_readlane_b32 s44, v249, 34
	s_lshl_b64 s[8:9], s[2:3], 12
	v_readlane_b32 s56, v249, 46
	v_readlane_b32 s57, v249, 47
	s_add_u32 s8, s56, s8
	v_lshrrev_b32_e32 v18, 1, v13
	s_addc_u32 s9, s57, s9
	v_and_b32_e32 v18, 24, v18
	s_add_u32 s10, s34, 0x28980000
	v_and_b32_e32 v17, 15, v13
	v_lshlrev_b32_e32 v19, 1, v18
	v_lshlrev_b32_e32 v13, 2, v13
	s_addc_u32 s11, s35, 0
	v_lshl_or_b32 v1, s0, 6, v17
	v_lshl_or_b32 v17, v17, 6, v19
	s_lshl_b32 s0, s0, 13
	v_and_b32_e32 v13, 32, v13
	v_bitop3_b32 v19, v17, s0, v13 bitop3:0xde
	s_lshl_b32 s0, s1, 5
	s_and_b32 s2, s0, 0x60
	s_add_i32 m0, s25, 0x18000
	v_lshl_add_u64 v[8:9], v[8:9], 0, s[76:77]
	s_lshl_b32 s0, s2, 7
	s_waitcnt vmcnt(2)
	s_barrier
	global_load_lds_dwordx4 v[8:9], off
	v_lshl_add_u64 v[6:7], v[6:7], 0, s[76:77]
	s_add_i32 m0, s25, 0x1a000
	s_add_i32 s70, s25, 0x8000
	s_add_i32 s71, s25, 0xa000
	v_bitop3_b32 v99, v17, s0, v13 bitop3:0xde
	global_load_lds_dwordx4 v[6:7], off
	v_lshl_add_u64 v[2:3], v[2:3], 0, s[76:77]
	s_mov_b32 m0, s70
	s_add_u32 s0, s26, 0x40080
	global_load_lds_dwordx4 v[2:3], off
	v_lshl_add_u64 v[2:3], v[4:5], 0, s[76:77]
	s_mov_b32 m0, s71
	s_addc_u32 s1, s27, 0
	global_load_lds_dwordx4 v[2:3], off
	s_add_i32 m0, s25, 0x1c000
	v_lshl_add_u64 v[2:3], s[0:1], 0, v[150:151]
	global_load_lds_dwordx4 v[2:3], off
	v_lshl_add_u64 v[2:3], s[0:1], 0, v[154:155]
	s_add_i32 m0, s25, 0x1e000
	v_readlane_b32 s45, v249, 35
	global_load_lds_dwordx4 v[2:3], off
	v_lshlrev_b32_e32 v2, 14, v14
	v_and_b32_e32 v2, 0xffff8000, v2
	v_lshl_add_u32 v2, v15, 11, v2
	v_and_b32_e32 v3, 1, v14
	v_lshl_or_b32 v2, v3, 6, v2
	v_lshl_add_u32 v156, v16, 1, v2
	v_lshlrev_b32_e32 v2, 14, v10
	v_and_b32_e32 v2, 0xffff8000, v2
	s_waitcnt vmcnt(6)
	v_lshl_add_u32 v2, v11, 11, v2
	v_and_b32_e32 v3, 1, v10
	v_readlane_b32 s48, v249, 38
	v_readlane_b32 s49, v249, 39
	v_readlane_b32 s50, v249, 40
	v_readlane_b32 s51, v249, 41
	s_cmpk_lt_u32 s12, 0x100
	v_lshl_or_b32 v2, v3, 6, v2
	s_cselect_b64 s[12:13], -1, 0
	v_or_b32_e32 v164, s2, v18
	v_mov_b32_e32 v157, v98
	v_lshl_add_u32 v158, v12, 1, v2
	v_mov_b32_e32 v159, v98
	s_mov_b32 s75, 0
	v_add_u32_e32 v165, 0, v19
	v_readlane_b32 s3, v252, 31
	v_readlane_b32 s44, v252, 33
	v_readlane_b32 s45, v252, 11
	v_readlane_b32 s48, v252, 12
	s_mov_b32 s49, 0x40000
	s_mov_b32 s50, 0x48000
	s_mov_b32 s51, 0x50000
	s_mov_b32 s66, 0x58000
	v_readlane_b32 s46, v249, 36
	v_readlane_b32 s47, v249, 37
	v_readlane_b32 s52, v249, 42
	v_readlane_b32 s53, v249, 43
	v_readlane_b32 s54, v249, 44
	v_readlane_b32 s55, v249, 45
	v_readlane_b32 s58, v249, 48
	v_readlane_b32 s59, v249, 49
	s_barrier
	s_branch .LBB0_924

; #define PG8_STAGE(bufoff, gbase, voff) do { _Pragma("unroll") for (int _i = 0; _i < 2; ++_i) \
;         __builtin_amdgcn_global_load_lds((const unsigned*)((const char*)(gbase) + (voff)[_i]), (PG8_LAS unsigned*)(lds + (bufoff) + ldsw + _i * 8192), 16, 0, AUX_A); } while (0)
; #define PG8_STAGEB(bufoff, gbase, voff) do { _Pragma("unroll") for (int _i = 0; _i < 2; ++_i) \
;         __builtin_amdgcn_global_load_lds((const unsigned*)((const char*)(gbase) + (voff)[_i]), (PG8_LAS unsigned*)(lds + (bufoff) + ldsw + _i * 8192), 16, 0, AUX_B); } while (0)
; #define PG8_LDA(dst, b, h) do { _Pragma("unroll") for (int m = 0; m < 4; ++m) _Pragma("unroll") for (int k = 0; k < 2; ++k) dst[m][k] = *(const PG8_LAS bf16x8*)(lds + PG8_SA(b, h) + aoff + m * 2048 + k * 1024); } while (0)
; #define PG8_LDB(dst, b, h) do { _Pragma("unroll") for (int n = 0; n < 2; ++n) _Pragma("unroll") for (int k = 0; k < 2; ++k) dst[n][k] = *(const PG8_LAS bf16x8*)(lds + PG8_SB(b, h) + boff + n * 2048 + k * 1024); } while (0)
; #define PG8_MMA(ai, bj, At, Bt) do { __builtin_amdgcn_s_setprio(1); _Pragma("unroll") for (int m = 0; m < 4; ++m) _Pragma("unroll") for (int n = 0; n < 2; ++n) _Pragma("unroll") for (int k = 0; k < 2; ++k) \
;         acc[ai][bj][m][n] = __builtin_amdgcn_mfma_f32_16x16x32_bf16(Bt[n][k], At[m][k], acc[ai][bj][m][n], 0, 0, 0); __builtin_amdgcn_s_setprio(0); } while (0)
; #define PG8_WAIT_V(n) asm volatile("s_waitcnt vmcnt(" #n ")" ::: "memory")
; #define PG8_WAIT_L(n) asm volatile("s_waitcnt lgkmcnt(" #n ")" ::: "memory")
; #define PG8_BAR __builtin_amdgcn_s_barrier()
; #define PG8_SCHED __builtin_amdgcn_sched_barrier(0)
; template <class Epi, class Sched, bool ALIGN_EPI = false, bool SP2 = false>
; __device__ __forceinline__ void gemm_phase(PG8_LAS unsigned char* lds, const Gemm g, const Sched& S, const Epi& E) {
;     ...
;             PG8_LDB(B0, 0, 0); PG8_LDB(B1, 0, 1); PG8_SCHED; PG8_LDA(At, 0, 0); PG8_STAGE(PG8_SA(1, 1), a1 + hstep, voffA);
;             PG8_WAIT_V(8); PG8_WAIT_L(0); PG8_BAR; PG8_MMA(0, 0, At, B0); PG8_MMA(0, 1, At, B1); PG8_BAR; PG8_SCHED;
;             PG8_LDA(At, 0, 1); PG8_STAGEB(PG8_SB(0, 0), b2, voffB); PG8_STAGEB(PG8_SB(0, 1), b2 + hstep, voffB); PG8_STAGE(PG8_SA(0, 0), a2, voffA);
;             PG8_WAIT_V(8); PG8_WAIT_L(0); PG8_BAR; PG8_MMA(1, 0, At, B0); PG8_MMA(1, 1, At, B1); PG8_BAR; PG8_SCHED;
.LBB0_936:
	s_add_i32 s81, s29, 2
	s_cmp_lt_u32 s29, 14
	s_cselect_b32 s0, 0, -16
	s_add_i32 s0, s81, s0
	s_ashr_i32 s1, s0, 31
	s_lshl_b64 s[0:1], s[0:1], 7
	s_add_u32 s2, s64, s0
	s_addc_u32 s46, s65, s1
	s_add_u32 s0, s26, s0
	s_addc_u32 s1, s27, s1
	s_cmp_eq_u32 s29, 14
	s_cselect_b32 s57, s15, s46
	s_cselect_b32 s56, s17, s2
	s_cselect_b32 s59, s43, s1
	s_cselect_b32 s58, s78, s0
	s_add_i32 s2, 0, 0x10000
	s_add_i32 s83, s2, s33
	s_add_i32 s46, 0, 0x14000
	s_add_i32 m0, s25, 0xc000
	s_add_i32 s82, s25, 0xe000
	s_add_i32 s84, s83, 0x2000
	s_add_u32 s60, s58, 0x40000
	s_addc_u32 s61, s59, 0
	s_add_i32 s88, s46, s33
	v_add_u32_e32 v160, s2, v99
	v_add_u32_e32 v166, s46, v99
	s_add_i32 s89, s88, 0x2000
	s_add_i32 s90, 0, 0x18000
	s_add_i32 s91, 0, 0x1c000
	ds_read_b128 v[22:25], v160
	ds_read_b128 v[34:37], v160 offset:1024
	ds_read_b128 v[38:41], v160 offset:2048
	ds_read_b128 v[160:163], v160 offset:3072
	ds_read_b128 v[180:183], v166
	ds_read_b128 v[184:187], v166 offset:1024
	ds_read_b128 v[188:191], v166 offset:2048
	ds_read_b128 v[192:195], v166 offset:3072
	s_add_u32 s54, s56, 0x40000
	s_addc_u32 s55, s57, 0
	s_add_i32 s1, s90, s33
	s_add_i32 s0, s1, 0x2000
	s_add_u32 s52, s58, 0x40080
	s_addc_u32 s53, s59, 0
	s_add_i32 s47, s91, s33
	s_add_i32 s46, s47, 0x2000
	ds_read_b128 v[196:199], v165
	ds_read_b128 v[200:203], v165 offset:1024
	ds_read_b128 v[222:225], v165 offset:2048
	ds_read_b128 v[226:229], v165 offset:3072
	ds_read_b128 v[230:233], v165 offset:4096
	ds_read_b128 v[234:237], v165 offset:5120
	ds_read_b128 v[238:241], v165 offset:6144
	ds_read_b128 v[242:245], v165 offset:7168
	global_load_lds_dwordx4 v[16:17], off
	s_mov_b32 m0, s82
	s_nop 0
	global_load_lds_dwordx4 v[14:15], off
	s_waitcnt vmcnt(8)
	s_waitcnt lgkmcnt(0)
	s_cmp_lg_u64 s[12:13], 0
	s_cbranch_scc1 .Lhb_9
	s_barrier
.Lhb_9:
	s_setprio 1
	s_waitcnt lgkmcnt(0)
	v_mfma_f32_16x16x32_bf16 v[144:147], v[22:25], v[196:199], v[144:147]
	v_mfma_f32_16x16x32_bf16 v[140:143], v[38:41], v[196:199], v[140:143]
	v_mfma_f32_16x16x32_bf16 v[128:131], v[22:25], v[222:225], v[128:131]
	v_mfma_f32_16x16x32_bf16 v[124:127], v[38:41], v[222:225], v[124:127]
	v_mfma_f32_16x16x32_bf16 v[112:115], v[22:25], v[230:233], v[112:115]
	v_mfma_f32_16x16x32_bf16 v[108:111], v[38:41], v[230:233], v[108:111]
	v_mfma_f32_16x16x32_bf16 v[94:97], v[22:25], v[238:241], v[94:97]
	v_mfma_f32_16x16x32_bf16 v[90:93], v[38:41], v[238:241], v[90:93]
	s_setprio 2
	v_mfma_f32_16x16x32_bf16 v[144:147], v[34:37], v[200:203], v[144:147]
	v_mfma_f32_16x16x32_bf16 v[140:143], v[160:163], v[200:203], v[140:143]
	v_mfma_f32_16x16x32_bf16 v[128:131], v[34:37], v[226:229], v[128:131]
	v_mfma_f32_16x16x32_bf16 v[124:127], v[160:163], v[226:229], v[124:127]
	v_mfma_f32_16x16x32_bf16 v[112:115], v[34:37], v[234:237], v[112:115]
	v_mfma_f32_16x16x32_bf16 v[108:111], v[160:163], v[234:237], v[108:111]
	v_mfma_f32_16x16x32_bf16 v[94:97], v[34:37], v[242:245], v[94:97]
	v_mfma_f32_16x16x32_bf16 v[90:93], v[160:163], v[242:245], v[90:93]
	v_mfma_f32_16x16x32_bf16 v[136:139], v[180:183], v[196:199], v[136:139]
	v_mfma_f32_16x16x32_bf16 v[132:135], v[188:191], v[196:199], v[132:135]
	v_mfma_f32_16x16x32_bf16 v[120:123], v[180:183], v[222:225], v[120:123]
	v_mfma_f32_16x16x32_bf16 v[116:119], v[188:191], v[222:225], v[116:119]
	s_setprio 3
	v_mfma_f32_16x16x32_bf16 v[104:107], v[180:183], v[230:233], v[104:107]
	v_mfma_f32_16x16x32_bf16 v[100:103], v[188:191], v[230:233], v[100:103]
	v_mfma_f32_16x16x32_bf16 v[86:89], v[180:183], v[238:241], v[86:89]
	v_mfma_f32_16x16x32_bf16 v[82:85], v[188:191], v[238:241], v[82:85]
	v_mfma_f32_16x16x32_bf16 v[136:139], v[184:187], v[200:203], v[136:139]
	v_mfma_f32_16x16x32_bf16 v[132:135], v[192:195], v[200:203], v[132:135]
	v_mfma_f32_16x16x32_bf16 v[120:123], v[184:187], v[226:229], v[120:123]
	v_mfma_f32_16x16x32_bf16 v[116:119], v[192:195], v[226:229], v[116:119]
	v_mfma_f32_16x16x32_bf16 v[104:107], v[184:187], v[234:237], v[104:107]
	v_mfma_f32_16x16x32_bf16 v[100:103], v[192:195], v[234:237], v[100:103]
	v_mfma_f32_16x16x32_bf16 v[86:89], v[184:187], v[242:245], v[86:89]
	v_mfma_f32_16x16x32_bf16 v[82:85], v[192:195], v[242:245], v[82:85]
	s_setprio 0
	s_cmp_eq_u64 s[12:13], 0
	s_cbranch_scc1 .Lhb_13
	s_barrier
.Lhb_13:
	s_mov_b32 m0, s83
	v_lshl_add_u64 v[166:167], s[58:59], 0, v[150:151]
	ds_read_b128 v[196:199], v165 offset:16384
	ds_read_b128 v[200:203], v165 offset:17408
	ds_read_b128 v[222:225], v165 offset:18432
	ds_read_b128 v[226:229], v165 offset:19456
	ds_read_b128 v[230:233], v165 offset:20480
	ds_read_b128 v[234:237], v165 offset:21504
	ds_read_b128 v[238:241], v165 offset:22528
	ds_read_b128 v[242:245], v165 offset:23552
	global_load_lds_dwordx4 v[166:167], off
	v_lshl_add_u64 v[168:169], s[58:59], 0, v[154:155]
	s_mov_b32 m0, s84
	v_lshl_add_u64 v[172:173], s[60:61], 0, v[150:151]
	global_load_lds_dwordx4 v[168:169], off
	s_mov_b32 m0, s88
	v_lshl_add_u64 v[212:213], s[56:57], 0, v[152:153]
	global_load_lds_dwordx4 v[172:173], off
	v_lshl_add_u64 v[172:173], s[60:61], 0, v[154:155]
	s_mov_b32 m0, s89
	s_nop 0
	global_load_lds_dwordx4 v[172:173], off
	v_lshl_add_u64 v[172:173], s[56:57], 0, v[148:149]
	s_mov_b32 m0, s25
	s_nop 0
	global_load_lds_dwordx4 v[172:173], off
	s_mov_b32 m0, s62
	s_nop 0
	global_load_lds_dwordx4 v[212:213], off
	s_waitcnt vmcnt(8)
	s_waitcnt lgkmcnt(0)
	s_cmp_lg_u64 s[12:13], 0
	s_cbranch_scc1 .Lhb_10
	s_barrier
; #define PG8_STAGE(bufoff, gbase, voff) do { _Pragma("unroll") for (int _i = 0; _i < 2; ++_i) \
;         __builtin_amdgcn_global_load_lds((const unsigned*)((const char*)(gbase) + (voff)[_i]), (PG8_LAS unsigned*)(lds + (bufoff) + ldsw + _i * 8192), 16, 0, AUX_A); } while (0)
; #define PG8_STAGEB(bufoff, gbase, voff) do { _Pragma("unroll") for (int _i = 0; _i < 2; ++_i) \
;         __builtin_amdgcn_global_load_lds((const unsigned*)((const char*)(gbase) + (voff)[_i]), (PG8_LAS unsigned*)(lds + (bufoff) + ldsw + _i * 8192), 16, 0, AUX_B); } while (0)
; #define PG8_LDA(dst, b, h) do { _Pragma("unroll") for (int m = 0; m < 4; ++m) _Pragma("unroll") for (int k = 0; k < 2; ++k) dst[m][k] = *(const PG8_LAS bf16x8*)(lds + PG8_SA(b, h) + aoff + m * 2048 + k * 1024); } while (0)
; #define PG8_LDB(dst, b, h) do { _Pragma("unroll") for (int n = 0; n < 2; ++n) _Pragma("unroll") for (int k = 0; k < 2; ++k) dst[n][k] = *(const PG8_LAS bf16x8*)(lds + PG8_SB(b, h) + boff + n * 2048 + k * 1024); } while (0)
; #define PG8_MMA(ai, bj, At, Bt) do { __builtin_amdgcn_s_setprio(1); _Pragma("unroll") for (int m = 0; m < 4; ++m) _Pragma("unroll") for (int n = 0; n < 2; ++n) _Pragma("unroll") for (int k = 0; k < 2; ++k) \
;         acc[ai][bj][m][n] = __builtin_amdgcn_mfma_f32_16x16x32_bf16(Bt[n][k], At[m][k], acc[ai][bj][m][n], 0, 0, 0); __builtin_amdgcn_s_setprio(0); } while (0)
; #define PG8_WAIT_V(n) asm volatile("s_waitcnt vmcnt(" #n ")" ::: "memory")
; #define PG8_WAIT_L(n) asm volatile("s_waitcnt lgkmcnt(" #n ")" ::: "memory")
; #define PG8_BAR __builtin_amdgcn_s_barrier()
; #define PG8_SCHED __builtin_amdgcn_sched_barrier(0)
; template <class Epi, class Sched, bool ALIGN_EPI = false, bool SP2 = false>
; __device__ __forceinline__ void gemm_phase(PG8_LAS unsigned char* lds, const Gemm g, const Sched& S, const Epi& E) {
;     ...
;             PG8_WAIT_V(8); PG8_WAIT_L(0); PG8_BAR; PG8_MMA(1, 0, At, B0); PG8_MMA(1, 1, At, B1); PG8_BAR; PG8_SCHED;
;             PG8_LDB(B0, 1, 0); PG8_LDB(B1, 1, 1); PG8_SCHED; PG8_LDA(At, 1, 0); PG8_STAGE(PG8_SA(0, 1), a2 + hstep, voffA);
;             PG8_WAIT_V(8); PG8_WAIT_L(0); PG8_BAR; PG8_MMA(0, 0, At, B0); PG8_MMA(0, 1, At, B1); PG8_BAR; PG8_SCHED;
;             PG8_LDA(At, 1, 1); PG8_STAGEB(PG8_SB(1, 0), b3, voffB); PG8_STAGEB(PG8_SB(1, 1), b3 + hstep, voffB); PG8_STAGE(PG8_SA(1, 0), a3, voffA);
.Lhb_10:
	s_setprio 1
	s_waitcnt lgkmcnt(0)
	v_mfma_f32_16x16x32_bf16 v[78:81], v[22:25], v[196:199], v[78:81]
	v_mfma_f32_16x16x32_bf16 v[74:77], v[38:41], v[196:199], v[74:77]
	v_mfma_f32_16x16x32_bf16 v[62:65], v[22:25], v[222:225], v[62:65]
	v_mfma_f32_16x16x32_bf16 v[58:61], v[38:41], v[222:225], v[58:61]
	v_mfma_f32_16x16x32_bf16 v[46:49], v[22:25], v[230:233], v[46:49]
	v_mfma_f32_16x16x32_bf16 v[42:45], v[38:41], v[230:233], v[42:45]
	v_mfma_f32_16x16x32_bf16 v[18:21], v[22:25], v[238:241], v[18:21]
	v_mfma_f32_16x16x32_bf16 v[10:13], v[38:41], v[238:241], v[10:13]
	s_setprio 2
	v_mfma_f32_16x16x32_bf16 v[78:81], v[34:37], v[200:203], v[78:81]
	v_mfma_f32_16x16x32_bf16 v[74:77], v[160:163], v[200:203], v[74:77]
	v_mfma_f32_16x16x32_bf16 v[62:65], v[34:37], v[226:229], v[62:65]
	v_mfma_f32_16x16x32_bf16 v[58:61], v[160:163], v[226:229], v[58:61]
	v_mfma_f32_16x16x32_bf16 v[46:49], v[34:37], v[234:237], v[46:49]
	v_mfma_f32_16x16x32_bf16 v[42:45], v[160:163], v[234:237], v[42:45]
	v_mfma_f32_16x16x32_bf16 v[18:21], v[34:37], v[242:245], v[18:21]
	v_mfma_f32_16x16x32_bf16 v[10:13], v[160:163], v[242:245], v[10:13]
	v_mfma_f32_16x16x32_bf16 v[50:53], v[188:191], v[222:225], v[50:53]
	v_mfma_f32_16x16x32_bf16 v[30:33], v[180:183], v[230:233], v[30:33]
	v_mfma_f32_16x16x32_bf16 v[26:29], v[188:191], v[230:233], v[26:29]
	v_mfma_f32_16x16x32_bf16 v[6:9], v[180:183], v[238:241], v[6:9]
	s_setprio 3
	v_mfma_f32_16x16x32_bf16 v[2:5], v[188:191], v[238:241], v[2:5]
	v_mfma_f32_16x16x32_bf16 v[22:25], v[180:183], v[196:199], v[70:73]
	v_mfma_f32_16x16x32_bf16 v[34:37], v[188:191], v[196:199], v[66:69]
	v_mfma_f32_16x16x32_bf16 v[38:41], v[180:183], v[222:225], v[54:57]
	v_mfma_f32_16x16x32_bf16 v[50:53], v[192:195], v[226:229], v[50:53]
	v_mfma_f32_16x16x32_bf16 v[30:33], v[184:187], v[234:237], v[30:33]
	v_mfma_f32_16x16x32_bf16 v[26:29], v[192:195], v[234:237], v[26:29]
	v_mfma_f32_16x16x32_bf16 v[6:9], v[184:187], v[242:245], v[6:9]
	v_mfma_f32_16x16x32_bf16 v[2:5], v[192:195], v[242:245], v[2:5]
	v_mfma_f32_16x16x32_bf16 v[22:25], v[184:187], v[200:203], v[22:25]
	v_mfma_f32_16x16x32_bf16 v[34:37], v[192:195], v[200:203], v[34:37]
	v_mfma_f32_16x16x32_bf16 v[38:41], v[184:187], v[226:229], v[38:41]
	s_setprio 0
	s_cmp_eq_u64 s[12:13], 0
	s_cbranch_scc1 .Lhb_14
	s_barrier
.Lhb_14:
	v_add_u32_e32 v160, s90, v99
	v_add_u32_e32 v192, s91, v99
	ds_read_b128 v[54:57], v160
	ds_read_b128 v[66:69], v160 offset:1024
	ds_read_b128 v[70:73], v160 offset:2048
	ds_read_b128 v[160:163], v160 offset:3072
	ds_read_b128 v[180:183], v192
	ds_read_b128 v[184:187], v192 offset:1024
	ds_read_b128 v[188:191], v192 offset:2048
	ds_read_b128 v[192:195], v192 offset:3072
	s_mov_b32 m0, s63
	v_lshl_add_u64 v[246:247], s[54:55], 0, v[148:149]
	ds_read_b128 v[196:199], v165 offset:32768
	ds_read_b128 v[200:203], v165 offset:33792
	ds_read_b128 v[222:225], v165 offset:34816
	ds_read_b128 v[226:229], v165 offset:35840
	ds_read_b128 v[230:233], v165 offset:36864
	ds_read_b128 v[234:237], v165 offset:37888
	ds_read_b128 v[238:241], v165 offset:38912
	ds_read_b128 v[242:245], v165 offset:39936
	global_load_lds_dwordx4 v[246:247], off
	v_lshl_add_u64 v[246:247], s[54:55], 0, v[152:153]
	s_mov_b32 m0, s69
	s_nop 0
	global_load_lds_dwordx4 v[246:247], off
	s_waitcnt vmcnt(8)
	s_waitcnt lgkmcnt(0)
	s_cmp_lg_u64 s[12:13], 0
	s_cbranch_scc1 .Lhb_11
	s_barrier
.Lhb_11:
	s_setprio 1
	s_waitcnt lgkmcnt(0)
	v_mfma_f32_16x16x32_bf16 v[144:147], v[54:57], v[196:199], v[144:147]
	v_mfma_f32_16x16x32_bf16 v[140:143], v[70:73], v[196:199], v[140:143]
	v_mfma_f32_16x16x32_bf16 v[128:131], v[54:57], v[222:225], v[128:131]
	v_mfma_f32_16x16x32_bf16 v[124:127], v[70:73], v[222:225], v[124:127]
	v_mfma_f32_16x16x32_bf16 v[112:115], v[54:57], v[230:233], v[112:115]
	v_mfma_f32_16x16x32_bf16 v[108:111], v[70:73], v[230:233], v[108:111]
	v_mfma_f32_16x16x32_bf16 v[94:97], v[54:57], v[238:241], v[94:97]
	v_mfma_f32_16x16x32_bf16 v[90:93], v[70:73], v[238:241], v[90:93]
	s_setprio 2
	v_mfma_f32_16x16x32_bf16 v[144:147], v[66:69], v[200:203], v[144:147]
	v_mfma_f32_16x16x32_bf16 v[140:143], v[160:163], v[200:203], v[140:143]
	v_mfma_f32_16x16x32_bf16 v[128:131], v[66:69], v[226:229], v[128:131]
	v_mfma_f32_16x16x32_bf16 v[124:127], v[160:163], v[226:229], v[124:127]
	v_mfma_f32_16x16x32_bf16 v[112:115], v[66:69], v[234:237], v[112:115]
	v_mfma_f32_16x16x32_bf16 v[108:111], v[160:163], v[234:237], v[108:111]
	v_mfma_f32_16x16x32_bf16 v[94:97], v[66:69], v[242:245], v[94:97]
	v_mfma_f32_16x16x32_bf16 v[90:93], v[160:163], v[242:245], v[90:93]
	v_mfma_f32_16x16x32_bf16 v[136:139], v[180:183], v[196:199], v[136:139]
	v_mfma_f32_16x16x32_bf16 v[132:135], v[188:191], v[196:199], v[132:135]
	v_mfma_f32_16x16x32_bf16 v[120:123], v[180:183], v[222:225], v[120:123]
	v_mfma_f32_16x16x32_bf16 v[116:119], v[188:191], v[222:225], v[116:119]
	s_setprio 3
	v_mfma_f32_16x16x32_bf16 v[104:107], v[180:183], v[230:233], v[104:107]
	v_mfma_f32_16x16x32_bf16 v[100:103], v[188:191], v[230:233], v[100:103]
	v_mfma_f32_16x16x32_bf16 v[86:89], v[180:183], v[238:241], v[86:89]
	v_mfma_f32_16x16x32_bf16 v[82:85], v[188:191], v[238:241], v[82:85]
	v_mfma_f32_16x16x32_bf16 v[136:139], v[184:187], v[200:203], v[136:139]
	v_mfma_f32_16x16x32_bf16 v[132:135], v[192:195], v[200:203], v[132:135]
	v_mfma_f32_16x16x32_bf16 v[120:123], v[184:187], v[226:229], v[120:123]
	v_mfma_f32_16x16x32_bf16 v[116:119], v[192:195], v[226:229], v[116:119]
	v_mfma_f32_16x16x32_bf16 v[104:107], v[184:187], v[234:237], v[104:107]
	v_mfma_f32_16x16x32_bf16 v[100:103], v[192:195], v[234:237], v[100:103]
	v_mfma_f32_16x16x32_bf16 v[86:89], v[184:187], v[242:245], v[86:89]
	v_mfma_f32_16x16x32_bf16 v[82:85], v[192:195], v[242:245], v[82:85]
	s_setprio 0
	s_cmp_eq_u64 s[12:13], 0
	s_cbranch_scc1 .Lhb_15
	s_barrier
; #define GAS __attribute__((address_space(1)))
; __device__ __forceinline__ u32x4 pack8(f32x4 v0, f32x4 v1) { u32x4 w; w.x = cvt_pk_bf16(v0[0], v0[1]); w.y = cvt_pk_bf16(v0[2], v0[3]); w.z = cvt_pk_bf16(v1[0], v1[1]); w.w = cvt_pk_bf16(v1[2], v1[3]); return w; }
; __device__ __forceinline__ void unpack8(u32x4 w, f32x4& v0, f32x4& v1) { v0 = (f32x4){bflo(w.x), bfhi(w.x), bflo(w.y), bfhi(w.y)}; v1 = (f32x4){bflo(w.z), bfhi(w.z), bflo(w.w), bfhi(w.w)}; }
; #define PG8_STAGE(bufoff, gbase, voff) do { _Pragma("unroll") for (int _i = 0; _i < 2; ++_i) \
;         __builtin_amdgcn_global_load_lds((const unsigned*)((const char*)(gbase) + (voff)[_i]), (PG8_LAS unsigned*)(lds + (bufoff) + ldsw + _i * 8192), 16, 0, AUX_A); } while (0)
; #define PG8_WAIT_V(n) asm volatile("s_waitcnt vmcnt(" #n ")" ::: "memory")
;     __device__ __forceinline__ void operator()(const f32x4 (&acc)[2][2][4][2], const Unit& u, int wr, int wc, int fr, int fq) const {
;         const int row0 = u.pm * BM + wr * 64 + fr, col0 = u.pn * BM + wc * 32 + 8 * fq;
;         f32x4 bv[2][2];
; #pragma unroll
;         for (int bj = 0; bj < 2; ++bj)
; #pragma unroll
;             for (int n = 0; n < 2; ++n) bv[bj][n] = *(const f32x4*)(bglu + col0 + bj * HALF + 4 * n);
;         const bf16_t* const zb = Z + (size_t)row0 * 1024 + col0; bf16_t* const sob = SO + (size_t)row0 * 1024 + col0;
; #pragma unroll
;         for (int ai = 0; ai < 2; ++ai)
; #pragma unroll
;             for (int m = 0; m < 4; ++m) { const size_t off = (size_t)(ai * HALF + m * 16) * 1024;
; #pragma unroll
;                 for (int bj = 0; bj < 2; ++bj) { f32x4 z0, z1; unpack8(*(const GAS u32x4*)(zb + off + bj * HALF), z0, z1);
;                     const f32x4 v0 = z0 * sigmoid4(acc[ai][bj][m][0] + bv[bj][0]), v1 = z1 * sigmoid4(acc[ai][bj][m][1] + bv[bj][1]);
;                     *(GAS u32x4*)(sob + off + bj * HALF) = pack8(v0, v1); } }
; template <class Epi, class Sched, bool ALIGN_EPI = false, bool SP2 = false>
; __device__ __forceinline__ void gemm_phase(PG8_LAS unsigned char* lds, const Gemm g, const Sched& S, const Epi& E) {
;     ...
;             PG8_LDA(At, 1, 1); PG8_STAGEB(PG8_SB(1, 0), b3, voffB); PG8_STAGEB(PG8_SB(1, 1), b3 + hstep, voffB); PG8_STAGE(PG8_SA(1, 0), a3, voffA);
;             PG8_WAIT_V(8); PG8_WAIT_L(0); PG8_BAR; PG8_MMA(1, 0, At, B0); PG8_MMA(1, 1, At, B1); PG8_BAR; PG8_SCHED;
.Lhb_15:
	s_mov_b32 m0, s1
	v_lshl_add_u64 v[166:167], v[166:167], 0, s[76:77]
	ds_read_b128 v[196:199], v165 offset:49152
	ds_read_b128 v[200:203], v165 offset:50176
	ds_read_b128 v[222:225], v165 offset:51200
	ds_read_b128 v[226:229], v165 offset:52224
	ds_read_b128 v[230:233], v165 offset:53248
	ds_read_b128 v[234:237], v165 offset:54272
	ds_read_b128 v[238:241], v165 offset:55296
	ds_read_b128 v[242:245], v165 offset:56320
	global_load_lds_dwordx4 v[166:167], off
	v_lshl_add_u64 v[166:167], v[168:169], 0, s[76:77]
	s_mov_b32 m0, s0
	s_nop 0
	global_load_lds_dwordx4 v[166:167], off
	v_lshl_add_u64 v[166:167], s[52:53], 0, v[150:151]
	s_mov_b32 m0, s47
	s_nop 0
	global_load_lds_dwordx4 v[166:167], off
	v_lshl_add_u64 v[166:167], s[52:53], 0, v[154:155]
	s_mov_b32 m0, s46
	s_nop 0
	global_load_lds_dwordx4 v[166:167], off
	v_lshl_add_u64 v[166:167], v[172:173], 0, s[76:77]
	s_mov_b32 m0, s70
	s_nop 0
	global_load_lds_dwordx4 v[166:167], off
	v_lshl_add_u64 v[166:167], v[212:213], 0, s[76:77]
	s_mov_b32 m0, s71
	s_nop 0
	global_load_lds_dwordx4 v[166:167], off
	s_waitcnt vmcnt(8)
	s_waitcnt lgkmcnt(0)
	s_cmp_lg_u64 s[12:13], 0
	s_cbranch_scc1 .Lhb_12
	s_barrier
.Lhb_12:
	s_setprio 1
	s_waitcnt lgkmcnt(0)
	v_mfma_f32_16x16x32_bf16 v[78:81], v[54:57], v[196:199], v[78:81]
	v_mfma_f32_16x16x32_bf16 v[74:77], v[70:73], v[196:199], v[74:77]
	v_mfma_f32_16x16x32_bf16 v[62:65], v[54:57], v[222:225], v[62:65]
	v_mfma_f32_16x16x32_bf16 v[58:61], v[70:73], v[222:225], v[58:61]
	v_mfma_f32_16x16x32_bf16 v[46:49], v[54:57], v[230:233], v[46:49]
	v_mfma_f32_16x16x32_bf16 v[42:45], v[70:73], v[230:233], v[42:45]
	v_mfma_f32_16x16x32_bf16 v[18:21], v[54:57], v[238:241], v[18:21]
	v_mfma_f32_16x16x32_bf16 v[10:13], v[70:73], v[238:241], v[10:13]
	s_setprio 2
	v_mfma_f32_16x16x32_bf16 v[78:81], v[66:69], v[200:203], v[78:81]
	v_mfma_f32_16x16x32_bf16 v[74:77], v[160:163], v[200:203], v[74:77]
	v_mfma_f32_16x16x32_bf16 v[62:65], v[66:69], v[226:229], v[62:65]
	v_mfma_f32_16x16x32_bf16 v[58:61], v[160:163], v[226:229], v[58:61]
	v_mfma_f32_16x16x32_bf16 v[46:49], v[66:69], v[234:237], v[46:49]
	v_mfma_f32_16x16x32_bf16 v[42:45], v[160:163], v[234:237], v[42:45]
	v_mfma_f32_16x16x32_bf16 v[18:21], v[66:69], v[242:245], v[18:21]
	v_mfma_f32_16x16x32_bf16 v[10:13], v[160:163], v[242:245], v[10:13]
	v_mfma_f32_16x16x32_bf16 v[22:25], v[180:183], v[196:199], v[22:25]
	v_mfma_f32_16x16x32_bf16 v[70:73], v[184:187], v[200:203], v[22:25]
	v_mfma_f32_16x16x32_bf16 v[22:25], v[188:191], v[196:199], v[34:37]
	v_mfma_f32_16x16x32_bf16 v[66:69], v[192:195], v[200:203], v[22:25]
	s_setprio 3
	v_mfma_f32_16x16x32_bf16 v[22:25], v[180:183], v[222:225], v[38:41]
	v_mfma_f32_16x16x32_bf16 v[54:57], v[184:187], v[226:229], v[22:25]
	v_mfma_f32_16x16x32_bf16 v[22:25], v[188:191], v[222:225], v[50:53]
	v_mfma_f32_16x16x32_bf16 v[50:53], v[192:195], v[226:229], v[22:25]
	v_mfma_f32_16x16x32_bf16 v[22:25], v[180:183], v[230:233], v[30:33]
	v_mfma_f32_16x16x32_bf16 v[30:33], v[184:187], v[234:237], v[22:25]
	v_mfma_f32_16x16x32_bf16 v[22:25], v[188:191], v[230:233], v[26:29]
	v_mfma_f32_16x16x32_bf16 v[6:9], v[180:183], v[238:241], v[6:9]
	v_mfma_f32_16x16x32_bf16 v[2:5], v[188:191], v[238:241], v[2:5]
	v_mfma_f32_16x16x32_bf16 v[26:29], v[192:195], v[234:237], v[22:25]
	v_mfma_f32_16x16x32_bf16 v[6:9], v[184:187], v[242:245], v[6:9]
	v_mfma_f32_16x16x32_bf16 v[2:5], v[192:195], v[242:245], v[2:5]
	s_setprio 0
	s_cmp_eq_u64 s[12:13], 0
	s_cbranch_scc1 .Lhb_16
	s_barrier
.Lhb_16:
	v_lshl_add_u64 v[14:15], v[14:15], 0, s[86:87]
	v_lshl_add_u64 v[16:17], v[16:17], 0, s[86:87]
	s_cmp_gt_u32 s81, 15
	s_mov_b32 s29, s81
	s_cbranch_scc0 .LBB0_936
	s_and_b64 vcc, exec, s[12:13]
	s_cbranch_vccz .LBB0_939
.LBB0_939:
	v_lshl_or_b32 v160, s24, 8, v164
	v_ashrrev_i32_e32 v161, 31, v160
	v_lshl_add_u64 v[22:23], v[160:161], 2, s[8:9]
	global_load_dwordx4 v[34:37], v[22:23], off offset:16
	global_load_dwordx4 v[38:41], v[22:23], off
	global_load_dwordx4 v[14:17], v[22:23], off offset:528
	s_nop 0
	global_load_dwordx4 v[22:25], v[22:23], off offset:512
	v_lshl_add_u32 v162, s42, 8, v1
	v_ashrrev_i32_e32 v163, 31, v162
	v_lshlrev_b64 v[166:167], 11, v[162:163]
	v_lshl_add_u64 v[162:163], s[4:5], 0, v[166:167]
	v_lshlrev_b64 v[160:161], 1, v[160:161]
	v_lshl_add_u64 v[162:163], v[162:163], 0, v[160:161]
	global_load_dwordx4 v[180:183], v[162:163], off
	v_lshl_add_u64 v[166:167], s[10:11], 0, v[166:167]
	v_lshl_add_u64 v[160:161], v[166:167], 0, v[160:161]
	v_readlane_b32 s90, v254, 50
	s_mov_b64 s[42:43], -1
	v_readlane_b32 s91, v254, 51
	s_waitcnt vmcnt(0)
; #define GAS __attribute__((address_space(1)))
; __device__ __forceinline__ u32x4 pack8(f32x4 v0, f32x4 v1) { u32x4 w; w.x = cvt_pk_bf16(v0[0], v0[1]); w.y = cvt_pk_bf16(v0[2], v0[3]); w.z = cvt_pk_bf16(v1[0], v1[1]); w.w = cvt_pk_bf16(v1[2], v1[3]); return w; }
; __device__ __forceinline__ void unpack8(u32x4 w, f32x4& v0, f32x4& v1) { v0 = (f32x4){bflo(w.x), bfhi(w.x), bflo(w.y), bfhi(w.y)}; v1 = (f32x4){bflo(w.z), bfhi(w.z), bflo(w.w), bfhi(w.w)}; }
; #define GAS __attribute__((address_space(1)))
;     __device__ __forceinline__ void operator()(const f32x4 (&acc)[2][2][4][2], const Unit& u, int wr, int wc, int fr, int fq) const {
;     ...
;             for (int n = 0; n < 2; ++n) bv[bj][n] = *(const f32x4*)(bglu + col0 + bj * HALF + 4 * n);
;         const bf16_t* const zb = Z + (size_t)row0 * 1024 + col0; bf16_t* const sob = SO + (size_t)row0 * 1024 + col0;
; #pragma unroll
;         for (int ai = 0; ai < 2; ++ai)
; #pragma unroll
;             for (int m = 0; m < 4; ++m) { const size_t off = (size_t)(ai * HALF + m * 16) * 1024;
; #pragma unroll
;                 for (int bj = 0; bj < 2; ++bj) { f32x4 z0, z1; unpack8(*(const GAS u32x4*)(zb + off + bj * HALF), z0, z1);
;                     const f32x4 v0 = z0 * sigmoid4(acc[ai][bj][m][0] + bv[bj][0]), v1 = z1 * sigmoid4(acc[ai][bj][m][1] + bv[bj][1]);
;                     *(GAS u32x4*)(sob + off + bj * HALF) = pack8(v0, v1); } }
	v_pk_add_f32 v[142:143], v[142:143], v[36:37]
	v_pk_add_f32 v[146:147], v[146:147], v[40:41]
	v_pk_add_f32 v[144:145], v[144:145], v[38:39]
	v_pk_add_f32 v[140:141], v[140:141], v[34:35]
	v_pk_mul_f32 v[144:145], v[144:145], s[74:75] op_sel_hi:[1,0]
	v_pk_mul_f32 v[146:147], v[146:147], s[74:75] op_sel_hi:[1,0]
	v_pk_mul_f32 v[140:141], v[140:141], s[74:75] op_sel_hi:[1,0]
	v_pk_mul_f32 v[142:143], v[142:143], s[74:75] op_sel_hi:[1,0]
	v_exp_f32_e32 v144, v144
	v_exp_f32_e32 v145, v145
	v_exp_f32_e32 v146, v146
	v_exp_f32_e32 v147, v147
	v_exp_f32_e32 v140, v140
	v_exp_f32_e32 v141, v141
	v_exp_f32_e32 v142, v142
	v_exp_f32_e32 v143, v143
	v_pk_add_f32 v[144:145], v[144:145], 1.0 op_sel_hi:[1,0]
	v_pk_add_f32 v[146:147], v[146:147], 1.0 op_sel_hi:[1,0]
	v_pk_add_f32 v[140:141], v[140:141], 1.0 op_sel_hi:[1,0]
	v_pk_add_f32 v[142:143], v[142:143], 1.0 op_sel_hi:[1,0]
	v_rcp_f32_e32 v144, v144
	v_rcp_f32_e32 v145, v145
	v_rcp_f32_e32 v146, v146
	v_rcp_f32_e32 v147, v147
	v_rcp_f32_e32 v140, v140
	v_rcp_f32_e32 v141, v141
	v_rcp_f32_e32 v142, v142
	v_rcp_f32_e32 v143, v143
	v_lshlrev_b32_e32 v166, 16, v180
	v_and_b32_e32 v167, 0xffff0000, v180
	v_lshlrev_b32_e32 v168, 16, v181
	v_and_b32_e32 v169, 0xffff0000, v181
	v_lshlrev_b32_e32 v172, 16, v182
	v_and_b32_e32 v173, 0xffff0000, v182
	v_lshlrev_b32_e32 v180, 16, v183
	v_and_b32_e32 v181, 0xffff0000, v183
	v_pk_mul_f32 v[146:147], v[146:147], v[168:169]
	v_pk_mul_f32 v[144:145], v[144:145], v[166:167]
	v_pk_mul_f32 v[166:167], v[142:143], v[180:181]
	v_pk_mul_f32 v[142:143], v[140:141], v[172:173]
	v_cvt_pk_bf16_f32 v140, v144, v145
	v_cvt_pk_bf16_f32 v141, v146, v147
	v_cvt_pk_bf16_f32 v142, v142, v143
	v_cvt_pk_bf16_f32 v143, v166, v167
	global_store_dwordx4 v[160:161], v[140:143], off
	global_load_dwordx4 v[140:143], v[162:163], off offset:256
	v_pk_add_f32 v[138:139], v[138:139], v[24:25]
	v_pk_add_f32 v[136:137], v[136:137], v[22:23]
	v_pk_add_f32 v[134:135], v[134:135], v[16:17]
	v_pk_add_f32 v[132:133], v[132:133], v[14:15]
	v_pk_mul_f32 v[136:137], v[136:137], s[74:75] op_sel_hi:[1,0]
	v_pk_mul_f32 v[138:139], v[138:139], s[74:75] op_sel_hi:[1,0]
	v_pk_mul_f32 v[132:133], v[132:133], s[74:75] op_sel_hi:[1,0]
	v_pk_mul_f32 v[134:135], v[134:135], s[74:75] op_sel_hi:[1,0]
	v_exp_f32_e32 v136, v136
	v_exp_f32_e32 v137, v137
	v_exp_f32_e32 v138, v138
	v_exp_f32_e32 v139, v139
	v_exp_f32_e32 v132, v132
	v_exp_f32_e32 v133, v133
	v_exp_f32_e32 v134, v134
	v_exp_f32_e32 v135, v135
	v_pk_add_f32 v[136:137], v[136:137], 1.0 op_sel_hi:[1,0]
	v_pk_add_f32 v[138:139], v[138:139], 1.0 op_sel_hi:[1,0]
	v_pk_add_f32 v[132:133], v[132:133], 1.0 op_sel_hi:[1,0]
	v_pk_add_f32 v[134:135], v[134:135], 1.0 op_sel_hi:[1,0]
	v_rcp_f32_e32 v136, v136
	v_rcp_f32_e32 v137, v137
	v_rcp_f32_e32 v138, v138
	v_rcp_f32_e32 v139, v139
	v_rcp_f32_e32 v132, v132
	v_rcp_f32_e32 v133, v133
	v_rcp_f32_e32 v134, v134
	v_rcp_f32_e32 v135, v135
	v_pk_add_f32 v[128:129], v[128:129], v[38:39]
	v_pk_add_f32 v[124:125], v[124:125], v[34:35]
	v_pk_add_f32 v[130:131], v[130:131], v[40:41]
	v_pk_mul_f32 v[128:129], v[128:129], s[74:75] op_sel_hi:[1,0]
	v_pk_add_f32 v[126:127], v[126:127], v[36:37]
	v_pk_mul_f32 v[124:125], v[124:125], s[74:75] op_sel_hi:[1,0]
	v_pk_mul_f32 v[130:131], v[130:131], s[74:75] op_sel_hi:[1,0]
	v_exp_f32_e32 v128, v128
	v_exp_f32_e32 v129, v129
	v_pk_mul_f32 v[126:127], v[126:127], s[74:75] op_sel_hi:[1,0]
	v_exp_f32_e32 v124, v124
	v_exp_f32_e32 v125, v125
	v_exp_f32_e32 v130, v130
	v_exp_f32_e32 v131, v131
	v_exp_f32_e32 v126, v126
	v_exp_f32_e32 v127, v127
	v_pk_add_f32 v[128:129], v[128:129], 1.0 op_sel_hi:[1,0]
	v_pk_add_f32 v[124:125], v[124:125], 1.0 op_sel_hi:[1,0]
	v_pk_add_f32 v[130:131], v[130:131], 1.0 op_sel_hi:[1,0]
	v_rcp_f32_e32 v128, v128
	v_rcp_f32_e32 v129, v129
	v_pk_add_f32 v[126:127], v[126:127], 1.0 op_sel_hi:[1,0]
	v_rcp_f32_e32 v124, v124
	v_rcp_f32_e32 v125, v125
	v_rcp_f32_e32 v130, v130
	v_rcp_f32_e32 v131, v131
	v_rcp_f32_e32 v126, v126
	v_rcp_f32_e32 v127, v127
	v_pk_add_f32 v[122:123], v[122:123], v[24:25]
	v_pk_add_f32 v[120:121], v[120:121], v[22:23]
	v_pk_add_f32 v[118:119], v[118:119], v[16:17]
	v_pk_add_f32 v[116:117], v[116:117], v[14:15]
	v_pk_mul_f32 v[120:121], v[120:121], s[74:75] op_sel_hi:[1,0]
	v_pk_mul_f32 v[122:123], v[122:123], s[74:75] op_sel_hi:[1,0]
	v_pk_mul_f32 v[116:117], v[116:117], s[74:75] op_sel_hi:[1,0]
	v_pk_mul_f32 v[118:119], v[118:119], s[74:75] op_sel_hi:[1,0]
	v_exp_f32_e32 v120, v120
	v_exp_f32_e32 v121, v121
	v_exp_f32_e32 v122, v122
	v_exp_f32_e32 v123, v123
	v_exp_f32_e32 v116, v116
	v_exp_f32_e32 v117, v117
	v_exp_f32_e32 v118, v118
	v_exp_f32_e32 v119, v119
	v_pk_add_f32 v[120:121], v[120:121], 1.0 op_sel_hi:[1,0]
	v_pk_add_f32 v[122:123], v[122:123], 1.0 op_sel_hi:[1,0]
	v_pk_add_f32 v[116:117], v[116:117], 1.0 op_sel_hi:[1,0]
	v_pk_add_f32 v[118:119], v[118:119], 1.0 op_sel_hi:[1,0]
	v_rcp_f32_e32 v120, v120
	v_rcp_f32_e32 v121, v121
	v_rcp_f32_e32 v122, v122
	s_waitcnt vmcnt(0)
; #define GAS __attribute__((address_space(1)))
; __device__ __forceinline__ u32x4 pack8(f32x4 v0, f32x4 v1) { u32x4 w; w.x = cvt_pk_bf16(v0[0], v0[1]); w.y = cvt_pk_bf16(v0[2], v0[3]); w.z = cvt_pk_bf16(v1[0], v1[1]); w.w = cvt_pk_bf16(v1[2], v1[3]); return w; }
; __device__ __forceinline__ void unpack8(u32x4 w, f32x4& v0, f32x4& v1) { v0 = (f32x4){bflo(w.x), bfhi(w.x), bflo(w.y), bfhi(w.y)}; v1 = (f32x4){bflo(w.z), bfhi(w.z), bflo(w.w), bfhi(w.w)}; }
; #define GAS __attribute__((address_space(1)))
;     __device__ __forceinline__ void operator()(const f32x4 (&acc)[2][2][4][2], const Unit& u, int wr, int wc, int fr, int fq) const {
;     ...
;             for (int m = 0; m < 4; ++m) { const size_t off = (size_t)(ai * HALF + m * 16) * 1024;
; #pragma unroll
;                 for (int bj = 0; bj < 2; ++bj) { f32x4 z0, z1; unpack8(*(const GAS u32x4*)(zb + off + bj * HALF), z0, z1);
;                     const f32x4 v0 = z0 * sigmoid4(acc[ai][bj][m][0] + bv[bj][0]), v1 = z1 * sigmoid4(acc[ai][bj][m][1] + bv[bj][1]);
;                     *(GAS u32x4*)(sob + off + bj * HALF) = pack8(v0, v1); } }
	v_lshlrev_b32_e32 v144, 16, v140
	v_and_b32_e32 v145, 0xffff0000, v140
	v_lshlrev_b32_e32 v140, 16, v141
	v_and_b32_e32 v141, 0xffff0000, v141
	v_lshlrev_b32_e32 v146, 16, v142
	v_and_b32_e32 v147, 0xffff0000, v142
	v_lshlrev_b32_e32 v142, 16, v143
	v_and_b32_e32 v143, 0xffff0000, v143
	v_pk_mul_f32 v[138:139], v[138:139], v[140:141]
	v_pk_mul_f32 v[136:137], v[136:137], v[144:145]
	v_pk_mul_f32 v[140:141], v[134:135], v[142:143]
	v_pk_mul_f32 v[134:135], v[132:133], v[146:147]
	v_cvt_pk_bf16_f32 v132, v136, v137
	v_cvt_pk_bf16_f32 v133, v138, v139
	v_cvt_pk_bf16_f32 v134, v134, v135
	v_cvt_pk_bf16_f32 v135, v140, v141
	global_store_dwordx4 v[160:161], v[132:135], off offset:256
	v_rcp_f32_e32 v123, v123
	v_rcp_f32_e32 v116, v116
	v_add_co_u32_e32 v132, vcc, s94, v162
	v_rcp_f32_e32 v117, v117
	s_nop 0
	v_addc_co_u32_e32 v133, vcc, 0, v163, vcc
	global_load_dwordx4 v[134:137], v[132:133], off
	v_rcp_f32_e32 v118, v118
	v_rcp_f32_e32 v119, v119
	v_pk_add_f32 v[112:113], v[112:113], v[38:39]
	v_pk_add_f32 v[108:109], v[108:109], v[34:35]
	v_pk_add_f32 v[114:115], v[114:115], v[40:41]
	v_pk_mul_f32 v[112:113], v[112:113], s[74:75] op_sel_hi:[1,0]
	v_pk_add_f32 v[110:111], v[110:111], v[36:37]
	v_pk_mul_f32 v[108:109], v[108:109], s[74:75] op_sel_hi:[1,0]
	v_pk_mul_f32 v[114:115], v[114:115], s[74:75] op_sel_hi:[1,0]
	v_exp_f32_e32 v112, v112
	v_exp_f32_e32 v113, v113
	v_pk_mul_f32 v[110:111], v[110:111], s[74:75] op_sel_hi:[1,0]
	v_exp_f32_e32 v108, v108
	v_exp_f32_e32 v109, v109
	v_exp_f32_e32 v114, v114
	v_exp_f32_e32 v115, v115
	v_exp_f32_e32 v110, v110
	v_exp_f32_e32 v111, v111
	v_pk_add_f32 v[112:113], v[112:113], 1.0 op_sel_hi:[1,0]
	v_pk_add_f32 v[108:109], v[108:109], 1.0 op_sel_hi:[1,0]
	v_pk_add_f32 v[114:115], v[114:115], 1.0 op_sel_hi:[1,0]
	v_rcp_f32_e32 v112, v112
	v_rcp_f32_e32 v113, v113
	v_pk_add_f32 v[110:111], v[110:111], 1.0 op_sel_hi:[1,0]
	v_rcp_f32_e32 v108, v108
	v_rcp_f32_e32 v109, v109
	v_rcp_f32_e32 v114, v114
	v_rcp_f32_e32 v115, v115
	v_rcp_f32_e32 v110, v110
	v_rcp_f32_e32 v111, v111
	v_pk_add_f32 v[106:107], v[106:107], v[24:25]
	v_pk_add_f32 v[104:105], v[104:105], v[22:23]
	v_pk_add_f32 v[102:103], v[102:103], v[16:17]
	v_pk_add_f32 v[100:101], v[100:101], v[14:15]
	v_pk_mul_f32 v[104:105], v[104:105], s[74:75] op_sel_hi:[1,0]
	v_pk_mul_f32 v[106:107], v[106:107], s[74:75] op_sel_hi:[1,0]
	v_pk_mul_f32 v[100:101], v[100:101], s[74:75] op_sel_hi:[1,0]
	v_pk_mul_f32 v[102:103], v[102:103], s[74:75] op_sel_hi:[1,0]
	v_exp_f32_e32 v104, v104
	v_exp_f32_e32 v105, v105
	v_exp_f32_e32 v106, v106
	v_exp_f32_e32 v107, v107
	v_exp_f32_e32 v100, v100
	v_exp_f32_e32 v101, v101
	v_exp_f32_e32 v102, v102
	v_exp_f32_e32 v103, v103
	v_pk_add_f32 v[104:105], v[104:105], 1.0 op_sel_hi:[1,0]
	v_pk_add_f32 v[106:107], v[106:107], 1.0 op_sel_hi:[1,0]
	v_pk_add_f32 v[100:101], v[100:101], 1.0 op_sel_hi:[1,0]
	v_pk_add_f32 v[102:103], v[102:103], 1.0 op_sel_hi:[1,0]
	v_rcp_f32_e32 v104, v104
	v_rcp_f32_e32 v105, v105
	v_rcp_f32_e32 v106, v106
	v_rcp_f32_e32 v107, v107
	v_rcp_f32_e32 v100, v100
	v_rcp_f32_e32 v101, v101
	v_rcp_f32_e32 v102, v102
	v_rcp_f32_e32 v103, v103
	v_pk_add_f32 v[94:95], v[94:95], v[38:39]
	v_pk_add_f32 v[90:91], v[90:91], v[34:35]
	v_pk_add_f32 v[96:97], v[96:97], v[40:41]
	v_pk_mul_f32 v[94:95], v[94:95], s[74:75] op_sel_hi:[1,0]
	v_pk_add_f32 v[92:93], v[92:93], v[36:37]
	v_pk_mul_f32 v[90:91], v[90:91], s[74:75] op_sel_hi:[1,0]
	v_pk_mul_f32 v[96:97], v[96:97], s[74:75] op_sel_hi:[1,0]
	v_exp_f32_e32 v94, v94
	v_exp_f32_e32 v95, v95
	v_pk_mul_f32 v[92:93], v[92:93], s[74:75] op_sel_hi:[1,0]
	v_exp_f32_e32 v90, v90
	v_exp_f32_e32 v91, v91
	v_exp_f32_e32 v96, v96
	v_exp_f32_e32 v97, v97
	v_exp_f32_e32 v92, v92
	v_exp_f32_e32 v93, v93
	v_pk_add_f32 v[94:95], v[94:95], 1.0 op_sel_hi:[1,0]
	v_pk_add_f32 v[90:91], v[90:91], 1.0 op_sel_hi:[1,0]
	v_pk_add_f32 v[96:97], v[96:97], 1.0 op_sel_hi:[1,0]
	v_rcp_f32_e32 v94, v94
	v_rcp_f32_e32 v95, v95
	s_waitcnt vmcnt(0)
	v_lshlrev_b32_e32 v138, 16, v134
	v_and_b32_e32 v139, 0xffff0000, v134
	v_lshlrev_b32_e32 v140, 16, v136
	v_and_b32_e32 v141, 0xffff0000, v136
	v_lshlrev_b32_e32 v134, 16, v135
	v_and_b32_e32 v135, 0xffff0000, v135
	v_lshlrev_b32_e32 v136, 16, v137
	v_and_b32_e32 v137, 0xffff0000, v137
	v_pk_mul_f32 v[128:129], v[128:129], v[138:139]
	v_pk_mul_f32 v[124:125], v[124:125], v[140:141]
	v_pk_mul_f32 v[130:131], v[130:131], v[134:135]
	v_pk_mul_f32 v[134:135], v[126:127], v[136:137]
	v_cvt_pk_bf16_f32 v126, v128, v129
	v_cvt_pk_bf16_f32 v128, v124, v125
	v_add_co_u32_e32 v124, vcc, s94, v160
	v_cvt_pk_bf16_f32 v127, v130, v131
	v_cvt_pk_bf16_f32 v129, v134, v135
	v_addc_co_u32_e32 v125, vcc, 0, v161, vcc
	global_store_dwordx4 v[124:125], v[126:129], off
	global_load_dwordx4 v[126:129], v[132:133], off offset:256
	v_pk_add_f32 v[92:93], v[92:93], 1.0 op_sel_hi:[1,0]
	v_rcp_f32_e32 v90, v90
	v_rcp_f32_e32 v91, v91
	v_rcp_f32_e32 v96, v96
	v_rcp_f32_e32 v97, v97
	v_rcp_f32_e32 v92, v92
	v_rcp_f32_e32 v93, v93
	v_pk_add_f32 v[88:89], v[88:89], v[24:25]
	v_pk_add_f32 v[86:87], v[86:87], v[22:23]
	v_pk_add_f32 v[84:85], v[84:85], v[16:17]
	v_pk_add_f32 v[82:83], v[82:83], v[14:15]
	v_pk_mul_f32 v[86:87], v[86:87], s[74:75] op_sel_hi:[1,0]
	v_pk_mul_f32 v[88:89], v[88:89], s[74:75] op_sel_hi:[1,0]
	v_pk_mul_f32 v[82:83], v[82:83], s[74:75] op_sel_hi:[1,0]
	v_pk_mul_f32 v[84:85], v[84:85], s[74:75] op_sel_hi:[1,0]
	v_exp_f32_e32 v86, v86
	v_exp_f32_e32 v87, v87
	v_exp_f32_e32 v88, v88
	v_exp_f32_e32 v89, v89
	v_exp_f32_e32 v82, v82
	v_exp_f32_e32 v83, v83
	v_exp_f32_e32 v84, v84
	v_exp_f32_e32 v85, v85
	v_pk_add_f32 v[86:87], v[86:87], 1.0 op_sel_hi:[1,0]
; #define GAS __attribute__((address_space(1)))
; __device__ __forceinline__ u32x4 pack8(f32x4 v0, f32x4 v1) { u32x4 w; w.x = cvt_pk_bf16(v0[0], v0[1]); w.y = cvt_pk_bf16(v0[2], v0[3]); w.z = cvt_pk_bf16(v1[0], v1[1]); w.w = cvt_pk_bf16(v1[2], v1[3]); return w; }
; __device__ __forceinline__ void unpack8(u32x4 w, f32x4& v0, f32x4& v1) { v0 = (f32x4){bflo(w.x), bfhi(w.x), bflo(w.y), bfhi(w.y)}; v1 = (f32x4){bflo(w.z), bfhi(w.z), bflo(w.w), bfhi(w.w)}; }
; #define GAS __attribute__((address_space(1)))
;     __device__ __forceinline__ void operator()(const f32x4 (&acc)[2][2][4][2], const Unit& u, int wr, int wc, int fr, int fq) const {
;     ...
;             for (int m = 0; m < 4; ++m) { const size_t off = (size_t)(ai * HALF + m * 16) * 1024;
; #pragma unroll
;                 for (int bj = 0; bj < 2; ++bj) { f32x4 z0, z1; unpack8(*(const GAS u32x4*)(zb + off + bj * HALF), z0, z1);
;                     const f32x4 v0 = z0 * sigmoid4(acc[ai][bj][m][0] + bv[bj][0]), v1 = z1 * sigmoid4(acc[ai][bj][m][1] + bv[bj][1]);
;                     *(GAS u32x4*)(sob + off + bj * HALF) = pack8(v0, v1); } }
	v_pk_add_f32 v[88:89], v[88:89], 1.0 op_sel_hi:[1,0]
	v_pk_add_f32 v[82:83], v[82:83], 1.0 op_sel_hi:[1,0]
	v_pk_add_f32 v[84:85], v[84:85], 1.0 op_sel_hi:[1,0]
	v_rcp_f32_e32 v86, v86
	v_rcp_f32_e32 v87, v87
	v_rcp_f32_e32 v88, v88
	v_rcp_f32_e32 v89, v89
	v_rcp_f32_e32 v82, v82
	v_rcp_f32_e32 v83, v83
	v_rcp_f32_e32 v84, v84
	v_rcp_f32_e32 v85, v85
	v_pk_add_f32 v[78:79], v[78:79], v[38:39]
	v_pk_add_f32 v[74:75], v[74:75], v[34:35]
	v_pk_add_f32 v[80:81], v[80:81], v[40:41]
	v_pk_mul_f32 v[78:79], v[78:79], s[74:75] op_sel_hi:[1,0]
	v_pk_add_f32 v[76:77], v[76:77], v[36:37]
	v_pk_mul_f32 v[74:75], v[74:75], s[74:75] op_sel_hi:[1,0]
	v_pk_mul_f32 v[80:81], v[80:81], s[74:75] op_sel_hi:[1,0]
	v_exp_f32_e32 v78, v78
	v_exp_f32_e32 v79, v79
	v_pk_mul_f32 v[76:77], v[76:77], s[74:75] op_sel_hi:[1,0]
	v_exp_f32_e32 v74, v74
	v_exp_f32_e32 v75, v75
	v_exp_f32_e32 v80, v80
	v_exp_f32_e32 v81, v81
	v_exp_f32_e32 v76, v76
	v_exp_f32_e32 v77, v77
	v_pk_add_f32 v[78:79], v[78:79], 1.0 op_sel_hi:[1,0]
	v_pk_add_f32 v[74:75], v[74:75], 1.0 op_sel_hi:[1,0]
	v_pk_add_f32 v[80:81], v[80:81], 1.0 op_sel_hi:[1,0]
	v_rcp_f32_e32 v78, v78
	v_rcp_f32_e32 v79, v79
	v_pk_add_f32 v[76:77], v[76:77], 1.0 op_sel_hi:[1,0]
	v_rcp_f32_e32 v74, v74
	v_rcp_f32_e32 v75, v75
	v_rcp_f32_e32 v80, v80
	v_rcp_f32_e32 v81, v81
	v_rcp_f32_e32 v76, v76
	v_rcp_f32_e32 v77, v77
	v_pk_add_f32 v[72:73], v[72:73], v[24:25]
	v_pk_add_f32 v[70:71], v[70:71], v[22:23]
	v_pk_add_f32 v[68:69], v[68:69], v[16:17]
	v_pk_add_f32 v[66:67], v[66:67], v[14:15]
	v_pk_mul_f32 v[70:71], v[70:71], s[74:75] op_sel_hi:[1,0]
	v_pk_mul_f32 v[72:73], v[72:73], s[74:75] op_sel_hi:[1,0]
	v_pk_mul_f32 v[66:67], v[66:67], s[74:75] op_sel_hi:[1,0]
	v_pk_mul_f32 v[68:69], v[68:69], s[74:75] op_sel_hi:[1,0]
	v_exp_f32_e32 v70, v70
	v_exp_f32_e32 v71, v71
	v_exp_f32_e32 v72, v72
	v_exp_f32_e32 v73, v73
	v_exp_f32_e32 v66, v66
	v_exp_f32_e32 v67, v67
	v_exp_f32_e32 v68, v68
	v_exp_f32_e32 v69, v69
	s_waitcnt vmcnt(0)
	v_lshlrev_b32_e32 v130, 16, v126
	v_and_b32_e32 v131, 0xffff0000, v126
	v_lshlrev_b32_e32 v126, 16, v127
	v_and_b32_e32 v127, 0xffff0000, v127
	v_lshlrev_b32_e32 v132, 16, v128
	v_and_b32_e32 v133, 0xffff0000, v128
	v_lshlrev_b32_e32 v128, 16, v129
	v_and_b32_e32 v129, 0xffff0000, v129
	v_pk_mul_f32 v[122:123], v[122:123], v[126:127]
	v_pk_mul_f32 v[120:121], v[120:121], v[130:131]
	v_pk_mul_f32 v[126:127], v[118:119], v[128:129]
	v_pk_mul_f32 v[118:119], v[116:117], v[132:133]
	v_cvt_pk_bf16_f32 v116, v120, v121
	v_cvt_pk_bf16_f32 v117, v122, v123
	v_cvt_pk_bf16_f32 v118, v118, v119
	v_cvt_pk_bf16_f32 v119, v126, v127
	global_store_dwordx4 v[124:125], v[116:119], off offset:256
	v_pk_add_f32 v[70:71], v[70:71], 1.0 op_sel_hi:[1,0]
	v_pk_add_f32 v[72:73], v[72:73], 1.0 op_sel_hi:[1,0]
	v_add_co_u32_e32 v116, vcc, s73, v162
	v_pk_add_f32 v[66:67], v[66:67], 1.0 op_sel_hi:[1,0]
	s_nop 0
	v_addc_co_u32_e32 v117, vcc, 0, v163, vcc
	global_load_dwordx4 v[118:121], v[116:117], off
	v_pk_add_f32 v[68:69], v[68:69], 1.0 op_sel_hi:[1,0]
	v_rcp_f32_e32 v70, v70
	v_rcp_f32_e32 v71, v71
	v_rcp_f32_e32 v72, v72
	v_rcp_f32_e32 v73, v73
	v_rcp_f32_e32 v66, v66
	v_rcp_f32_e32 v67, v67
	v_rcp_f32_e32 v68, v68
	v_rcp_f32_e32 v69, v69
	v_pk_add_f32 v[62:63], v[62:63], v[38:39]
	v_pk_add_f32 v[58:59], v[58:59], v[34:35]
	v_pk_add_f32 v[64:65], v[64:65], v[40:41]
	v_pk_mul_f32 v[62:63], v[62:63], s[74:75] op_sel_hi:[1,0]
	v_pk_add_f32 v[60:61], v[60:61], v[36:37]
	v_pk_mul_f32 v[58:59], v[58:59], s[74:75] op_sel_hi:[1,0]
	v_pk_mul_f32 v[64:65], v[64:65], s[74:75] op_sel_hi:[1,0]
	v_exp_f32_e32 v62, v62
	v_exp_f32_e32 v63, v63
	v_pk_mul_f32 v[60:61], v[60:61], s[74:75] op_sel_hi:[1,0]
	v_exp_f32_e32 v58, v58
	v_exp_f32_e32 v59, v59
	v_exp_f32_e32 v64, v64
	v_exp_f32_e32 v65, v65
	v_exp_f32_e32 v60, v60
	v_exp_f32_e32 v61, v61
	v_pk_add_f32 v[62:63], v[62:63], 1.0 op_sel_hi:[1,0]
	v_pk_add_f32 v[58:59], v[58:59], 1.0 op_sel_hi:[1,0]
	v_pk_add_f32 v[64:65], v[64:65], 1.0 op_sel_hi:[1,0]
	v_rcp_f32_e32 v62, v62
	v_rcp_f32_e32 v63, v63
	v_pk_add_f32 v[60:61], v[60:61], 1.0 op_sel_hi:[1,0]
	v_rcp_f32_e32 v58, v58
	v_rcp_f32_e32 v59, v59
	v_rcp_f32_e32 v64, v64
	v_rcp_f32_e32 v65, v65
	v_rcp_f32_e32 v60, v60
	v_rcp_f32_e32 v61, v61
	v_pk_add_f32 v[56:57], v[56:57], v[24:25]
	v_pk_add_f32 v[54:55], v[54:55], v[22:23]
	v_pk_add_f32 v[52:53], v[52:53], v[16:17]
	v_pk_add_f32 v[50:51], v[50:51], v[14:15]
	v_pk_mul_f32 v[54:55], v[54:55], s[74:75] op_sel_hi:[1,0]
	v_pk_mul_f32 v[56:57], v[56:57], s[74:75] op_sel_hi:[1,0]
	v_pk_mul_f32 v[50:51], v[50:51], s[74:75] op_sel_hi:[1,0]
	v_pk_mul_f32 v[52:53], v[52:53], s[74:75] op_sel_hi:[1,0]
	v_exp_f32_e32 v54, v54
	v_exp_f32_e32 v55, v55
	v_exp_f32_e32 v56, v56
	v_exp_f32_e32 v57, v57
	v_exp_f32_e32 v50, v50
	v_exp_f32_e32 v51, v51
	v_exp_f32_e32 v52, v52
	v_exp_f32_e32 v53, v53
	v_pk_add_f32 v[54:55], v[54:55], 1.0 op_sel_hi:[1,0]
	v_pk_add_f32 v[56:57], v[56:57], 1.0 op_sel_hi:[1,0]
	v_pk_add_f32 v[50:51], v[50:51], 1.0 op_sel_hi:[1,0]
	v_pk_add_f32 v[52:53], v[52:53], 1.0 op_sel_hi:[1,0]
	v_rcp_f32_e32 v54, v54
	v_rcp_f32_e32 v55, v55
	v_rcp_f32_e32 v56, v56
	v_rcp_f32_e32 v57, v57
	v_rcp_f32_e32 v50, v50
	v_rcp_f32_e32 v51, v51
	v_rcp_f32_e32 v52, v52
	v_rcp_f32_e32 v53, v53
	v_pk_add_f32 v[46:47], v[46:47], v[38:39]
	v_pk_add_f32 v[42:43], v[42:43], v[34:35]
	v_pk_add_f32 v[48:49], v[48:49], v[40:41]
	v_pk_mul_f32 v[46:47], v[46:47], s[74:75] op_sel_hi:[1,0]
	v_pk_add_f32 v[44:45], v[44:45], v[36:37]
	v_pk_mul_f32 v[42:43], v[42:43], s[74:75] op_sel_hi:[1,0]
	v_pk_mul_f32 v[48:49], v[48:49], s[74:75] op_sel_hi:[1,0]
	v_exp_f32_e32 v46, v46
	v_exp_f32_e32 v47, v47
	v_pk_mul_f32 v[44:45], v[44:45], s[74:75] op_sel_hi:[1,0]
	v_exp_f32_e32 v42, v42
	v_exp_f32_e32 v43, v43
	v_exp_f32_e32 v48, v48
	v_exp_f32_e32 v49, v49
	s_waitcnt vmcnt(0)
; #define GAS __attribute__((address_space(1)))
; __device__ __forceinline__ u32x4 pack8(f32x4 v0, f32x4 v1) { u32x4 w; w.x = cvt_pk_bf16(v0[0], v0[1]); w.y = cvt_pk_bf16(v0[2], v0[3]); w.z = cvt_pk_bf16(v1[0], v1[1]); w.w = cvt_pk_bf16(v1[2], v1[3]); return w; }
; __device__ __forceinline__ void unpack8(u32x4 w, f32x4& v0, f32x4& v1) { v0 = (f32x4){bflo(w.x), bfhi(w.x), bflo(w.y), bfhi(w.y)}; v1 = (f32x4){bflo(w.z), bfhi(w.z), bflo(w.w), bfhi(w.w)}; }
; #define GAS __attribute__((address_space(1)))
;     __device__ __forceinline__ void operator()(const f32x4 (&acc)[2][2][4][2], const Unit& u, int wr, int wc, int fr, int fq) const {
;     ...
;             for (int m = 0; m < 4; ++m) { const size_t off = (size_t)(ai * HALF + m * 16) * 1024;
; #pragma unroll
;                 for (int bj = 0; bj < 2; ++bj) { f32x4 z0, z1; unpack8(*(const GAS u32x4*)(zb + off + bj * HALF), z0, z1);
;                     const f32x4 v0 = z0 * sigmoid4(acc[ai][bj][m][0] + bv[bj][0]), v1 = z1 * sigmoid4(acc[ai][bj][m][1] + bv[bj][1]);
;                     *(GAS u32x4*)(sob + off + bj * HALF) = pack8(v0, v1); } }
	v_lshlrev_b32_e32 v122, 16, v118
	v_and_b32_e32 v123, 0xffff0000, v118
	v_lshlrev_b32_e32 v124, 16, v120
	v_and_b32_e32 v125, 0xffff0000, v120
	v_lshlrev_b32_e32 v118, 16, v119
	v_and_b32_e32 v119, 0xffff0000, v119
	v_lshlrev_b32_e32 v120, 16, v121
	v_and_b32_e32 v121, 0xffff0000, v121
	v_pk_mul_f32 v[112:113], v[112:113], v[122:123]
	v_pk_mul_f32 v[108:109], v[108:109], v[124:125]
	v_pk_mul_f32 v[114:115], v[114:115], v[118:119]
	v_pk_mul_f32 v[118:119], v[110:111], v[120:121]
	v_cvt_pk_bf16_f32 v110, v112, v113
	v_cvt_pk_bf16_f32 v112, v108, v109
	v_add_co_u32_e32 v108, vcc, s73, v160
	v_cvt_pk_bf16_f32 v111, v114, v115
	v_cvt_pk_bf16_f32 v113, v118, v119
	v_addc_co_u32_e32 v109, vcc, 0, v161, vcc
	global_store_dwordx4 v[108:109], v[110:113], off
	global_load_dwordx4 v[110:113], v[116:117], off offset:256
	v_exp_f32_e32 v44, v44
	v_exp_f32_e32 v45, v45
	v_pk_add_f32 v[46:47], v[46:47], 1.0 op_sel_hi:[1,0]
	v_pk_add_f32 v[42:43], v[42:43], 1.0 op_sel_hi:[1,0]
	v_pk_add_f32 v[48:49], v[48:49], 1.0 op_sel_hi:[1,0]
	v_rcp_f32_e32 v46, v46
	v_rcp_f32_e32 v47, v47
	v_pk_add_f32 v[44:45], v[44:45], 1.0 op_sel_hi:[1,0]
	v_rcp_f32_e32 v42, v42
	v_rcp_f32_e32 v43, v43
	v_rcp_f32_e32 v48, v48
	v_rcp_f32_e32 v49, v49
	v_rcp_f32_e32 v44, v44
	v_rcp_f32_e32 v45, v45
	v_pk_add_f32 v[32:33], v[32:33], v[24:25]
	v_pk_add_f32 v[30:31], v[30:31], v[22:23]
	v_pk_add_f32 v[28:29], v[28:29], v[16:17]
	v_pk_add_f32 v[26:27], v[26:27], v[14:15]
	v_pk_mul_f32 v[30:31], v[30:31], s[74:75] op_sel_hi:[1,0]
	v_pk_mul_f32 v[32:33], v[32:33], s[74:75] op_sel_hi:[1,0]
	v_pk_mul_f32 v[26:27], v[26:27], s[74:75] op_sel_hi:[1,0]
	v_pk_mul_f32 v[28:29], v[28:29], s[74:75] op_sel_hi:[1,0]
	v_exp_f32_e32 v30, v30
	v_exp_f32_e32 v31, v31
	v_exp_f32_e32 v32, v32
	v_exp_f32_e32 v33, v33
	v_exp_f32_e32 v26, v26
	v_exp_f32_e32 v27, v27
	v_exp_f32_e32 v28, v28
	v_exp_f32_e32 v29, v29
	v_pk_add_f32 v[30:31], v[30:31], 1.0 op_sel_hi:[1,0]
	v_pk_add_f32 v[32:33], v[32:33], 1.0 op_sel_hi:[1,0]
	v_pk_add_f32 v[26:27], v[26:27], 1.0 op_sel_hi:[1,0]
	v_pk_add_f32 v[28:29], v[28:29], 1.0 op_sel_hi:[1,0]
	v_rcp_f32_e32 v30, v30
	v_rcp_f32_e32 v31, v31
	v_rcp_f32_e32 v32, v32
	v_rcp_f32_e32 v33, v33
	v_rcp_f32_e32 v26, v26
	v_rcp_f32_e32 v27, v27
	v_rcp_f32_e32 v28, v28
	v_rcp_f32_e32 v29, v29
	v_pk_add_f32 v[18:19], v[18:19], v[38:39]
	v_pk_add_f32 v[20:21], v[20:21], v[40:41]
	v_pk_mul_f32 v[18:19], v[18:19], s[74:75] op_sel_hi:[1,0]
	v_pk_add_f32 v[12:13], v[12:13], v[36:37]
	v_pk_add_f32 v[10:11], v[10:11], v[34:35]
	v_pk_mul_f32 v[20:21], v[20:21], s[74:75] op_sel_hi:[1,0]
	v_exp_f32_e32 v18, v18
	v_exp_f32_e32 v19, v19
	v_pk_mul_f32 v[10:11], v[10:11], s[74:75] op_sel_hi:[1,0]
	v_pk_mul_f32 v[12:13], v[12:13], s[74:75] op_sel_hi:[1,0]
	v_exp_f32_e32 v20, v20
	v_exp_f32_e32 v21, v21
	v_exp_f32_e32 v10, v10
	v_exp_f32_e32 v11, v11
	v_exp_f32_e32 v12, v12
	v_exp_f32_e32 v13, v13
	v_pk_add_f32 v[18:19], v[18:19], 1.0 op_sel_hi:[1,0]
	v_pk_add_f32 v[20:21], v[20:21], 1.0 op_sel_hi:[1,0]
	v_rcp_f32_e32 v18, v18
	v_rcp_f32_e32 v19, v19
	v_pk_add_f32 v[10:11], v[10:11], 1.0 op_sel_hi:[1,0]
	v_pk_add_f32 v[12:13], v[12:13], 1.0 op_sel_hi:[1,0]
	v_rcp_f32_e32 v20, v20
	v_rcp_f32_e32 v21, v21
	v_rcp_f32_e32 v10, v10
	v_rcp_f32_e32 v11, v11
	v_rcp_f32_e32 v12, v12
	v_rcp_f32_e32 v13, v13
	v_pk_add_f32 v[8:9], v[8:9], v[24:25]
	v_pk_add_f32 v[6:7], v[6:7], v[22:23]
	v_pk_add_f32 v[4:5], v[4:5], v[16:17]
	v_pk_add_f32 v[2:3], v[2:3], v[14:15]
	v_pk_mul_f32 v[6:7], v[6:7], s[74:75] op_sel_hi:[1,0]
	v_pk_mul_f32 v[8:9], v[8:9], s[74:75] op_sel_hi:[1,0]
	v_pk_mul_f32 v[2:3], v[2:3], s[74:75] op_sel_hi:[1,0]
	v_pk_mul_f32 v[4:5], v[4:5], s[74:75] op_sel_hi:[1,0]
	v_exp_f32_e32 v6, v6
	s_waitcnt vmcnt(0)
	v_lshlrev_b32_e32 v114, 16, v110
	v_and_b32_e32 v115, 0xffff0000, v110
	v_lshlrev_b32_e32 v110, 16, v111
	v_and_b32_e32 v111, 0xffff0000, v111
	v_lshlrev_b32_e32 v116, 16, v112
	v_and_b32_e32 v117, 0xffff0000, v112
	v_lshlrev_b32_e32 v112, 16, v113
	v_and_b32_e32 v113, 0xffff0000, v113
	v_pk_mul_f32 v[106:107], v[106:107], v[110:111]
	v_pk_mul_f32 v[104:105], v[104:105], v[114:115]
	v_pk_mul_f32 v[110:111], v[102:103], v[112:113]
	v_pk_mul_f32 v[102:103], v[100:101], v[116:117]
	v_cvt_pk_bf16_f32 v100, v104, v105
	v_cvt_pk_bf16_f32 v101, v106, v107
	v_cvt_pk_bf16_f32 v102, v102, v103
	v_cvt_pk_bf16_f32 v103, v110, v111
	global_store_dwordx4 v[108:109], v[100:103], off offset:256
	v_exp_f32_e32 v7, v7
	v_exp_f32_e32 v8, v8
	v_add_co_u32_e32 v100, vcc, s93, v162
	v_exp_f32_e32 v9, v9
	s_nop 0
	v_addc_co_u32_e32 v101, vcc, 0, v163, vcc
	global_load_dwordx4 v[102:105], v[100:101], off
	v_exp_f32_e32 v2, v2
	v_exp_f32_e32 v3, v3
	v_exp_f32_e32 v4, v4
	v_exp_f32_e32 v5, v5
	v_pk_add_f32 v[6:7], v[6:7], 1.0 op_sel_hi:[1,0]
	v_pk_add_f32 v[8:9], v[8:9], 1.0 op_sel_hi:[1,0]
	v_pk_add_f32 v[2:3], v[2:3], 1.0 op_sel_hi:[1,0]
	v_pk_add_f32 v[4:5], v[4:5], 1.0 op_sel_hi:[1,0]
	v_rcp_f32_e32 v6, v6
	v_rcp_f32_e32 v7, v7
	v_rcp_f32_e32 v8, v8
	v_rcp_f32_e32 v9, v9
	v_rcp_f32_e32 v2, v2
	v_rcp_f32_e32 v3, v3
	v_rcp_f32_e32 v4, v4
	v_rcp_f32_e32 v5, v5
	s_waitcnt vmcnt(0)
	v_lshlrev_b32_e32 v106, 16, v102
	v_and_b32_e32 v107, 0xffff0000, v102
	v_lshlrev_b32_e32 v108, 16, v104
	v_and_b32_e32 v109, 0xffff0000, v104
	v_lshlrev_b32_e32 v102, 16, v103
	v_and_b32_e32 v103, 0xffff0000, v103
	v_lshlrev_b32_e32 v104, 16, v105
	v_and_b32_e32 v105, 0xffff0000, v105
	v_pk_mul_f32 v[94:95], v[94:95], v[106:107]
	v_pk_mul_f32 v[90:91], v[90:91], v[108:109]
	v_pk_mul_f32 v[96:97], v[96:97], v[102:103]
	v_pk_mul_f32 v[102:103], v[92:93], v[104:105]
	v_cvt_pk_bf16_f32 v92, v94, v95
	v_cvt_pk_bf16_f32 v94, v90, v91
	v_add_co_u32_e32 v90, vcc, s93, v160
	v_cvt_pk_bf16_f32 v93, v96, v97
	v_cvt_pk_bf16_f32 v95, v102, v103
	v_addc_co_u32_e32 v91, vcc, 0, v161, vcc
	global_store_dwordx4 v[90:91], v[92:95], off
	global_load_dwordx4 v[92:95], v[100:101], off offset:256
	s_waitcnt vmcnt(0)
; #define GAS __attribute__((address_space(1)))
; __device__ __forceinline__ u32x4 pack8(f32x4 v0, f32x4 v1) { u32x4 w; w.x = cvt_pk_bf16(v0[0], v0[1]); w.y = cvt_pk_bf16(v0[2], v0[3]); w.z = cvt_pk_bf16(v1[0], v1[1]); w.w = cvt_pk_bf16(v1[2], v1[3]); return w; }
; __device__ __forceinline__ void unpack8(u32x4 w, f32x4& v0, f32x4& v1) { v0 = (f32x4){bflo(w.x), bfhi(w.x), bflo(w.y), bfhi(w.y)}; v1 = (f32x4){bflo(w.z), bfhi(w.z), bflo(w.w), bfhi(w.w)}; }
; #define PG8_BAR __builtin_amdgcn_s_barrier()
; #define GAS __attribute__((address_space(1)))
;     __device__ __forceinline__ void operator()(const f32x4 (&acc)[2][2][4][2], const Unit& u, int wr, int wc, int fr, int fq) const {
;     ...
;             for (int m = 0; m < 4; ++m) { const size_t off = (size_t)(ai * HALF + m * 16) * 1024;
; #pragma unroll
;                 for (int bj = 0; bj < 2; ++bj) { f32x4 z0, z1; unpack8(*(const GAS u32x4*)(zb + off + bj * HALF), z0, z1);
;                     const f32x4 v0 = z0 * sigmoid4(acc[ai][bj][m][0] + bv[bj][0]), v1 = z1 * sigmoid4(acc[ai][bj][m][1] + bv[bj][1]);
;                     *(GAS u32x4*)(sob + off + bj * HALF) = pack8(v0, v1); } }
; template <class Epi, class Sched, bool ALIGN_EPI = false, bool SP2 = false>
; __device__ __forceinline__ void gemm_phase(PG8_LAS unsigned char* lds, const Gemm g, const Sched& S, const Epi& E) {
;     ...
;         cur = nxt; cA = nA; cB = nB; ++ui;
;         if constexpr (ALIGN_EPI) { if (wr == 1) PG8_BAR; }
	v_lshlrev_b32_e32 v96, 16, v92
	v_and_b32_e32 v97, 0xffff0000, v92
	v_lshlrev_b32_e32 v92, 16, v93
	v_and_b32_e32 v93, 0xffff0000, v93
	v_lshlrev_b32_e32 v100, 16, v94
	v_and_b32_e32 v101, 0xffff0000, v94
	v_lshlrev_b32_e32 v94, 16, v95
	v_and_b32_e32 v95, 0xffff0000, v95
	v_pk_mul_f32 v[88:89], v[88:89], v[92:93]
	v_pk_mul_f32 v[86:87], v[86:87], v[96:97]
	v_pk_mul_f32 v[92:93], v[84:85], v[94:95]
	v_pk_mul_f32 v[84:85], v[82:83], v[100:101]
	v_cvt_pk_bf16_f32 v82, v86, v87
	v_cvt_pk_bf16_f32 v83, v88, v89
	v_cvt_pk_bf16_f32 v84, v84, v85
	v_cvt_pk_bf16_f32 v85, v92, v93
	global_store_dwordx4 v[90:91], v[82:85], off offset:256
	s_nop 1
	v_add_co_u32_e32 v82, vcc, s49, v162
	s_nop 1
	v_addc_co_u32_e32 v83, vcc, 0, v163, vcc
	global_load_dwordx4 v[84:87], v[82:83], off
	s_waitcnt vmcnt(0)
	v_lshlrev_b32_e32 v88, 16, v84
	v_and_b32_e32 v89, 0xffff0000, v84
	v_lshlrev_b32_e32 v90, 16, v86
	v_and_b32_e32 v91, 0xffff0000, v86
	v_lshlrev_b32_e32 v84, 16, v85
	v_and_b32_e32 v85, 0xffff0000, v85
	v_lshlrev_b32_e32 v86, 16, v87
	v_and_b32_e32 v87, 0xffff0000, v87
	v_pk_mul_f32 v[78:79], v[78:79], v[88:89]
	v_pk_mul_f32 v[74:75], v[74:75], v[90:91]
	v_pk_mul_f32 v[80:81], v[80:81], v[84:85]
	v_pk_mul_f32 v[84:85], v[76:77], v[86:87]
	v_cvt_pk_bf16_f32 v76, v78, v79
	v_cvt_pk_bf16_f32 v78, v74, v75
	v_add_co_u32_e32 v74, vcc, s49, v160
	v_cvt_pk_bf16_f32 v77, v80, v81
	v_cvt_pk_bf16_f32 v79, v84, v85
	v_addc_co_u32_e32 v75, vcc, 0, v161, vcc
	global_store_dwordx4 v[74:75], v[76:79], off
	global_load_dwordx4 v[76:79], v[82:83], off offset:256
	s_waitcnt vmcnt(0)
	v_lshlrev_b32_e32 v80, 16, v76
	v_and_b32_e32 v81, 0xffff0000, v76
	v_lshlrev_b32_e32 v76, 16, v77
	v_and_b32_e32 v77, 0xffff0000, v77
	v_lshlrev_b32_e32 v82, 16, v78
	v_and_b32_e32 v83, 0xffff0000, v78
	v_lshlrev_b32_e32 v78, 16, v79
	v_and_b32_e32 v79, 0xffff0000, v79
	v_pk_mul_f32 v[72:73], v[72:73], v[76:77]
	v_pk_mul_f32 v[70:71], v[70:71], v[80:81]
	v_pk_mul_f32 v[76:77], v[68:69], v[78:79]
	v_pk_mul_f32 v[68:69], v[66:67], v[82:83]
	v_cvt_pk_bf16_f32 v66, v70, v71
	v_cvt_pk_bf16_f32 v67, v72, v73
	v_cvt_pk_bf16_f32 v68, v68, v69
	v_cvt_pk_bf16_f32 v69, v76, v77
	global_store_dwordx4 v[74:75], v[66:69], off offset:256
	s_nop 1
	v_add_co_u32_e32 v66, vcc, s50, v162
	s_nop 1
	v_addc_co_u32_e32 v67, vcc, 0, v163, vcc
	global_load_dwordx4 v[68:71], v[66:67], off
	s_waitcnt vmcnt(0)
	v_lshlrev_b32_e32 v72, 16, v68
	v_and_b32_e32 v73, 0xffff0000, v68
	v_lshlrev_b32_e32 v74, 16, v70
	v_and_b32_e32 v75, 0xffff0000, v70
	v_lshlrev_b32_e32 v68, 16, v69
	v_and_b32_e32 v69, 0xffff0000, v69
	v_lshlrev_b32_e32 v70, 16, v71
	v_and_b32_e32 v71, 0xffff0000, v71
	v_pk_mul_f32 v[62:63], v[62:63], v[72:73]
	v_pk_mul_f32 v[58:59], v[58:59], v[74:75]
	v_pk_mul_f32 v[64:65], v[64:65], v[68:69]
	v_pk_mul_f32 v[68:69], v[60:61], v[70:71]
	v_cvt_pk_bf16_f32 v60, v62, v63
	v_cvt_pk_bf16_f32 v62, v58, v59
	v_add_co_u32_e32 v58, vcc, s50, v160
	v_cvt_pk_bf16_f32 v61, v64, v65
	v_cvt_pk_bf16_f32 v63, v68, v69
	v_addc_co_u32_e32 v59, vcc, 0, v161, vcc
	global_store_dwordx4 v[58:59], v[60:63], off
	global_load_dwordx4 v[60:63], v[66:67], off offset:256
	s_waitcnt vmcnt(0)
	v_lshlrev_b32_e32 v64, 16, v60
	v_and_b32_e32 v65, 0xffff0000, v60
	v_lshlrev_b32_e32 v60, 16, v61
	v_and_b32_e32 v61, 0xffff0000, v61
	v_lshlrev_b32_e32 v66, 16, v62
	v_and_b32_e32 v67, 0xffff0000, v62
	v_lshlrev_b32_e32 v62, 16, v63
	v_and_b32_e32 v63, 0xffff0000, v63
	v_pk_mul_f32 v[56:57], v[56:57], v[60:61]
	v_pk_mul_f32 v[54:55], v[54:55], v[64:65]
	v_pk_mul_f32 v[60:61], v[52:53], v[62:63]
	v_pk_mul_f32 v[52:53], v[50:51], v[66:67]
	v_cvt_pk_bf16_f32 v50, v54, v55
	v_cvt_pk_bf16_f32 v51, v56, v57
	v_cvt_pk_bf16_f32 v52, v52, v53
	v_cvt_pk_bf16_f32 v53, v60, v61
	global_store_dwordx4 v[58:59], v[50:53], off offset:256
	s_nop 1
	v_add_co_u32_e32 v50, vcc, s51, v162
	s_nop 1
	v_addc_co_u32_e32 v51, vcc, 0, v163, vcc
	global_load_dwordx4 v[52:55], v[50:51], off
	s_waitcnt vmcnt(0)
	v_lshlrev_b32_e32 v56, 16, v52
	v_and_b32_e32 v57, 0xffff0000, v52
	v_lshlrev_b32_e32 v58, 16, v54
	v_and_b32_e32 v59, 0xffff0000, v54
	v_lshlrev_b32_e32 v52, 16, v53
	v_and_b32_e32 v53, 0xffff0000, v53
	v_lshlrev_b32_e32 v54, 16, v55
	v_and_b32_e32 v55, 0xffff0000, v55
	v_pk_mul_f32 v[46:47], v[46:47], v[56:57]
	v_pk_mul_f32 v[42:43], v[42:43], v[58:59]
	v_pk_mul_f32 v[48:49], v[48:49], v[52:53]
	v_pk_mul_f32 v[52:53], v[44:45], v[54:55]
	v_cvt_pk_bf16_f32 v44, v46, v47
	v_cvt_pk_bf16_f32 v46, v42, v43
	v_add_co_u32_e32 v42, vcc, s51, v160
	v_cvt_pk_bf16_f32 v45, v48, v49
	v_cvt_pk_bf16_f32 v47, v52, v53
	v_addc_co_u32_e32 v43, vcc, 0, v161, vcc
	global_store_dwordx4 v[42:43], v[44:47], off
	global_load_dwordx4 v[44:47], v[50:51], off offset:256
	s_waitcnt vmcnt(0)
	v_lshlrev_b32_e32 v48, 16, v44
	v_and_b32_e32 v49, 0xffff0000, v44
	v_lshlrev_b32_e32 v44, 16, v45
	v_and_b32_e32 v45, 0xffff0000, v45
	v_lshlrev_b32_e32 v50, 16, v46
	v_and_b32_e32 v51, 0xffff0000, v46
	v_lshlrev_b32_e32 v46, 16, v47
	v_and_b32_e32 v47, 0xffff0000, v47
	v_pk_mul_f32 v[32:33], v[32:33], v[44:45]
	v_pk_mul_f32 v[30:31], v[30:31], v[48:49]
	v_pk_mul_f32 v[44:45], v[28:29], v[46:47]
	v_pk_mul_f32 v[28:29], v[26:27], v[50:51]
	v_cvt_pk_bf16_f32 v26, v30, v31
	v_cvt_pk_bf16_f32 v27, v32, v33
	v_cvt_pk_bf16_f32 v28, v28, v29
	v_cvt_pk_bf16_f32 v29, v44, v45
	global_store_dwordx4 v[42:43], v[26:29], off offset:256
	s_nop 1
	v_add_co_u32_e32 v26, vcc, s66, v162
	s_nop 1
	v_addc_co_u32_e32 v27, vcc, 0, v163, vcc
	global_load_dwordx4 v[28:31], v[26:27], off
	s_waitcnt vmcnt(0)
	v_lshlrev_b32_e32 v32, 16, v28
	v_and_b32_e32 v33, 0xffff0000, v28
	v_lshlrev_b32_e32 v28, 16, v29
	v_and_b32_e32 v29, 0xffff0000, v29
	v_lshlrev_b32_e32 v42, 16, v30
	v_and_b32_e32 v43, 0xffff0000, v30
	v_lshlrev_b32_e32 v30, 16, v31
	v_and_b32_e32 v31, 0xffff0000, v31
	v_pk_mul_f32 v[18:19], v[18:19], v[32:33]
	v_pk_mul_f32 v[20:21], v[20:21], v[28:29]
	v_pk_mul_f32 v[28:29], v[12:13], v[30:31]
	v_pk_mul_f32 v[12:13], v[10:11], v[42:43]
	v_cvt_pk_bf16_f32 v10, v18, v19
	v_add_co_u32_e32 v18, vcc, s66, v160
	v_cvt_pk_bf16_f32 v11, v20, v21
	v_cvt_pk_bf16_f32 v12, v12, v13
	v_cvt_pk_bf16_f32 v13, v28, v29
	v_addc_co_u32_e32 v19, vcc, 0, v161, vcc
	global_store_dwordx4 v[18:19], v[10:13], off
	global_load_dwordx4 v[10:13], v[26:27], off offset:256
	s_andn2_b64 vcc, exec, s[18:19]
	s_waitcnt vmcnt(0)
	v_lshlrev_b32_e32 v20, 16, v10
	v_and_b32_e32 v21, 0xffff0000, v10
	v_lshlrev_b32_e32 v10, 16, v11
	v_and_b32_e32 v11, 0xffff0000, v11
	v_lshlrev_b32_e32 v26, 16, v12
	v_and_b32_e32 v27, 0xffff0000, v12
	v_lshlrev_b32_e32 v12, 16, v13
	v_and_b32_e32 v13, 0xffff0000, v13
	v_pk_mul_f32 v[8:9], v[8:9], v[10:11]
	v_pk_mul_f32 v[6:7], v[6:7], v[20:21]
	v_pk_mul_f32 v[10:11], v[4:5], v[12:13]
	v_pk_mul_f32 v[4:5], v[2:3], v[26:27]
	v_cvt_pk_bf16_f32 v2, v6, v7
	v_cvt_pk_bf16_f32 v3, v8, v9
	v_cvt_pk_bf16_f32 v4, v4, v5
	v_cvt_pk_bf16_f32 v5, v10, v11
	global_store_dwordx4 v[18:19], v[2:5], off offset:256
	s_cbranch_vccnz .LBB0_923
	s_andn2_b64 vcc, exec, s[6:7]
	s_cbranch_vccnz .LBB0_922
	s_branch .LBB0_922

; #define PG8_WAIT_V(n) asm volatile("s_waitcnt vmcnt(" #n ")" ::: "memory")
; #define PG8_BAR __builtin_amdgcn_s_barrier()
; template <class Epi, class Sched, bool ALIGN_EPI = false, bool SP2 = false>
; __device__ __forceinline__ void gemm_phase(PG8_LAS unsigned char* lds, const Gemm g, const Sched& S, const Epi& E) {
;     ...
;     const int tid = tid_l, wid = __builtin_amdgcn_readfirstlane(tid >> 6), lane = tid & 63, wr = wid >> 2, wc = wid & 3, fr = lane & 15, fq = lane >> 4;
;     const int K = g.K;
;     unsigned voffA[2], voffB[2];
; #pragma unroll
;     for (int i = 0; i < 2; ++i) { int R, C; stage_rc(tid * 16 + i * 8192, R, C); const int Rb = Epi::PERM ? ((R & ~31) + perm32(R & 31)) : R;
;         voffA[i] = (unsigned)(R * K + C) * 2u; voffB[i] = (unsigned)(Rb * K + C) * 2u; }
;     const size_t kstep = (size_t)(BK * 2);
;     const size_t hstep = (size_t)HALF * K * 2;
;     const size_t tstep = 2 * hstep;
;     const unsigned ldsw = (unsigned)wid * 1024u;
;     const int aoff = lds_byte(wr * 64 + fr, fq * 8), boff = lds_byte(wc * 32 + fr, fq * 8);
;     ...
;     Unit cur, nxt; int ui = 0;
;     if (!S.next(0, cur)) return;
;     f32x4 acc[2][2][4][2];
; #pragma unroll
;     for (int a = 0; a < 2; ++a)
; #pragma unroll
;         for (int b = 0; b < 2; ++b)
; #pragma unroll
;             for (int m = 0; m < 4; ++m)
; #pragma unroll
;                 for (int n = 0; n < 2; ++n) acc[a][b][m][n] = (f32x4){0.f, 0.f, 0.f, 0.f};
;     bf16x8 At[4][2], B0[2][2], B1[2][2];
;     const char* cA = (const char*)g.A + (size_t)cur.pm * tstep + (size_t)cur.kt0 * kstep; const char* cB = (const char*)g.Bt + (size_t)cur.pn * tstep + (size_t)cur.kt0 * kstep;
;     S.a_ready(cur);
;     ...
;     { const int rot0 = cur.krot, nt0 = cur.nkt; const char* sA0 = PG8_KP(cA, 0, rot0, nt0); const char* sA1 = PG8_KP(cA, 1, rot0, nt0); const char* sB0 = PG8_KP(cB, 0, rot0, nt0); const char* sB1 = PG8_KP(cB, 1, rot0, nt0);
;     if constexpr (SP2) {
;         PG8_STAGEB(PG8_SB(0, 0), sB0, voffB); PG8_STAGEB(PG8_SB(0, 1), sB0 + hstep, voffB); PG8_STAGE(PG8_SA(0, 0), sA0, voffA); PG8_STAGE(PG8_SA(0, 1), sA0 + hstep, voffA);
;         if (wr == 1) PG8_BAR;
;         PG8_WAIT_V(2); PG8_BAR;
;         PG8_STAGEB(PG8_SB(1, 0), sB1, voffB); PG8_STAGE(PG8_SA(1, 0), sA1, voffA); PG8_STAGEB(PG8_SB(1, 1), sB1 + hstep, voffB);
;         PG8_WAIT_V(6); PG8_BAR;
;     } else {
.LBB0_1052:
	s_andn2_b64 vcc, exec, s[4:5]
	s_cbranch_vccnz .LBB0_1288
	v_readlane_b32 s0, v254, 53
	v_readlane_b32 s1, v254, 54
	s_mov_b32 s1, s79
	s_lshl_b64 s[44:45], s[0:1], 22
	v_writelane_b32 v254, s0, 53
	s_mov_b64 s[4:5], s[66:67]
	v_mov_b32_e32 v16, v0
	v_writelane_b32 v254, s1, 54
	s_lshl_b64 s[0:1], s[0:1], 13
	s_add_u32 s2, s4, s44
	s_addc_u32 s6, s5, s45
	s_add_u32 s34, s2, 0x8000000
	s_addc_u32 s35, s6, 0
	s_add_u32 s8, s4, 0x1ec00000
	s_addc_u32 s9, s5, 0
	s_add_u32 s10, s4, 0x2ad80000
	s_addc_u32 s11, s5, 0
	s_add_u32 s0, s4, s0
	s_addc_u32 s1, s5, s1
	s_add_u32 s30, s0, 0x8000
	s_addc_u32 s31, s1, 0
	v_readlane_b32 s0, v252, 55
	v_readlane_b32 s1, v252, 56
	s_andn2_b64 vcc, exec, s[0:1]
	v_readfirstlane_b32 s12, v16
	v_cndmask_b32_e64 v1, 0, 1, s[0:1]
	v_cmp_ne_u32_e64 s[38:39], 1, v1
	s_cbranch_vccnz .LBB0_1143
	v_lshlrev_b32_e32 v1, 4, v16
	v_add_u32_e32 v2, 0x2000, v1
	v_ashrrev_i32_e32 v3, 31, v2
	v_lshrrev_b32_e32 v3, 22, v3
	v_add_u32_e32 v3, v2, v3
	v_ashrrev_i32_e32 v10, 10, v3
	v_mul_i32_i24_e32 v3, 0x400, v10
	v_sub_u32_e32 v2, v2, v3
	v_lshrrev_b32_e32 v3, 4, v2
	v_bitop3_b32 v2, v3, v2, 32 bitop3:0x6c
	v_ashrrev_i32_e32 v3, 31, v2
	v_lshrrev_b32_e32 v3, 26, v3
	v_add_u32_e32 v3, v2, v3
	v_lshlrev_b32_e32 v4, 3, v10
	v_ashrrev_i32_e32 v11, 6, v3
	v_and_b32_e32 v4, -16, v4
	v_add_u32_e32 v4, v11, v4
	v_and_b32_e32 v5, 3, v11
	s_mov_b32 s2, 0x1fffe0
	v_lshrrev_b32_e32 v6, 2, v4
	v_lshlrev_b32_e32 v7, 1, v4
	v_and_b32_e32 v3, 0xc0, v3
	v_and_or_b32 v5, v4, s2, v5
	v_and_b32_e32 v6, 4, v6
	v_and_b32_e32 v7, 24, v7
	v_sub_u32_e32 v2, v2, v3
	v_or3_b32 v5, v5, v6, v7
	v_lshlrev_b32_e32 v6, 5, v10
	v_ashrrev_i16_sdwa v2, v207, sext(v2) dst_sel:DWORD dst_unused:UNUSED_PAD src0_sel:DWORD src1_sel:BYTE_0
	v_and_b32_e32 v6, 32, v6
	v_bfe_i32 v12, v2, 0, 16
	v_add_lshl_u32 v2, v6, v12, 1
	s_waitcnt vmcnt(0)
	v_lshl_add_u32 v132, v5, 11, v2
	v_lshl_add_u32 v134, v4, 11, v2
	v_bfe_i32 v2, v16, 27, 1
	v_lshrrev_b32_e32 v2, 22, v2
	v_add_u32_e32 v2, v1, v2
	v_and_b32_e32 v2, 0xfffffc00, v2
	v_sub_u32_e32 v1, v1, v2
	v_lshrrev_b32_e32 v2, 4, v1
	v_ashrrev_i32_e32 v3, 31, v16
	v_bitop3_b32 v1, v2, v1, 32 bitop3:0x6c
	v_lshrrev_b32_e32 v3, 26, v3
	v_ashrrev_i32_e32 v2, 31, v1
	v_add_u32_e32 v3, v16, v3
	v_lshrrev_b32_e32 v2, 26, v2
	v_ashrrev_i32_e32 v14, 6, v3
	v_add_u32_e32 v2, v1, v2
	v_lshlrev_b32_e32 v3, 3, v14
	v_ashrrev_i32_e32 v13, 6, v2
	v_and_b32_e32 v3, -16, v3
	v_add_u32_e32 v3, v13, v3
	s_add_u32 s33, s4, 0x28980000
	v_and_b32_e32 v4, 3, v13
	v_lshrrev_b32_e32 v5, 2, v3
	v_lshlrev_b32_e32 v6, 1, v3
	v_and_b32_e32 v2, 0xc0, v2
	s_addc_u32 s69, s5, 0
	s_ashr_i32 s0, s12, 6
	v_and_or_b32 v4, v3, s2, v4
	v_and_b32_e32 v5, 4, v5
	v_and_b32_e32 v6, 24, v6
	v_sub_u32_e32 v1, v1, v2
	s_ashr_i32 s1, s12, 8
	s_lshl_b32 s70, s0, 10
	v_or3_b32 v4, v4, v5, v6
	v_lshlrev_b32_e32 v5, 5, v14
	v_ashrrev_i16_sdwa v1, v207, sext(v1) dst_sel:DWORD dst_unused:UNUSED_PAD src0_sel:DWORD src1_sel:BYTE_0
	v_readlane_b32 s2, v253, 3
	v_and_b32_e32 v5, 32, v5
	v_bfe_i32 v15, v1, 0, 16
	v_readlane_b32 s3, v253, 4
	s_add_u32 s42, s34, s2
	v_add_lshl_u32 v1, v5, v15, 1
	s_addc_u32 s43, s35, s3
	s_add_i32 s71, s70, 0
	v_lshl_add_u32 v136, v4, 11, v1
	s_add_i32 m0, s71, 0x10000
	v_readlane_b32 s2, v252, 63
	global_load_lds_dwordx4 v136, s[42:43]
	s_add_i32 m0, s71, 0x12000
	v_readlane_b32 s3, v253, 0
	s_add_u32 s52, s33, s2
	s_addc_u32 s53, s69, s3
	s_add_u32 s6, s42, 0x40000
	global_load_lds_dwordx4 v132, s[42:43]
	s_addc_u32 s7, s43, 0
	s_add_i32 m0, s71, 0x14000
	s_add_i32 s75, s71, 0x2000
	global_load_lds_dwordx4 v136, s[6:7]
	s_add_i32 m0, s71, 0x16000
	v_lshl_add_u32 v138, v3, 11, v1
	global_load_lds_dwordx4 v132, s[6:7]
	s_mov_b32 m0, s71
	s_add_u32 s6, s52, 0x40000
	global_load_lds_dwordx4 v138, s[52:53]
	s_mov_b32 m0, s75
	s_addc_u32 s7, s53, 0
	s_add_i32 s78, s71, 0x4000
	global_load_lds_dwordx4 v134, s[52:53]
	s_mov_b32 m0, s78
	s_add_i32 s82, s71, 0x6000
	global_load_lds_dwordx4 v138, s[6:7]
	s_mov_b32 m0, s82
	v_mov_b32_e32 v137, v98
	global_load_lds_dwordx4 v134, s[6:7]
	v_mov_b32_e32 v133, v98
	v_mov_b32_e32 v139, v98
	v_mov_b32_e32 v135, v98
	s_cmp_eq_u32 s1, 1
	v_lshl_add_u64 v[8:9], s[42:43], 0, v[136:137]
	v_lshl_add_u64 v[6:7], s[42:43], 0, v[132:133]
	v_lshl_add_u64 v[2:3], s[52:53], 0, v[138:139]
	s_cselect_b64 s[6:7], -1, 0
	s_cmp_lg_u32 s1, 1
	v_lshl_add_u64 v[4:5], s[52:53], 0, v[134:135]
	s_cbranch_scc1 .LBB0_1056
.LBB0_1056:
	v_bfe_u32 v18, v16, 4, 2
	s_lshl_b32 s0, s0, 5
	v_and_b32_e32 v17, 15, v16
	v_lshlrev_b32_e32 v19, 4, v18
	v_lshlrev_b32_e32 v16, 2, v16
	s_and_b32 s2, s0, 0x60
	s_add_i32 m0, s71, 0x18000
	v_lshl_add_u64 v[8:9], v[8:9], 0, s[76:77]
	v_lshl_or_b32 v1, s1, 6, v17
	v_lshl_or_b32 v19, v17, 6, v19
	s_lshl_b32 s1, s1, 13
	v_and_b32_e32 v16, 32, v16
	s_lshl_b32 s0, s2, 7
	s_waitcnt vmcnt(2)
	s_barrier
	global_load_lds_dwordx4 v[8:9], off
	v_lshl_add_u64 v[6:7], v[6:7], 0, s[76:77]
	s_add_i32 m0, s71, 0x1a000
	s_add_i32 s83, s71, 0x8000
	s_add_i32 s88, s71, 0xa000
	v_bitop3_b32 v99, v19, s0, v16 bitop3:0xde
	global_load_lds_dwordx4 v[6:7], off
	v_lshl_add_u64 v[2:3], v[2:3], 0, s[76:77]
	s_mov_b32 m0, s83
	s_add_u32 s0, s42, 0x40080
	v_bitop3_b32 v20, v19, s1, v16 bitop3:0xde
	global_load_lds_dwordx4 v[2:3], off
	v_lshl_add_u64 v[2:3], v[4:5], 0, s[76:77]
	s_mov_b32 m0, s88
	s_addc_u32 s1, s43, 0
	global_load_lds_dwordx4 v[2:3], off
	s_add_i32 m0, s71, 0x1c000
	v_lshl_add_u64 v[2:3], s[0:1], 0, v[136:137]
	global_load_lds_dwordx4 v[2:3], off
	v_lshl_add_u64 v[2:3], s[0:1], 0, v[132:133]
	s_add_i32 m0, s71, 0x1e000
	v_lshl_or_b32 v150, v18, 3, s2
	global_load_lds_dwordx4 v[2:3], off
	v_or_b32_e32 v2, v18, v17
	v_cmp_eq_u32_e64 s[40:41], 0, v2
	v_lshlrev_b32_e32 v2, 14, v10
	v_and_b32_e32 v2, 0xffff8000, v2
	v_lshl_add_u32 v2, v11, 11, v2
	v_and_b32_e32 v3, 1, v10
	v_lshl_or_b32 v2, v3, 6, v2
	v_lshl_add_u32 v140, v12, 1, v2
	v_lshlrev_b32_e32 v2, 14, v14
	v_and_b32_e32 v2, 0xffff8000, v2
	v_readlane_b32 s2, v253, 1
	s_waitcnt vmcnt(6)
	v_lshl_add_u32 v2, v13, 11, v2
	v_and_b32_e32 v3, 1, v14
	v_readlane_b32 s3, v253, 2
	s_cmpk_lt_u32 s12, 0x100
	v_lshl_or_b32 v2, v3, 6, v2
	s_mov_b32 s91, s2
	v_readlane_b32 s2, v252, 61
	s_cselect_b64 s[12:13], -1, 0
	s_mov_b32 s0, 0
	v_mov_b32_e32 v141, v98
	v_lshl_add_u32 v142, v15, 1, v2
	v_mov_b32_e32 v143, v98
	v_add_u32_e32 v151, 0, v20
	s_mov_b32 s90, s2
	s_barrier
	v_readlane_b32 s3, v252, 62
	s_branch .LBB0_1059

; #define PG8_STAGE(bufoff, gbase, voff) do { _Pragma("unroll") for (int _i = 0; _i < 2; ++_i) \
;         __builtin_amdgcn_global_load_lds((const unsigned*)((const char*)(gbase) + (voff)[_i]), (PG8_LAS unsigned*)(lds + (bufoff) + ldsw + _i * 8192), 16, 0, AUX_A); } while (0)
; #define PG8_STAGEB(bufoff, gbase, voff) do { _Pragma("unroll") for (int _i = 0; _i < 2; ++_i) \
;         __builtin_amdgcn_global_load_lds((const unsigned*)((const char*)(gbase) + (voff)[_i]), (PG8_LAS unsigned*)(lds + (bufoff) + ldsw + _i * 8192), 16, 0, AUX_B); } while (0)
; #define PG8_WAIT_V(n) asm volatile("s_waitcnt vmcnt(" #n ")" ::: "memory")
; #define PG8_WAIT_L(n) asm volatile("s_waitcnt lgkmcnt(" #n ")" ::: "memory")
; template <class Epi, class Sched, bool ALIGN_EPI = false, bool SP2 = false>
; __device__ __forceinline__ void gemm_phase(PG8_LAS unsigned char* lds, const Gemm g, const Sched& S, const Epi& E) {
;     ...
;         for (int t = 0; t < nt; t += 2) {
;             const bool last = (t == nt - 2);
;             const char* a1 = PG8_KP(cA, t + 1, rot, nt);
;             const char* a2 = last ? nAr : PG8_KP(cA, t + 2, rot, nt); const char* b2 = last ? nBr : PG8_KP(cB, t + 2, rot, nt);
;             const char* a3 = a2 + kstep; const char* b3 = b2 + kstep;
;             if (last && has_next) S.a_ready(nxt);
;             if constexpr (SP2) {
;             PG8_LDB(B0, 0, 0); PG8_LDB(B1, 0, 1); PG8_SCHED; PG8_LDA(At, 0, 0); PG8_STAGE(PG8_SA(1, 1), a1 + hstep, voffA);
;             PG8_WAIT_V(8); PG8_WAIT_L(0); PG8_BAR; PG8_MMA(0, 0, At, B0); PG8_MMA(0, 1, At, B1); PG8_BAR; PG8_SCHED;
;             PG8_LDA(At, 0, 1); PG8_STAGEB(PG8_SB(0, 0), b2, voffB); PG8_STAGEB(PG8_SB(0, 1), b2 + hstep, voffB); PG8_STAGE(PG8_SA(0, 0), a2, voffA);
;             PG8_WAIT_V(8); PG8_WAIT_L(0); PG8_BAR; PG8_MMA(1, 0, At, B0); PG8_MMA(1, 1, At, B1); PG8_BAR; PG8_SCHED;
;             PG8_LDB(B0, 1, 0); PG8_LDB(B1, 1, 1); PG8_SCHED; PG8_LDA(At, 1, 0); PG8_STAGE(PG8_SA(0, 1), a2 + hstep, voffA);
;             PG8_WAIT_V(8); PG8_WAIT_L(0); PG8_BAR; PG8_MMA(0, 0, At, B0); PG8_MMA(0, 1, At, B1); PG8_BAR; PG8_SCHED;
;             PG8_LDA(At, 1, 1); PG8_STAGEB(PG8_SB(1, 0), b3, voffB); PG8_STAGEB(PG8_SB(1, 1), b3 + hstep, voffB); PG8_STAGE(PG8_SA(1, 0), a3, voffA);
;             PG8_WAIT_V(8); PG8_WAIT_L(0); PG8_BAR; PG8_MMA(1, 0, At, B0); PG8_MMA(1, 1, At, B1); PG8_BAR; PG8_SCHED;
.LBB0_1067:
	s_add_i32 s81, s29, 2
	s_cmp_lt_u32 s29, 14
	s_cselect_b32 s0, 0, -16
	s_add_i32 s0, s81, s0
	s_ashr_i32 s1, s0, 31
	s_lshl_b64 s[0:1], s[0:1], 7
	s_add_u32 s2, s52, s0
	s_addc_u32 s46, s53, s1
	s_add_u32 s0, s42, s0
	s_addc_u32 s1, s43, s1
	s_cmp_eq_u32 s29, 14
	s_cselect_b32 s59, s15, s46
	s_cselect_b32 s58, s17, s2
	s_cselect_b32 s61, s92, s1
	s_cselect_b32 s60, s93, s0
	s_add_i32 s2, 0, 0x10000
	s_add_i32 s94, s2, s70
	s_add_i32 s46, 0, 0x14000
	s_add_i32 m0, s71, 0xc000
	s_add_i32 s84, s71, 0xe000
	s_add_i32 s95, s94, 0x2000
	s_add_u32 s62, s60, 0x40000
	v_add_u32_e32 v148, s2, v99
	s_addc_u32 s63, s61, 0
	s_add_i32 s96, s46, s70
	ds_read_b128 v[152:155], v148
	ds_read_b128 v[156:159], v148 offset:1024
	ds_read_b128 v[160:163], v148 offset:2048
	ds_read_b128 v[164:167], v148 offset:3072
	v_add_u32_e32 v148, s46, v99
	s_add_i32 s97, s96, 0x2000
	s_add_i32 vcc_lo, 0, 0x18000
	s_add_i32 vcc_hi, 0, 0x1c000
	ds_read_b128 v[180:183], v148
	ds_read_b128 v[184:187], v148 offset:1024
	ds_read_b128 v[188:191], v148 offset:2048
	ds_read_b128 v[192:195], v148 offset:3072
	s_add_u32 s56, s58, 0x40000
	s_addc_u32 s57, s59, 0
	s_add_i32 s1, vcc_lo, s70
	s_add_i32 s0, s1, 0x2000
	s_add_u32 s54, s60, 0x40080
	s_addc_u32 s55, s61, 0
	s_add_i32 s47, vcc_hi, s70
	s_add_i32 s46, s47, 0x2000
	ds_read_b128 v[196:199], v151
	ds_read_b128 v[200:203], v151 offset:1024
	ds_read_b128 v[222:225], v151 offset:2048
	ds_read_b128 v[226:229], v151 offset:3072
	ds_read_b128 v[230:233], v151 offset:4096
	ds_read_b128 v[234:237], v151 offset:5120
	ds_read_b128 v[238:241], v151 offset:6144
	ds_read_b128 v[242:245], v151 offset:7168
	global_load_lds_dwordx4 v[146:147], off
	s_mov_b32 m0, s84
	s_nop 0
	global_load_lds_dwordx4 v[144:145], off
	s_waitcnt vmcnt(8)
	s_waitcnt lgkmcnt(0)
	s_cmp_lg_u64 s[12:13], 0
	s_cbranch_scc1 .Lhb_17
	s_barrier
.Lhb_17:
	s_setprio 1
	s_waitcnt lgkmcnt(0)
	v_mfma_f32_16x16x32_bf16 v[128:131], v[152:155], v[196:199], v[128:131]
	v_mfma_f32_16x16x32_bf16 v[124:127], v[160:163], v[196:199], v[124:127]
	v_mfma_f32_16x16x32_bf16 v[112:115], v[152:155], v[222:225], v[112:115]
	v_mfma_f32_16x16x32_bf16 v[108:111], v[160:163], v[222:225], v[108:111]
	v_mfma_f32_16x16x32_bf16 v[94:97], v[152:155], v[230:233], v[94:97]
	v_mfma_f32_16x16x32_bf16 v[90:93], v[160:163], v[230:233], v[90:93]
	v_mfma_f32_16x16x32_bf16 v[78:81], v[152:155], v[238:241], v[78:81]
	v_mfma_f32_16x16x32_bf16 v[74:77], v[160:163], v[238:241], v[74:77]
	s_setprio 2
	v_mfma_f32_16x16x32_bf16 v[128:131], v[156:159], v[200:203], v[128:131]
	v_mfma_f32_16x16x32_bf16 v[124:127], v[164:167], v[200:203], v[124:127]
	v_mfma_f32_16x16x32_bf16 v[112:115], v[156:159], v[226:229], v[112:115]
	v_mfma_f32_16x16x32_bf16 v[108:111], v[164:167], v[226:229], v[108:111]
	v_mfma_f32_16x16x32_bf16 v[94:97], v[156:159], v[234:237], v[94:97]
	v_mfma_f32_16x16x32_bf16 v[90:93], v[164:167], v[234:237], v[90:93]
	v_mfma_f32_16x16x32_bf16 v[78:81], v[156:159], v[242:245], v[78:81]
	v_mfma_f32_16x16x32_bf16 v[74:77], v[164:167], v[242:245], v[74:77]
	v_mfma_f32_16x16x32_bf16 v[120:123], v[180:183], v[196:199], v[120:123]
	v_mfma_f32_16x16x32_bf16 v[116:119], v[188:191], v[196:199], v[116:119]
	v_mfma_f32_16x16x32_bf16 v[104:107], v[180:183], v[222:225], v[104:107]
	v_mfma_f32_16x16x32_bf16 v[100:103], v[188:191], v[222:225], v[100:103]
	s_setprio 3
	v_mfma_f32_16x16x32_bf16 v[86:89], v[180:183], v[230:233], v[86:89]
	v_mfma_f32_16x16x32_bf16 v[82:85], v[188:191], v[230:233], v[82:85]
	v_mfma_f32_16x16x32_bf16 v[70:73], v[180:183], v[238:241], v[70:73]
	v_mfma_f32_16x16x32_bf16 v[66:69], v[188:191], v[238:241], v[66:69]
	v_mfma_f32_16x16x32_bf16 v[120:123], v[184:187], v[200:203], v[120:123]
	v_mfma_f32_16x16x32_bf16 v[116:119], v[192:195], v[200:203], v[116:119]
	v_mfma_f32_16x16x32_bf16 v[104:107], v[184:187], v[226:229], v[104:107]
	v_mfma_f32_16x16x32_bf16 v[100:103], v[192:195], v[226:229], v[100:103]
	v_mfma_f32_16x16x32_bf16 v[86:89], v[184:187], v[234:237], v[86:89]
	v_mfma_f32_16x16x32_bf16 v[82:85], v[192:195], v[234:237], v[82:85]
	v_mfma_f32_16x16x32_bf16 v[70:73], v[184:187], v[242:245], v[70:73]
	v_mfma_f32_16x16x32_bf16 v[66:69], v[192:195], v[242:245], v[66:69]
	s_setprio 0
	s_cmp_eq_u64 s[12:13], 0
	s_cbranch_scc1 .Lhb_21
	s_barrier
; #define PG8_STAGE(bufoff, gbase, voff) do { _Pragma("unroll") for (int _i = 0; _i < 2; ++_i) \
;         __builtin_amdgcn_global_load_lds((const unsigned*)((const char*)(gbase) + (voff)[_i]), (PG8_LAS unsigned*)(lds + (bufoff) + ldsw + _i * 8192), 16, 0, AUX_A); } while (0)
; #define PG8_STAGEB(bufoff, gbase, voff) do { _Pragma("unroll") for (int _i = 0; _i < 2; ++_i) \
;         __builtin_amdgcn_global_load_lds((const unsigned*)((const char*)(gbase) + (voff)[_i]), (PG8_LAS unsigned*)(lds + (bufoff) + ldsw + _i * 8192), 16, 0, AUX_B); } while (0)
; #define PG8_WAIT_V(n) asm volatile("s_waitcnt vmcnt(" #n ")" ::: "memory")
; #define PG8_WAIT_L(n) asm volatile("s_waitcnt lgkmcnt(" #n ")" ::: "memory")
; template <class Epi, class Sched, bool ALIGN_EPI = false, bool SP2 = false>
; __device__ __forceinline__ void gemm_phase(PG8_LAS unsigned char* lds, const Gemm g, const Sched& S, const Epi& E) {
;     ...
;         for (int t = 0; t < nt; t += 2) {
;             const bool last = (t == nt - 2);
;             const char* a1 = PG8_KP(cA, t + 1, rot, nt);
;             const char* a2 = last ? nAr : PG8_KP(cA, t + 2, rot, nt); const char* b2 = last ? nBr : PG8_KP(cB, t + 2, rot, nt);
;             const char* a3 = a2 + kstep; const char* b3 = b2 + kstep;
;             if (last && has_next) S.a_ready(nxt);
;             if constexpr (SP2) {
;             PG8_LDB(B0, 0, 0); PG8_LDB(B1, 0, 1); PG8_SCHED; PG8_LDA(At, 0, 0); PG8_STAGE(PG8_SA(1, 1), a1 + hstep, voffA);
;             PG8_WAIT_V(8); PG8_WAIT_L(0); PG8_BAR; PG8_MMA(0, 0, At, B0); PG8_MMA(0, 1, At, B1); PG8_BAR; PG8_SCHED;
;             PG8_LDA(At, 0, 1); PG8_STAGEB(PG8_SB(0, 0), b2, voffB); PG8_STAGEB(PG8_SB(0, 1), b2 + hstep, voffB); PG8_STAGE(PG8_SA(0, 0), a2, voffA);
;             PG8_WAIT_V(8); PG8_WAIT_L(0); PG8_BAR; PG8_MMA(1, 0, At, B0); PG8_MMA(1, 1, At, B1); PG8_BAR; PG8_SCHED;
;             PG8_LDB(B0, 1, 0); PG8_LDB(B1, 1, 1); PG8_SCHED; PG8_LDA(At, 1, 0); PG8_STAGE(PG8_SA(0, 1), a2 + hstep, voffA);
;             PG8_WAIT_V(8); PG8_WAIT_L(0); PG8_BAR; PG8_MMA(0, 0, At, B0); PG8_MMA(0, 1, At, B1); PG8_BAR; PG8_SCHED;
;             PG8_LDA(At, 1, 1); PG8_STAGEB(PG8_SB(1, 0), b3, voffB); PG8_STAGEB(PG8_SB(1, 1), b3 + hstep, voffB); PG8_STAGE(PG8_SA(1, 0), a3, voffA);
;             PG8_WAIT_V(8); PG8_WAIT_L(0); PG8_BAR; PG8_MMA(1, 0, At, B0); PG8_MMA(1, 1, At, B1); PG8_BAR; PG8_SCHED;
.Lhb_21:
	s_mov_b32 m0, s94
	v_lshl_add_u64 v[148:149], s[60:61], 0, v[136:137]
	ds_read_b128 v[196:199], v151 offset:16384
	ds_read_b128 v[200:203], v151 offset:17408
	ds_read_b128 v[222:225], v151 offset:18432
	ds_read_b128 v[226:229], v151 offset:19456
	ds_read_b128 v[230:233], v151 offset:20480
	ds_read_b128 v[234:237], v151 offset:21504
	ds_read_b128 v[238:241], v151 offset:22528
	ds_read_b128 v[242:245], v151 offset:23552
	global_load_lds_dwordx4 v[148:149], off
	v_lshl_add_u64 v[168:169], s[60:61], 0, v[132:133]
	s_mov_b32 m0, s95
	v_lshl_add_u64 v[172:173], s[62:63], 0, v[136:137]
	global_load_lds_dwordx4 v[168:169], off
	s_mov_b32 m0, s96
	v_lshl_add_u64 v[212:213], s[58:59], 0, v[134:135]
	global_load_lds_dwordx4 v[172:173], off
	v_lshl_add_u64 v[172:173], s[62:63], 0, v[132:133]
	s_mov_b32 m0, s97
	s_nop 0
	global_load_lds_dwordx4 v[172:173], off
	v_lshl_add_u64 v[172:173], s[58:59], 0, v[138:139]
	s_mov_b32 m0, s71
	s_nop 0
	global_load_lds_dwordx4 v[172:173], off
	s_mov_b32 m0, s75
	s_nop 0
	global_load_lds_dwordx4 v[212:213], off
	s_waitcnt vmcnt(8)
	s_waitcnt lgkmcnt(0)
	s_cmp_lg_u64 s[12:13], 0
	s_cbranch_scc1 .Lhb_18
	s_barrier
.Lhb_18:
	s_setprio 1
	s_waitcnt lgkmcnt(0)
	v_mfma_f32_16x16x32_bf16 v[62:65], v[152:155], v[196:199], v[62:65]
	v_mfma_f32_16x16x32_bf16 v[58:61], v[160:163], v[196:199], v[58:61]
	v_mfma_f32_16x16x32_bf16 v[46:49], v[152:155], v[222:225], v[46:49]
	v_mfma_f32_16x16x32_bf16 v[42:45], v[160:163], v[222:225], v[42:45]
	v_mfma_f32_16x16x32_bf16 v[30:33], v[152:155], v[230:233], v[30:33]
	v_mfma_f32_16x16x32_bf16 v[26:29], v[160:163], v[230:233], v[26:29]
	v_mfma_f32_16x16x32_bf16 v[14:17], v[152:155], v[238:241], v[14:17]
	v_mfma_f32_16x16x32_bf16 v[10:13], v[160:163], v[238:241], v[10:13]
	s_setprio 2
	v_mfma_f32_16x16x32_bf16 v[62:65], v[156:159], v[200:203], v[62:65]
	v_mfma_f32_16x16x32_bf16 v[58:61], v[164:167], v[200:203], v[58:61]
	v_mfma_f32_16x16x32_bf16 v[46:49], v[156:159], v[226:229], v[46:49]
	v_mfma_f32_16x16x32_bf16 v[42:45], v[164:167], v[226:229], v[42:45]
	v_mfma_f32_16x16x32_bf16 v[30:33], v[156:159], v[234:237], v[30:33]
	v_mfma_f32_16x16x32_bf16 v[26:29], v[164:167], v[234:237], v[26:29]
	v_mfma_f32_16x16x32_bf16 v[14:17], v[156:159], v[242:245], v[14:17]
	v_mfma_f32_16x16x32_bf16 v[10:13], v[164:167], v[242:245], v[10:13]
	v_mfma_f32_16x16x32_bf16 v[54:57], v[180:183], v[196:199], v[54:57]
	v_mfma_f32_16x16x32_bf16 v[50:53], v[188:191], v[196:199], v[50:53]
	v_mfma_f32_16x16x32_bf16 v[38:41], v[180:183], v[222:225], v[38:41]
	v_mfma_f32_16x16x32_bf16 v[34:37], v[188:191], v[222:225], v[34:37]
	s_setprio 3
	v_mfma_f32_16x16x32_bf16 v[22:25], v[180:183], v[230:233], v[22:25]
	v_mfma_f32_16x16x32_bf16 v[18:21], v[188:191], v[230:233], v[18:21]
	v_mfma_f32_16x16x32_bf16 v[6:9], v[180:183], v[238:241], v[6:9]
	v_mfma_f32_16x16x32_bf16 v[2:5], v[188:191], v[238:241], v[2:5]
	v_mfma_f32_16x16x32_bf16 v[54:57], v[184:187], v[200:203], v[54:57]
	v_mfma_f32_16x16x32_bf16 v[50:53], v[192:195], v[200:203], v[50:53]
	v_mfma_f32_16x16x32_bf16 v[38:41], v[184:187], v[226:229], v[38:41]
	v_mfma_f32_16x16x32_bf16 v[34:37], v[192:195], v[226:229], v[34:37]
	v_mfma_f32_16x16x32_bf16 v[22:25], v[184:187], v[234:237], v[22:25]
	v_mfma_f32_16x16x32_bf16 v[18:21], v[192:195], v[234:237], v[18:21]
	v_mfma_f32_16x16x32_bf16 v[6:9], v[184:187], v[242:245], v[6:9]
	v_mfma_f32_16x16x32_bf16 v[2:5], v[192:195], v[242:245], v[2:5]
	s_setprio 0
	s_cmp_eq_u64 s[12:13], 0
	s_cbranch_scc1 .Lhb_22
	s_barrier
.Lhb_22:
	v_add_u32_e32 v164, vcc_lo, v99
	v_add_u32_e32 v192, vcc_hi, v99
	ds_read_b128 v[152:155], v164
	ds_read_b128 v[156:159], v164 offset:1024
	ds_read_b128 v[160:163], v164 offset:2048
	ds_read_b128 v[164:167], v164 offset:3072
	ds_read_b128 v[180:183], v192
	ds_read_b128 v[184:187], v192 offset:1024
	ds_read_b128 v[188:191], v192 offset:2048
	ds_read_b128 v[192:195], v192 offset:3072
	s_mov_b32 m0, s78
	v_lshl_add_u64 v[246:247], s[56:57], 0, v[138:139]
	ds_read_b128 v[196:199], v151 offset:32768
	ds_read_b128 v[200:203], v151 offset:33792
	ds_read_b128 v[222:225], v151 offset:34816
	ds_read_b128 v[226:229], v151 offset:35840
	ds_read_b128 v[230:233], v151 offset:36864
	ds_read_b128 v[234:237], v151 offset:37888
	ds_read_b128 v[238:241], v151 offset:38912
	ds_read_b128 v[242:245], v151 offset:39936
	global_load_lds_dwordx4 v[246:247], off
	v_lshl_add_u64 v[246:247], s[56:57], 0, v[134:135]
	s_mov_b32 m0, s82
	s_nop 0
	global_load_lds_dwordx4 v[246:247], off
	s_waitcnt vmcnt(8)
	s_waitcnt lgkmcnt(0)
	s_cmp_lg_u64 s[12:13], 0
	s_cbranch_scc1 .Lhb_19
	s_barrier

; #define PG8_STAGE(bufoff, gbase, voff) do { _Pragma("unroll") for (int _i = 0; _i < 2; ++_i) \
;         __builtin_amdgcn_global_load_lds((const unsigned*)((const char*)(gbase) + (voff)[_i]), (PG8_LAS unsigned*)(lds + (bufoff) + ldsw + _i * 8192), 16, 0, AUX_A); } while (0)
; #define PG8_STAGEB(bufoff, gbase, voff) do { _Pragma("unroll") for (int _i = 0; _i < 2; ++_i) \
;         __builtin_amdgcn_global_load_lds((const unsigned*)((const char*)(gbase) + (voff)[_i]), (PG8_LAS unsigned*)(lds + (bufoff) + ldsw + _i * 8192), 16, 0, AUX_B); } while (0)
; #define PG8_LDA(dst, b, h) do { _Pragma("unroll") for (int m = 0; m < 4; ++m) _Pragma("unroll") for (int k = 0; k < 2; ++k) dst[m][k] = *(const PG8_LAS bf16x8*)(lds + PG8_SA(b, h) + aoff + m * 2048 + k * 1024); } while (0)
; #define PG8_LDB(dst, b, h) do { _Pragma("unroll") for (int n = 0; n < 2; ++n) _Pragma("unroll") for (int k = 0; k < 2; ++k) dst[n][k] = *(const PG8_LAS bf16x8*)(lds + PG8_SB(b, h) + boff + n * 2048 + k * 1024); } while (0)
; #define PG8_MMA(ai, bj, At, Bt) do { __builtin_amdgcn_s_setprio(1); _Pragma("unroll") for (int m = 0; m < 4; ++m) _Pragma("unroll") for (int n = 0; n < 2; ++n) _Pragma("unroll") for (int k = 0; k < 2; ++k) \
;         acc[ai][bj][m][n] = __builtin_amdgcn_mfma_f32_16x16x32_bf16(Bt[n][k], At[m][k], acc[ai][bj][m][n], 0, 0, 0); __builtin_amdgcn_s_setprio(0); } while (0)
; #define PG8_WAIT_V(n) asm volatile("s_waitcnt vmcnt(" #n ")" ::: "memory")
; #define PG8_WAIT_L(n) asm volatile("s_waitcnt lgkmcnt(" #n ")" ::: "memory")
; template <class Epi, class Sched, bool ALIGN_EPI = false, bool SP2 = false>
; __device__ __forceinline__ void gemm_phase(PG8_LAS unsigned char* lds, const Gemm g, const Sched& S, const Epi& E) {
;     ...
;             PG8_WAIT_V(8); PG8_WAIT_L(0); PG8_BAR; PG8_MMA(1, 0, At, B0); PG8_MMA(1, 1, At, B1); PG8_BAR; PG8_SCHED;
;             PG8_LDB(B0, 1, 0); PG8_LDB(B1, 1, 1); PG8_SCHED; PG8_LDA(At, 1, 0); PG8_STAGE(PG8_SA(0, 1), a2 + hstep, voffA);
;             PG8_WAIT_V(8); PG8_WAIT_L(0); PG8_BAR; PG8_MMA(0, 0, At, B0); PG8_MMA(0, 1, At, B1); PG8_BAR; PG8_SCHED;
;             PG8_LDA(At, 1, 1); PG8_STAGEB(PG8_SB(1, 0), b3, voffB); PG8_STAGEB(PG8_SB(1, 1), b3 + hstep, voffB); PG8_STAGE(PG8_SA(1, 0), a3, voffA);
;             PG8_WAIT_V(8); PG8_WAIT_L(0); PG8_BAR; PG8_MMA(1, 0, At, B0); PG8_MMA(1, 1, At, B1); PG8_BAR; PG8_SCHED;
.Lhb_23:
	s_mov_b32 m0, s1
	v_lshl_add_u64 v[148:149], v[148:149], 0, s[76:77]
	ds_read_b128 v[196:199], v151 offset:49152
	ds_read_b128 v[200:203], v151 offset:50176
	ds_read_b128 v[222:225], v151 offset:51200
	ds_read_b128 v[226:229], v151 offset:52224
	ds_read_b128 v[230:233], v151 offset:53248
	ds_read_b128 v[234:237], v151 offset:54272
	ds_read_b128 v[238:241], v151 offset:55296
	ds_read_b128 v[242:245], v151 offset:56320
	global_load_lds_dwordx4 v[148:149], off
	v_lshl_add_u64 v[148:149], v[168:169], 0, s[76:77]
	s_mov_b32 m0, s0
	s_nop 0
	global_load_lds_dwordx4 v[148:149], off
	v_lshl_add_u64 v[148:149], s[54:55], 0, v[136:137]
	s_mov_b32 m0, s47
	s_nop 0
	global_load_lds_dwordx4 v[148:149], off
	v_lshl_add_u64 v[148:149], s[54:55], 0, v[132:133]
	s_mov_b32 m0, s46
	s_nop 0
	global_load_lds_dwordx4 v[148:149], off
	v_lshl_add_u64 v[148:149], v[172:173], 0, s[76:77]
	s_mov_b32 m0, s83
	s_nop 0
	global_load_lds_dwordx4 v[148:149], off
	v_lshl_add_u64 v[148:149], v[212:213], 0, s[76:77]
	s_mov_b32 m0, s88
	s_nop 0
	global_load_lds_dwordx4 v[148:149], off
	s_waitcnt vmcnt(8)
	s_waitcnt lgkmcnt(0)
	s_cmp_lg_u64 s[12:13], 0
	s_cbranch_scc1 .Lhb_20
	s_barrier

; #define PG8_BAR __builtin_amdgcn_s_barrier()
; template <class Epi, class Sched, bool ALIGN_EPI = false, bool SP2 = false>
; __device__ __forceinline__ void gemm_phase(PG8_LAS unsigned char* lds, const Gemm g, const Sched& S, const Epi& E) {
;     ...
;         for (int t = 0; t < nt; t += 2) {
;             const bool last = (t == nt - 2);
;             const char* a1 = PG8_KP(cA, t + 1, rot, nt);
;             const char* a2 = last ? nAr : PG8_KP(cA, t + 2, rot, nt); const char* b2 = last ? nBr : PG8_KP(cB, t + 2, rot, nt);
;             const char* a3 = a2 + kstep; const char* b3 = b2 + kstep;
;     ...
;         if constexpr (ALIGN_EPI) { if (wr == 0) PG8_BAR; }
.Lhb_24:
	v_lshl_add_u64 v[144:145], v[144:145], 0, s[86:87]
	v_lshl_add_u64 v[146:147], v[146:147], 0, s[86:87]
	s_cmp_gt_u32 s81, 15
	s_mov_b32 s29, s81
	s_cbranch_scc0 .LBB0_1067
	s_and_b64 vcc, exec, s[12:13]
	s_cbranch_vccz .LBB0_1070

; #define PG8_BAR __builtin_amdgcn_s_barrier()
; template <class Epi, class Sched, bool ALIGN_EPI = false, bool SP2 = false>
; __device__ __forceinline__ void gemm_phase(PG8_LAS unsigned char* lds, const Gemm g, const Sched& S, const Epi& E) {
;     ...
;         cur = nxt; cA = nA; cB = nB; ++ui;
;         if constexpr (ALIGN_EPI) { if (wr == 1) PG8_BAR; }
.LBB0_1140:
	s_andn2_b64 vcc, exec, s[6:7]
	s_cbranch_vccnz .LBB0_1057
	s_branch .LBB0_1057

; #define VM_WAIT() asm volatile("s_waitcnt vmcnt(0)" ::: "memory")
; template <class Epi, class Sched, bool ALIGN_EPI = false, bool SP2 = false>
; __device__ __forceinline__ void gemm_phase(PG8_LAS unsigned char* lds, const Gemm g, const Sched& S, const Epi& E) {
;     ...
;     const int tid = tid_l, wid = __builtin_amdgcn_readfirstlane(tid >> 6), lane = tid & 63, wr = wid >> 2, wc = wid & 3, fr = lane & 15, fq = lane >> 4;
;     const int K = g.K;
;     unsigned voffA[2], voffB[2];
; #pragma unroll
;     for (int i = 0; i < 2; ++i) { int R, C; stage_rc(tid * 16 + i * 8192, R, C); const int Rb = Epi::PERM ? ((R & ~31) + perm32(R & 31)) : R;
;         voffA[i] = (unsigned)(R * K + C) * 2u; voffB[i] = (unsigned)(Rb * K + C) * 2u; }
;     const size_t kstep = (size_t)(BK * 2);
;     const size_t hstep = (size_t)HALF * K * 2;
;     const size_t tstep = 2 * hstep;
;     const unsigned ldsw = (unsigned)wid * 1024u;
;     const int aoff = lds_byte(wr * 64 + fr, fq * 8), boff = lds_byte(wc * 32 + fr, fq * 8);
;     ...
;     Unit cur, nxt; int ui = 0;
;     if (!S.next(0, cur)) return;
;     f32x4 acc[2][2][4][2];
; #pragma unroll
;     for (int a = 0; a < 2; ++a)
; #pragma unroll
;         for (int b = 0; b < 2; ++b)
; #pragma unroll
;             for (int m = 0; m < 4; ++m)
; #pragma unroll
;                 for (int n = 0; n < 2; ++n) acc[a][b][m][n] = (f32x4){0.f, 0.f, 0.f, 0.f};
;     bf16x8 At[4][2], B0[2][2], B1[2][2];
;     const char* cA = (const char*)g.A + (size_t)cur.pm * tstep + (size_t)cur.kt0 * kstep; const char* cB = (const char*)g.Bt + (size_t)cur.pn * tstep + (size_t)cur.kt0 * kstep;
;     S.a_ready(cur);
;     ...
;     { const int rot0 = cur.krot, nt0 = cur.nkt; const char* sA0 = PG8_KP(cA, 0, rot0, nt0); const char* sA1 = PG8_KP(cA, 1, rot0, nt0); const char* sB0 = PG8_KP(cB, 0, rot0, nt0); const char* sB1 = PG8_KP(cB, 1, rot0, nt0);
;     if constexpr (SP2) {
; __global__ void __launch_bounds__(NWAVES * 64, 2) enc_fwd(Args args) {
;     ...
;             VM_WAIT(); __syncthreads();
;             { pg8::Gemm g{AO, (const bf16*)(ws + WS_WPA + l * SZ_WP), NTOK, 2048, 1024}; pg8::PROrder S; S.init(NTOK, 2048, 1024, G, bx, 4);
;               pg8::EpiPR<1> E{P, T1, MX, (unsigned*)(ws + WS_CTL + 32768) + (size_t)l * 32 * 64};
;               pg8::gemm_phase<pg8::EpiPR<1>, pg8::PROrder, PG8_ALIGN, PG8_SP2>(lds + RING_OFF, g, S, E); }
.LBB0_1143:
	s_add_u32 s0, s4, s44
	s_waitcnt vmcnt(0)
	s_addc_u32 s1, s5, s45
	s_add_u32 s6, s0, 0x9000000
	v_mov_b32_e32 v16, v0
	s_waitcnt vmcnt(0) lgkmcnt(0)
	s_barrier
	s_addc_u32 s7, s1, 0
	s_and_b64 vcc, exec, s[38:39]
	v_readfirstlane_b32 s16, v16
	s_cbranch_vccnz .LBB0_1182
	v_lshlrev_b32_e32 v1, 4, v16
	v_add_u32_e32 v2, 0x2000, v1
	v_ashrrev_i32_e32 v3, 31, v2
	v_lshrrev_b32_e32 v3, 22, v3
	v_add_u32_e32 v3, v2, v3
	v_ashrrev_i32_e32 v10, 10, v3
	v_mul_i32_i24_e32 v3, 0x400, v10
	v_sub_u32_e32 v2, v2, v3
	v_lshrrev_b32_e32 v3, 4, v2
	v_bitop3_b32 v2, v3, v2, 32 bitop3:0x6c
	v_ashrrev_i32_e32 v3, 31, v2
	v_lshrrev_b32_e32 v3, 26, v3
	v_add_u32_e32 v3, v2, v3
	v_lshlrev_b32_e32 v4, 3, v10
	v_ashrrev_i32_e32 v11, 6, v3
	v_and_b32_e32 v4, -16, v4
	v_add_u32_e32 v4, v11, v4
	v_and_b32_e32 v5, 3, v11
	s_mov_b32 s2, 0x1fffe0
	v_lshrrev_b32_e32 v6, 2, v4
	v_lshlrev_b32_e32 v7, 1, v4
	v_and_b32_e32 v3, 0xc0, v3
	v_and_or_b32 v5, v4, s2, v5
	v_and_b32_e32 v6, 4, v6
	v_and_b32_e32 v7, 24, v7
	v_sub_u32_e32 v2, v2, v3
	v_or3_b32 v5, v5, v6, v7
	v_lshlrev_b32_e32 v6, 5, v10
	v_ashrrev_i16_sdwa v2, v207, sext(v2) dst_sel:DWORD dst_unused:UNUSED_PAD src0_sel:DWORD src1_sel:BYTE_0
	v_and_b32_e32 v6, 32, v6
	v_bfe_i32 v12, v2, 0, 16
	v_add_lshl_u32 v2, v6, v12, 1
	v_lshl_add_u32 v132, v5, 11, v2
	v_lshl_add_u32 v134, v4, 11, v2
	v_bfe_i32 v2, v16, 27, 1
	v_lshrrev_b32_e32 v2, 22, v2
	v_add_u32_e32 v2, v1, v2
	v_and_b32_e32 v2, 0xfffffc00, v2
	v_sub_u32_e32 v1, v1, v2
	v_lshrrev_b32_e32 v2, 4, v1
	v_ashrrev_i32_e32 v3, 31, v16
	v_bitop3_b32 v1, v2, v1, 32 bitop3:0x6c
	v_lshrrev_b32_e32 v3, 26, v3
	v_ashrrev_i32_e32 v2, 31, v1
	v_add_u32_e32 v3, v16, v3
	v_lshrrev_b32_e32 v2, 26, v2
	v_ashrrev_i32_e32 v14, 6, v3
	v_add_u32_e32 v2, v1, v2
	v_lshlrev_b32_e32 v3, 3, v14
	v_ashrrev_i32_e32 v13, 6, v2
	v_and_b32_e32 v3, -16, v3
	v_add_u32_e32 v3, v13, v3
	s_add_u32 s33, s4, 0x29b80000
	v_and_b32_e32 v4, 3, v13
	v_lshrrev_b32_e32 v5, 2, v3
	v_lshlrev_b32_e32 v6, 1, v3
	v_and_b32_e32 v2, 0xc0, v2
	s_addc_u32 s69, s5, 0
	s_ashr_i32 s0, s16, 6
	v_and_or_b32 v4, v3, s2, v4
	v_and_b32_e32 v5, 4, v5
	v_and_b32_e32 v6, 24, v6
	v_sub_u32_e32 v1, v1, v2
	s_ashr_i32 s1, s16, 8
	s_lshl_b32 s70, s0, 10
	v_or3_b32 v4, v4, v5, v6
	v_lshlrev_b32_e32 v5, 5, v14
	v_ashrrev_i16_sdwa v1, v207, sext(v1) dst_sel:DWORD dst_unused:UNUSED_PAD src0_sel:DWORD src1_sel:BYTE_0
	v_readlane_b32 s2, v253, 3
	v_and_b32_e32 v5, 32, v5
	v_bfe_i32 v15, v1, 0, 16
	v_readlane_b32 s3, v253, 4
	s_add_u32 s50, s6, s2
	v_add_lshl_u32 v1, v5, v15, 1
	s_addc_u32 s51, s7, s3
	s_add_i32 s71, s70, 0
	v_lshl_add_u32 v136, v4, 11, v1
	s_add_i32 m0, s71, 0x10000
	v_readlane_b32 s2, v252, 63
	global_load_lds_dwordx4 v136, s[50:51]
	s_add_i32 m0, s71, 0x12000
	v_readlane_b32 s3, v253, 0
	s_add_u32 s52, s33, s2
	s_addc_u32 s53, s69, s3
	s_add_u32 s12, s50, 0x40000
	global_load_lds_dwordx4 v132, s[50:51]
	s_addc_u32 s13, s51, 0
	s_add_i32 m0, s71, 0x14000
	s_add_i32 s75, s71, 0x2000
	global_load_lds_dwordx4 v136, s[12:13]
	s_add_i32 m0, s71, 0x16000
	v_lshl_add_u32 v138, v3, 11, v1
	global_load_lds_dwordx4 v132, s[12:13]
	s_mov_b32 m0, s71
	s_add_u32 s12, s52, 0x40000
	global_load_lds_dwordx4 v138, s[52:53]
	s_mov_b32 m0, s75
	s_addc_u32 s13, s53, 0
	s_add_i32 s78, s71, 0x4000
	global_load_lds_dwordx4 v134, s[52:53]
	s_mov_b32 m0, s78
	s_add_i32 s82, s71, 0x6000
	global_load_lds_dwordx4 v138, s[12:13]
	s_mov_b32 m0, s82
	v_mov_b32_e32 v137, v98
	global_load_lds_dwordx4 v134, s[12:13]
	v_mov_b32_e32 v133, v98
	v_mov_b32_e32 v139, v98
	v_mov_b32_e32 v135, v98
	s_cmp_eq_u32 s1, 1
	v_lshl_add_u64 v[8:9], s[50:51], 0, v[136:137]
	v_lshl_add_u64 v[6:7], s[50:51], 0, v[132:133]
	v_lshl_add_u64 v[2:3], s[52:53], 0, v[138:139]
	s_cselect_b64 s[12:13], -1, 0
	s_cmp_lg_u32 s1, 1
	v_lshl_add_u64 v[4:5], s[52:53], 0, v[134:135]
	s_cbranch_scc1 .LBB0_1146
.LBB0_1146:
	s_add_u32 s14, s4, 0x2d180000
	v_lshrrev_b32_e32 v18, 1, v16
	s_addc_u32 s15, s5, 0
	v_and_b32_e32 v18, 24, v18
	s_lshl_b32 s0, s0, 5
	v_and_b32_e32 v17, 15, v16
	v_lshlrev_b32_e32 v19, 1, v18
	v_lshlrev_b32_e32 v16, 2, v16
	s_and_b32 s2, s0, 0x60
	s_add_i32 m0, s71, 0x18000
	v_lshl_add_u64 v[8:9], v[8:9], 0, s[76:77]
	v_lshl_or_b32 v1, s1, 6, v17
	v_lshl_or_b32 v17, v17, 6, v19
	s_lshl_b32 s1, s1, 13
	v_and_b32_e32 v16, 32, v16
	s_lshl_b32 s0, s2, 7
	s_waitcnt vmcnt(2)
	s_barrier
	global_load_lds_dwordx4 v[8:9], off
	v_lshl_add_u64 v[6:7], v[6:7], 0, s[76:77]
	s_add_i32 m0, s71, 0x1a000
	s_add_i32 s83, s71, 0x8000
	s_add_i32 s88, s71, 0xa000
	v_bitop3_b32 v99, v17, s0, v16 bitop3:0xde
	global_load_lds_dwordx4 v[6:7], off
	v_lshl_add_u64 v[2:3], v[2:3], 0, s[76:77]
	s_mov_b32 m0, s83
	s_add_u32 s0, s50, 0x40080
	v_bitop3_b32 v19, v17, s1, v16 bitop3:0xde
	global_load_lds_dwordx4 v[2:3], off
	v_lshl_add_u64 v[2:3], v[4:5], 0, s[76:77]
	s_mov_b32 m0, s88
	s_addc_u32 s1, s51, 0
	global_load_lds_dwordx4 v[2:3], off
	s_add_i32 m0, s71, 0x1c000
	v_lshl_add_u64 v[2:3], s[0:1], 0, v[136:137]
	global_load_lds_dwordx4 v[2:3], off
	v_lshl_add_u64 v[2:3], s[0:1], 0, v[132:133]
	s_add_i32 m0, s71, 0x1e000
	v_or_b32_e32 v152, s2, v18
	global_load_lds_dwordx4 v[2:3], off
	v_lshlrev_b32_e32 v2, 14, v10
	v_and_b32_e32 v2, 0xffff8000, v2
	v_lshl_add_u32 v2, v11, 11, v2
	v_and_b32_e32 v3, 1, v10
	v_lshl_or_b32 v2, v3, 6, v2
	v_lshl_add_u32 v140, v12, 1, v2
	v_lshlrev_b32_e32 v2, 14, v14
	v_and_b32_e32 v2, 0xffff8000, v2
	v_readlane_b32 s2, v253, 1
	s_waitcnt vmcnt(6)
	v_lshl_add_u32 v2, v13, 11, v2
	v_and_b32_e32 v3, 1, v14
	v_readlane_b32 s3, v253, 2
	s_cmpk_lt_u32 s16, 0x100
	v_lshl_or_b32 v2, v3, 6, v2
	s_mov_b32 s91, s2
	v_readlane_b32 s2, v252, 61
	s_cselect_b64 s[16:17], -1, 0
	v_mov_b32_e32 v141, v98
	v_lshl_add_u32 v142, v15, 1, v2
	v_mov_b32_e32 v143, v98
	s_mov_b32 s0, 0
	v_add_u32_e32 v153, 0, v19
	s_mov_b32 s90, s2
	s_barrier
	v_readlane_b32 s3, v252, 62
	s_branch .LBB0_1149

; #define PG8_STAGE(bufoff, gbase, voff) do { _Pragma("unroll") for (int _i = 0; _i < 2; ++_i) \
;         __builtin_amdgcn_global_load_lds((const unsigned*)((const char*)(gbase) + (voff)[_i]), (PG8_LAS unsigned*)(lds + (bufoff) + ldsw + _i * 8192), 16, 0, AUX_A); } while (0)
; #define PG8_STAGEB(bufoff, gbase, voff) do { _Pragma("unroll") for (int _i = 0; _i < 2; ++_i) \
;         __builtin_amdgcn_global_load_lds((const unsigned*)((const char*)(gbase) + (voff)[_i]), (PG8_LAS unsigned*)(lds + (bufoff) + ldsw + _i * 8192), 16, 0, AUX_B); } while (0)
; #define PG8_WAIT_V(n) asm volatile("s_waitcnt vmcnt(" #n ")" ::: "memory")
; #define PG8_WAIT_L(n) asm volatile("s_waitcnt lgkmcnt(" #n ")" ::: "memory")
; template <class Epi, class Sched, bool ALIGN_EPI = false, bool SP2 = false>
; __device__ __forceinline__ void gemm_phase(PG8_LAS unsigned char* lds, const Gemm g, const Sched& S, const Epi& E) {
;     ...
;         for (int t = 0; t < nt; t += 2) {
;             const bool last = (t == nt - 2);
;             const char* a1 = PG8_KP(cA, t + 1, rot, nt);
;             const char* a2 = last ? nAr : PG8_KP(cA, t + 2, rot, nt); const char* b2 = last ? nBr : PG8_KP(cB, t + 2, rot, nt);
;             const char* a3 = a2 + kstep; const char* b3 = b2 + kstep;
;             if (last && has_next) S.a_ready(nxt);
;             if constexpr (SP2) {
;             PG8_LDB(B0, 0, 0); PG8_LDB(B1, 0, 1); PG8_SCHED; PG8_LDA(At, 0, 0); PG8_STAGE(PG8_SA(1, 1), a1 + hstep, voffA);
;             PG8_WAIT_V(8); PG8_WAIT_L(0); PG8_BAR; PG8_MMA(0, 0, At, B0); PG8_MMA(0, 1, At, B1); PG8_BAR; PG8_SCHED;
;             PG8_LDA(At, 0, 1); PG8_STAGEB(PG8_SB(0, 0), b2, voffB); PG8_STAGEB(PG8_SB(0, 1), b2 + hstep, voffB); PG8_STAGE(PG8_SA(0, 0), a2, voffA);
;             PG8_WAIT_V(8); PG8_WAIT_L(0); PG8_BAR; PG8_MMA(1, 0, At, B0); PG8_MMA(1, 1, At, B1); PG8_BAR; PG8_SCHED;
;             PG8_LDB(B0, 1, 0); PG8_LDB(B1, 1, 1); PG8_SCHED; PG8_LDA(At, 1, 0); PG8_STAGE(PG8_SA(0, 1), a2 + hstep, voffA);
;             PG8_WAIT_V(8); PG8_WAIT_L(0); PG8_BAR; PG8_MMA(0, 0, At, B0); PG8_MMA(0, 1, At, B1); PG8_BAR; PG8_SCHED;
;             PG8_LDA(At, 1, 1); PG8_STAGEB(PG8_SB(1, 0), b3, voffB); PG8_STAGEB(PG8_SB(1, 1), b3 + hstep, voffB); PG8_STAGE(PG8_SA(1, 0), a3, voffA);
;             PG8_WAIT_V(8); PG8_WAIT_L(0); PG8_BAR; PG8_MMA(1, 0, At, B0); PG8_MMA(1, 1, At, B1); PG8_BAR; PG8_SCHED;
.LBB0_1157:
	s_add_i32 s81, s29, 2
	s_cmp_lt_u32 s29, 14
	s_cselect_b32 s0, 0, -16
	s_add_i32 s0, s81, s0
	s_ashr_i32 s1, s0, 31
	s_lshl_b64 s[0:1], s[0:1], 7
	s_add_u32 s2, s52, s0
	s_addc_u32 s46, s53, s1
	s_add_u32 s0, s50, s0
	s_addc_u32 s1, s51, s1
	s_cmp_eq_u32 s29, 14
	s_cselect_b32 s59, s19, s46
	s_cselect_b32 s58, s39, s2
	s_cselect_b32 s61, s92, s1
	s_cselect_b32 s60, s93, s0
	s_add_i32 s2, 0, 0x10000
	s_add_i32 s94, s2, s70
	s_add_i32 s46, 0, 0x14000
	s_add_i32 m0, s71, 0xc000
	s_add_i32 s84, s71, 0xe000
	s_add_i32 s95, s94, 0x2000
	s_add_u32 s62, s60, 0x40000
	s_addc_u32 s63, s61, 0
	s_add_i32 s96, s46, s70
	v_add_u32_e32 v162, s2, v99
	v_add_u32_e32 v166, s46, v99
	s_add_i32 s97, s96, 0x2000
	s_add_i32 vcc_lo, 0, 0x18000
	s_add_i32 vcc_hi, 0, 0x1c000
	ds_read_b128 v[148:151], v162
	ds_read_b128 v[154:157], v162 offset:1024
	ds_read_b128 v[158:161], v162 offset:2048
	ds_read_b128 v[162:165], v162 offset:3072
	ds_read_b128 v[180:183], v166
	ds_read_b128 v[184:187], v166 offset:1024
	ds_read_b128 v[188:191], v166 offset:2048
	ds_read_b128 v[192:195], v166 offset:3072
	s_add_u32 s56, s58, 0x40000
	s_addc_u32 s57, s59, 0
	s_add_i32 s1, vcc_lo, s70
	s_add_i32 s0, s1, 0x2000
	s_add_u32 s54, s60, 0x40080
	s_addc_u32 s55, s61, 0
	s_add_i32 s47, vcc_hi, s70
	s_add_i32 s46, s47, 0x2000
	ds_read_b128 v[196:199], v153
	ds_read_b128 v[200:203], v153 offset:1024
	ds_read_b128 v[222:225], v153 offset:2048
	ds_read_b128 v[226:229], v153 offset:3072
	ds_read_b128 v[230:233], v153 offset:4096
	ds_read_b128 v[234:237], v153 offset:5120
	ds_read_b128 v[238:241], v153 offset:6144
	ds_read_b128 v[242:245], v153 offset:7168
	global_load_lds_dwordx4 v[146:147], off
	s_mov_b32 m0, s84
	s_nop 0
	global_load_lds_dwordx4 v[144:145], off
	s_waitcnt vmcnt(8)
	s_waitcnt lgkmcnt(0)
	s_cmp_lg_u64 s[16:17], 0
	s_cbranch_scc1 .Lhb_25
	s_barrier
.Lhb_25:
	s_setprio 1
	s_waitcnt lgkmcnt(0)
	v_mfma_f32_16x16x32_bf16 v[128:131], v[148:151], v[196:199], v[128:131]
	v_mfma_f32_16x16x32_bf16 v[124:127], v[158:161], v[196:199], v[124:127]
	v_mfma_f32_16x16x32_bf16 v[112:115], v[148:151], v[222:225], v[112:115]
	v_mfma_f32_16x16x32_bf16 v[108:111], v[158:161], v[222:225], v[108:111]
	v_mfma_f32_16x16x32_bf16 v[94:97], v[148:151], v[230:233], v[94:97]
	v_mfma_f32_16x16x32_bf16 v[90:93], v[158:161], v[230:233], v[90:93]
	v_mfma_f32_16x16x32_bf16 v[78:81], v[148:151], v[238:241], v[78:81]
	v_mfma_f32_16x16x32_bf16 v[74:77], v[158:161], v[238:241], v[74:77]
	s_setprio 2
	v_mfma_f32_16x16x32_bf16 v[128:131], v[154:157], v[200:203], v[128:131]
	v_mfma_f32_16x16x32_bf16 v[124:127], v[162:165], v[200:203], v[124:127]
	v_mfma_f32_16x16x32_bf16 v[112:115], v[154:157], v[226:229], v[112:115]
	v_mfma_f32_16x16x32_bf16 v[108:111], v[162:165], v[226:229], v[108:111]
	v_mfma_f32_16x16x32_bf16 v[94:97], v[154:157], v[234:237], v[94:97]
	v_mfma_f32_16x16x32_bf16 v[90:93], v[162:165], v[234:237], v[90:93]
	v_mfma_f32_16x16x32_bf16 v[78:81], v[154:157], v[242:245], v[78:81]
	v_mfma_f32_16x16x32_bf16 v[74:77], v[162:165], v[242:245], v[74:77]
	v_mfma_f32_16x16x32_bf16 v[120:123], v[180:183], v[196:199], v[120:123]
	v_mfma_f32_16x16x32_bf16 v[116:119], v[188:191], v[196:199], v[116:119]
	v_mfma_f32_16x16x32_bf16 v[104:107], v[180:183], v[222:225], v[104:107]
	v_mfma_f32_16x16x32_bf16 v[100:103], v[188:191], v[222:225], v[100:103]
	s_setprio 3
	v_mfma_f32_16x16x32_bf16 v[86:89], v[180:183], v[230:233], v[86:89]
	v_mfma_f32_16x16x32_bf16 v[82:85], v[188:191], v[230:233], v[82:85]
	v_mfma_f32_16x16x32_bf16 v[70:73], v[180:183], v[238:241], v[70:73]
	v_mfma_f32_16x16x32_bf16 v[66:69], v[188:191], v[238:241], v[66:69]
	v_mfma_f32_16x16x32_bf16 v[120:123], v[184:187], v[200:203], v[120:123]
	v_mfma_f32_16x16x32_bf16 v[116:119], v[192:195], v[200:203], v[116:119]
	v_mfma_f32_16x16x32_bf16 v[104:107], v[184:187], v[226:229], v[104:107]
	v_mfma_f32_16x16x32_bf16 v[100:103], v[192:195], v[226:229], v[100:103]
	v_mfma_f32_16x16x32_bf16 v[86:89], v[184:187], v[234:237], v[86:89]
	v_mfma_f32_16x16x32_bf16 v[82:85], v[192:195], v[234:237], v[82:85]
	v_mfma_f32_16x16x32_bf16 v[70:73], v[184:187], v[242:245], v[70:73]
	v_mfma_f32_16x16x32_bf16 v[66:69], v[192:195], v[242:245], v[66:69]
	s_setprio 0
	s_cmp_eq_u64 s[16:17], 0
	s_cbranch_scc1 .Lhb_29
	s_barrier
; #define PG8_STAGE(bufoff, gbase, voff) do { _Pragma("unroll") for (int _i = 0; _i < 2; ++_i) \
;         __builtin_amdgcn_global_load_lds((const unsigned*)((const char*)(gbase) + (voff)[_i]), (PG8_LAS unsigned*)(lds + (bufoff) + ldsw + _i * 8192), 16, 0, AUX_A); } while (0)
; #define PG8_STAGEB(bufoff, gbase, voff) do { _Pragma("unroll") for (int _i = 0; _i < 2; ++_i) \
;         __builtin_amdgcn_global_load_lds((const unsigned*)((const char*)(gbase) + (voff)[_i]), (PG8_LAS unsigned*)(lds + (bufoff) + ldsw + _i * 8192), 16, 0, AUX_B); } while (0)
; #define PG8_WAIT_V(n) asm volatile("s_waitcnt vmcnt(" #n ")" ::: "memory")
; #define PG8_WAIT_L(n) asm volatile("s_waitcnt lgkmcnt(" #n ")" ::: "memory")
; template <class Epi, class Sched, bool ALIGN_EPI = false, bool SP2 = false>
; __device__ __forceinline__ void gemm_phase(PG8_LAS unsigned char* lds, const Gemm g, const Sched& S, const Epi& E) {
;     ...
;         for (int t = 0; t < nt; t += 2) {
;             const bool last = (t == nt - 2);
;             const char* a1 = PG8_KP(cA, t + 1, rot, nt);
;             const char* a2 = last ? nAr : PG8_KP(cA, t + 2, rot, nt); const char* b2 = last ? nBr : PG8_KP(cB, t + 2, rot, nt);
;             const char* a3 = a2 + kstep; const char* b3 = b2 + kstep;
;             if (last && has_next) S.a_ready(nxt);
;             if constexpr (SP2) {
;             PG8_LDB(B0, 0, 0); PG8_LDB(B1, 0, 1); PG8_SCHED; PG8_LDA(At, 0, 0); PG8_STAGE(PG8_SA(1, 1), a1 + hstep, voffA);
;             PG8_WAIT_V(8); PG8_WAIT_L(0); PG8_BAR; PG8_MMA(0, 0, At, B0); PG8_MMA(0, 1, At, B1); PG8_BAR; PG8_SCHED;
;             PG8_LDA(At, 0, 1); PG8_STAGEB(PG8_SB(0, 0), b2, voffB); PG8_STAGEB(PG8_SB(0, 1), b2 + hstep, voffB); PG8_STAGE(PG8_SA(0, 0), a2, voffA);
;             PG8_WAIT_V(8); PG8_WAIT_L(0); PG8_BAR; PG8_MMA(1, 0, At, B0); PG8_MMA(1, 1, At, B1); PG8_BAR; PG8_SCHED;
;             PG8_LDB(B0, 1, 0); PG8_LDB(B1, 1, 1); PG8_SCHED; PG8_LDA(At, 1, 0); PG8_STAGE(PG8_SA(0, 1), a2 + hstep, voffA);
;             PG8_WAIT_V(8); PG8_WAIT_L(0); PG8_BAR; PG8_MMA(0, 0, At, B0); PG8_MMA(0, 1, At, B1); PG8_BAR; PG8_SCHED;
;             PG8_LDA(At, 1, 1); PG8_STAGEB(PG8_SB(1, 0), b3, voffB); PG8_STAGEB(PG8_SB(1, 1), b3 + hstep, voffB); PG8_STAGE(PG8_SA(1, 0), a3, voffA);
;             PG8_WAIT_V(8); PG8_WAIT_L(0); PG8_BAR; PG8_MMA(1, 0, At, B0); PG8_MMA(1, 1, At, B1); PG8_BAR; PG8_SCHED;
.Lhb_29:
	s_mov_b32 m0, s94
	v_lshl_add_u64 v[166:167], s[60:61], 0, v[136:137]
	ds_read_b128 v[196:199], v153 offset:16384
	ds_read_b128 v[200:203], v153 offset:17408
	ds_read_b128 v[222:225], v153 offset:18432
	ds_read_b128 v[226:229], v153 offset:19456
	ds_read_b128 v[230:233], v153 offset:20480
	ds_read_b128 v[234:237], v153 offset:21504
	ds_read_b128 v[238:241], v153 offset:22528
	ds_read_b128 v[242:245], v153 offset:23552
	global_load_lds_dwordx4 v[166:167], off
	v_lshl_add_u64 v[168:169], s[60:61], 0, v[132:133]
	s_mov_b32 m0, s95
	v_lshl_add_u64 v[172:173], s[62:63], 0, v[136:137]
	global_load_lds_dwordx4 v[168:169], off
	s_mov_b32 m0, s96
	v_lshl_add_u64 v[212:213], s[58:59], 0, v[134:135]
	global_load_lds_dwordx4 v[172:173], off
	v_lshl_add_u64 v[172:173], s[62:63], 0, v[132:133]
	s_mov_b32 m0, s97
	s_nop 0
	global_load_lds_dwordx4 v[172:173], off
	v_lshl_add_u64 v[172:173], s[58:59], 0, v[138:139]
	s_mov_b32 m0, s71
	s_nop 0
	global_load_lds_dwordx4 v[172:173], off
	s_mov_b32 m0, s75
	s_nop 0
	global_load_lds_dwordx4 v[212:213], off
	s_waitcnt vmcnt(8)
	s_waitcnt lgkmcnt(0)
	s_cmp_lg_u64 s[16:17], 0
	s_cbranch_scc1 .Lhb_26
	s_barrier
.Lhb_26:
	s_setprio 1
	s_waitcnt lgkmcnt(0)
	v_mfma_f32_16x16x32_bf16 v[62:65], v[148:151], v[196:199], v[62:65]
	v_mfma_f32_16x16x32_bf16 v[58:61], v[158:161], v[196:199], v[58:61]
	v_mfma_f32_16x16x32_bf16 v[46:49], v[148:151], v[222:225], v[46:49]
	v_mfma_f32_16x16x32_bf16 v[42:45], v[158:161], v[222:225], v[42:45]
	v_mfma_f32_16x16x32_bf16 v[30:33], v[148:151], v[230:233], v[30:33]
	v_mfma_f32_16x16x32_bf16 v[26:29], v[158:161], v[230:233], v[26:29]
	v_mfma_f32_16x16x32_bf16 v[14:17], v[148:151], v[238:241], v[14:17]
	v_mfma_f32_16x16x32_bf16 v[10:13], v[158:161], v[238:241], v[10:13]
	s_setprio 2
	v_mfma_f32_16x16x32_bf16 v[62:65], v[154:157], v[200:203], v[62:65]
	v_mfma_f32_16x16x32_bf16 v[58:61], v[162:165], v[200:203], v[58:61]
	v_mfma_f32_16x16x32_bf16 v[46:49], v[154:157], v[226:229], v[46:49]
	v_mfma_f32_16x16x32_bf16 v[42:45], v[162:165], v[226:229], v[42:45]
	v_mfma_f32_16x16x32_bf16 v[30:33], v[154:157], v[234:237], v[30:33]
	v_mfma_f32_16x16x32_bf16 v[26:29], v[162:165], v[234:237], v[26:29]
	v_mfma_f32_16x16x32_bf16 v[14:17], v[154:157], v[242:245], v[14:17]
	v_mfma_f32_16x16x32_bf16 v[10:13], v[162:165], v[242:245], v[10:13]
	v_mfma_f32_16x16x32_bf16 v[54:57], v[180:183], v[196:199], v[54:57]
	v_mfma_f32_16x16x32_bf16 v[50:53], v[188:191], v[196:199], v[50:53]
	v_mfma_f32_16x16x32_bf16 v[38:41], v[180:183], v[222:225], v[38:41]
	v_mfma_f32_16x16x32_bf16 v[34:37], v[188:191], v[222:225], v[34:37]
	s_setprio 3
	v_mfma_f32_16x16x32_bf16 v[22:25], v[180:183], v[230:233], v[22:25]
	v_mfma_f32_16x16x32_bf16 v[18:21], v[188:191], v[230:233], v[18:21]
	v_mfma_f32_16x16x32_bf16 v[6:9], v[180:183], v[238:241], v[6:9]
	v_mfma_f32_16x16x32_bf16 v[2:5], v[188:191], v[238:241], v[2:5]
	v_mfma_f32_16x16x32_bf16 v[54:57], v[184:187], v[200:203], v[54:57]
	v_mfma_f32_16x16x32_bf16 v[50:53], v[192:195], v[200:203], v[50:53]
	v_mfma_f32_16x16x32_bf16 v[38:41], v[184:187], v[226:229], v[38:41]
	v_mfma_f32_16x16x32_bf16 v[34:37], v[192:195], v[226:229], v[34:37]
	v_mfma_f32_16x16x32_bf16 v[22:25], v[184:187], v[234:237], v[22:25]
	v_mfma_f32_16x16x32_bf16 v[18:21], v[192:195], v[234:237], v[18:21]
	v_mfma_f32_16x16x32_bf16 v[6:9], v[184:187], v[242:245], v[6:9]
	v_mfma_f32_16x16x32_bf16 v[2:5], v[192:195], v[242:245], v[2:5]
	s_setprio 0
	s_cmp_eq_u64 s[16:17], 0
	s_cbranch_scc1 .Lhb_30
	s_barrier
.Lhb_30:
	v_add_u32_e32 v162, vcc_lo, v99
	v_add_u32_e32 v192, vcc_hi, v99
	ds_read_b128 v[148:151], v162
	ds_read_b128 v[154:157], v162 offset:1024
	ds_read_b128 v[158:161], v162 offset:2048
	ds_read_b128 v[162:165], v162 offset:3072
	ds_read_b128 v[180:183], v192
	ds_read_b128 v[184:187], v192 offset:1024
	ds_read_b128 v[188:191], v192 offset:2048
	ds_read_b128 v[192:195], v192 offset:3072
	s_mov_b32 m0, s78
	v_lshl_add_u64 v[246:247], s[56:57], 0, v[138:139]
	ds_read_b128 v[196:199], v153 offset:32768
	ds_read_b128 v[200:203], v153 offset:33792
	ds_read_b128 v[222:225], v153 offset:34816
	ds_read_b128 v[226:229], v153 offset:35840
	ds_read_b128 v[230:233], v153 offset:36864
	ds_read_b128 v[234:237], v153 offset:37888
	ds_read_b128 v[238:241], v153 offset:38912
	ds_read_b128 v[242:245], v153 offset:39936
	global_load_lds_dwordx4 v[246:247], off
	v_lshl_add_u64 v[246:247], s[56:57], 0, v[134:135]
	s_mov_b32 m0, s82
	s_nop 0
	global_load_lds_dwordx4 v[246:247], off
	s_waitcnt vmcnt(8)
	s_waitcnt lgkmcnt(0)
	s_cmp_lg_u64 s[16:17], 0
	s_cbranch_scc1 .Lhb_27
	s_barrier

; #define PG8_STAGE(bufoff, gbase, voff) do { _Pragma("unroll") for (int _i = 0; _i < 2; ++_i) \
;         __builtin_amdgcn_global_load_lds((const unsigned*)((const char*)(gbase) + (voff)[_i]), (PG8_LAS unsigned*)(lds + (bufoff) + ldsw + _i * 8192), 16, 0, AUX_A); } while (0)
; #define PG8_STAGEB(bufoff, gbase, voff) do { _Pragma("unroll") for (int _i = 0; _i < 2; ++_i) \
;         __builtin_amdgcn_global_load_lds((const unsigned*)((const char*)(gbase) + (voff)[_i]), (PG8_LAS unsigned*)(lds + (bufoff) + ldsw + _i * 8192), 16, 0, AUX_B); } while (0)
; #define PG8_LDA(dst, b, h) do { _Pragma("unroll") for (int m = 0; m < 4; ++m) _Pragma("unroll") for (int k = 0; k < 2; ++k) dst[m][k] = *(const PG8_LAS bf16x8*)(lds + PG8_SA(b, h) + aoff + m * 2048 + k * 1024); } while (0)
; #define PG8_LDB(dst, b, h) do { _Pragma("unroll") for (int n = 0; n < 2; ++n) _Pragma("unroll") for (int k = 0; k < 2; ++k) dst[n][k] = *(const PG8_LAS bf16x8*)(lds + PG8_SB(b, h) + boff + n * 2048 + k * 1024); } while (0)
; #define PG8_MMA(ai, bj, At, Bt) do { __builtin_amdgcn_s_setprio(1); _Pragma("unroll") for (int m = 0; m < 4; ++m) _Pragma("unroll") for (int n = 0; n < 2; ++n) _Pragma("unroll") for (int k = 0; k < 2; ++k) \
;         acc[ai][bj][m][n] = __builtin_amdgcn_mfma_f32_16x16x32_bf16(Bt[n][k], At[m][k], acc[ai][bj][m][n], 0, 0, 0); __builtin_amdgcn_s_setprio(0); } while (0)
; #define PG8_WAIT_V(n) asm volatile("s_waitcnt vmcnt(" #n ")" ::: "memory")
; #define PG8_WAIT_L(n) asm volatile("s_waitcnt lgkmcnt(" #n ")" ::: "memory")
; template <class Epi, class Sched, bool ALIGN_EPI = false, bool SP2 = false>
; __device__ __forceinline__ void gemm_phase(PG8_LAS unsigned char* lds, const Gemm g, const Sched& S, const Epi& E) {
;     ...
;             PG8_WAIT_V(8); PG8_WAIT_L(0); PG8_BAR; PG8_MMA(1, 0, At, B0); PG8_MMA(1, 1, At, B1); PG8_BAR; PG8_SCHED;
;             PG8_LDB(B0, 1, 0); PG8_LDB(B1, 1, 1); PG8_SCHED; PG8_LDA(At, 1, 0); PG8_STAGE(PG8_SA(0, 1), a2 + hstep, voffA);
;             PG8_WAIT_V(8); PG8_WAIT_L(0); PG8_BAR; PG8_MMA(0, 0, At, B0); PG8_MMA(0, 1, At, B1); PG8_BAR; PG8_SCHED;
;             PG8_LDA(At, 1, 1); PG8_STAGEB(PG8_SB(1, 0), b3, voffB); PG8_STAGEB(PG8_SB(1, 1), b3 + hstep, voffB); PG8_STAGE(PG8_SA(1, 0), a3, voffA);
;             PG8_WAIT_V(8); PG8_WAIT_L(0); PG8_BAR; PG8_MMA(1, 0, At, B0); PG8_MMA(1, 1, At, B1); PG8_BAR; PG8_SCHED;
.Lhb_31:
	s_mov_b32 m0, s1
	v_lshl_add_u64 v[166:167], v[166:167], 0, s[76:77]
	ds_read_b128 v[196:199], v153 offset:49152
	ds_read_b128 v[200:203], v153 offset:50176
	ds_read_b128 v[222:225], v153 offset:51200
	ds_read_b128 v[226:229], v153 offset:52224
	ds_read_b128 v[230:233], v153 offset:53248
	ds_read_b128 v[234:237], v153 offset:54272
	ds_read_b128 v[238:241], v153 offset:55296
	ds_read_b128 v[242:245], v153 offset:56320
	global_load_lds_dwordx4 v[166:167], off
	v_lshl_add_u64 v[166:167], v[168:169], 0, s[76:77]
	s_mov_b32 m0, s0
	s_nop 0
	global_load_lds_dwordx4 v[166:167], off
	v_lshl_add_u64 v[166:167], s[54:55], 0, v[136:137]
	s_mov_b32 m0, s47
	s_nop 0
	global_load_lds_dwordx4 v[166:167], off
	v_lshl_add_u64 v[166:167], s[54:55], 0, v[132:133]
	s_mov_b32 m0, s46
	s_nop 0
	global_load_lds_dwordx4 v[166:167], off
	v_lshl_add_u64 v[166:167], v[172:173], 0, s[76:77]
	s_mov_b32 m0, s83
	s_nop 0
	global_load_lds_dwordx4 v[166:167], off
	v_lshl_add_u64 v[166:167], v[212:213], 0, s[76:77]
	s_mov_b32 m0, s88
	s_nop 0
	global_load_lds_dwordx4 v[166:167], off
	s_waitcnt vmcnt(8)
	s_waitcnt lgkmcnt(0)
	s_cmp_lg_u64 s[16:17], 0
	s_cbranch_scc1 .Lhb_28
	s_barrier

; #define PG8_BAR __builtin_amdgcn_s_barrier()
; template <class Epi, class Sched, bool ALIGN_EPI = false, bool SP2 = false>
; __device__ __forceinline__ void gemm_phase(PG8_LAS unsigned char* lds, const Gemm g, const Sched& S, const Epi& E) {
;     ...
;         for (int t = 0; t < nt; t += 2) {
;             const bool last = (t == nt - 2);
;             const char* a1 = PG8_KP(cA, t + 1, rot, nt);
;             const char* a2 = last ? nAr : PG8_KP(cA, t + 2, rot, nt); const char* b2 = last ? nBr : PG8_KP(cB, t + 2, rot, nt);
;             const char* a3 = a2 + kstep; const char* b3 = b2 + kstep;
;     ...
;         if constexpr (ALIGN_EPI) { if (wr == 0) PG8_BAR; }
.Lhb_32:
	v_lshl_add_u64 v[144:145], v[144:145], 0, s[86:87]
	v_lshl_add_u64 v[146:147], v[146:147], 0, s[86:87]
	s_cmp_gt_u32 s81, 15
	s_mov_b32 s29, s81
	s_cbranch_scc0 .LBB0_1157
	s_and_b64 vcc, exec, s[16:17]
	s_cbranch_vccz .LBB0_1160

; #define GAS __attribute__((address_space(1)))
; __device__ __forceinline__ u32x4 pack8(f32x4 v0, f32x4 v1) { u32x4 w; w.x = cvt_pk_bf16(v0[0], v0[1]); w.y = cvt_pk_bf16(v0[2], v0[3]); w.z = cvt_pk_bf16(v1[0], v1[1]); w.w = cvt_pk_bf16(v1[2], v1[3]); return w; }
; __device__ __forceinline__ void unpack8(u32x4 w, f32x4& v0, f32x4& v1) { v0 = (f32x4){bflo(w.x), bfhi(w.x), bflo(w.y), bfhi(w.y)}; v1 = (f32x4){bflo(w.z), bfhi(w.z), bflo(w.w), bfhi(w.w)}; }
; #define GAS __attribute__((address_space(1)))
;     __device__ __forceinline__ void operator()(const f32x4 (&acc)[2][2][4][2], const Unit& u, int wr, int wc, int fr, int fq) const {
;     ...
;             for (int m = 0; m < 4; ++m) { const size_t r = (size_t)(row0 + ai * HALF + m * 16); const size_t off = r * 2048 + col0; const bf16_t* gp = P + r * NPJ + 2560 + MODE * 2048 + col0;
; #pragma unroll
;                 for (int bj = 0; bj < 2; ++bj) { f32x4 g0, g1; unpack8(*(const GAS u32x4*)(gp + bj * HALF), g0, g1);
;                     f32x4 v0 = g0 * acc[ai][bj][m][0], v1 = g1 * acc[ai][bj][m][1];
;                     if (MODE == 1) { f32x4 t0, t1; unpack8(*(const GAS u32x4*)(T1 + off + bj * HALF), t0, t1); v0 += t0; v1 += t1; }
;                     const u32x4 w = pack8(v0, v1);
;                     if (MODE == 0 && samp) asm volatile("global_store_dwordx4 %0, %1, off sc1\n\ts_nop 1" :: "v"(O + off + bj * HALF), "v"(w) : "memory");
;                     else *(GAS u32x4*)(O + off + bj * HALF) = w; } }
.LBB0_1178:
	v_or_b32_e32 v144, s19, v152
	v_lshl_add_u32 v146, s90, 8, v1
	v_ashrrev_i32_e32 v145, 31, v144
	v_mov_b64_e32 v[148:149], s[8:9]
	v_ashrrev_i32_e32 v147, 31, v146
	v_mad_i64_i32 v[154:155], s[0:1], v146, s95, v[148:149]
	v_lshlrev_b64 v[150:151], 1, v[144:145]
	v_lshlrev_b64 v[158:159], 11, v[146:147]
	v_lshl_add_u64 v[162:163], v[154:155], 0, v[150:151]
	v_lshl_add_u64 v[158:159], v[158:159], 0, v[144:145]
	v_add_co_u32_e32 v154, vcc, 0x2000, v162
	v_lshlrev_b64 v[164:165], 1, v[158:159]
	s_nop 0
	v_addc_co_u32_e32 v155, vcc, 0, v163, vcc
	v_lshl_add_u64 v[166:167], s[10:11], 0, v[164:165]
	global_load_dwordx4 v[154:157], v[154:155], off offset:1024
	s_mov_b64 s[2:3], 0x2400
	global_load_dwordx4 v[158:161], v[166:167], off
	v_lshl_add_u64 v[164:165], s[14:15], 0, v[164:165]
	v_lshl_add_u64 v[162:163], v[162:163], 0, s[2:3]
	s_movk_i32 s19, 0x2000
	s_waitcnt vmcnt(0)
	v_lshlrev_b32_e32 v168, 16, v154
	v_and_b32_e32 v169, 0xffff0000, v154
	v_lshlrev_b32_e32 v154, 16, v155
	v_and_b32_e32 v155, 0xffff0000, v155
	v_lshlrev_b32_e32 v172, 16, v156
	v_and_b32_e32 v173, 0xffff0000, v156
	v_lshlrev_b32_e32 v156, 16, v157
	v_and_b32_e32 v157, 0xffff0000, v157
	v_lshlrev_b32_e32 v180, 16, v158
	v_and_b32_e32 v181, 0xffff0000, v158
	v_lshlrev_b32_e32 v158, 16, v159
	v_and_b32_e32 v159, 0xffff0000, v159
	v_lshlrev_b32_e32 v182, 16, v160
	v_and_b32_e32 v183, 0xffff0000, v160
	v_lshlrev_b32_e32 v160, 16, v161
	v_and_b32_e32 v161, 0xffff0000, v161
	v_pk_fma_f32 v[130:131], v[130:131], v[154:155], v[158:159]
	v_pk_fma_f32 v[128:129], v[128:129], v[168:169], v[180:181]
	v_pk_fma_f32 v[154:155], v[126:127], v[156:157], v[160:161]
	v_pk_fma_f32 v[126:127], v[124:125], v[172:173], v[182:183]
	v_cvt_pk_bf16_f32 v124, v128, v129
	v_cvt_pk_bf16_f32 v125, v130, v131
	v_cvt_pk_bf16_f32 v126, v126, v127
	v_cvt_pk_bf16_f32 v127, v154, v155
	global_store_dwordx4 v[164:165], v[124:127], off
	global_load_dwordx4 v[124:127], v[162:163], off offset:256
	s_nop 0
	global_load_dwordx4 v[128:131], v[166:167], off offset:256
	v_or_b32_e32 v154, 16, v146
	v_ashrrev_i32_e32 v155, 31, v154
	v_mad_i64_i32 v[156:157], s[0:1], v154, s95, v[148:149]
	v_lshl_add_u64 v[156:157], v[156:157], 0, v[150:151]
	v_add_co_u32_e32 v158, vcc, s19, v156
	s_waitcnt vmcnt(1)
	v_lshlrev_b32_e32 v160, 16, v124
	v_and_b32_e32 v161, 0xffff0000, v124
	s_waitcnt vmcnt(0)
	v_lshlrev_b32_e32 v166, 16, v128
	v_and_b32_e32 v167, 0xffff0000, v128
	v_lshlrev_b32_e32 v124, 16, v125
	v_and_b32_e32 v125, 0xffff0000, v125
	v_lshlrev_b32_e32 v162, 16, v126
	v_and_b32_e32 v163, 0xffff0000, v126
	v_lshlrev_b32_e32 v126, 16, v127
	v_and_b32_e32 v127, 0xffff0000, v127
	v_lshlrev_b32_e32 v128, 16, v129
	v_and_b32_e32 v129, 0xffff0000, v129
	v_lshlrev_b32_e32 v168, 16, v130
	v_and_b32_e32 v169, 0xffff0000, v130
	v_lshlrev_b32_e32 v130, 16, v131
	v_and_b32_e32 v131, 0xffff0000, v131
	v_pk_fma_f32 v[120:121], v[120:121], v[160:161], v[166:167]
	v_pk_fma_f32 v[122:123], v[122:123], v[124:125], v[128:129]
	v_pk_fma_f32 v[124:125], v[118:119], v[126:127], v[130:131]
	v_pk_fma_f32 v[118:119], v[116:117], v[162:163], v[168:169]
	v_cvt_pk_bf16_f32 v116, v120, v121
	v_lshlrev_b64 v[120:121], 11, v[154:155]
	v_lshl_add_u64 v[120:121], v[120:121], 0, v[144:145]
	v_cvt_pk_bf16_f32 v117, v122, v123
	v_cvt_pk_bf16_f32 v118, v118, v119
	v_cvt_pk_bf16_f32 v119, v124, v125
	v_lshlrev_b64 v[124:125], 1, v[120:121]
	v_addc_co_u32_e32 v159, vcc, 0, v157, vcc
	global_store_dwordx4 v[164:165], v[116:119], off offset:256
	v_lshl_add_u64 v[126:127], s[10:11], 0, v[124:125]
	global_load_dwordx4 v[116:119], v[158:159], off offset:1024
	global_load_dwordx4 v[120:123], v[126:127], off
	v_lshl_add_u64 v[128:129], v[156:157], 0, s[2:3]
	v_lshl_add_u64 v[124:125], s[14:15], 0, v[124:125]
	s_waitcnt vmcnt(1)
	v_lshlrev_b32_e32 v130, 16, v116
	v_and_b32_e32 v131, 0xffff0000, v116
	v_lshlrev_b32_e32 v116, 16, v117
	v_and_b32_e32 v117, 0xffff0000, v117
	v_lshlrev_b32_e32 v154, 16, v118
	v_and_b32_e32 v155, 0xffff0000, v118
	v_lshlrev_b32_e32 v118, 16, v119
	v_and_b32_e32 v119, 0xffff0000, v119
	s_waitcnt vmcnt(0)
	v_lshlrev_b32_e32 v156, 16, v120
	v_and_b32_e32 v157, 0xffff0000, v120
	v_lshlrev_b32_e32 v120, 16, v121
	v_and_b32_e32 v121, 0xffff0000, v121
	v_lshlrev_b32_e32 v158, 16, v122
	v_and_b32_e32 v159, 0xffff0000, v122
	v_lshlrev_b32_e32 v122, 16, v123
	v_and_b32_e32 v123, 0xffff0000, v123
	v_pk_fma_f32 v[114:115], v[114:115], v[116:117], v[120:121]
	v_pk_fma_f32 v[112:113], v[112:113], v[130:131], v[156:157]
	v_pk_fma_f32 v[116:117], v[110:111], v[118:119], v[122:123]
	v_pk_fma_f32 v[110:111], v[108:109], v[154:155], v[158:159]
	v_cvt_pk_bf16_f32 v108, v112, v113
	v_cvt_pk_bf16_f32 v109, v114, v115
	v_cvt_pk_bf16_f32 v110, v110, v111
	v_cvt_pk_bf16_f32 v111, v116, v117
	global_store_dwordx4 v[124:125], v[108:111], off
	global_load_dwordx4 v[108:111], v[128:129], off offset:256
	s_nop 0
	global_load_dwordx4 v[112:115], v[126:127], off offset:256
	v_or_b32_e32 v116, 32, v146
	v_ashrrev_i32_e32 v117, 31, v116
	v_mad_i64_i32 v[118:119], s[0:1], v116, s95, v[148:149]
	v_lshl_add_u64 v[118:119], v[118:119], 0, v[150:151]
	v_add_co_u32_e32 v120, vcc, s19, v118
	s_waitcnt vmcnt(1)
	v_lshlrev_b32_e32 v122, 16, v108
	v_and_b32_e32 v123, 0xffff0000, v108
	s_waitcnt vmcnt(0)
; #define GAS __attribute__((address_space(1)))
; __device__ __forceinline__ u32x4 pack8(f32x4 v0, f32x4 v1) { u32x4 w; w.x = cvt_pk_bf16(v0[0], v0[1]); w.y = cvt_pk_bf16(v0[2], v0[3]); w.z = cvt_pk_bf16(v1[0], v1[1]); w.w = cvt_pk_bf16(v1[2], v1[3]); return w; }
; __device__ __forceinline__ void unpack8(u32x4 w, f32x4& v0, f32x4& v1) { v0 = (f32x4){bflo(w.x), bfhi(w.x), bflo(w.y), bfhi(w.y)}; v1 = (f32x4){bflo(w.z), bfhi(w.z), bflo(w.w), bfhi(w.w)}; }
; #define GAS __attribute__((address_space(1)))
;     __device__ __forceinline__ void operator()(const f32x4 (&acc)[2][2][4][2], const Unit& u, int wr, int wc, int fr, int fq) const {
;     ...
;             for (int m = 0; m < 4; ++m) { const size_t r = (size_t)(row0 + ai * HALF + m * 16); const size_t off = r * 2048 + col0; const bf16_t* gp = P + r * NPJ + 2560 + MODE * 2048 + col0;
; #pragma unroll
;                 for (int bj = 0; bj < 2; ++bj) { f32x4 g0, g1; unpack8(*(const GAS u32x4*)(gp + bj * HALF), g0, g1);
;                     f32x4 v0 = g0 * acc[ai][bj][m][0], v1 = g1 * acc[ai][bj][m][1];
;                     if (MODE == 1) { f32x4 t0, t1; unpack8(*(const GAS u32x4*)(T1 + off + bj * HALF), t0, t1); v0 += t0; v1 += t1; }
;                     const u32x4 w = pack8(v0, v1);
;                     if (MODE == 0 && samp) asm volatile("global_store_dwordx4 %0, %1, off sc1\n\ts_nop 1" :: "v"(O + off + bj * HALF), "v"(w) : "memory");
;                     else *(GAS u32x4*)(O + off + bj * HALF) = w; } }
	v_lshlrev_b32_e32 v128, 16, v112
	v_and_b32_e32 v129, 0xffff0000, v112
	v_lshlrev_b32_e32 v108, 16, v109
	v_and_b32_e32 v109, 0xffff0000, v109
	v_lshlrev_b32_e32 v126, 16, v110
	v_and_b32_e32 v127, 0xffff0000, v110
	v_lshlrev_b32_e32 v110, 16, v111
	v_and_b32_e32 v111, 0xffff0000, v111
	v_lshlrev_b32_e32 v112, 16, v113
	v_and_b32_e32 v113, 0xffff0000, v113
	v_lshlrev_b32_e32 v130, 16, v114
	v_and_b32_e32 v131, 0xffff0000, v114
	v_lshlrev_b32_e32 v114, 16, v115
	v_and_b32_e32 v115, 0xffff0000, v115
	v_pk_fma_f32 v[104:105], v[104:105], v[122:123], v[128:129]
	v_pk_fma_f32 v[106:107], v[106:107], v[108:109], v[112:113]
	v_pk_fma_f32 v[108:109], v[102:103], v[110:111], v[114:115]
	v_pk_fma_f32 v[102:103], v[100:101], v[126:127], v[130:131]
	v_cvt_pk_bf16_f32 v100, v104, v105
	v_lshlrev_b64 v[104:105], 11, v[116:117]
	v_lshl_add_u64 v[104:105], v[104:105], 0, v[144:145]
	v_cvt_pk_bf16_f32 v101, v106, v107
	v_cvt_pk_bf16_f32 v102, v102, v103
	v_cvt_pk_bf16_f32 v103, v108, v109
	v_lshlrev_b64 v[108:109], 1, v[104:105]
	v_addc_co_u32_e32 v121, vcc, 0, v119, vcc
	global_store_dwordx4 v[124:125], v[100:103], off offset:256
	v_lshl_add_u64 v[110:111], s[10:11], 0, v[108:109]
	global_load_dwordx4 v[100:103], v[120:121], off offset:1024
	global_load_dwordx4 v[104:107], v[110:111], off
	v_lshl_add_u64 v[112:113], v[118:119], 0, s[2:3]
	v_lshl_add_u64 v[108:109], s[14:15], 0, v[108:109]
	s_waitcnt vmcnt(1)
	v_lshlrev_b32_e32 v114, 16, v100
	v_and_b32_e32 v115, 0xffff0000, v100
	v_lshlrev_b32_e32 v100, 16, v101
	v_and_b32_e32 v101, 0xffff0000, v101
	v_lshlrev_b32_e32 v116, 16, v102
	v_and_b32_e32 v117, 0xffff0000, v102
	v_lshlrev_b32_e32 v102, 16, v103
	v_and_b32_e32 v103, 0xffff0000, v103
	s_waitcnt vmcnt(0)
	v_lshlrev_b32_e32 v118, 16, v104
	v_and_b32_e32 v119, 0xffff0000, v104
	v_lshlrev_b32_e32 v104, 16, v105
	v_and_b32_e32 v105, 0xffff0000, v105
	v_lshlrev_b32_e32 v120, 16, v106
	v_and_b32_e32 v121, 0xffff0000, v106
	v_lshlrev_b32_e32 v106, 16, v107
	v_and_b32_e32 v107, 0xffff0000, v107
	v_pk_fma_f32 v[96:97], v[96:97], v[100:101], v[104:105]
	v_pk_fma_f32 v[94:95], v[94:95], v[114:115], v[118:119]
	v_pk_fma_f32 v[100:101], v[92:93], v[102:103], v[106:107]
	v_pk_fma_f32 v[92:93], v[90:91], v[116:117], v[120:121]
	v_cvt_pk_bf16_f32 v90, v94, v95
	v_cvt_pk_bf16_f32 v91, v96, v97
	v_cvt_pk_bf16_f32 v92, v92, v93
	v_cvt_pk_bf16_f32 v93, v100, v101
	global_store_dwordx4 v[108:109], v[90:93], off
	global_load_dwordx4 v[90:93], v[112:113], off offset:256
	s_nop 0
	global_load_dwordx4 v[94:97], v[110:111], off offset:256
	v_or_b32_e32 v100, 48, v146
	v_ashrrev_i32_e32 v101, 31, v100
	v_mad_i64_i32 v[102:103], s[0:1], v100, s95, v[148:149]
	v_lshl_add_u64 v[102:103], v[102:103], 0, v[150:151]
	v_add_co_u32_e32 v104, vcc, s19, v102
	s_waitcnt vmcnt(1)
	v_lshlrev_b32_e32 v106, 16, v90
	v_and_b32_e32 v107, 0xffff0000, v90
	s_waitcnt vmcnt(0)
	v_lshlrev_b32_e32 v112, 16, v94
	v_and_b32_e32 v113, 0xffff0000, v94
	v_lshlrev_b32_e32 v90, 16, v91
	v_and_b32_e32 v91, 0xffff0000, v91
	v_lshlrev_b32_e32 v110, 16, v92
	v_and_b32_e32 v111, 0xffff0000, v92
	v_lshlrev_b32_e32 v92, 16, v93
	v_and_b32_e32 v93, 0xffff0000, v93
	v_lshlrev_b32_e32 v94, 16, v95
	v_and_b32_e32 v95, 0xffff0000, v95
	v_lshlrev_b32_e32 v114, 16, v96
	v_and_b32_e32 v115, 0xffff0000, v96
	v_lshlrev_b32_e32 v96, 16, v97
	v_and_b32_e32 v97, 0xffff0000, v97
	v_pk_fma_f32 v[86:87], v[86:87], v[106:107], v[112:113]
	v_pk_fma_f32 v[88:89], v[88:89], v[90:91], v[94:95]
	v_pk_fma_f32 v[90:91], v[84:85], v[92:93], v[96:97]
	v_pk_fma_f32 v[84:85], v[82:83], v[110:111], v[114:115]
	v_cvt_pk_bf16_f32 v82, v86, v87
	v_lshlrev_b64 v[86:87], 11, v[100:101]
	v_lshl_add_u64 v[86:87], v[86:87], 0, v[144:145]
	v_cvt_pk_bf16_f32 v83, v88, v89
	v_cvt_pk_bf16_f32 v84, v84, v85
	v_cvt_pk_bf16_f32 v85, v90, v91
	v_lshlrev_b64 v[90:91], 1, v[86:87]
	v_addc_co_u32_e32 v105, vcc, 0, v103, vcc
	global_store_dwordx4 v[108:109], v[82:85], off offset:256
	v_lshl_add_u64 v[92:93], s[10:11], 0, v[90:91]
	global_load_dwordx4 v[82:85], v[104:105], off offset:1024
	global_load_dwordx4 v[86:89], v[92:93], off
	v_lshl_add_u64 v[94:95], v[102:103], 0, s[2:3]
	v_lshl_add_u64 v[90:91], s[14:15], 0, v[90:91]
	s_waitcnt vmcnt(1)
	v_lshlrev_b32_e32 v96, 16, v82
	v_and_b32_e32 v97, 0xffff0000, v82
	v_lshlrev_b32_e32 v82, 16, v83
	v_and_b32_e32 v83, 0xffff0000, v83
	v_lshlrev_b32_e32 v100, 16, v84
	v_and_b32_e32 v101, 0xffff0000, v84
	v_lshlrev_b32_e32 v84, 16, v85
	v_and_b32_e32 v85, 0xffff0000, v85
	s_waitcnt vmcnt(0)
	v_lshlrev_b32_e32 v102, 16, v86
	v_and_b32_e32 v103, 0xffff0000, v86
	v_lshlrev_b32_e32 v86, 16, v87
	v_and_b32_e32 v87, 0xffff0000, v87
	v_lshlrev_b32_e32 v104, 16, v88
	v_and_b32_e32 v105, 0xffff0000, v88
	v_lshlrev_b32_e32 v88, 16, v89
	v_and_b32_e32 v89, 0xffff0000, v89
	v_pk_fma_f32 v[80:81], v[80:81], v[82:83], v[86:87]
	v_pk_fma_f32 v[78:79], v[78:79], v[96:97], v[102:103]
	v_pk_fma_f32 v[82:83], v[76:77], v[84:85], v[88:89]
	v_pk_fma_f32 v[76:77], v[74:75], v[100:101], v[104:105]
	v_cvt_pk_bf16_f32 v74, v78, v79
	v_cvt_pk_bf16_f32 v75, v80, v81
	v_cvt_pk_bf16_f32 v76, v76, v77
	v_cvt_pk_bf16_f32 v77, v82, v83
	global_store_dwordx4 v[90:91], v[74:77], off
	global_load_dwordx4 v[74:77], v[94:95], off offset:256
	s_nop 0
	global_load_dwordx4 v[78:81], v[92:93], off offset:256
	v_add_u32_e32 v82, 0x80, v146
	v_ashrrev_i32_e32 v83, 31, v82
	v_mad_i64_i32 v[84:85], s[0:1], v82, s95, v[148:149]
	v_lshl_add_u64 v[84:85], v[84:85], 0, v[150:151]
	v_add_co_u32_e32 v86, vcc, s19, v84
	s_waitcnt vmcnt(1)
	v_lshlrev_b32_e32 v88, 16, v74
	v_and_b32_e32 v89, 0xffff0000, v74
	s_waitcnt vmcnt(0)
; #define GAS __attribute__((address_space(1)))
; __device__ __forceinline__ u32x4 pack8(f32x4 v0, f32x4 v1) { u32x4 w; w.x = cvt_pk_bf16(v0[0], v0[1]); w.y = cvt_pk_bf16(v0[2], v0[3]); w.z = cvt_pk_bf16(v1[0], v1[1]); w.w = cvt_pk_bf16(v1[2], v1[3]); return w; }
; __device__ __forceinline__ void unpack8(u32x4 w, f32x4& v0, f32x4& v1) { v0 = (f32x4){bflo(w.x), bfhi(w.x), bflo(w.y), bfhi(w.y)}; v1 = (f32x4){bflo(w.z), bfhi(w.z), bflo(w.w), bfhi(w.w)}; }
; #define GAS __attribute__((address_space(1)))
;     __device__ __forceinline__ void operator()(const f32x4 (&acc)[2][2][4][2], const Unit& u, int wr, int wc, int fr, int fq) const {
;     ...
;             for (int m = 0; m < 4; ++m) { const size_t r = (size_t)(row0 + ai * HALF + m * 16); const size_t off = r * 2048 + col0; const bf16_t* gp = P + r * NPJ + 2560 + MODE * 2048 + col0;
; #pragma unroll
;                 for (int bj = 0; bj < 2; ++bj) { f32x4 g0, g1; unpack8(*(const GAS u32x4*)(gp + bj * HALF), g0, g1);
;                     f32x4 v0 = g0 * acc[ai][bj][m][0], v1 = g1 * acc[ai][bj][m][1];
;                     if (MODE == 1) { f32x4 t0, t1; unpack8(*(const GAS u32x4*)(T1 + off + bj * HALF), t0, t1); v0 += t0; v1 += t1; }
;                     const u32x4 w = pack8(v0, v1);
;                     if (MODE == 0 && samp) asm volatile("global_store_dwordx4 %0, %1, off sc1\n\ts_nop 1" :: "v"(O + off + bj * HALF), "v"(w) : "memory");
;                     else *(GAS u32x4*)(O + off + bj * HALF) = w; } }
	v_lshlrev_b32_e32 v94, 16, v78
	v_and_b32_e32 v95, 0xffff0000, v78
	v_lshlrev_b32_e32 v74, 16, v75
	v_and_b32_e32 v75, 0xffff0000, v75
	v_lshlrev_b32_e32 v92, 16, v76
	v_and_b32_e32 v93, 0xffff0000, v76
	v_lshlrev_b32_e32 v76, 16, v77
	v_and_b32_e32 v77, 0xffff0000, v77
	v_lshlrev_b32_e32 v78, 16, v79
	v_and_b32_e32 v79, 0xffff0000, v79
	v_lshlrev_b32_e32 v96, 16, v80
	v_and_b32_e32 v97, 0xffff0000, v80
	v_lshlrev_b32_e32 v80, 16, v81
	v_and_b32_e32 v81, 0xffff0000, v81
	v_pk_fma_f32 v[70:71], v[70:71], v[88:89], v[94:95]
	v_pk_fma_f32 v[72:73], v[72:73], v[74:75], v[78:79]
	v_pk_fma_f32 v[74:75], v[68:69], v[76:77], v[80:81]
	v_pk_fma_f32 v[68:69], v[66:67], v[92:93], v[96:97]
	v_cvt_pk_bf16_f32 v66, v70, v71
	v_lshlrev_b64 v[70:71], 11, v[82:83]
	v_lshl_add_u64 v[70:71], v[70:71], 0, v[144:145]
	v_cvt_pk_bf16_f32 v67, v72, v73
	v_cvt_pk_bf16_f32 v68, v68, v69
	v_cvt_pk_bf16_f32 v69, v74, v75
	v_lshlrev_b64 v[74:75], 1, v[70:71]
	v_addc_co_u32_e32 v87, vcc, 0, v85, vcc
	global_store_dwordx4 v[90:91], v[66:69], off offset:256
	v_lshl_add_u64 v[76:77], s[10:11], 0, v[74:75]
	global_load_dwordx4 v[66:69], v[86:87], off offset:1024
	global_load_dwordx4 v[70:73], v[76:77], off
	v_lshl_add_u64 v[78:79], v[84:85], 0, s[2:3]
	v_lshl_add_u64 v[74:75], s[14:15], 0, v[74:75]
	s_waitcnt vmcnt(1)
	v_lshlrev_b32_e32 v80, 16, v66
	v_and_b32_e32 v81, 0xffff0000, v66
	v_lshlrev_b32_e32 v66, 16, v67
	v_and_b32_e32 v67, 0xffff0000, v67
	v_lshlrev_b32_e32 v82, 16, v68
	v_and_b32_e32 v83, 0xffff0000, v68
	v_lshlrev_b32_e32 v68, 16, v69
	v_and_b32_e32 v69, 0xffff0000, v69
	s_waitcnt vmcnt(0)
	v_lshlrev_b32_e32 v84, 16, v70
	v_and_b32_e32 v85, 0xffff0000, v70
	v_lshlrev_b32_e32 v70, 16, v71
	v_and_b32_e32 v71, 0xffff0000, v71
	v_lshlrev_b32_e32 v86, 16, v72
	v_and_b32_e32 v87, 0xffff0000, v72
	v_lshlrev_b32_e32 v72, 16, v73
	v_and_b32_e32 v73, 0xffff0000, v73
	v_pk_fma_f32 v[64:65], v[64:65], v[66:67], v[70:71]
	v_pk_fma_f32 v[62:63], v[62:63], v[80:81], v[84:85]
	v_pk_fma_f32 v[66:67], v[60:61], v[68:69], v[72:73]
	v_pk_fma_f32 v[60:61], v[58:59], v[82:83], v[86:87]
	v_cvt_pk_bf16_f32 v58, v62, v63
	v_cvt_pk_bf16_f32 v59, v64, v65
	v_cvt_pk_bf16_f32 v60, v60, v61
	v_cvt_pk_bf16_f32 v61, v66, v67
	global_store_dwordx4 v[74:75], v[58:61], off
	global_load_dwordx4 v[58:61], v[78:79], off offset:256
	s_nop 0
	global_load_dwordx4 v[62:65], v[76:77], off offset:256
	v_add_u32_e32 v66, 0x90, v146
	v_ashrrev_i32_e32 v67, 31, v66
	v_mad_i64_i32 v[68:69], s[0:1], v66, s95, v[148:149]
	v_lshl_add_u64 v[68:69], v[68:69], 0, v[150:151]
	v_add_co_u32_e32 v70, vcc, s19, v68
	s_waitcnt vmcnt(1)
	v_lshlrev_b32_e32 v72, 16, v58
	v_and_b32_e32 v73, 0xffff0000, v58
	s_waitcnt vmcnt(0)
	v_lshlrev_b32_e32 v78, 16, v62
	v_and_b32_e32 v79, 0xffff0000, v62
	v_lshlrev_b32_e32 v58, 16, v59
	v_and_b32_e32 v59, 0xffff0000, v59
	v_lshlrev_b32_e32 v76, 16, v60
	v_and_b32_e32 v77, 0xffff0000, v60
	v_lshlrev_b32_e32 v60, 16, v61
	v_and_b32_e32 v61, 0xffff0000, v61
	v_lshlrev_b32_e32 v62, 16, v63
	v_and_b32_e32 v63, 0xffff0000, v63
	v_lshlrev_b32_e32 v80, 16, v64
	v_and_b32_e32 v81, 0xffff0000, v64
	v_lshlrev_b32_e32 v64, 16, v65
	v_and_b32_e32 v65, 0xffff0000, v65
	v_pk_fma_f32 v[54:55], v[54:55], v[72:73], v[78:79]
	v_pk_fma_f32 v[56:57], v[56:57], v[58:59], v[62:63]
	v_pk_fma_f32 v[58:59], v[52:53], v[60:61], v[64:65]
	v_pk_fma_f32 v[52:53], v[50:51], v[76:77], v[80:81]
	v_cvt_pk_bf16_f32 v50, v54, v55
	v_lshlrev_b64 v[54:55], 11, v[66:67]
	v_lshl_add_u64 v[54:55], v[54:55], 0, v[144:145]
	v_cvt_pk_bf16_f32 v51, v56, v57
	v_cvt_pk_bf16_f32 v52, v52, v53
	v_cvt_pk_bf16_f32 v53, v58, v59
	v_lshlrev_b64 v[58:59], 1, v[54:55]
	v_addc_co_u32_e32 v71, vcc, 0, v69, vcc
	global_store_dwordx4 v[74:75], v[50:53], off offset:256
	v_lshl_add_u64 v[60:61], s[10:11], 0, v[58:59]
	global_load_dwordx4 v[50:53], v[70:71], off offset:1024
	global_load_dwordx4 v[54:57], v[60:61], off
	v_lshl_add_u64 v[62:63], v[68:69], 0, s[2:3]
	v_lshl_add_u64 v[58:59], s[14:15], 0, v[58:59]
	s_waitcnt vmcnt(1)
	v_lshlrev_b32_e32 v64, 16, v50
	v_and_b32_e32 v65, 0xffff0000, v50
	v_lshlrev_b32_e32 v50, 16, v51
	v_and_b32_e32 v51, 0xffff0000, v51
	v_lshlrev_b32_e32 v66, 16, v52
	v_and_b32_e32 v67, 0xffff0000, v52
	v_lshlrev_b32_e32 v52, 16, v53
	v_and_b32_e32 v53, 0xffff0000, v53
	s_waitcnt vmcnt(0)
	v_lshlrev_b32_e32 v68, 16, v54
	v_and_b32_e32 v69, 0xffff0000, v54
	v_lshlrev_b32_e32 v54, 16, v55
	v_and_b32_e32 v55, 0xffff0000, v55
	v_lshlrev_b32_e32 v70, 16, v56
	v_and_b32_e32 v71, 0xffff0000, v56
	v_lshlrev_b32_e32 v56, 16, v57
	v_and_b32_e32 v57, 0xffff0000, v57
	v_pk_fma_f32 v[48:49], v[48:49], v[50:51], v[54:55]
	v_pk_fma_f32 v[46:47], v[46:47], v[64:65], v[68:69]
	v_pk_fma_f32 v[50:51], v[44:45], v[52:53], v[56:57]
	v_pk_fma_f32 v[44:45], v[42:43], v[66:67], v[70:71]
	v_cvt_pk_bf16_f32 v42, v46, v47
	v_cvt_pk_bf16_f32 v43, v48, v49
	v_cvt_pk_bf16_f32 v44, v44, v45
	v_cvt_pk_bf16_f32 v45, v50, v51
	global_store_dwordx4 v[58:59], v[42:45], off
	global_load_dwordx4 v[42:45], v[62:63], off offset:256
	s_nop 0
	global_load_dwordx4 v[46:49], v[60:61], off offset:256
	v_add_u32_e32 v50, 0xa0, v146
	v_ashrrev_i32_e32 v51, 31, v50
	v_mad_i64_i32 v[52:53], s[0:1], v50, s95, v[148:149]
	v_lshl_add_u64 v[52:53], v[52:53], 0, v[150:151]
	v_add_co_u32_e32 v54, vcc, s19, v52
	s_waitcnt vmcnt(1)
	v_lshlrev_b32_e32 v56, 16, v42
	v_and_b32_e32 v57, 0xffff0000, v42
	s_waitcnt vmcnt(0)
; #define GAS __attribute__((address_space(1)))
; __device__ __forceinline__ u32x4 pack8(f32x4 v0, f32x4 v1) { u32x4 w; w.x = cvt_pk_bf16(v0[0], v0[1]); w.y = cvt_pk_bf16(v0[2], v0[3]); w.z = cvt_pk_bf16(v1[0], v1[1]); w.w = cvt_pk_bf16(v1[2], v1[3]); return w; }
; __device__ __forceinline__ void unpack8(u32x4 w, f32x4& v0, f32x4& v1) { v0 = (f32x4){bflo(w.x), bfhi(w.x), bflo(w.y), bfhi(w.y)}; v1 = (f32x4){bflo(w.z), bfhi(w.z), bflo(w.w), bfhi(w.w)}; }
; #define PG8_BAR __builtin_amdgcn_s_barrier()
; #define GAS __attribute__((address_space(1)))
;     __device__ __forceinline__ void operator()(const f32x4 (&acc)[2][2][4][2], const Unit& u, int wr, int wc, int fr, int fq) const {
;     ...
;             for (int m = 0; m < 4; ++m) { const size_t r = (size_t)(row0 + ai * HALF + m * 16); const size_t off = r * 2048 + col0; const bf16_t* gp = P + r * NPJ + 2560 + MODE * 2048 + col0;
; #pragma unroll
;                 for (int bj = 0; bj < 2; ++bj) { f32x4 g0, g1; unpack8(*(const GAS u32x4*)(gp + bj * HALF), g0, g1);
;                     f32x4 v0 = g0 * acc[ai][bj][m][0], v1 = g1 * acc[ai][bj][m][1];
;                     if (MODE == 1) { f32x4 t0, t1; unpack8(*(const GAS u32x4*)(T1 + off + bj * HALF), t0, t1); v0 += t0; v1 += t1; }
;                     const u32x4 w = pack8(v0, v1);
;                     if (MODE == 0 && samp) asm volatile("global_store_dwordx4 %0, %1, off sc1\n\ts_nop 1" :: "v"(O + off + bj * HALF), "v"(w) : "memory");
;                     else *(GAS u32x4*)(O + off + bj * HALF) = w; } }
; template <class Epi, class Sched, bool ALIGN_EPI = false, bool SP2 = false>
; __device__ __forceinline__ void gemm_phase(PG8_LAS unsigned char* lds, const Gemm g, const Sched& S, const Epi& E) {
;     ...
;         cur = nxt; cA = nA; cB = nB; ++ui;
;         if constexpr (ALIGN_EPI) { if (wr == 1) PG8_BAR; }
	v_lshlrev_b32_e32 v62, 16, v46
	v_and_b32_e32 v63, 0xffff0000, v46
	v_lshlrev_b32_e32 v42, 16, v43
	v_and_b32_e32 v43, 0xffff0000, v43
	v_lshlrev_b32_e32 v60, 16, v44
	v_and_b32_e32 v61, 0xffff0000, v44
	v_lshlrev_b32_e32 v44, 16, v45
	v_and_b32_e32 v45, 0xffff0000, v45
	v_lshlrev_b32_e32 v46, 16, v47
	v_and_b32_e32 v47, 0xffff0000, v47
	v_lshlrev_b32_e32 v64, 16, v48
	v_and_b32_e32 v65, 0xffff0000, v48
	v_lshlrev_b32_e32 v48, 16, v49
	v_and_b32_e32 v49, 0xffff0000, v49
	v_pk_fma_f32 v[38:39], v[38:39], v[56:57], v[62:63]
	v_pk_fma_f32 v[40:41], v[40:41], v[42:43], v[46:47]
	v_pk_fma_f32 v[42:43], v[36:37], v[44:45], v[48:49]
	v_pk_fma_f32 v[36:37], v[34:35], v[60:61], v[64:65]
	v_cvt_pk_bf16_f32 v34, v38, v39
	v_lshlrev_b64 v[38:39], 11, v[50:51]
	v_lshl_add_u64 v[38:39], v[38:39], 0, v[144:145]
	v_cvt_pk_bf16_f32 v35, v40, v41
	v_cvt_pk_bf16_f32 v36, v36, v37
	v_cvt_pk_bf16_f32 v37, v42, v43
	v_lshlrev_b64 v[42:43], 1, v[38:39]
	v_addc_co_u32_e32 v55, vcc, 0, v53, vcc
	global_store_dwordx4 v[58:59], v[34:37], off offset:256
	v_lshl_add_u64 v[44:45], s[10:11], 0, v[42:43]
	global_load_dwordx4 v[34:37], v[54:55], off offset:1024
	global_load_dwordx4 v[38:41], v[44:45], off
	v_lshl_add_u64 v[46:47], v[52:53], 0, s[2:3]
	v_lshl_add_u64 v[42:43], s[14:15], 0, v[42:43]
	s_waitcnt vmcnt(1)
	v_lshlrev_b32_e32 v48, 16, v34
	v_and_b32_e32 v49, 0xffff0000, v34
	v_lshlrev_b32_e32 v34, 16, v35
	v_and_b32_e32 v35, 0xffff0000, v35
	v_lshlrev_b32_e32 v50, 16, v36
	v_and_b32_e32 v51, 0xffff0000, v36
	v_lshlrev_b32_e32 v36, 16, v37
	v_and_b32_e32 v37, 0xffff0000, v37
	s_waitcnt vmcnt(0)
	v_lshlrev_b32_e32 v52, 16, v38
	v_and_b32_e32 v53, 0xffff0000, v38
	v_lshlrev_b32_e32 v38, 16, v39
	v_and_b32_e32 v39, 0xffff0000, v39
	v_lshlrev_b32_e32 v54, 16, v40
	v_and_b32_e32 v55, 0xffff0000, v40
	v_lshlrev_b32_e32 v40, 16, v41
	v_and_b32_e32 v41, 0xffff0000, v41
	v_pk_fma_f32 v[32:33], v[32:33], v[34:35], v[38:39]
	v_pk_fma_f32 v[30:31], v[30:31], v[48:49], v[52:53]
	v_pk_fma_f32 v[34:35], v[28:29], v[36:37], v[40:41]
	v_pk_fma_f32 v[28:29], v[26:27], v[50:51], v[54:55]
	v_cvt_pk_bf16_f32 v26, v30, v31
	v_cvt_pk_bf16_f32 v27, v32, v33
	v_cvt_pk_bf16_f32 v28, v28, v29
	v_cvt_pk_bf16_f32 v29, v34, v35
	global_store_dwordx4 v[42:43], v[26:29], off
	global_load_dwordx4 v[26:29], v[46:47], off offset:256
	s_nop 0
	global_load_dwordx4 v[30:33], v[44:45], off offset:256
	v_add_u32_e32 v34, 0xb0, v146
	v_ashrrev_i32_e32 v35, 31, v34
	v_mad_i64_i32 v[36:37], s[0:1], v34, s95, v[148:149]
	v_lshl_add_u64 v[36:37], v[36:37], 0, v[150:151]
	v_add_co_u32_e32 v38, vcc, s19, v36
	s_waitcnt vmcnt(1)
	v_lshlrev_b32_e32 v40, 16, v26
	v_and_b32_e32 v41, 0xffff0000, v26
	s_waitcnt vmcnt(0)
	v_lshlrev_b32_e32 v46, 16, v30
	v_and_b32_e32 v47, 0xffff0000, v30
	v_lshlrev_b32_e32 v26, 16, v27
	v_and_b32_e32 v27, 0xffff0000, v27
	v_lshlrev_b32_e32 v44, 16, v28
	v_and_b32_e32 v45, 0xffff0000, v28
	v_lshlrev_b32_e32 v28, 16, v29
	v_and_b32_e32 v29, 0xffff0000, v29
	v_lshlrev_b32_e32 v30, 16, v31
	v_and_b32_e32 v31, 0xffff0000, v31
	v_lshlrev_b32_e32 v48, 16, v32
	v_and_b32_e32 v49, 0xffff0000, v32
	v_lshlrev_b32_e32 v32, 16, v33
	v_and_b32_e32 v33, 0xffff0000, v33
	v_pk_fma_f32 v[22:23], v[22:23], v[40:41], v[46:47]
	v_pk_fma_f32 v[24:25], v[24:25], v[26:27], v[30:31]
	v_pk_fma_f32 v[26:27], v[20:21], v[28:29], v[32:33]
	v_pk_fma_f32 v[20:21], v[18:19], v[44:45], v[48:49]
	v_cvt_pk_bf16_f32 v18, v22, v23
	v_lshlrev_b64 v[22:23], 11, v[34:35]
	v_lshl_add_u64 v[22:23], v[22:23], 0, v[144:145]
	v_cvt_pk_bf16_f32 v19, v24, v25
	v_cvt_pk_bf16_f32 v20, v20, v21
	v_cvt_pk_bf16_f32 v21, v26, v27
	v_lshlrev_b64 v[26:27], 1, v[22:23]
	v_addc_co_u32_e32 v39, vcc, 0, v37, vcc
	global_store_dwordx4 v[42:43], v[18:21], off offset:256
	v_lshl_add_u64 v[28:29], s[10:11], 0, v[26:27]
	global_load_dwordx4 v[18:21], v[38:39], off offset:1024
	global_load_dwordx4 v[22:25], v[28:29], off
	v_lshl_add_u64 v[30:31], v[36:37], 0, s[2:3]
	v_lshl_add_u64 v[26:27], s[14:15], 0, v[26:27]
	s_andn2_b64 vcc, exec, s[42:43]
	s_mov_b64 s[42:43], -1
	s_waitcnt vmcnt(1)
	v_lshlrev_b32_e32 v32, 16, v18
	v_and_b32_e32 v33, 0xffff0000, v18
	v_lshlrev_b32_e32 v18, 16, v19
	v_and_b32_e32 v19, 0xffff0000, v19
	v_lshlrev_b32_e32 v34, 16, v20
	v_and_b32_e32 v35, 0xffff0000, v20
	v_lshlrev_b32_e32 v20, 16, v21
	v_and_b32_e32 v21, 0xffff0000, v21
	s_waitcnt vmcnt(0)
	v_lshlrev_b32_e32 v36, 16, v22
	v_and_b32_e32 v37, 0xffff0000, v22
	v_lshlrev_b32_e32 v22, 16, v23
	v_and_b32_e32 v23, 0xffff0000, v23
	v_lshlrev_b32_e32 v38, 16, v24
	v_and_b32_e32 v39, 0xffff0000, v24
	v_lshlrev_b32_e32 v24, 16, v25
	v_and_b32_e32 v25, 0xffff0000, v25
	v_pk_fma_f32 v[16:17], v[16:17], v[18:19], v[22:23]
	v_pk_fma_f32 v[14:15], v[14:15], v[32:33], v[36:37]
	v_pk_fma_f32 v[18:19], v[12:13], v[20:21], v[24:25]
	v_pk_fma_f32 v[12:13], v[10:11], v[34:35], v[38:39]
	v_cvt_pk_bf16_f32 v10, v14, v15
	v_cvt_pk_bf16_f32 v11, v16, v17
	v_cvt_pk_bf16_f32 v12, v12, v13
	v_cvt_pk_bf16_f32 v13, v18, v19
	global_store_dwordx4 v[26:27], v[10:13], off
	global_load_dwordx4 v[10:13], v[30:31], off offset:256
	s_nop 0
	global_load_dwordx4 v[14:17], v[28:29], off offset:256
	s_waitcnt vmcnt(1)
	v_lshlrev_b32_e32 v18, 16, v10
	v_and_b32_e32 v19, 0xffff0000, v10
	v_lshlrev_b32_e32 v10, 16, v11
	v_and_b32_e32 v11, 0xffff0000, v11
	v_lshlrev_b32_e32 v20, 16, v12
	v_and_b32_e32 v21, 0xffff0000, v12
	v_lshlrev_b32_e32 v12, 16, v13
	v_and_b32_e32 v13, 0xffff0000, v13
	s_waitcnt vmcnt(0)
	v_lshlrev_b32_e32 v22, 16, v14
	v_and_b32_e32 v23, 0xffff0000, v14
	v_lshlrev_b32_e32 v14, 16, v15
	v_and_b32_e32 v15, 0xffff0000, v15
	v_lshlrev_b32_e32 v24, 16, v16
	v_and_b32_e32 v25, 0xffff0000, v16
	v_lshlrev_b32_e32 v16, 16, v17
	v_and_b32_e32 v17, 0xffff0000, v17
	v_pk_fma_f32 v[8:9], v[8:9], v[10:11], v[14:15]
	v_pk_fma_f32 v[6:7], v[6:7], v[18:19], v[22:23]
	v_pk_fma_f32 v[10:11], v[4:5], v[12:13], v[16:17]
	v_pk_fma_f32 v[4:5], v[2:3], v[20:21], v[24:25]
	v_cvt_pk_bf16_f32 v2, v6, v7
	v_cvt_pk_bf16_f32 v3, v8, v9
	v_cvt_pk_bf16_f32 v4, v4, v5
	v_cvt_pk_bf16_f32 v5, v10, v11
	global_store_dwordx4 v[26:27], v[2:5], off offset:256
	s_cbranch_vccnz .LBB0_1148
	s_andn2_b64 vcc, exec, s[12:13]
	s_cbranch_vccnz .LBB0_1147
	s_branch .LBB0_1147

; #define PG8_WAIT_V(n) asm volatile("s_waitcnt vmcnt(" #n ")" ::: "memory")
; #define PG8_BAR __builtin_amdgcn_s_barrier()
; template <class Epi, class Sched, bool ALIGN_EPI = false, bool SP2 = false>
; __device__ __forceinline__ void gemm_phase(PG8_LAS unsigned char* lds, const Gemm g, const Sched& S, const Epi& E) {
;     ...
;     const int tid = tid_l, wid = __builtin_amdgcn_readfirstlane(tid >> 6), lane = tid & 63, wr = wid >> 2, wc = wid & 3, fr = lane & 15, fq = lane >> 4;
;     const int K = g.K;
;     unsigned voffA[2], voffB[2];
; #pragma unroll
;     for (int i = 0; i < 2; ++i) { int R, C; stage_rc(tid * 16 + i * 8192, R, C); const int Rb = Epi::PERM ? ((R & ~31) + perm32(R & 31)) : R;
;         voffA[i] = (unsigned)(R * K + C) * 2u; voffB[i] = (unsigned)(Rb * K + C) * 2u; }
;     const size_t kstep = (size_t)(BK * 2);
;     const size_t hstep = (size_t)HALF * K * 2;
;     const size_t tstep = 2 * hstep;
;     const unsigned ldsw = (unsigned)wid * 1024u;
;     const int aoff = lds_byte(wr * 64 + fr, fq * 8), boff = lds_byte(wc * 32 + fr, fq * 8);
;     ...
;     Unit cur, nxt; int ui = 0;
;     if (!S.next(0, cur)) return;
;     f32x4 acc[2][2][4][2];
; #pragma unroll
;     for (int a = 0; a < 2; ++a)
; #pragma unroll
;         for (int b = 0; b < 2; ++b)
; #pragma unroll
;             for (int m = 0; m < 4; ++m)
; #pragma unroll
;                 for (int n = 0; n < 2; ++n) acc[a][b][m][n] = (f32x4){0.f, 0.f, 0.f, 0.f};
;     bf16x8 At[4][2], B0[2][2], B1[2][2];
;     const char* cA = (const char*)g.A + (size_t)cur.pm * tstep + (size_t)cur.kt0 * kstep; const char* cB = (const char*)g.Bt + (size_t)cur.pn * tstep + (size_t)cur.kt0 * kstep;
;     S.a_ready(cur);
;     ...
;     { const int rot0 = cur.krot, nt0 = cur.nkt; const char* sA0 = PG8_KP(cA, 0, rot0, nt0); const char* sA1 = PG8_KP(cA, 1, rot0, nt0); const char* sB0 = PG8_KP(cB, 0, rot0, nt0); const char* sB1 = PG8_KP(cB, 1, rot0, nt0);
;     if constexpr (SP2) {
;         PG8_STAGEB(PG8_SB(0, 0), sB0, voffB); PG8_STAGEB(PG8_SB(0, 1), sB0 + hstep, voffB); PG8_STAGE(PG8_SA(0, 0), sA0, voffA); PG8_STAGE(PG8_SA(0, 1), sA0 + hstep, voffA);
;         if (wr == 1) PG8_BAR;
;         PG8_WAIT_V(2); PG8_BAR;
;         PG8_STAGEB(PG8_SB(1, 0), sB1, voffB); PG8_STAGE(PG8_SA(1, 0), sA1, voffA); PG8_STAGEB(PG8_SB(1, 1), sB1 + hstep, voffB);
;         PG8_WAIT_V(6); PG8_BAR;
;     } else {
.LBB0_1290:
	v_readlane_b32 s0, v252, 26
	v_readlane_b32 s1, v252, 27
	s_andn2_b64 vcc, exec, s[4:5]
	s_nop 0
	v_cndmask_b32_e64 v1, 0, 1, s[0:1]
	v_cmp_ne_u32_e64 s[0:1], 1, v1
	s_nop 1
	v_writelane_b32 v254, s0, 58
	s_nop 1
	v_writelane_b32 v254, s1, 59
	s_cbranch_vccnz .LBB0_1377
	v_readlane_b32 s0, v254, 58
	s_mov_b64 s[8:9], s[66:67]
	v_mov_b32_e32 v16, v0
	v_readlane_b32 s1, v254, 59
	s_and_b64 vcc, exec, s[0:1]
	v_readfirstlane_b32 s10, v16
	s_cbranch_vccnz .LBB0_1323
	v_lshlrev_b32_e32 v1, 4, v16
	v_add_u32_e32 v2, 0x2000, v1
	v_ashrrev_i32_e32 v3, 31, v2
	v_lshrrev_b32_e32 v3, 22, v3
	v_add_u32_e32 v3, v2, v3
	v_ashrrev_i32_e32 v10, 10, v3
	v_mul_i32_i24_e32 v3, 0x400, v10
	v_sub_u32_e32 v2, v2, v3
	v_lshrrev_b32_e32 v3, 4, v2
	v_bitop3_b32 v2, v3, v2, 32 bitop3:0x6c
	v_ashrrev_i32_e32 v3, 31, v2
	v_lshrrev_b32_e32 v3, 26, v3
	v_add_u32_e32 v3, v2, v3
	v_lshlrev_b32_e32 v4, 3, v10
	v_ashrrev_i32_e32 v11, 6, v3
	v_and_b32_e32 v4, -16, v4
	v_add_u32_e32 v4, v11, v4
	v_and_b32_e32 v5, 3, v11
	s_mov_b32 s2, 0xfffe0
	v_lshrrev_b32_e32 v6, 2, v4
	v_lshlrev_b32_e32 v7, 1, v4
	v_and_b32_e32 v3, 0xc0, v3
	v_and_or_b32 v5, v4, s2, v5
	v_and_b32_e32 v6, 4, v6
	v_and_b32_e32 v7, 24, v7
	v_sub_u32_e32 v2, v2, v3
	v_or3_b32 v5, v5, v6, v7
	v_lshlrev_b32_e32 v6, 5, v10
	v_ashrrev_i16_sdwa v2, v207, sext(v2) dst_sel:DWORD dst_unused:UNUSED_PAD src0_sel:DWORD src1_sel:BYTE_0
	v_and_b32_e32 v6, 32, v6
	v_bfe_i32 v12, v2, 0, 16
	v_add_lshl_u32 v2, v6, v12, 1
	v_lshl_add_u32 v152, v5, 12, v2
	v_lshl_add_u32 v154, v4, 12, v2
	v_bfe_i32 v2, v16, 27, 1
	v_lshrrev_b32_e32 v2, 22, v2
	v_readlane_b32 s64, v254, 53
	v_add_u32_e32 v2, v1, v2
	v_readlane_b32 s65, v254, 54
	v_and_b32_e32 v2, 0xfffffc00, v2
	s_mov_b32 s65, s79
	v_sub_u32_e32 v1, v1, v2
	s_lshl_b64 s[0:1], s[64:65], 23
	v_lshrrev_b32_e32 v2, 4, v1
	v_ashrrev_i32_e32 v3, 31, v16
	s_add_u32 s30, s8, 0x2d180000
	v_bitop3_b32 v1, v2, v1, 32 bitop3:0x6c
	v_lshrrev_b32_e32 v3, 26, v3
	s_addc_u32 s31, s9, 0
	v_ashrrev_i32_e32 v2, 31, v1
	v_add_u32_e32 v3, v16, v3
	s_add_u32 s0, s8, s0
	v_lshrrev_b32_e32 v2, 26, v2
	v_ashrrev_i32_e32 v14, 6, v3
	s_addc_u32 s1, s9, s1
	v_add_u32_e32 v2, v1, v2
	v_lshlrev_b32_e32 v3, 3, v14
	s_add_u32 s33, s0, 0xa000000
	v_ashrrev_i32_e32 v13, 6, v2
	v_and_b32_e32 v3, -16, v3
	s_addc_u32 s48, s1, 0
	s_ashr_i32 s0, s10, 6
	v_add_u32_e32 v3, v13, v3
	v_and_b32_e32 v4, 3, v13
	s_ashr_i32 s1, s10, 8
	s_lshl_b32 s49, s0, 10
	v_and_or_b32 v4, v3, s2, v4
	v_readlane_b32 s2, v252, 58
	s_add_u32 s2, s30, s2
	v_lshrrev_b32_e32 v5, 2, v3
	v_lshlrev_b32_e32 v6, 1, v3
	v_and_b32_e32 v2, 0xc0, v2
	s_addc_u32 s4, s31, 0
	v_readlane_b32 s3, v252, 60
	v_and_b32_e32 v5, 4, v5
	v_and_b32_e32 v6, 24, v6
	v_sub_u32_e32 v1, v1, v2
	s_add_u32 s5, s33, s3
	v_or3_b32 v4, v4, v5, v6
	v_lshlrev_b32_e32 v5, 5, v14
	v_ashrrev_i16_sdwa v1, v207, sext(v1) dst_sel:DWORD dst_unused:UNUSED_PAD src0_sel:DWORD src1_sel:BYTE_0
	s_addc_u32 s6, s48, 0
	v_readlane_b32 s3, v252, 41
	v_and_b32_e32 v5, 32, v5
	v_bfe_i32 v15, v1, 0, 16
	s_add_u32 s34, s5, s3
	v_add_lshl_u32 v1, v5, v15, 1
	s_addc_u32 s35, s6, 0
	s_add_i32 s50, s49, 0
	v_lshl_add_u32 v156, v4, 12, v1
	s_add_i32 m0, s50, 0x10000
	v_lshl_add_u32 v158, v3, 12, v1
	global_load_lds_dwordx4 v156, s[34:35]
	s_add_i32 m0, s50, 0x12000
	s_add_u32 s40, s2, s3
	s_addc_u32 s41, s4, 0
	s_add_u32 s4, s34, 0x80000
	global_load_lds_dwordx4 v152, s[34:35]
	s_addc_u32 s5, s35, 0
	s_add_i32 m0, s50, 0x14000
	s_add_i32 s51, s50, 0x2000
	global_load_lds_dwordx4 v156, s[4:5]
	s_add_i32 m0, s50, 0x16000
	v_mov_b32_e32 v157, v98
	global_load_lds_dwordx4 v152, s[4:5]
	s_mov_b32 m0, s50
	s_add_u32 s4, s40, 0x80000
	global_load_lds_dwordx4 v158, s[40:41]
	s_mov_b32 m0, s51
	s_addc_u32 s5, s41, 0
	s_add_i32 s52, s50, 0x4000
	global_load_lds_dwordx4 v154, s[40:41]
	s_mov_b32 m0, s52
	s_add_i32 s53, s50, 0x6000
	global_load_lds_dwordx4 v158, s[4:5]
	s_mov_b32 m0, s53
	v_mov_b32_e32 v153, v98
	global_load_lds_dwordx4 v154, s[4:5]
	v_mov_b32_e32 v159, v98
	v_mov_b32_e32 v155, v98
	s_cmp_eq_u32 s1, 1
	v_lshl_add_u64 v[8:9], s[34:35], 0, v[156:157]
	v_lshl_add_u64 v[6:7], s[34:35], 0, v[152:153]
	v_lshl_add_u64 v[2:3], s[40:41], 0, v[158:159]
	s_cselect_b64 s[4:5], -1, 0
	s_cmp_lg_u32 s1, 1
	v_lshl_add_u64 v[4:5], s[40:41], 0, v[154:155]
	s_cbranch_scc1 .LBB0_1294
.LBB0_1294:
	s_add_u32 s6, s8, 0x39880000
	s_mul_i32 s11, s64, 0xf0000
	s_addc_u32 s7, s9, 0
	s_mul_hi_u32 s2, s64, 0xf0000
	s_add_u32 s11, s8, s11
	s_addc_u32 s2, s9, s2
	s_add_u32 s54, s11, 0x104000
	s_addc_u32 s55, s2, 0
	s_add_u32 s56, s8, 0x35880000
	v_lshrrev_b32_e32 v17, 1, v16
	s_addc_u32 s57, s9, 0
	v_and_b32_e32 v17, 24, v17
	s_lshl_b32 s0, s0, 5
	v_and_b32_e32 v1, 15, v16
	v_lshlrev_b32_e32 v18, 1, v17
	v_lshlrev_b32_e32 v16, 2, v16
	s_and_b32 s2, s0, 0x60
	s_add_i32 m0, s50, 0x18000
	v_lshl_add_u64 v[8:9], v[8:9], 0, s[76:77]
	s_lshl_b32 s58, s1, 6
	v_lshl_or_b32 v18, v1, 6, v18
	s_lshl_b32 s1, s1, 13
	v_and_b32_e32 v16, 32, v16
	s_lshl_b32 s0, s2, 7
	s_waitcnt vmcnt(2)
	s_barrier
	global_load_lds_dwordx4 v[8:9], off
	v_lshl_add_u64 v[6:7], v[6:7], 0, s[76:77]
	s_add_i32 m0, s50, 0x1a000
	s_add_i32 s59, s50, 0x8000
	s_add_i32 s60, s50, 0xa000
	v_bitop3_b32 v99, v18, s0, v16 bitop3:0xde
	global_load_lds_dwordx4 v[6:7], off
	v_lshl_add_u64 v[2:3], v[2:3], 0, s[76:77]
	s_mov_b32 m0, s59
	s_add_u32 s0, s34, 0x80080
	v_bitop3_b32 v19, v18, s1, v16 bitop3:0xde
	global_load_lds_dwordx4 v[2:3], off
	v_lshl_add_u64 v[2:3], v[4:5], 0, s[76:77]
	s_mov_b32 m0, s60
	s_addc_u32 s1, s35, 0
	global_load_lds_dwordx4 v[2:3], off
	s_add_i32 m0, s50, 0x1c000
	v_lshl_add_u64 v[2:3], s[0:1], 0, v[156:157]
	global_load_lds_dwordx4 v[2:3], off
	v_lshl_add_u64 v[2:3], s[0:1], 0, v[152:153]
	s_add_i32 m0, s50, 0x1e000
	s_cmpk_lt_u32 s10, 0x100
	global_load_lds_dwordx4 v[2:3], off
	v_lshlrev_b32_e32 v2, 15, v10
	v_and_b32_e32 v2, 0xffff0000, v2
	v_lshl_add_u32 v2, v11, 12, v2
	v_and_b32_e32 v3, 1, v10
	v_lshl_or_b32 v2, v3, 6, v2
	v_lshl_add_u32 v160, v12, 1, v2
	v_lshlrev_b32_e32 v2, 15, v14
	v_and_b32_e32 v2, 0xffff0000, v2
	s_waitcnt vmcnt(6)
	v_lshl_add_u32 v2, v13, 12, v2
	v_and_b32_e32 v3, 1, v14
	v_lshl_or_b32 v2, v3, 6, v2
	v_readlane_b32 s0, v252, 45
	s_cselect_b64 s[8:9], -1, 0
	v_or_b32_e32 v180, s2, v17
	v_mov_b32_e32 v161, v98
	v_lshl_add_u32 v162, v15, 1, v2
	v_mov_b32_e32 v163, v98
	s_mov_b32 s61, 0
	v_add_u32_e32 v181, 0, v19
	s_mov_b32 s78, s0
	v_readlane_b32 s71, v252, 46
	v_readlane_b32 s70, v252, 59
	v_readlane_b32 s69, v252, 57
	s_mov_b32 s3, 0x20000
	s_mov_b32 s46, 0x30000
	s_barrier
	s_branch .LBB0_1297

; #define PG8_STAGE(bufoff, gbase, voff) do { _Pragma("unroll") for (int _i = 0; _i < 2; ++_i) \
;         __builtin_amdgcn_global_load_lds((const unsigned*)((const char*)(gbase) + (voff)[_i]), (PG8_LAS unsigned*)(lds + (bufoff) + ldsw + _i * 8192), 16, 0, AUX_A); } while (0)
; #define PG8_STAGEB(bufoff, gbase, voff) do { _Pragma("unroll") for (int _i = 0; _i < 2; ++_i) \
;         __builtin_amdgcn_global_load_lds((const unsigned*)((const char*)(gbase) + (voff)[_i]), (PG8_LAS unsigned*)(lds + (bufoff) + ldsw + _i * 8192), 16, 0, AUX_B); } while (0)
; #define PG8_WAIT_V(n) asm volatile("s_waitcnt vmcnt(" #n ")" ::: "memory")
; #define PG8_WAIT_L(n) asm volatile("s_waitcnt lgkmcnt(" #n ")" ::: "memory")
; template <class Epi, class Sched, bool ALIGN_EPI = false, bool SP2 = false>
; __device__ __forceinline__ void gemm_phase(PG8_LAS unsigned char* lds, const Gemm g, const Sched& S, const Epi& E) {
;     ...
;         for (int t = 0; t < nt; t += 2) {
;             const bool last = (t == nt - 2);
;             const char* a1 = PG8_KP(cA, t + 1, rot, nt);
;             const char* a2 = last ? nAr : PG8_KP(cA, t + 2, rot, nt); const char* b2 = last ? nBr : PG8_KP(cB, t + 2, rot, nt);
;             const char* a3 = a2 + kstep; const char* b3 = b2 + kstep;
;             if (last && has_next) S.a_ready(nxt);
;             if constexpr (SP2) {
;             PG8_LDB(B0, 0, 0); PG8_LDB(B1, 0, 1); PG8_SCHED; PG8_LDA(At, 0, 0); PG8_STAGE(PG8_SA(1, 1), a1 + hstep, voffA);
;             PG8_WAIT_V(8); PG8_WAIT_L(0); PG8_BAR; PG8_MMA(0, 0, At, B0); PG8_MMA(0, 1, At, B1); PG8_BAR; PG8_SCHED;
;             PG8_LDA(At, 0, 1); PG8_STAGEB(PG8_SB(0, 0), b2, voffB); PG8_STAGEB(PG8_SB(0, 1), b2 + hstep, voffB); PG8_STAGE(PG8_SA(0, 0), a2, voffA);
;             PG8_WAIT_V(8); PG8_WAIT_L(0); PG8_BAR; PG8_MMA(1, 0, At, B0); PG8_MMA(1, 1, At, B1); PG8_BAR; PG8_SCHED;
;             PG8_LDB(B0, 1, 0); PG8_LDB(B1, 1, 1); PG8_SCHED; PG8_LDA(At, 1, 0); PG8_STAGE(PG8_SA(0, 1), a2 + hstep, voffA);
;             PG8_WAIT_V(8); PG8_WAIT_L(0); PG8_BAR; PG8_MMA(0, 0, At, B0); PG8_MMA(0, 1, At, B1); PG8_BAR; PG8_SCHED;
;             PG8_LDA(At, 1, 1); PG8_STAGEB(PG8_SB(1, 0), b3, voffB); PG8_STAGEB(PG8_SB(1, 1), b3 + hstep, voffB); PG8_STAGE(PG8_SA(1, 0), a3, voffA);
;             PG8_WAIT_V(8); PG8_WAIT_L(0); PG8_BAR; PG8_MMA(1, 0, At, B0); PG8_MMA(1, 1, At, B1); PG8_BAR; PG8_SCHED;
.LBB0_1308:
	s_or_b32 s0, s11, 1
	s_cmp_ge_i32 s0, s71
	s_cselect_b32 s2, s71, 0
	s_add_i32 s11, s11, 2
	s_cmp_ge_i32 s11, s71
	s_cselect_b32 s0, s71, 0
	s_sub_i32 s0, s13, s0
	s_ashr_i32 s1, s0, 31
	s_lshl_b64 s[0:1], s[0:1], 7
	s_add_u32 s15, s40, s0
	s_addc_u32 s29, s41, s1
	s_add_u32 s0, s34, s0
	s_addc_u32 s1, s35, s1
	s_cmp_eq_u32 s71, s13
	s_cselect_b32 s45, s43, s29
	s_cselect_b32 s44, s42, s15
	s_cselect_b32 s37, s19, s1
	s_cselect_b32 s36, s18, s0
	s_add_i32 s15, 0, 0x10000
	s_add_i32 s29, 0, 0x14000
	v_add_u32_e32 v148, s15, v99
	v_add_u32_e32 v168, s29, v99
	ds_read_b128 v[136:139], v148
	ds_read_b128 v[140:143], v148 offset:1024
	ds_read_b128 v[144:147], v148 offset:2048
	ds_read_b128 v[148:151], v148 offset:3072
	ds_read_b128 v[164:167], v168
	ds_read_b128 v[182:185], v168 offset:1024
	ds_read_b128 v[186:189], v168 offset:2048
	ds_read_b128 v[190:193], v168 offset:3072
	v_mad_i64_i32 v[168:169], s[0:1], s2, v220, v[134:135]
	s_add_i32 m0, s50, 0xc000
	ds_read_b128 v[194:197], v181
	ds_read_b128 v[198:201], v181 offset:1024
	ds_read_b128 v[222:225], v181 offset:2048
	ds_read_b128 v[226:229], v181 offset:3072
	ds_read_b128 v[230:233], v181 offset:4096
	ds_read_b128 v[234:237], v181 offset:5120
	ds_read_b128 v[238:241], v181 offset:6144
	ds_read_b128 v[242:245], v181 offset:7168
	global_load_lds_dwordx4 v[168:169], off
	v_mad_i64_i32 v[168:169], s[0:1], s2, v220, v[132:133]
	s_add_i32 m0, s50, 0xe000
	s_nop 0
	global_load_lds_dwordx4 v[168:169], off
	s_waitcnt vmcnt(8)
	s_waitcnt lgkmcnt(0)
	s_cmp_lg_u64 s[8:9], 0
	s_cbranch_scc1 .Lhb_33
	s_barrier
.Lhb_33:
	s_setprio 1
	s_waitcnt lgkmcnt(0)
	v_mfma_f32_16x16x32_bf16 v[128:131], v[136:139], v[194:197], v[128:131]
	v_mfma_f32_16x16x32_bf16 v[124:127], v[144:147], v[194:197], v[124:127]
	v_mfma_f32_16x16x32_bf16 v[120:123], v[136:139], v[222:225], v[120:123]
	v_mfma_f32_16x16x32_bf16 v[112:115], v[144:147], v[222:225], v[112:115]
	v_mfma_f32_16x16x32_bf16 v[104:107], v[136:139], v[230:233], v[104:107]
	v_mfma_f32_16x16x32_bf16 v[94:97], v[144:147], v[230:233], v[94:97]
	v_mfma_f32_16x16x32_bf16 v[86:89], v[136:139], v[238:241], v[86:89]
	v_mfma_f32_16x16x32_bf16 v[78:81], v[144:147], v[238:241], v[78:81]
	s_setprio 2
	v_mfma_f32_16x16x32_bf16 v[128:131], v[140:143], v[198:201], v[128:131]
	v_mfma_f32_16x16x32_bf16 v[124:127], v[148:151], v[198:201], v[124:127]
	v_mfma_f32_16x16x32_bf16 v[120:123], v[140:143], v[226:229], v[120:123]
	v_mfma_f32_16x16x32_bf16 v[112:115], v[148:151], v[226:229], v[112:115]
	v_mfma_f32_16x16x32_bf16 v[104:107], v[140:143], v[234:237], v[104:107]
	v_mfma_f32_16x16x32_bf16 v[94:97], v[148:151], v[234:237], v[94:97]
	v_mfma_f32_16x16x32_bf16 v[86:89], v[140:143], v[242:245], v[86:89]
	v_mfma_f32_16x16x32_bf16 v[78:81], v[148:151], v[242:245], v[78:81]
	v_mfma_f32_16x16x32_bf16 v[116:119], v[164:167], v[194:197], v[116:119]
	v_mfma_f32_16x16x32_bf16 v[108:111], v[186:189], v[194:197], v[108:111]
	v_mfma_f32_16x16x32_bf16 v[100:103], v[164:167], v[222:225], v[100:103]
	v_mfma_f32_16x16x32_bf16 v[90:93], v[186:189], v[222:225], v[90:93]
	s_setprio 3
	v_mfma_f32_16x16x32_bf16 v[82:85], v[164:167], v[230:233], v[82:85]
	v_mfma_f32_16x16x32_bf16 v[74:77], v[186:189], v[230:233], v[74:77]
	v_mfma_f32_16x16x32_bf16 v[70:73], v[164:167], v[238:241], v[70:73]
	v_mfma_f32_16x16x32_bf16 v[66:69], v[186:189], v[238:241], v[66:69]
	v_mfma_f32_16x16x32_bf16 v[116:119], v[182:185], v[198:201], v[116:119]
	v_mfma_f32_16x16x32_bf16 v[108:111], v[190:193], v[198:201], v[108:111]
	v_mfma_f32_16x16x32_bf16 v[100:103], v[182:185], v[226:229], v[100:103]
	v_mfma_f32_16x16x32_bf16 v[90:93], v[190:193], v[226:229], v[90:93]
	v_mfma_f32_16x16x32_bf16 v[82:85], v[182:185], v[234:237], v[82:85]
	v_mfma_f32_16x16x32_bf16 v[74:77], v[190:193], v[234:237], v[74:77]
	v_mfma_f32_16x16x32_bf16 v[70:73], v[182:185], v[242:245], v[70:73]
	v_mfma_f32_16x16x32_bf16 v[66:69], v[190:193], v[242:245], v[66:69]
	s_setprio 0
	s_cmp_eq_u64 s[8:9], 0
	s_cbranch_scc1 .Lhb_37
	s_barrier
; #define PG8_STAGE(bufoff, gbase, voff) do { _Pragma("unroll") for (int _i = 0; _i < 2; ++_i) \
;         __builtin_amdgcn_global_load_lds((const unsigned*)((const char*)(gbase) + (voff)[_i]), (PG8_LAS unsigned*)(lds + (bufoff) + ldsw + _i * 8192), 16, 0, AUX_A); } while (0)
; #define PG8_STAGEB(bufoff, gbase, voff) do { _Pragma("unroll") for (int _i = 0; _i < 2; ++_i) \
;         __builtin_amdgcn_global_load_lds((const unsigned*)((const char*)(gbase) + (voff)[_i]), (PG8_LAS unsigned*)(lds + (bufoff) + ldsw + _i * 8192), 16, 0, AUX_B); } while (0)
; #define PG8_WAIT_V(n) asm volatile("s_waitcnt vmcnt(" #n ")" ::: "memory")
; #define PG8_WAIT_L(n) asm volatile("s_waitcnt lgkmcnt(" #n ")" ::: "memory")
; template <class Epi, class Sched, bool ALIGN_EPI = false, bool SP2 = false>
; __device__ __forceinline__ void gemm_phase(PG8_LAS unsigned char* lds, const Gemm g, const Sched& S, const Epi& E) {
;     ...
;         for (int t = 0; t < nt; t += 2) {
;             const bool last = (t == nt - 2);
;             const char* a1 = PG8_KP(cA, t + 1, rot, nt);
;             const char* a2 = last ? nAr : PG8_KP(cA, t + 2, rot, nt); const char* b2 = last ? nBr : PG8_KP(cB, t + 2, rot, nt);
;             const char* a3 = a2 + kstep; const char* b3 = b2 + kstep;
;             if (last && has_next) S.a_ready(nxt);
;             if constexpr (SP2) {
;             PG8_LDB(B0, 0, 0); PG8_LDB(B1, 0, 1); PG8_SCHED; PG8_LDA(At, 0, 0); PG8_STAGE(PG8_SA(1, 1), a1 + hstep, voffA);
;             PG8_WAIT_V(8); PG8_WAIT_L(0); PG8_BAR; PG8_MMA(0, 0, At, B0); PG8_MMA(0, 1, At, B1); PG8_BAR; PG8_SCHED;
;             PG8_LDA(At, 0, 1); PG8_STAGEB(PG8_SB(0, 0), b2, voffB); PG8_STAGEB(PG8_SB(0, 1), b2 + hstep, voffB); PG8_STAGE(PG8_SA(0, 0), a2, voffA);
;             PG8_WAIT_V(8); PG8_WAIT_L(0); PG8_BAR; PG8_MMA(1, 0, At, B0); PG8_MMA(1, 1, At, B1); PG8_BAR; PG8_SCHED;
;             PG8_LDB(B0, 1, 0); PG8_LDB(B1, 1, 1); PG8_SCHED; PG8_LDA(At, 1, 0); PG8_STAGE(PG8_SA(0, 1), a2 + hstep, voffA);
;             PG8_WAIT_V(8); PG8_WAIT_L(0); PG8_BAR; PG8_MMA(0, 0, At, B0); PG8_MMA(0, 1, At, B1); PG8_BAR; PG8_SCHED;
;             PG8_LDA(At, 1, 1); PG8_STAGEB(PG8_SB(1, 0), b3, voffB); PG8_STAGEB(PG8_SB(1, 1), b3 + hstep, voffB); PG8_STAGE(PG8_SA(1, 0), a3, voffA);
;             PG8_WAIT_V(8); PG8_WAIT_L(0); PG8_BAR; PG8_MMA(1, 0, At, B0); PG8_MMA(1, 1, At, B1); PG8_BAR; PG8_SCHED;
.Lhb_37:
	s_add_i32 s0, s15, s49
	v_lshl_add_u64 v[168:169], s[36:37], 0, v[156:157]
	s_mov_b32 m0, s0
	ds_read_b128 v[194:197], v181 offset:16384
	ds_read_b128 v[198:201], v181 offset:17408
	ds_read_b128 v[222:225], v181 offset:18432
	ds_read_b128 v[226:229], v181 offset:19456
	ds_read_b128 v[230:233], v181 offset:20480
	ds_read_b128 v[234:237], v181 offset:21504
	ds_read_b128 v[238:241], v181 offset:22528
	ds_read_b128 v[242:245], v181 offset:23552
	global_load_lds_dwordx4 v[168:169], off
	s_add_i32 m0, s0, 0x2000
	s_add_u32 s0, s36, 0x80000
	v_lshl_add_u64 v[172:173], s[36:37], 0, v[152:153]
	s_addc_u32 s1, s37, 0
	s_add_i32 s2, s29, s49
	global_load_lds_dwordx4 v[172:173], off
	v_lshl_add_u64 v[202:203], s[0:1], 0, v[156:157]
	s_mov_b32 m0, s2
	v_lshl_add_u64 v[212:213], s[44:45], 0, v[154:155]
	global_load_lds_dwordx4 v[202:203], off
	v_lshl_add_u64 v[202:203], s[0:1], 0, v[152:153]
	s_add_i32 m0, s2, 0x2000
	s_nop 0
	global_load_lds_dwordx4 v[202:203], off
	v_lshl_add_u64 v[202:203], s[44:45], 0, v[158:159]
	s_mov_b32 m0, s50
	s_nop 0
	global_load_lds_dwordx4 v[202:203], off
	s_mov_b32 m0, s51
	s_nop 0
	global_load_lds_dwordx4 v[212:213], off
	s_waitcnt vmcnt(8)
	s_waitcnt lgkmcnt(0)
	s_cmp_lg_u64 s[8:9], 0
	s_cbranch_scc1 .Lhb_34
	s_barrier
.Lhb_34:
	s_setprio 1
	s_waitcnt lgkmcnt(0)
	v_mfma_f32_16x16x32_bf16 v[62:65], v[136:139], v[194:197], v[62:65]
	v_mfma_f32_16x16x32_bf16 v[58:61], v[144:147], v[194:197], v[58:61]
	v_mfma_f32_16x16x32_bf16 v[54:57], v[136:139], v[222:225], v[54:57]
	v_mfma_f32_16x16x32_bf16 v[46:49], v[144:147], v[222:225], v[46:49]
	v_mfma_f32_16x16x32_bf16 v[38:41], v[136:139], v[230:233], v[38:41]
	v_mfma_f32_16x16x32_bf16 v[30:33], v[144:147], v[230:233], v[30:33]
	v_mfma_f32_16x16x32_bf16 v[22:25], v[136:139], v[238:241], v[22:25]
	v_mfma_f32_16x16x32_bf16 v[14:17], v[144:147], v[238:241], v[14:17]
	s_setprio 2
	v_mfma_f32_16x16x32_bf16 v[62:65], v[140:143], v[198:201], v[62:65]
	v_mfma_f32_16x16x32_bf16 v[58:61], v[148:151], v[198:201], v[58:61]
	v_mfma_f32_16x16x32_bf16 v[54:57], v[140:143], v[226:229], v[54:57]
	v_mfma_f32_16x16x32_bf16 v[46:49], v[148:151], v[226:229], v[46:49]
	v_mfma_f32_16x16x32_bf16 v[38:41], v[140:143], v[234:237], v[38:41]
	v_mfma_f32_16x16x32_bf16 v[30:33], v[148:151], v[234:237], v[30:33]
	v_mfma_f32_16x16x32_bf16 v[22:25], v[140:143], v[242:245], v[22:25]
	v_mfma_f32_16x16x32_bf16 v[14:17], v[148:151], v[242:245], v[14:17]
	v_mfma_f32_16x16x32_bf16 v[50:53], v[164:167], v[194:197], v[50:53]
	v_mfma_f32_16x16x32_bf16 v[42:45], v[186:189], v[194:197], v[42:45]
	v_mfma_f32_16x16x32_bf16 v[34:37], v[164:167], v[222:225], v[34:37]
	v_mfma_f32_16x16x32_bf16 v[26:29], v[186:189], v[222:225], v[26:29]
	s_setprio 3
	v_mfma_f32_16x16x32_bf16 v[18:21], v[164:167], v[230:233], v[18:21]
	v_mfma_f32_16x16x32_bf16 v[10:13], v[186:189], v[230:233], v[10:13]
	v_mfma_f32_16x16x32_bf16 v[6:9], v[164:167], v[238:241], v[6:9]
	v_mfma_f32_16x16x32_bf16 v[2:5], v[186:189], v[238:241], v[2:5]
	v_mfma_f32_16x16x32_bf16 v[50:53], v[182:185], v[198:201], v[50:53]
	v_mfma_f32_16x16x32_bf16 v[42:45], v[190:193], v[198:201], v[42:45]
	v_mfma_f32_16x16x32_bf16 v[34:37], v[182:185], v[226:229], v[34:37]
	v_mfma_f32_16x16x32_bf16 v[26:29], v[190:193], v[226:229], v[26:29]
	v_mfma_f32_16x16x32_bf16 v[18:21], v[182:185], v[234:237], v[18:21]
	v_mfma_f32_16x16x32_bf16 v[10:13], v[190:193], v[234:237], v[10:13]
	v_mfma_f32_16x16x32_bf16 v[6:9], v[182:185], v[242:245], v[6:9]
	v_mfma_f32_16x16x32_bf16 v[2:5], v[190:193], v[242:245], v[2:5]
	s_setprio 0
	s_cmp_eq_u64 s[8:9], 0
	s_cbranch_scc1 .Lhb_38
	s_barrier
.Lhb_38:
	s_add_i32 s2, 0, 0x18000
	s_add_i32 s15, 0, 0x1c000
	v_add_u32_e32 v148, s2, v99
	v_add_u32_e32 v190, s15, v99
	ds_read_b128 v[136:139], v148
	ds_read_b128 v[140:143], v148 offset:1024
	ds_read_b128 v[144:147], v148 offset:2048
	ds_read_b128 v[148:151], v148 offset:3072
	ds_read_b128 v[164:167], v190
	ds_read_b128 v[182:185], v190 offset:1024
	ds_read_b128 v[186:189], v190 offset:2048
	ds_read_b128 v[190:193], v190 offset:3072
	s_add_u32 s0, s44, 0x80000
	s_addc_u32 s1, s45, 0
	s_mov_b32 m0, s52
	v_lshl_add_u64 v[246:247], s[0:1], 0, v[158:159]
	ds_read_b128 v[194:197], v181 offset:32768
	ds_read_b128 v[198:201], v181 offset:33792
	ds_read_b128 v[222:225], v181 offset:34816
	ds_read_b128 v[226:229], v181 offset:35840
	ds_read_b128 v[230:233], v181 offset:36864
	ds_read_b128 v[234:237], v181 offset:37888
	ds_read_b128 v[238:241], v181 offset:38912
	ds_read_b128 v[242:245], v181 offset:39936
	global_load_lds_dwordx4 v[246:247], off
	v_lshl_add_u64 v[246:247], s[0:1], 0, v[154:155]
	s_mov_b32 m0, s53
	s_nop 0
	global_load_lds_dwordx4 v[246:247], off
	s_waitcnt vmcnt(8)
	s_waitcnt lgkmcnt(0)
	s_cmp_lg_u64 s[8:9], 0
	s_cbranch_scc1 .Lhb_35
	s_barrier

; #define PG8_STAGE(bufoff, gbase, voff) do { _Pragma("unroll") for (int _i = 0; _i < 2; ++_i) \
;         __builtin_amdgcn_global_load_lds((const unsigned*)((const char*)(gbase) + (voff)[_i]), (PG8_LAS unsigned*)(lds + (bufoff) + ldsw + _i * 8192), 16, 0, AUX_A); } while (0)
; #define PG8_STAGEB(bufoff, gbase, voff) do { _Pragma("unroll") for (int _i = 0; _i < 2; ++_i) \
;         __builtin_amdgcn_global_load_lds((const unsigned*)((const char*)(gbase) + (voff)[_i]), (PG8_LAS unsigned*)(lds + (bufoff) + ldsw + _i * 8192), 16, 0, AUX_B); } while (0)
; #define PG8_LDA(dst, b, h) do { _Pragma("unroll") for (int m = 0; m < 4; ++m) _Pragma("unroll") for (int k = 0; k < 2; ++k) dst[m][k] = *(const PG8_LAS bf16x8*)(lds + PG8_SA(b, h) + aoff + m * 2048 + k * 1024); } while (0)
; #define PG8_LDB(dst, b, h) do { _Pragma("unroll") for (int n = 0; n < 2; ++n) _Pragma("unroll") for (int k = 0; k < 2; ++k) dst[n][k] = *(const PG8_LAS bf16x8*)(lds + PG8_SB(b, h) + boff + n * 2048 + k * 1024); } while (0)
; #define PG8_MMA(ai, bj, At, Bt) do { __builtin_amdgcn_s_setprio(1); _Pragma("unroll") for (int m = 0; m < 4; ++m) _Pragma("unroll") for (int n = 0; n < 2; ++n) _Pragma("unroll") for (int k = 0; k < 2; ++k) \
;         acc[ai][bj][m][n] = __builtin_amdgcn_mfma_f32_16x16x32_bf16(Bt[n][k], At[m][k], acc[ai][bj][m][n], 0, 0, 0); __builtin_amdgcn_s_setprio(0); } while (0)
; #define PG8_WAIT_V(n) asm volatile("s_waitcnt vmcnt(" #n ")" ::: "memory")
; #define PG8_WAIT_L(n) asm volatile("s_waitcnt lgkmcnt(" #n ")" ::: "memory")
; template <class Epi, class Sched, bool ALIGN_EPI = false, bool SP2 = false>
; __device__ __forceinline__ void gemm_phase(PG8_LAS unsigned char* lds, const Gemm g, const Sched& S, const Epi& E) {
;     ...
;             PG8_WAIT_V(8); PG8_WAIT_L(0); PG8_BAR; PG8_MMA(1, 0, At, B0); PG8_MMA(1, 1, At, B1); PG8_BAR; PG8_SCHED;
;             PG8_LDB(B0, 1, 0); PG8_LDB(B1, 1, 1); PG8_SCHED; PG8_LDA(At, 1, 0); PG8_STAGE(PG8_SA(0, 1), a2 + hstep, voffA);
;             PG8_WAIT_V(8); PG8_WAIT_L(0); PG8_BAR; PG8_MMA(0, 0, At, B0); PG8_MMA(0, 1, At, B1); PG8_BAR; PG8_SCHED;
;             PG8_LDA(At, 1, 1); PG8_STAGEB(PG8_SB(1, 0), b3, voffB); PG8_STAGEB(PG8_SB(1, 1), b3 + hstep, voffB); PG8_STAGE(PG8_SA(1, 0), a3, voffA);
;             PG8_WAIT_V(8); PG8_WAIT_L(0); PG8_BAR; PG8_MMA(1, 0, At, B0); PG8_MMA(1, 1, At, B1); PG8_BAR; PG8_SCHED;
.Lhb_39:
	s_add_i32 s0, s2, s49
	v_lshl_add_u64 v[168:169], v[168:169], 0, s[76:77]
	s_mov_b32 m0, s0
	ds_read_b128 v[194:197], v181 offset:49152
	ds_read_b128 v[198:201], v181 offset:50176
	ds_read_b128 v[222:225], v181 offset:51200
	ds_read_b128 v[226:229], v181 offset:52224
	ds_read_b128 v[230:233], v181 offset:53248
	ds_read_b128 v[234:237], v181 offset:54272
	ds_read_b128 v[238:241], v181 offset:55296
	ds_read_b128 v[242:245], v181 offset:56320
	global_load_lds_dwordx4 v[168:169], off
	s_add_i32 m0, s0, 0x2000
	s_add_u32 s0, s36, 0x80080
	v_lshl_add_u64 v[168:169], v[172:173], 0, s[76:77]
	s_addc_u32 s1, s37, 0
	s_add_i32 s2, s15, s49
	global_load_lds_dwordx4 v[168:169], off
	v_lshl_add_u64 v[168:169], s[0:1], 0, v[156:157]
	s_mov_b32 m0, s2
	s_nop 0
	global_load_lds_dwordx4 v[168:169], off
	v_lshl_add_u64 v[168:169], s[0:1], 0, v[152:153]
	s_add_i32 m0, s2, 0x2000
	s_nop 0
	global_load_lds_dwordx4 v[168:169], off
	v_lshl_add_u64 v[168:169], v[202:203], 0, s[76:77]
	s_mov_b32 m0, s59
	s_nop 0
	global_load_lds_dwordx4 v[168:169], off
	v_lshl_add_u64 v[168:169], v[212:213], 0, s[76:77]
	s_mov_b32 m0, s60
	s_nop 0
	global_load_lds_dwordx4 v[168:169], off
	s_waitcnt vmcnt(8)
	s_waitcnt lgkmcnt(0)
	s_cmp_lg_u64 s[8:9], 0
	s_cbranch_scc1 .Lhb_36
	s_barrier

; #define PG8_BAR __builtin_amdgcn_s_barrier()
; template <class Epi, class Sched, bool ALIGN_EPI = false, bool SP2 = false>
; __device__ __forceinline__ void gemm_phase(PG8_LAS unsigned char* lds, const Gemm g, const Sched& S, const Epi& E) {
;     ...
;         for (int t = 0; t < nt; t += 2) {
;             const bool last = (t == nt - 2);
;             const char* a1 = PG8_KP(cA, t + 1, rot, nt);
;             const char* a2 = last ? nAr : PG8_KP(cA, t + 2, rot, nt); const char* b2 = last ? nBr : PG8_KP(cB, t + 2, rot, nt);
;             const char* a3 = a2 + kstep; const char* b3 = b2 + kstep;
;     ...
;         if constexpr (ALIGN_EPI) { if (wr == 0) PG8_BAR; }
.Lhb_40:
	s_add_i32 s0, s13, 2
	v_lshl_add_u64 v[132:133], v[132:133], 0, s[86:87]
	v_lshl_add_u64 v[134:135], v[134:135], 0, s[86:87]
	s_cmp_ge_i32 s13, s71
	s_mov_b32 s13, s0
	s_cbranch_scc0 .LBB0_1308
	s_and_b64 vcc, exec, s[8:9]
	s_cbranch_vccz .LBB0_1311

; #define PG8_BAR __builtin_amdgcn_s_barrier()
; template <class Epi, class Sched, bool ALIGN_EPI = false, bool SP2 = false>
; __device__ __forceinline__ void gemm_phase(PG8_LAS unsigned char* lds, const Gemm g, const Sched& S, const Epi& E) {
;     ...
;         cur = nxt; cA = nA; cB = nB; ++ui;
;         if constexpr (ALIGN_EPI) { if (wr == 1) PG8_BAR; }
.LBB0_1320:
	s_andn2_b64 vcc, exec, s[4:5]
	s_cbranch_vccnz .LBB0_1295
	s_branch .LBB0_1295

; #define PG8_STAGE(bufoff, gbase, voff) do { _Pragma("unroll") for (int _i = 0; _i < 2; ++_i) \
;         __builtin_amdgcn_global_load_lds((const unsigned*)((const char*)(gbase) + (voff)[_i]), (PG8_LAS unsigned*)(lds + (bufoff) + ldsw + _i * 8192), 16, 0, AUX_A); } while (0)
; #define PG8_STAGEB(bufoff, gbase, voff) do { _Pragma("unroll") for (int _i = 0; _i < 2; ++_i) \
;         __builtin_amdgcn_global_load_lds((const unsigned*)((const char*)(gbase) + (voff)[_i]), (PG8_LAS unsigned*)(lds + (bufoff) + ldsw + _i * 8192), 16, 0, AUX_B); } while (0)
; #define PG8_WAIT_V(n) asm volatile("s_waitcnt vmcnt(" #n ")" ::: "memory")
; #define PG8_WAIT_L(n) asm volatile("s_waitcnt lgkmcnt(" #n ")" ::: "memory")
; template <class Epi, class Sched, bool ALIGN_EPI = false, bool SP2 = false>
; __device__ __forceinline__ void gemm_phase(PG8_LAS unsigned char* lds, const Gemm g, const Sched& S, const Epi& E) {
;     ...
;         for (int t = 0; t < nt; t += 2) {
;             const bool last = (t == nt - 2);
;             const char* a1 = PG8_KP(cA, t + 1, rot, nt);
;             const char* a2 = last ? nAr : PG8_KP(cA, t + 2, rot, nt); const char* b2 = last ? nBr : PG8_KP(cB, t + 2, rot, nt);
;             const char* a3 = a2 + kstep; const char* b3 = b2 + kstep;
;             if (last && has_next) S.a_ready(nxt);
;             if constexpr (SP2) {
;             PG8_LDB(B0, 0, 0); PG8_LDB(B1, 0, 1); PG8_SCHED; PG8_LDA(At, 0, 0); PG8_STAGE(PG8_SA(1, 1), a1 + hstep, voffA);
;             PG8_WAIT_V(8); PG8_WAIT_L(0); PG8_BAR; PG8_MMA(0, 0, At, B0); PG8_MMA(0, 1, At, B1); PG8_BAR; PG8_SCHED;
;             PG8_LDA(At, 0, 1); PG8_STAGEB(PG8_SB(0, 0), b2, voffB); PG8_STAGEB(PG8_SB(0, 1), b2 + hstep, voffB); PG8_STAGE(PG8_SA(0, 0), a2, voffA);
;             PG8_WAIT_V(8); PG8_WAIT_L(0); PG8_BAR; PG8_MMA(1, 0, At, B0); PG8_MMA(1, 1, At, B1); PG8_BAR; PG8_SCHED;
;             PG8_LDB(B0, 1, 0); PG8_LDB(B1, 1, 1); PG8_SCHED; PG8_LDA(At, 1, 0); PG8_STAGE(PG8_SA(0, 1), a2 + hstep, voffA);
;             PG8_WAIT_V(8); PG8_WAIT_L(0); PG8_BAR; PG8_MMA(0, 0, At, B0); PG8_MMA(0, 1, At, B1); PG8_BAR; PG8_SCHED;
;             PG8_LDA(At, 1, 1); PG8_STAGEB(PG8_SB(1, 0), b3, voffB); PG8_STAGEB(PG8_SB(1, 1), b3 + hstep, voffB); PG8_STAGE(PG8_SA(1, 0), a3, voffA);
;             PG8_WAIT_V(8); PG8_WAIT_L(0); PG8_BAR; PG8_MMA(1, 0, At, B0); PG8_MMA(1, 1, At, B1); PG8_BAR; PG8_SCHED;
.LBB0_1458:
	s_add_i32 s30, s29, 2
	s_cmp_lt_u32 s29, 30
	s_cselect_b32 s0, 0, 0xffffffe0
	s_add_i32 s0, s30, s0
	s_ashr_i32 s1, s0, 31
	s_lshl_b64 s[0:1], s[0:1], 7
	s_add_u32 s2, s40, s0
	s_addc_u32 s31, s41, s1
	s_add_u32 s0, s34, s0
	s_addc_u32 s1, s35, s1
	s_cmp_eq_u32 s29, 30
	s_cselect_b32 s45, s13, s31
	s_cselect_b32 s44, s15, s2
	s_cselect_b32 s49, s71, s1
	s_cselect_b32 s48, s75, s0
	s_add_i32 s2, 0, 0x10000
	s_add_i32 s78, s2, s56
	s_add_i32 s31, 0, 0x14000
	s_add_i32 m0, s57, 0xc000
	s_add_i32 s47, s57, 0xe000
	s_add_i32 s81, s78, 0x2000
	s_add_u32 s50, s48, 0x80000
	s_addc_u32 s51, s49, 0
	s_add_i32 s82, s31, s56
	v_add_u32_e32 v162, s2, v99
	v_add_u32_e32 v166, s31, v99
	s_add_i32 s83, s82, 0x2000
	s_add_i32 s84, 0, 0x18000
	s_add_i32 s88, 0, 0x1c000
	ds_read_b128 v[150:153], v162
	ds_read_b128 v[154:157], v162 offset:1024
	ds_read_b128 v[158:161], v162 offset:2048
	ds_read_b128 v[162:165], v162 offset:3072
	ds_read_b128 v[180:183], v166
	ds_read_b128 v[184:187], v166 offset:1024
	ds_read_b128 v[188:191], v166 offset:2048
	ds_read_b128 v[192:195], v166 offset:3072
	s_add_u32 s42, s44, 0x80000
	s_addc_u32 s43, s45, 0
	s_add_i32 s1, s84, s56
	s_add_i32 s0, s1, 0x2000
	s_add_u32 s36, s48, 0x80080
	s_addc_u32 s37, s49, 0
	s_add_i32 s46, s88, s56
	s_add_i32 s31, s46, 0x2000
	ds_read_b128 v[196:199], v149
	ds_read_b128 v[200:203], v149 offset:1024
	ds_read_b128 v[222:225], v149 offset:2048
	ds_read_b128 v[226:229], v149 offset:3072
	ds_read_b128 v[230:233], v149 offset:4096
	ds_read_b128 v[234:237], v149 offset:5120
	ds_read_b128 v[238:241], v149 offset:6144
	ds_read_b128 v[242:245], v149 offset:7168
	global_load_lds_dwordx4 v[146:147], off
	s_mov_b32 m0, s47
	s_nop 0
	global_load_lds_dwordx4 v[144:145], off
	s_waitcnt vmcnt(8)
	s_waitcnt lgkmcnt(0)
	s_cmp_lg_u64 s[10:11], 0
	s_cbranch_scc1 .Lhb_41
	s_barrier
.Lhb_41:
	s_setprio 1
	s_waitcnt lgkmcnt(0)
	v_mfma_f32_16x16x32_bf16 v[128:131], v[150:153], v[196:199], v[128:131]
	v_mfma_f32_16x16x32_bf16 v[120:123], v[158:161], v[196:199], v[120:123]
	v_mfma_f32_16x16x32_bf16 v[112:115], v[150:153], v[222:225], v[112:115]
	v_mfma_f32_16x16x32_bf16 v[104:107], v[158:161], v[222:225], v[104:107]
	v_mfma_f32_16x16x32_bf16 v[94:97], v[150:153], v[230:233], v[94:97]
	v_mfma_f32_16x16x32_bf16 v[86:89], v[158:161], v[230:233], v[86:89]
	v_mfma_f32_16x16x32_bf16 v[78:81], v[150:153], v[238:241], v[78:81]
	v_mfma_f32_16x16x32_bf16 v[70:73], v[158:161], v[238:241], v[70:73]
	s_setprio 2
	v_mfma_f32_16x16x32_bf16 v[128:131], v[154:157], v[200:203], v[128:131]
	v_mfma_f32_16x16x32_bf16 v[120:123], v[162:165], v[200:203], v[120:123]
	v_mfma_f32_16x16x32_bf16 v[112:115], v[154:157], v[226:229], v[112:115]
	v_mfma_f32_16x16x32_bf16 v[104:107], v[162:165], v[226:229], v[104:107]
	v_mfma_f32_16x16x32_bf16 v[94:97], v[154:157], v[234:237], v[94:97]
	v_mfma_f32_16x16x32_bf16 v[86:89], v[162:165], v[234:237], v[86:89]
	v_mfma_f32_16x16x32_bf16 v[78:81], v[154:157], v[242:245], v[78:81]
	v_mfma_f32_16x16x32_bf16 v[70:73], v[162:165], v[242:245], v[70:73]
	v_mfma_f32_16x16x32_bf16 v[124:127], v[180:183], v[196:199], v[124:127]
	v_mfma_f32_16x16x32_bf16 v[116:119], v[188:191], v[196:199], v[116:119]
	v_mfma_f32_16x16x32_bf16 v[108:111], v[180:183], v[222:225], v[108:111]
	v_mfma_f32_16x16x32_bf16 v[100:103], v[188:191], v[222:225], v[100:103]
	s_setprio 3
	v_mfma_f32_16x16x32_bf16 v[90:93], v[180:183], v[230:233], v[90:93]
	v_mfma_f32_16x16x32_bf16 v[82:85], v[188:191], v[230:233], v[82:85]
	v_mfma_f32_16x16x32_bf16 v[74:77], v[180:183], v[238:241], v[74:77]
	v_mfma_f32_16x16x32_bf16 v[66:69], v[188:191], v[238:241], v[66:69]
	v_mfma_f32_16x16x32_bf16 v[124:127], v[184:187], v[200:203], v[124:127]
	v_mfma_f32_16x16x32_bf16 v[116:119], v[192:195], v[200:203], v[116:119]
	v_mfma_f32_16x16x32_bf16 v[108:111], v[184:187], v[226:229], v[108:111]
	v_mfma_f32_16x16x32_bf16 v[100:103], v[192:195], v[226:229], v[100:103]
	v_mfma_f32_16x16x32_bf16 v[90:93], v[184:187], v[234:237], v[90:93]
	v_mfma_f32_16x16x32_bf16 v[82:85], v[192:195], v[234:237], v[82:85]
	v_mfma_f32_16x16x32_bf16 v[74:77], v[184:187], v[242:245], v[74:77]
	v_mfma_f32_16x16x32_bf16 v[66:69], v[192:195], v[242:245], v[66:69]
	s_setprio 0
	s_cmp_eq_u64 s[10:11], 0
	s_cbranch_scc1 .Lhb_45
	s_barrier
; #define PG8_STAGE(bufoff, gbase, voff) do { _Pragma("unroll") for (int _i = 0; _i < 2; ++_i) \
;         __builtin_amdgcn_global_load_lds((const unsigned*)((const char*)(gbase) + (voff)[_i]), (PG8_LAS unsigned*)(lds + (bufoff) + ldsw + _i * 8192), 16, 0, AUX_A); } while (0)
; #define PG8_STAGEB(bufoff, gbase, voff) do { _Pragma("unroll") for (int _i = 0; _i < 2; ++_i) \
;         __builtin_amdgcn_global_load_lds((const unsigned*)((const char*)(gbase) + (voff)[_i]), (PG8_LAS unsigned*)(lds + (bufoff) + ldsw + _i * 8192), 16, 0, AUX_B); } while (0)
; #define PG8_LDA(dst, b, h) do { _Pragma("unroll") for (int m = 0; m < 4; ++m) _Pragma("unroll") for (int k = 0; k < 2; ++k) dst[m][k] = *(const PG8_LAS bf16x8*)(lds + PG8_SA(b, h) + aoff + m * 2048 + k * 1024); } while (0)
; #define PG8_LDB(dst, b, h) do { _Pragma("unroll") for (int n = 0; n < 2; ++n) _Pragma("unroll") for (int k = 0; k < 2; ++k) dst[n][k] = *(const PG8_LAS bf16x8*)(lds + PG8_SB(b, h) + boff + n * 2048 + k * 1024); } while (0)
; #define PG8_WAIT_V(n) asm volatile("s_waitcnt vmcnt(" #n ")" ::: "memory")
; #define PG8_WAIT_L(n) asm volatile("s_waitcnt lgkmcnt(" #n ")" ::: "memory")
; template <class Epi, class Sched, bool ALIGN_EPI = false, bool SP2 = false>
; __device__ __forceinline__ void gemm_phase(PG8_LAS unsigned char* lds, const Gemm g, const Sched& S, const Epi& E) {
;     ...
;             PG8_LDB(B0, 0, 0); PG8_LDB(B1, 0, 1); PG8_SCHED; PG8_LDA(At, 0, 0); PG8_STAGE(PG8_SA(1, 1), a1 + hstep, voffA);
;             PG8_WAIT_V(8); PG8_WAIT_L(0); PG8_BAR; PG8_MMA(0, 0, At, B0); PG8_MMA(0, 1, At, B1); PG8_BAR; PG8_SCHED;
;             PG8_LDA(At, 0, 1); PG8_STAGEB(PG8_SB(0, 0), b2, voffB); PG8_STAGEB(PG8_SB(0, 1), b2 + hstep, voffB); PG8_STAGE(PG8_SA(0, 0), a2, voffA);
;             PG8_WAIT_V(8); PG8_WAIT_L(0); PG8_BAR; PG8_MMA(1, 0, At, B0); PG8_MMA(1, 1, At, B1); PG8_BAR; PG8_SCHED;
;             PG8_LDB(B0, 1, 0); PG8_LDB(B1, 1, 1); PG8_SCHED; PG8_LDA(At, 1, 0); PG8_STAGE(PG8_SA(0, 1), a2 + hstep, voffA);
;             PG8_WAIT_V(8); PG8_WAIT_L(0); PG8_BAR; PG8_MMA(0, 0, At, B0); PG8_MMA(0, 1, At, B1); PG8_BAR; PG8_SCHED;
;             PG8_LDA(At, 1, 1); PG8_STAGEB(PG8_SB(1, 0), b3, voffB); PG8_STAGEB(PG8_SB(1, 1), b3 + hstep, voffB); PG8_STAGE(PG8_SA(1, 0), a3, voffA);
;             PG8_WAIT_V(8); PG8_WAIT_L(0); PG8_BAR; PG8_MMA(1, 0, At, B0); PG8_MMA(1, 1, At, B1); PG8_BAR; PG8_SCHED;
.Lhb_45:
	s_mov_b32 m0, s78
	v_lshl_add_u64 v[166:167], s[48:49], 0, v[136:137]
	ds_read_b128 v[196:199], v149 offset:16384
	ds_read_b128 v[200:203], v149 offset:17408
	ds_read_b128 v[222:225], v149 offset:18432
	ds_read_b128 v[226:229], v149 offset:19456
	ds_read_b128 v[230:233], v149 offset:20480
	ds_read_b128 v[234:237], v149 offset:21504
	ds_read_b128 v[238:241], v149 offset:22528
	ds_read_b128 v[242:245], v149 offset:23552
	global_load_lds_dwordx4 v[166:167], off
	v_lshl_add_u64 v[168:169], s[48:49], 0, v[132:133]
	s_mov_b32 m0, s81
	v_lshl_add_u64 v[172:173], s[50:51], 0, v[136:137]
	global_load_lds_dwordx4 v[168:169], off
	s_mov_b32 m0, s82
	v_lshl_add_u64 v[212:213], s[44:45], 0, v[134:135]
	global_load_lds_dwordx4 v[172:173], off
	v_lshl_add_u64 v[172:173], s[50:51], 0, v[132:133]
	s_mov_b32 m0, s83
	s_nop 0
	global_load_lds_dwordx4 v[172:173], off
	v_lshl_add_u64 v[172:173], s[44:45], 0, v[138:139]
	s_mov_b32 m0, s57
	s_nop 0
	global_load_lds_dwordx4 v[172:173], off
	s_mov_b32 m0, s58
	s_nop 0
	global_load_lds_dwordx4 v[212:213], off
	s_waitcnt vmcnt(8)
	s_waitcnt lgkmcnt(0)
	s_cmp_lg_u64 s[10:11], 0
	s_cbranch_scc1 .Lhb_42
	s_barrier
.Lhb_42:
	s_setprio 1
	s_waitcnt lgkmcnt(0)
	v_mfma_f32_16x16x32_bf16 v[62:65], v[150:153], v[196:199], v[62:65]
	v_mfma_f32_16x16x32_bf16 v[54:57], v[158:161], v[196:199], v[54:57]
	v_mfma_f32_16x16x32_bf16 v[46:49], v[150:153], v[222:225], v[46:49]
	v_mfma_f32_16x16x32_bf16 v[38:41], v[158:161], v[222:225], v[38:41]
	v_mfma_f32_16x16x32_bf16 v[30:33], v[150:153], v[230:233], v[30:33]
	v_mfma_f32_16x16x32_bf16 v[22:25], v[158:161], v[230:233], v[22:25]
	v_mfma_f32_16x16x32_bf16 v[14:17], v[150:153], v[238:241], v[14:17]
	v_mfma_f32_16x16x32_bf16 v[6:9], v[158:161], v[238:241], v[6:9]
	s_setprio 2
	v_mfma_f32_16x16x32_bf16 v[62:65], v[154:157], v[200:203], v[62:65]
	v_mfma_f32_16x16x32_bf16 v[54:57], v[162:165], v[200:203], v[54:57]
	v_mfma_f32_16x16x32_bf16 v[46:49], v[154:157], v[226:229], v[46:49]
	v_mfma_f32_16x16x32_bf16 v[38:41], v[162:165], v[226:229], v[38:41]
	v_mfma_f32_16x16x32_bf16 v[30:33], v[154:157], v[234:237], v[30:33]
	v_mfma_f32_16x16x32_bf16 v[22:25], v[162:165], v[234:237], v[22:25]
	v_mfma_f32_16x16x32_bf16 v[14:17], v[154:157], v[242:245], v[14:17]
	v_mfma_f32_16x16x32_bf16 v[6:9], v[162:165], v[242:245], v[6:9]
	v_mfma_f32_16x16x32_bf16 v[58:61], v[180:183], v[196:199], v[58:61]
	v_mfma_f32_16x16x32_bf16 v[50:53], v[188:191], v[196:199], v[50:53]
	v_mfma_f32_16x16x32_bf16 v[42:45], v[180:183], v[222:225], v[42:45]
	v_mfma_f32_16x16x32_bf16 v[34:37], v[188:191], v[222:225], v[34:37]
	s_setprio 3
	v_mfma_f32_16x16x32_bf16 v[26:29], v[180:183], v[230:233], v[26:29]
	v_mfma_f32_16x16x32_bf16 v[18:21], v[188:191], v[230:233], v[18:21]
	v_mfma_f32_16x16x32_bf16 v[10:13], v[180:183], v[238:241], v[10:13]
	v_mfma_f32_16x16x32_bf16 v[2:5], v[188:191], v[238:241], v[2:5]
	v_mfma_f32_16x16x32_bf16 v[58:61], v[184:187], v[200:203], v[58:61]
	v_mfma_f32_16x16x32_bf16 v[50:53], v[192:195], v[200:203], v[50:53]
	v_mfma_f32_16x16x32_bf16 v[42:45], v[184:187], v[226:229], v[42:45]
	v_mfma_f32_16x16x32_bf16 v[34:37], v[192:195], v[226:229], v[34:37]
	v_mfma_f32_16x16x32_bf16 v[26:29], v[184:187], v[234:237], v[26:29]
	v_mfma_f32_16x16x32_bf16 v[18:21], v[192:195], v[234:237], v[18:21]
	v_mfma_f32_16x16x32_bf16 v[10:13], v[184:187], v[242:245], v[10:13]
	v_mfma_f32_16x16x32_bf16 v[2:5], v[192:195], v[242:245], v[2:5]
	s_setprio 0
	s_cmp_eq_u64 s[10:11], 0
	s_cbranch_scc1 .Lhb_46
	s_barrier
.Lhb_46:
	v_add_u32_e32 v162, s84, v99
	v_add_u32_e32 v192, s88, v99
	ds_read_b128 v[150:153], v162
	ds_read_b128 v[154:157], v162 offset:1024
	ds_read_b128 v[158:161], v162 offset:2048
	ds_read_b128 v[162:165], v162 offset:3072
	ds_read_b128 v[180:183], v192
	ds_read_b128 v[184:187], v192 offset:1024
	ds_read_b128 v[188:191], v192 offset:2048
	ds_read_b128 v[192:195], v192 offset:3072
	s_mov_b32 m0, s59
	v_lshl_add_u64 v[246:247], s[42:43], 0, v[138:139]
	ds_read_b128 v[196:199], v149 offset:32768
	ds_read_b128 v[200:203], v149 offset:33792
	ds_read_b128 v[222:225], v149 offset:34816
	ds_read_b128 v[226:229], v149 offset:35840
	ds_read_b128 v[230:233], v149 offset:36864
	ds_read_b128 v[234:237], v149 offset:37888
	ds_read_b128 v[238:241], v149 offset:38912
	ds_read_b128 v[242:245], v149 offset:39936
	global_load_lds_dwordx4 v[246:247], off
	v_lshl_add_u64 v[246:247], s[42:43], 0, v[134:135]
	s_mov_b32 m0, s60
	s_nop 0
	global_load_lds_dwordx4 v[246:247], off
	s_waitcnt vmcnt(8)
	s_waitcnt lgkmcnt(0)
	s_cmp_lg_u64 s[10:11], 0
	s_cbranch_scc1 .Lhb_43
	s_barrier

; #define PG8_STAGE(bufoff, gbase, voff) do { _Pragma("unroll") for (int _i = 0; _i < 2; ++_i) \
;         __builtin_amdgcn_global_load_lds((const unsigned*)((const char*)(gbase) + (voff)[_i]), (PG8_LAS unsigned*)(lds + (bufoff) + ldsw + _i * 8192), 16, 0, AUX_A); } while (0)
; #define PG8_STAGEB(bufoff, gbase, voff) do { _Pragma("unroll") for (int _i = 0; _i < 2; ++_i) \
;         __builtin_amdgcn_global_load_lds((const unsigned*)((const char*)(gbase) + (voff)[_i]), (PG8_LAS unsigned*)(lds + (bufoff) + ldsw + _i * 8192), 16, 0, AUX_B); } while (0)
; #define PG8_LDA(dst, b, h) do { _Pragma("unroll") for (int m = 0; m < 4; ++m) _Pragma("unroll") for (int k = 0; k < 2; ++k) dst[m][k] = *(const PG8_LAS bf16x8*)(lds + PG8_SA(b, h) + aoff + m * 2048 + k * 1024); } while (0)
; #define PG8_MMA(ai, bj, At, Bt) do { __builtin_amdgcn_s_setprio(1); _Pragma("unroll") for (int m = 0; m < 4; ++m) _Pragma("unroll") for (int n = 0; n < 2; ++n) _Pragma("unroll") for (int k = 0; k < 2; ++k) \
;         acc[ai][bj][m][n] = __builtin_amdgcn_mfma_f32_16x16x32_bf16(Bt[n][k], At[m][k], acc[ai][bj][m][n], 0, 0, 0); __builtin_amdgcn_s_setprio(0); } while (0)
; #define PG8_WAIT_V(n) asm volatile("s_waitcnt vmcnt(" #n ")" ::: "memory")
; #define PG8_WAIT_L(n) asm volatile("s_waitcnt lgkmcnt(" #n ")" ::: "memory")
; #define PG8_BAR __builtin_amdgcn_s_barrier()
; #define PG8_SCHED __builtin_amdgcn_sched_barrier(0)
; template <class Epi, class Sched, bool ALIGN_EPI = false, bool SP2 = false>
; __device__ __forceinline__ void gemm_phase(PG8_LAS unsigned char* lds, const Gemm g, const Sched& S, const Epi& E) {
;     ...
;             PG8_LDA(At, 1, 1); PG8_STAGEB(PG8_SB(1, 0), b3, voffB); PG8_STAGEB(PG8_SB(1, 1), b3 + hstep, voffB); PG8_STAGE(PG8_SA(1, 0), a3, voffA);
;             PG8_WAIT_V(8); PG8_WAIT_L(0); PG8_BAR; PG8_MMA(1, 0, At, B0); PG8_MMA(1, 1, At, B1); PG8_BAR; PG8_SCHED;
.Lhb_47:
	s_mov_b32 m0, s1
	v_lshl_add_u64 v[166:167], v[166:167], 0, s[76:77]
	ds_read_b128 v[196:199], v149 offset:49152
	ds_read_b128 v[200:203], v149 offset:50176
	ds_read_b128 v[222:225], v149 offset:51200
	ds_read_b128 v[226:229], v149 offset:52224
	ds_read_b128 v[230:233], v149 offset:53248
	ds_read_b128 v[234:237], v149 offset:54272
	ds_read_b128 v[238:241], v149 offset:55296
	ds_read_b128 v[242:245], v149 offset:56320
	global_load_lds_dwordx4 v[166:167], off
	v_lshl_add_u64 v[166:167], v[168:169], 0, s[76:77]
	s_mov_b32 m0, s0
	s_nop 0
	global_load_lds_dwordx4 v[166:167], off
	v_lshl_add_u64 v[166:167], s[36:37], 0, v[136:137]
	s_mov_b32 m0, s46
	s_nop 0
	global_load_lds_dwordx4 v[166:167], off
	v_lshl_add_u64 v[166:167], s[36:37], 0, v[132:133]
	s_mov_b32 m0, s31
	s_nop 0
	global_load_lds_dwordx4 v[166:167], off
	v_lshl_add_u64 v[166:167], v[172:173], 0, s[76:77]
	s_mov_b32 m0, s61
	s_nop 0
	global_load_lds_dwordx4 v[166:167], off
	v_lshl_add_u64 v[166:167], v[212:213], 0, s[76:77]
	s_mov_b32 m0, s62
	s_nop 0
	global_load_lds_dwordx4 v[166:167], off
	s_waitcnt vmcnt(8)
	s_waitcnt lgkmcnt(0)
	s_cmp_lg_u64 s[10:11], 0
	s_cbranch_scc1 .Lhb_44
	s_barrier

; #define GAS __attribute__((address_space(1)))
; __device__ __forceinline__ u32x4 pack8(f32x4 v0, f32x4 v1) { u32x4 w; w.x = cvt_pk_bf16(v0[0], v0[1]); w.y = cvt_pk_bf16(v0[2], v0[3]); w.z = cvt_pk_bf16(v1[0], v1[1]); w.w = cvt_pk_bf16(v1[2], v1[3]); return w; }
; #define PG8_BAR __builtin_amdgcn_s_barrier()
; #define GAS __attribute__((address_space(1)))
; __device__ __forceinline__ void store16_wt(void* p, u32x4 w) {
;     if (WT_STORES) asm volatile("global_store_dwordx4 %0, %1, off sc1\n\ts_nop 1" :: "v"(p), "v"(w) : "memory");
;     else *(GAS u32x4*)p = w;
; }
;     __device__ __forceinline__ void operator()(const f32x4 (&acc)[2][2][4][2], const Unit& u, int wr, int wc, int fr, int fq) const {
;         const int row0 = u.pm * BM + wr * 64 + fr, col0 = u.pn * HALF + wc * 32 + 8 * fq;
;         bf16_t* const p0 = ACT + (size_t)row0 * 5632 + col0;
; #pragma unroll
;         for (int ai = 0; ai < 2; ++ai)
; #pragma unroll
;             for (int m = 0; m < 4; ++m) {
;                 const f32x4 g0 = acc[ai][0][m][0], g1 = acc[ai][0][m][1];
;                 const f32x4 v0 = g0 * sigmoid4(g0) * acc[ai][1][m][0], v1 = g1 * sigmoid4(g1) * acc[ai][1][m][1];
;                 store16_wt(p0 + (size_t)(ai * HALF + m * 16) * 5632, pack8(v0, v1)); }
; template <class Epi, class Sched, bool ALIGN_EPI = false, bool SP2 = false>
; __device__ __forceinline__ void gemm_phase(PG8_LAS unsigned char* lds, const Gemm g, const Sched& S, const Epi& E) {
;     ...
;         if constexpr (ALIGN_EPI) { if (wr == 0) PG8_BAR; }
.Lhb_48:
	v_lshl_add_u64 v[144:145], v[144:145], 0, s[86:87]
	v_lshl_add_u64 v[146:147], v[146:147], 0, s[86:87]
	s_cmp_gt_u32 s30, 31
	s_mov_b32 s29, s30
	s_cbranch_scc0 .LBB0_1458
	s_and_b64 vcc, exec, s[10:11]
	s_cbranch_vccz .LBB0_1461
.LBB0_1461:
	v_lshl_add_u32 v145, s70, 8, v1
	v_lshl_or_b32 v144, s69, 7, v148
	v_mov_b64_e32 v[146:147], s[8:9]
	s_movk_i32 s0, 0x2c00
	v_mad_i64_i32 v[146:147], s[0:1], v145, s0, v[146:147]
	v_ashrrev_i32_e32 v145, 31, v144
	v_lshl_add_u64 v[144:145], v[144:145], 1, v[146:147]
	v_pk_mul_f32 v[146:147], v[128:129], s[74:75] op_sel_hi:[1,0]
	v_pk_mul_f32 v[150:151], v[130:131], s[74:75] op_sel_hi:[1,0]
	v_exp_f32_e32 v146, v146
	v_exp_f32_e32 v147, v147
	v_exp_f32_e32 v150, v150
	v_exp_f32_e32 v151, v151
	s_mov_b32 s0, 0x160000
	v_pk_add_f32 v[146:147], v[146:147], 1.0 op_sel_hi:[1,0]
	s_mov_b64 s[34:35], -1
	v_pk_add_f32 v[150:151], v[150:151], 1.0 op_sel_hi:[1,0]
	v_rcp_f32_e32 v146, v146
	v_rcp_f32_e32 v147, v147
	v_rcp_f32_e32 v150, v150
	v_rcp_f32_e32 v151, v151
	v_pk_mul_f32 v[128:129], v[128:129], v[146:147]
	s_nop 0
	v_pk_mul_f32 v[124:125], v[124:125], v[128:129]
	v_pk_mul_f32 v[130:131], v[130:131], v[150:151]
	v_pk_mul_f32 v[128:129], v[120:121], s[74:75] op_sel_hi:[1,0]
	v_pk_mul_f32 v[126:127], v[126:127], v[130:131]
	v_pk_mul_f32 v[130:131], v[122:123], s[74:75] op_sel_hi:[1,0]
	v_exp_f32_e32 v128, v128
	v_exp_f32_e32 v129, v129
	v_exp_f32_e32 v130, v130
	v_exp_f32_e32 v131, v131
	v_pk_add_f32 v[128:129], v[128:129], 1.0 op_sel_hi:[1,0]
	s_nop 0
	v_rcp_f32_e32 v128, v128
	v_pk_add_f32 v[130:131], v[130:131], 1.0 op_sel_hi:[1,0]
	v_rcp_f32_e32 v129, v129
	v_rcp_f32_e32 v130, v130
	v_rcp_f32_e32 v131, v131
	v_pk_mul_f32 v[120:121], v[120:121], v[128:129]
	v_pk_mul_f32 v[122:123], v[122:123], v[130:131]
	s_nop 0
	v_pk_mul_f32 v[122:123], v[118:119], v[122:123]
	v_pk_mul_f32 v[118:119], v[116:117], v[120:121]
	v_cvt_pk_bf16_f32 v116, v124, v125
	v_cvt_pk_bf16_f32 v117, v126, v127
	v_cvt_pk_bf16_f32 v118, v118, v119
	v_cvt_pk_bf16_f32 v119, v122, v123
	global_store_dwordx4 v[144:145], v[116:119], off
	s_nop 1
	v_pk_mul_f32 v[116:117], v[112:113], s[74:75] op_sel_hi:[1,0]
	v_pk_mul_f32 v[118:119], v[114:115], s[74:75] op_sel_hi:[1,0]
	v_exp_f32_e32 v116, v116
	v_exp_f32_e32 v117, v117
	v_exp_f32_e32 v118, v118
	v_exp_f32_e32 v119, v119
	v_pk_add_f32 v[116:117], v[116:117], 1.0 op_sel_hi:[1,0]
	s_nop 0
	v_rcp_f32_e32 v116, v116
	v_pk_add_f32 v[118:119], v[118:119], 1.0 op_sel_hi:[1,0]
	v_rcp_f32_e32 v117, v117
	v_rcp_f32_e32 v118, v118
	v_rcp_f32_e32 v119, v119
	v_pk_mul_f32 v[112:113], v[112:113], v[116:117]
	s_nop 0
	v_pk_mul_f32 v[108:109], v[108:109], v[112:113]
	v_pk_mul_f32 v[114:115], v[114:115], v[118:119]
	v_pk_mul_f32 v[112:113], v[104:105], s[74:75] op_sel_hi:[1,0]
	v_pk_mul_f32 v[110:111], v[110:111], v[114:115]
	v_pk_mul_f32 v[114:115], v[106:107], s[74:75] op_sel_hi:[1,0]
	v_exp_f32_e32 v112, v112
	v_exp_f32_e32 v113, v113
	v_exp_f32_e32 v114, v114
	v_exp_f32_e32 v115, v115
	v_pk_add_f32 v[112:113], v[112:113], 1.0 op_sel_hi:[1,0]
	s_nop 0
	v_rcp_f32_e32 v112, v112
	v_pk_add_f32 v[114:115], v[114:115], 1.0 op_sel_hi:[1,0]
	v_rcp_f32_e32 v113, v113
	v_rcp_f32_e32 v114, v114
	v_rcp_f32_e32 v115, v115
	v_pk_mul_f32 v[104:105], v[104:105], v[112:113]
	v_pk_mul_f32 v[106:107], v[106:107], v[114:115]
	s_nop 0
	v_pk_mul_f32 v[106:107], v[102:103], v[106:107]
	v_pk_mul_f32 v[102:103], v[100:101], v[104:105]
	v_add_co_u32_e32 v104, vcc, s65, v144
	v_cvt_pk_bf16_f32 v100, v108, v109
	v_cvt_pk_bf16_f32 v101, v110, v111
	v_cvt_pk_bf16_f32 v102, v102, v103
	v_cvt_pk_bf16_f32 v103, v106, v107
	v_addc_co_u32_e32 v105, vcc, 0, v145, vcc
	global_store_dwordx4 v[104:105], v[100:103], off
	s_nop 1
	v_pk_mul_f32 v[100:101], v[94:95], s[74:75] op_sel_hi:[1,0]
	v_pk_mul_f32 v[102:103], v[96:97], s[74:75] op_sel_hi:[1,0]
	v_exp_f32_e32 v100, v100
	v_exp_f32_e32 v101, v101
	v_exp_f32_e32 v102, v102
	v_exp_f32_e32 v103, v103
	v_pk_add_f32 v[100:101], v[100:101], 1.0 op_sel_hi:[1,0]
	s_nop 0
	v_rcp_f32_e32 v100, v100
	v_pk_add_f32 v[102:103], v[102:103], 1.0 op_sel_hi:[1,0]
	v_rcp_f32_e32 v101, v101
	v_rcp_f32_e32 v102, v102
	v_rcp_f32_e32 v103, v103
	v_pk_mul_f32 v[94:95], v[94:95], v[100:101]
	s_nop 0
	v_pk_mul_f32 v[90:91], v[90:91], v[94:95]
	v_pk_mul_f32 v[96:97], v[96:97], v[102:103]
	v_pk_mul_f32 v[94:95], v[86:87], s[74:75] op_sel_hi:[1,0]
	v_pk_mul_f32 v[92:93], v[92:93], v[96:97]
	v_pk_mul_f32 v[96:97], v[88:89], s[74:75] op_sel_hi:[1,0]
	v_exp_f32_e32 v94, v94
	v_exp_f32_e32 v95, v95
	v_exp_f32_e32 v96, v96
	v_exp_f32_e32 v97, v97
	v_pk_add_f32 v[94:95], v[94:95], 1.0 op_sel_hi:[1,0]
	s_nop 0
	v_rcp_f32_e32 v94, v94
	v_pk_add_f32 v[96:97], v[96:97], 1.0 op_sel_hi:[1,0]
	v_rcp_f32_e32 v95, v95
	v_rcp_f32_e32 v96, v96
	v_rcp_f32_e32 v97, v97
	v_pk_mul_f32 v[86:87], v[86:87], v[94:95]
	v_pk_mul_f32 v[88:89], v[88:89], v[96:97]
	s_nop 0
	v_pk_mul_f32 v[88:89], v[84:85], v[88:89]
	v_pk_mul_f32 v[84:85], v[82:83], v[86:87]
	v_add_co_u32_e32 v86, vcc, s64, v144
	v_cvt_pk_bf16_f32 v82, v90, v91
	v_cvt_pk_bf16_f32 v83, v92, v93
	v_cvt_pk_bf16_f32 v84, v84, v85
	v_cvt_pk_bf16_f32 v85, v88, v89
	v_addc_co_u32_e32 v87, vcc, 0, v145, vcc
	global_store_dwordx4 v[86:87], v[82:85], off
	s_nop 1
	v_pk_mul_f32 v[82:83], v[78:79], s[74:75] op_sel_hi:[1,0]
	v_pk_mul_f32 v[84:85], v[80:81], s[74:75] op_sel_hi:[1,0]
	v_exp_f32_e32 v82, v82
	v_exp_f32_e32 v83, v83
	v_exp_f32_e32 v84, v84
	v_exp_f32_e32 v85, v85
	v_pk_add_f32 v[82:83], v[82:83], 1.0 op_sel_hi:[1,0]
	s_nop 0
	v_rcp_f32_e32 v82, v82
	v_pk_add_f32 v[84:85], v[84:85], 1.0 op_sel_hi:[1,0]
	v_rcp_f32_e32 v83, v83
	v_rcp_f32_e32 v84, v84
	v_rcp_f32_e32 v85, v85
; __device__ __forceinline__ u32x4 pack8(f32x4 v0, f32x4 v1) { u32x4 w; w.x = cvt_pk_bf16(v0[0], v0[1]); w.y = cvt_pk_bf16(v0[2], v0[3]); w.z = cvt_pk_bf16(v1[0], v1[1]); w.w = cvt_pk_bf16(v1[2], v1[3]); return w; }
; __device__ __forceinline__ f32x4 sigmoid4(f32x4 v) {
;     const f32x2 t0 = (f32x2){v[0], v[1]} * -1.4426950408889634f, t1 = (f32x2){v[2], v[3]} * -1.4426950408889634f;
;     const f32x2 d0 = (f32x2){__builtin_amdgcn_exp2f(t0.x), __builtin_amdgcn_exp2f(t0.y)} + 1.0f, d1 = (f32x2){__builtin_amdgcn_exp2f(t1.x), __builtin_amdgcn_exp2f(t1.y)} + 1.0f;
;     return (f32x4){__builtin_amdgcn_rcpf(d0.x), __builtin_amdgcn_rcpf(d0.y), __builtin_amdgcn_rcpf(d1.x), __builtin_amdgcn_rcpf(d1.y)}; }
;     __device__ __forceinline__ void operator()(const f32x4 (&acc)[2][2][4][2], const Unit& u, int wr, int wc, int fr, int fq) const {
;         const int row0 = u.pm * BM + wr * 64 + fr, col0 = u.pn * HALF + wc * 32 + 8 * fq;
;         bf16_t* const p0 = ACT + (size_t)row0 * 5632 + col0;
; #pragma unroll
;         for (int ai = 0; ai < 2; ++ai)
; #pragma unroll
;             for (int m = 0; m < 4; ++m) {
;                 const f32x4 g0 = acc[ai][0][m][0], g1 = acc[ai][0][m][1];
;                 const f32x4 v0 = g0 * sigmoid4(g0) * acc[ai][1][m][0], v1 = g1 * sigmoid4(g1) * acc[ai][1][m][1];
;                 store16_wt(p0 + (size_t)(ai * HALF + m * 16) * 5632, pack8(v0, v1)); }
	v_pk_mul_f32 v[78:79], v[78:79], v[82:83]
	s_nop 0
	v_pk_mul_f32 v[74:75], v[74:75], v[78:79]
	v_pk_mul_f32 v[80:81], v[80:81], v[84:85]
	v_pk_mul_f32 v[78:79], v[70:71], s[74:75] op_sel_hi:[1,0]
	v_pk_mul_f32 v[76:77], v[76:77], v[80:81]
	v_pk_mul_f32 v[80:81], v[72:73], s[74:75] op_sel_hi:[1,0]
	v_exp_f32_e32 v78, v78
	v_exp_f32_e32 v79, v79
	v_exp_f32_e32 v80, v80
	v_exp_f32_e32 v81, v81
	v_pk_add_f32 v[78:79], v[78:79], 1.0 op_sel_hi:[1,0]
	s_nop 0
	v_rcp_f32_e32 v78, v78
	v_pk_add_f32 v[80:81], v[80:81], 1.0 op_sel_hi:[1,0]
	v_rcp_f32_e32 v79, v79
	v_rcp_f32_e32 v80, v80
	v_rcp_f32_e32 v81, v81
	v_pk_mul_f32 v[70:71], v[70:71], v[78:79]
	v_pk_mul_f32 v[72:73], v[72:73], v[80:81]
	s_nop 0
	v_pk_mul_f32 v[72:73], v[68:69], v[72:73]
	v_pk_mul_f32 v[68:69], v[66:67], v[70:71]
	v_add_co_u32_e32 v70, vcc, s66, v144
	v_cvt_pk_bf16_f32 v66, v74, v75
	v_cvt_pk_bf16_f32 v67, v76, v77
	v_cvt_pk_bf16_f32 v68, v68, v69
	v_cvt_pk_bf16_f32 v69, v72, v73
	v_addc_co_u32_e32 v71, vcc, 0, v145, vcc
	global_store_dwordx4 v[70:71], v[66:69], off
	s_nop 1
	v_pk_mul_f32 v[66:67], v[62:63], s[74:75] op_sel_hi:[1,0]
	v_pk_mul_f32 v[68:69], v[64:65], s[74:75] op_sel_hi:[1,0]
	v_exp_f32_e32 v66, v66
	v_exp_f32_e32 v67, v67
	v_exp_f32_e32 v68, v68
	v_exp_f32_e32 v69, v69
	v_pk_add_f32 v[66:67], v[66:67], 1.0 op_sel_hi:[1,0]
	s_nop 0
	v_rcp_f32_e32 v66, v66
	v_pk_add_f32 v[68:69], v[68:69], 1.0 op_sel_hi:[1,0]
	v_rcp_f32_e32 v67, v67
	v_rcp_f32_e32 v68, v68
	v_rcp_f32_e32 v69, v69
	v_pk_mul_f32 v[62:63], v[62:63], v[66:67]
	s_nop 0
	v_pk_mul_f32 v[58:59], v[58:59], v[62:63]
	v_pk_mul_f32 v[64:65], v[64:65], v[68:69]
	v_pk_mul_f32 v[62:63], v[54:55], s[74:75] op_sel_hi:[1,0]
	v_pk_mul_f32 v[60:61], v[60:61], v[64:65]
	v_pk_mul_f32 v[64:65], v[56:57], s[74:75] op_sel_hi:[1,0]
	v_exp_f32_e32 v62, v62
	v_exp_f32_e32 v63, v63
	v_exp_f32_e32 v64, v64
	v_exp_f32_e32 v65, v65
	v_pk_add_f32 v[62:63], v[62:63], 1.0 op_sel_hi:[1,0]
	s_nop 0
	v_rcp_f32_e32 v62, v62
	v_pk_add_f32 v[64:65], v[64:65], 1.0 op_sel_hi:[1,0]
	v_rcp_f32_e32 v63, v63
	v_rcp_f32_e32 v64, v64
	v_rcp_f32_e32 v65, v65
	v_pk_mul_f32 v[54:55], v[54:55], v[62:63]
	v_pk_mul_f32 v[56:57], v[56:57], v[64:65]
	s_nop 0
	v_pk_mul_f32 v[56:57], v[52:53], v[56:57]
	v_pk_mul_f32 v[52:53], v[50:51], v[54:55]
	v_add_co_u32_e32 v54, vcc, s0, v144
	v_cvt_pk_bf16_f32 v50, v58, v59
	v_cvt_pk_bf16_f32 v51, v60, v61
	v_cvt_pk_bf16_f32 v52, v52, v53
	v_cvt_pk_bf16_f32 v53, v56, v57
	v_addc_co_u32_e32 v55, vcc, 0, v145, vcc
	global_store_dwordx4 v[54:55], v[50:53], off
	s_mov_b32 s0, 0x18c000
	s_nop 0
	v_pk_mul_f32 v[50:51], v[46:47], s[74:75] op_sel_hi:[1,0]
	v_pk_mul_f32 v[52:53], v[48:49], s[74:75] op_sel_hi:[1,0]
	v_exp_f32_e32 v50, v50
	v_exp_f32_e32 v51, v51
	v_exp_f32_e32 v52, v52
	v_exp_f32_e32 v53, v53
	v_pk_add_f32 v[50:51], v[50:51], 1.0 op_sel_hi:[1,0]
	s_nop 0
	v_rcp_f32_e32 v50, v50
	v_pk_add_f32 v[52:53], v[52:53], 1.0 op_sel_hi:[1,0]
	v_rcp_f32_e32 v51, v51
	v_rcp_f32_e32 v52, v52
	v_rcp_f32_e32 v53, v53
	v_pk_mul_f32 v[46:47], v[46:47], v[50:51]
	s_nop 0
	v_pk_mul_f32 v[42:43], v[42:43], v[46:47]
	v_pk_mul_f32 v[48:49], v[48:49], v[52:53]
	v_pk_mul_f32 v[46:47], v[38:39], s[74:75] op_sel_hi:[1,0]
	v_pk_mul_f32 v[44:45], v[44:45], v[48:49]
	v_pk_mul_f32 v[48:49], v[40:41], s[74:75] op_sel_hi:[1,0]
	v_exp_f32_e32 v46, v46
	v_exp_f32_e32 v47, v47
	v_exp_f32_e32 v48, v48
	v_exp_f32_e32 v49, v49
	v_pk_add_f32 v[46:47], v[46:47], 1.0 op_sel_hi:[1,0]
	s_nop 0
	v_rcp_f32_e32 v46, v46
	v_pk_add_f32 v[48:49], v[48:49], 1.0 op_sel_hi:[1,0]
	v_rcp_f32_e32 v47, v47
	v_rcp_f32_e32 v48, v48
; __device__ __forceinline__ u32x4 pack8(f32x4 v0, f32x4 v1) { u32x4 w; w.x = cvt_pk_bf16(v0[0], v0[1]); w.y = cvt_pk_bf16(v0[2], v0[3]); w.z = cvt_pk_bf16(v1[0], v1[1]); w.w = cvt_pk_bf16(v1[2], v1[3]); return w; }
; #define PG8_BAR __builtin_amdgcn_s_barrier()
;     __device__ __forceinline__ void operator()(const f32x4 (&acc)[2][2][4][2], const Unit& u, int wr, int wc, int fr, int fq) const {
;         const int row0 = u.pm * BM + wr * 64 + fr, col0 = u.pn * HALF + wc * 32 + 8 * fq;
;         bf16_t* const p0 = ACT + (size_t)row0 * 5632 + col0;
; #pragma unroll
;         for (int ai = 0; ai < 2; ++ai)
; #pragma unroll
;             for (int m = 0; m < 4; ++m) {
;                 const f32x4 g0 = acc[ai][0][m][0], g1 = acc[ai][0][m][1];
;                 const f32x4 v0 = g0 * sigmoid4(g0) * acc[ai][1][m][0], v1 = g1 * sigmoid4(g1) * acc[ai][1][m][1];
;                 store16_wt(p0 + (size_t)(ai * HALF + m * 16) * 5632, pack8(v0, v1)); }
; template <class Epi, class Sched, bool ALIGN_EPI = false, bool SP2 = false>
; __device__ __forceinline__ void gemm_phase(PG8_LAS unsigned char* lds, const Gemm g, const Sched& S, const Epi& E) {
;     ...
;         cur = nxt; cA = nA; cB = nB; ++ui;
;         if constexpr (ALIGN_EPI) { if (wr == 1) PG8_BAR; }
	v_rcp_f32_e32 v49, v49
	v_pk_mul_f32 v[38:39], v[38:39], v[46:47]
	v_pk_mul_f32 v[40:41], v[40:41], v[48:49]
	s_nop 0
	v_pk_mul_f32 v[40:41], v[36:37], v[40:41]
	v_pk_mul_f32 v[36:37], v[34:35], v[38:39]
	v_add_co_u32_e32 v38, vcc, s0, v144
	v_cvt_pk_bf16_f32 v34, v42, v43
	v_cvt_pk_bf16_f32 v35, v44, v45
	v_cvt_pk_bf16_f32 v36, v36, v37
	v_cvt_pk_bf16_f32 v37, v40, v41
	v_addc_co_u32_e32 v39, vcc, 0, v145, vcc
	global_store_dwordx4 v[38:39], v[34:37], off
	s_mov_b32 s0, 0x1b8000
	s_nop 0
	v_pk_mul_f32 v[34:35], v[30:31], s[74:75] op_sel_hi:[1,0]
	v_pk_mul_f32 v[36:37], v[32:33], s[74:75] op_sel_hi:[1,0]
	v_exp_f32_e32 v34, v34
	v_exp_f32_e32 v35, v35
	v_exp_f32_e32 v36, v36
	v_exp_f32_e32 v37, v37
	v_pk_add_f32 v[34:35], v[34:35], 1.0 op_sel_hi:[1,0]
	s_nop 0
	v_rcp_f32_e32 v34, v34
	v_pk_add_f32 v[36:37], v[36:37], 1.0 op_sel_hi:[1,0]
	v_rcp_f32_e32 v35, v35
	v_rcp_f32_e32 v36, v36
	v_rcp_f32_e32 v37, v37
	v_pk_mul_f32 v[30:31], v[30:31], v[34:35]
	s_nop 0
	v_pk_mul_f32 v[26:27], v[26:27], v[30:31]
	v_pk_mul_f32 v[32:33], v[32:33], v[36:37]
	v_pk_mul_f32 v[30:31], v[22:23], s[74:75] op_sel_hi:[1,0]
	v_pk_mul_f32 v[28:29], v[28:29], v[32:33]
	v_pk_mul_f32 v[32:33], v[24:25], s[74:75] op_sel_hi:[1,0]
	v_exp_f32_e32 v30, v30
	v_exp_f32_e32 v31, v31
	v_exp_f32_e32 v32, v32
	v_exp_f32_e32 v33, v33
	v_pk_add_f32 v[30:31], v[30:31], 1.0 op_sel_hi:[1,0]
	s_nop 0
	v_rcp_f32_e32 v30, v30
	v_pk_add_f32 v[32:33], v[32:33], 1.0 op_sel_hi:[1,0]
	v_rcp_f32_e32 v31, v31
	v_rcp_f32_e32 v32, v32
	v_rcp_f32_e32 v33, v33
	v_pk_mul_f32 v[22:23], v[22:23], v[30:31]
	v_pk_mul_f32 v[24:25], v[24:25], v[32:33]
	s_nop 0
	v_pk_mul_f32 v[24:25], v[20:21], v[24:25]
	v_pk_mul_f32 v[20:21], v[18:19], v[22:23]
	v_add_co_u32_e32 v22, vcc, s0, v144
	v_cvt_pk_bf16_f32 v18, v26, v27
	v_cvt_pk_bf16_f32 v19, v28, v29
	v_cvt_pk_bf16_f32 v20, v20, v21
	v_cvt_pk_bf16_f32 v21, v24, v25
	v_addc_co_u32_e32 v23, vcc, 0, v145, vcc
	global_store_dwordx4 v[22:23], v[18:21], off
	s_nop 1
	v_pk_mul_f32 v[18:19], v[14:15], s[74:75] op_sel_hi:[1,0]
	v_pk_mul_f32 v[20:21], v[16:17], s[74:75] op_sel_hi:[1,0]
	v_exp_f32_e32 v18, v18
	v_exp_f32_e32 v19, v19
	v_exp_f32_e32 v20, v20
	v_exp_f32_e32 v21, v21
	v_pk_add_f32 v[18:19], v[18:19], 1.0 op_sel_hi:[1,0]
	s_nop 0
	v_rcp_f32_e32 v18, v18
	v_pk_add_f32 v[20:21], v[20:21], 1.0 op_sel_hi:[1,0]
	v_rcp_f32_e32 v19, v19
	v_rcp_f32_e32 v20, v20
	v_rcp_f32_e32 v21, v21
	v_pk_mul_f32 v[14:15], v[14:15], v[18:19]
	s_nop 0
	v_pk_mul_f32 v[10:11], v[10:11], v[14:15]
	v_pk_mul_f32 v[16:17], v[16:17], v[20:21]
	v_pk_mul_f32 v[14:15], v[6:7], s[74:75] op_sel_hi:[1,0]
	v_pk_mul_f32 v[12:13], v[12:13], v[16:17]
	v_pk_mul_f32 v[16:17], v[8:9], s[74:75] op_sel_hi:[1,0]
	v_exp_f32_e32 v14, v14
	v_exp_f32_e32 v15, v15
	v_exp_f32_e32 v16, v16
	v_exp_f32_e32 v17, v17
	v_pk_add_f32 v[14:15], v[14:15], 1.0 op_sel_hi:[1,0]
	s_nop 0
	v_rcp_f32_e32 v14, v14
	v_pk_add_f32 v[16:17], v[16:17], 1.0 op_sel_hi:[1,0]
	v_rcp_f32_e32 v15, v15
	v_rcp_f32_e32 v16, v16
	v_rcp_f32_e32 v17, v17
	v_pk_mul_f32 v[6:7], v[6:7], v[14:15]
	v_pk_mul_f32 v[8:9], v[8:9], v[16:17]
	s_nop 0
	v_pk_mul_f32 v[8:9], v[4:5], v[8:9]
	v_pk_mul_f32 v[4:5], v[2:3], v[6:7]
	v_add_co_u32_e32 v6, vcc, 0x1e4000, v144
	v_cvt_pk_bf16_f32 v2, v10, v11
	s_nop 0
	v_addc_co_u32_e32 v7, vcc, 0, v145, vcc
	v_cvt_pk_bf16_f32 v3, v12, v13
	v_cvt_pk_bf16_f32 v4, v4, v5
	v_cvt_pk_bf16_f32 v5, v8, v9
	s_andn2_b64 vcc, exec, s[38:39]
	global_store_dwordx4 v[6:7], v[2:5], off
	s_cbranch_vccnz .LBB0_1454
	s_andn2_b64 vcc, exec, s[6:7]
	s_cbranch_vccnz .LBB0_1453
	s_branch .LBB0_1453

; #define PG8_WAIT_V(n) asm volatile("s_waitcnt vmcnt(" #n ")" ::: "memory")
; #define PG8_BAR __builtin_amdgcn_s_barrier()
; template <class Epi, class Sched, bool ALIGN_EPI = false, bool SP2 = false>
; __device__ __forceinline__ void gemm_phase(PG8_LAS unsigned char* lds, const Gemm g, const Sched& S, const Epi& E) {
;     ...
;     const int tid = tid_l, wid = __builtin_amdgcn_readfirstlane(tid >> 6), lane = tid & 63, wr = wid >> 2, wc = wid & 3, fr = lane & 15, fq = lane >> 4;
;     const int K = g.K;
;     unsigned voffA[2], voffB[2];
; #pragma unroll
;     for (int i = 0; i < 2; ++i) { int R, C; stage_rc(tid * 16 + i * 8192, R, C); const int Rb = Epi::PERM ? ((R & ~31) + perm32(R & 31)) : R;
;         voffA[i] = (unsigned)(R * K + C) * 2u; voffB[i] = (unsigned)(Rb * K + C) * 2u; }
;     const size_t kstep = (size_t)(BK * 2);
;     const size_t hstep = (size_t)HALF * K * 2;
;     const size_t tstep = 2 * hstep;
;     const unsigned ldsw = (unsigned)wid * 1024u;
;     const int aoff = lds_byte(wr * 64 + fr, fq * 8), boff = lds_byte(wc * 32 + fr, fq * 8);
;     ...
;     Unit cur, nxt; int ui = 0;
;     if (!S.next(0, cur)) return;
;     f32x4 acc[2][2][4][2];
; #pragma unroll
;     for (int a = 0; a < 2; ++a)
; #pragma unroll
;         for (int b = 0; b < 2; ++b)
; #pragma unroll
;             for (int m = 0; m < 4; ++m)
; #pragma unroll
;                 for (int n = 0; n < 2; ++n) acc[a][b][m][n] = (f32x4){0.f, 0.f, 0.f, 0.f};
;     bf16x8 At[4][2], B0[2][2], B1[2][2];
;     const char* cA = (const char*)g.A + (size_t)cur.pm * tstep + (size_t)cur.kt0 * kstep; const char* cB = (const char*)g.Bt + (size_t)cur.pn * tstep + (size_t)cur.kt0 * kstep;
;     S.a_ready(cur);
;     ...
;     { const int rot0 = cur.krot, nt0 = cur.nkt; const char* sA0 = PG8_KP(cA, 0, rot0, nt0); const char* sA1 = PG8_KP(cA, 1, rot0, nt0); const char* sB0 = PG8_KP(cB, 0, rot0, nt0); const char* sB1 = PG8_KP(cB, 1, rot0, nt0);
;     if constexpr (SP2) {
;         PG8_STAGEB(PG8_SB(0, 0), sB0, voffB); PG8_STAGEB(PG8_SB(0, 1), sB0 + hstep, voffB); PG8_STAGE(PG8_SA(0, 0), sA0, voffA); PG8_STAGE(PG8_SA(0, 1), sA0 + hstep, voffA);
;         if (wr == 1) PG8_BAR;
;         PG8_WAIT_V(2); PG8_BAR;
;         PG8_STAGEB(PG8_SB(1, 0), sB1, voffB); PG8_STAGE(PG8_SA(1, 0), sA1, voffA); PG8_STAGEB(PG8_SB(1, 1), sB1 + hstep, voffB);
;         PG8_WAIT_V(6); PG8_BAR;
;     } else {
.LBB0_1638:
	v_readlane_b32 s0, v254, 58
	s_mov_b64 s[12:13], s[66:67]
	v_mov_b32_e32 v18, v0
	v_readlane_b32 s1, v254, 59
	s_and_b64 vcc, exec, s[0:1]
	v_readfirstlane_b32 s14, v18
	s_cbranch_vccnz .LBB0_1733
	v_lshlrev_b32_e32 v1, 4, v18
	v_add_u32_e32 v2, 0x2000, v1
	v_ashrrev_i32_e32 v3, 31, v2
	v_lshrrev_b32_e32 v3, 22, v3
	v_add_u32_e32 v3, v2, v3
	v_ashrrev_i32_e32 v10, 10, v3
	v_mul_i32_i24_e32 v3, 0x400, v10
	v_sub_u32_e32 v2, v2, v3
	v_lshrrev_b32_e32 v3, 4, v2
	v_bitop3_b32 v2, v3, v2, 32 bitop3:0x6c
	v_ashrrev_i32_e32 v3, 31, v2
	v_lshrrev_b32_e32 v3, 26, v3
	v_add_u32_e32 v3, v2, v3
	v_lshlrev_b32_e32 v4, 3, v10
	v_ashrrev_i32_e32 v11, 6, v3
	v_and_b32_e32 v4, -16, v4
	v_add_u32_e32 v4, v11, v4
	v_and_b32_e32 v5, 3, v11
	s_mov_b32 s3, 0x7fffe0
	v_lshrrev_b32_e32 v6, 2, v4
	v_lshlrev_b32_e32 v7, 1, v4
	v_and_b32_e32 v3, 0xc0, v3
	v_and_or_b32 v5, v4, s3, v5
	v_and_b32_e32 v6, 4, v6
	v_and_b32_e32 v7, 24, v7
	v_sub_u32_e32 v2, v2, v3
	v_or3_b32 v5, v5, v6, v7
	v_lshlrev_b32_e32 v6, 5, v10
	v_ashrrev_i16_sdwa v2, v207, sext(v2) dst_sel:DWORD dst_unused:UNUSED_PAD src0_sel:DWORD src1_sel:BYTE_0
	v_and_b32_e32 v12, 32, v6
	v_bfe_i32 v13, v2, 0, 16
	s_movk_i32 s2, 0x1600
	v_mul_u32_u24_e32 v5, 0x1600, v5
	v_add_u32_e32 v2, v12, v13
	v_mul_lo_u32 v3, v4, s2
	v_add_lshl_u32 v156, v5, v2, 1
	v_add_lshl_u32 v158, v2, v3, 1
	v_bfe_i32 v2, v18, 27, 1
	v_lshrrev_b32_e32 v2, 22, v2
	v_add_u32_e32 v2, v1, v2
	v_and_b32_e32 v2, 0xfffffc00, v2
	v_sub_u32_e32 v1, v1, v2
	v_lshrrev_b32_e32 v2, 4, v1
	v_ashrrev_i32_e32 v3, 31, v18
	v_bitop3_b32 v1, v2, v1, 32 bitop3:0x6c
	v_lshrrev_b32_e32 v3, 26, v3
	v_readlane_b32 s8, v254, 53
	s_add_u32 s30, s12, 0x2f580000
	v_ashrrev_i32_e32 v2, 31, v1
	v_add_u32_e32 v3, v18, v3
	s_mul_i32 s1, s8, 0x1600000
	s_addc_u32 s31, s13, 0
	v_lshrrev_b32_e32 v2, 26, v2
	v_ashrrev_i32_e32 v15, 6, v3
	s_mul_hi_u32 s0, s8, 0x1600000
	s_add_u32 s1, s12, s1
	v_add_u32_e32 v2, v1, v2
	v_lshlrev_b32_e32 v3, 3, v15
	s_addc_u32 s0, s13, s0
	v_ashrrev_i32_e32 v14, 6, v2
	v_and_b32_e32 v3, -16, v3
	s_add_u32 s33, s1, 0x17000000
	v_add_u32_e32 v3, v14, v3
	v_and_b32_e32 v2, 0xc0, v2
	s_addc_u32 s48, s0, 0
	s_ashr_i32 s0, s14, 6
	v_sub_u32_e32 v1, v1, v2
	v_mul_lo_u32 v2, v3, s2
	v_readlane_b32 s2, v252, 57
	s_ashr_i32 s1, s14, 8
	s_lshl_b32 s49, s0, 10
	v_and_b32_e32 v4, 3, v14
	s_mul_i32 s2, s2, 0x2c0000
	v_and_or_b32 v4, v3, s3, v4
	s_add_u32 s2, s30, s2
	v_readlane_b32 s3, v252, 59
	v_lshrrev_b32_e32 v5, 2, v3
	v_lshlrev_b32_e32 v6, 1, v3
	s_addc_u32 s4, s31, 0
	s_mul_i32 s5, s3, 0x2c0000
	v_and_b32_e32 v5, 4, v5
	v_and_b32_e32 v6, 24, v6
	s_add_u32 s5, s33, s5
	v_or3_b32 v4, v4, v5, v6
	v_lshlrev_b32_e32 v5, 5, v15
	v_ashrrev_i16_sdwa v1, v207, sext(v1) dst_sel:DWORD dst_unused:UNUSED_PAD src0_sel:DWORD src1_sel:BYTE_0
	s_addc_u32 s6, s48, 0
	v_readlane_b32 s3, v252, 43
	v_and_b32_e32 v16, 32, v5
	v_bfe_i32 v17, v1, 0, 16
	s_add_u32 s34, s5, s3
	v_mul_u32_u24_e32 v4, 0x1600, v4
	v_add_u32_e32 v1, v16, v17
	s_addc_u32 s35, s6, 0
	s_add_i32 s50, s49, 0
	v_add_lshl_u32 v160, v4, v1, 1
	s_add_i32 m0, s50, 0x10000
	v_add_lshl_u32 v162, v1, v2, 1
	global_load_lds_dwordx4 v160, s[34:35]
	s_add_i32 m0, s50, 0x12000
	s_add_u32 s38, s2, s3
	s_addc_u32 s39, s4, 0
	s_add_u32 s4, s34, 0x160000
	global_load_lds_dwordx4 v156, s[34:35]
	s_addc_u32 s5, s35, 0
	s_add_i32 m0, s50, 0x14000
	s_add_i32 s51, s50, 0x2000
	global_load_lds_dwordx4 v160, s[4:5]
	s_add_i32 m0, s50, 0x16000
	v_mov_b32_e32 v161, v98
	global_load_lds_dwordx4 v156, s[4:5]
	s_mov_b32 m0, s50
	s_add_u32 s4, s38, 0x160000
	global_load_lds_dwordx4 v162, s[38:39]
	s_mov_b32 m0, s51
	s_addc_u32 s5, s39, 0
	s_add_i32 s52, s50, 0x4000
	global_load_lds_dwordx4 v158, s[38:39]
	s_mov_b32 m0, s52
	s_add_i32 s53, s50, 0x6000
	global_load_lds_dwordx4 v162, s[4:5]
	s_mov_b32 m0, s53
	v_mov_b32_e32 v157, v98
	global_load_lds_dwordx4 v158, s[4:5]
	v_mov_b32_e32 v163, v98
	v_mov_b32_e32 v159, v98
	s_cmp_eq_u32 s1, 1
	v_lshl_add_u64 v[8:9], s[34:35], 0, v[160:161]
	v_lshl_add_u64 v[6:7], s[34:35], 0, v[156:157]
	v_lshl_add_u64 v[2:3], s[38:39], 0, v[162:163]
	s_cselect_b64 s[4:5], -1, 0
	s_cmp_lg_u32 s1, 1
	v_lshl_add_u64 v[4:5], s[38:39], 0, v[158:159]
	v_readlane_b32 s9, v254, 54
	s_cbranch_scc1 .LBB0_1641
.LBB0_1641:
	s_cmp_eq_u32 s8, 3
	s_cselect_b32 s7, s65, 0
	s_cselect_b32 s6, s64, 0
	s_cmp_lg_u64 s[6:7], 0
	s_cselect_b64 s[8:9], -1, 0
	s_add_u32 s10, s12, 0x39880000
	s_addc_u32 s11, s13, 0
	v_readlane_b32 s2, v254, 57
	s_add_u32 s2, s12, s2
	v_readlane_b32 s3, v254, 56
	s_addc_u32 s15, s13, s3
	s_add_u32 s55, s2, 0x10a000
	s_addc_u32 s56, s15, 0
	s_add_u32 s57, s12, 0x35880000
	v_lshrrev_b32_e32 v19, 1, v18
	s_addc_u32 s58, s13, 0
	v_and_b32_e32 v19, 24, v19
	s_lshl_b32 s0, s0, 5
	v_and_b32_e32 v1, 15, v18
	v_lshlrev_b32_e32 v20, 1, v19
	v_lshlrev_b32_e32 v18, 2, v18
	s_and_b32 s2, s0, 0x60
	s_add_i32 m0, s50, 0x18000
	v_lshl_add_u64 v[8:9], v[8:9], 0, s[76:77]
	s_lshl_b32 s59, s1, 6
	v_lshl_or_b32 v20, v1, 6, v20
	s_lshl_b32 s1, s1, 13
	v_and_b32_e32 v18, 32, v18
	s_lshl_b32 s0, s2, 7
	s_waitcnt vmcnt(2)
	s_barrier
	global_load_lds_dwordx4 v[8:9], off
	v_lshl_add_u64 v[6:7], v[6:7], 0, s[76:77]
	s_add_i32 m0, s50, 0x1a000
	s_add_i32 s60, s50, 0x8000
	s_add_i32 s61, s50, 0xa000
	v_bitop3_b32 v99, v20, s0, v18 bitop3:0xde
	global_load_lds_dwordx4 v[6:7], off
	v_lshl_add_u64 v[2:3], v[2:3], 0, s[76:77]
	s_mov_b32 m0, s60
	s_add_u32 s0, s34, 0x160080
	v_bitop3_b32 v21, v20, s1, v18 bitop3:0xde
	global_load_lds_dwordx4 v[2:3], off
	v_lshl_add_u64 v[2:3], v[4:5], 0, s[76:77]
	s_mov_b32 m0, s61
	s_addc_u32 s1, s35, 0
	global_load_lds_dwordx4 v[2:3], off
	s_add_i32 m0, s50, 0x1c000
	v_lshl_add_u64 v[2:3], s[0:1], 0, v[160:161]
	global_load_lds_dwordx4 v[2:3], off
	v_lshl_add_u64 v[2:3], s[0:1], 0, v[156:157]
	s_add_i32 m0, s50, 0x1e000
	v_or_b32_e32 v188, s2, v19
	global_load_lds_dwordx4 v[2:3], off
	s_movk_i32 s2, 0x1600
	v_lshrrev_b32_e32 v3, 1, v10
	v_mul_lo_u32 v2, v11, s2
	s_mov_b32 s3, 0x16000
	v_mad_u64_u32 v[2:3], s[0:1], v3, s3, v[2:3]
	v_or_b32_e32 v2, v2, v12
	v_add_lshl_u32 v164, v2, v13, 1
	v_lshrrev_b32_e32 v3, 1, v15
	v_mul_lo_u32 v2, v14, s2
	s_waitcnt vmcnt(6)
	v_mad_u64_u32 v[2:3], s[0:1], v3, s3, v[2:3]
	s_cmpk_lt_u32 s14, 0x100
	v_or_b32_e32 v2, v2, v16
	v_readlane_b32 s0, v252, 45
	s_mov_b32 s54, 0
	s_cselect_b64 s[12:13], -1, 0
	v_mov_b32_e32 v165, v98
	v_add_lshl_u32 v166, v2, v17, 1
	v_mov_b32_e32 v167, v98
	v_add_u32_e32 v189, 0, v21
	s_mov_b32 s78, s0
	v_readlane_b32 s82, v252, 42
	v_readlane_b32 s75, v252, 59
	v_readlane_b32 s71, v252, 57
	s_mov_b32 s3, 0x20000
	s_mov_b32 s47, 0x30000
	s_mov_b64 s[64:65], 0x40000
	s_mov_b64 s[66:67], 0x10000
	s_barrier
	s_branch .LBB0_1644

; #define PG8_STAGE(bufoff, gbase, voff) do { _Pragma("unroll") for (int _i = 0; _i < 2; ++_i) \
;         __builtin_amdgcn_global_load_lds((const unsigned*)((const char*)(gbase) + (voff)[_i]), (PG8_LAS unsigned*)(lds + (bufoff) + ldsw + _i * 8192), 16, 0, AUX_A); } while (0)
; #define PG8_STAGEB(bufoff, gbase, voff) do { _Pragma("unroll") for (int _i = 0; _i < 2; ++_i) \
;         __builtin_amdgcn_global_load_lds((const unsigned*)((const char*)(gbase) + (voff)[_i]), (PG8_LAS unsigned*)(lds + (bufoff) + ldsw + _i * 8192), 16, 0, AUX_B); } while (0)
; #define PG8_WAIT_V(n) asm volatile("s_waitcnt vmcnt(" #n ")" ::: "memory")
; #define PG8_WAIT_L(n) asm volatile("s_waitcnt lgkmcnt(" #n ")" ::: "memory")
; template <class Epi, class Sched, bool ALIGN_EPI = false, bool SP2 = false>
; __device__ __forceinline__ void gemm_phase(PG8_LAS unsigned char* lds, const Gemm g, const Sched& S, const Epi& E) {
;     ...
;         for (int t = 0; t < nt; t += 2) {
;             const bool last = (t == nt - 2);
;             const char* a1 = PG8_KP(cA, t + 1, rot, nt);
;             const char* a2 = last ? nAr : PG8_KP(cA, t + 2, rot, nt); const char* b2 = last ? nBr : PG8_KP(cB, t + 2, rot, nt);
;             const char* a3 = a2 + kstep; const char* b3 = b2 + kstep;
;             if (last && has_next) S.a_ready(nxt);
;             if constexpr (SP2) {
;             PG8_LDB(B0, 0, 0); PG8_LDB(B1, 0, 1); PG8_SCHED; PG8_LDA(At, 0, 0); PG8_STAGE(PG8_SA(1, 1), a1 + hstep, voffA);
;             PG8_WAIT_V(8); PG8_WAIT_L(0); PG8_BAR; PG8_MMA(0, 0, At, B0); PG8_MMA(0, 1, At, B1); PG8_BAR; PG8_SCHED;
;             PG8_LDA(At, 0, 1); PG8_STAGEB(PG8_SB(0, 0), b2, voffB); PG8_STAGEB(PG8_SB(0, 1), b2 + hstep, voffB); PG8_STAGE(PG8_SA(0, 0), a2, voffA);
;             PG8_WAIT_V(8); PG8_WAIT_L(0); PG8_BAR; PG8_MMA(1, 0, At, B0); PG8_MMA(1, 1, At, B1); PG8_BAR; PG8_SCHED;
;             PG8_LDB(B0, 1, 0); PG8_LDB(B1, 1, 1); PG8_SCHED; PG8_LDA(At, 1, 0); PG8_STAGE(PG8_SA(0, 1), a2 + hstep, voffA);
;             PG8_WAIT_V(8); PG8_WAIT_L(0); PG8_BAR; PG8_MMA(0, 0, At, B0); PG8_MMA(0, 1, At, B1); PG8_BAR; PG8_SCHED;
;             PG8_LDA(At, 1, 1); PG8_STAGEB(PG8_SB(1, 0), b3, voffB); PG8_STAGEB(PG8_SB(1, 1), b3 + hstep, voffB); PG8_STAGE(PG8_SA(1, 0), a3, voffA);
;             PG8_WAIT_V(8); PG8_WAIT_L(0); PG8_BAR; PG8_MMA(1, 0, At, B0); PG8_MMA(1, 1, At, B1); PG8_BAR; PG8_SCHED;
.LBB0_1654:
	s_or_b32 s0, s15, 1
	s_cmp_ge_i32 s0, s82
	s_cselect_b32 s2, s82, 0
	s_add_i32 s15, s15, 2
	s_cmp_ge_i32 s15, s82
	s_cselect_b32 s0, s82, 0
	s_sub_i32 s0, s83, s0
	s_ashr_i32 s1, s0, 31
	s_lshl_b64 s[0:1], s[0:1], 7
	s_add_u32 s29, s38, s0
	s_addc_u32 s42, s39, s1
	s_add_u32 s0, s34, s0
	s_addc_u32 s1, s35, s1
	s_cmp_eq_u32 s82, s83
	s_cselect_b32 s45, s41, s42
	s_cselect_b32 s44, s40, s29
	s_cselect_b32 s43, s19, s1
	s_cselect_b32 s42, s18, s0
	s_add_i32 s29, 0, 0x10000
	s_add_i32 s46, 0, 0x14000
	v_add_u32_e32 v148, s29, v99
	v_add_u32_e32 v168, s46, v99
	ds_read_b128 v[136:139], v148
	ds_read_b128 v[140:143], v148 offset:1024
	ds_read_b128 v[144:147], v148 offset:2048
	ds_read_b128 v[148:151], v148 offset:3072
	ds_read_b128 v[152:155], v168
	ds_read_b128 v[180:183], v168 offset:1024
	ds_read_b128 v[184:187], v168 offset:2048
	ds_read_b128 v[190:193], v168 offset:3072
	v_mad_i64_i32 v[168:169], s[0:1], s2, v220, v[134:135]
	s_add_i32 m0, s50, 0xc000
	ds_read_b128 v[194:197], v189
	ds_read_b128 v[198:201], v189 offset:1024
	ds_read_b128 v[222:225], v189 offset:2048
	ds_read_b128 v[226:229], v189 offset:3072
	ds_read_b128 v[230:233], v189 offset:4096
	ds_read_b128 v[234:237], v189 offset:5120
	ds_read_b128 v[238:241], v189 offset:6144
	ds_read_b128 v[242:245], v189 offset:7168
	global_load_lds_dwordx4 v[168:169], off
	v_mad_i64_i32 v[168:169], s[0:1], s2, v220, v[132:133]
	s_add_i32 m0, s50, 0xe000
	s_nop 0
	global_load_lds_dwordx4 v[168:169], off
	s_waitcnt vmcnt(8)
	s_waitcnt lgkmcnt(0)
	s_cmp_lg_u64 s[12:13], 0
	s_cbranch_scc1 .Lhb_49
	s_barrier
.Lhb_49:
	s_setprio 1
	s_waitcnt lgkmcnt(0)
	v_mfma_f32_16x16x32_bf16 v[128:131], v[136:139], v[194:197], v[128:131]
	v_mfma_f32_16x16x32_bf16 v[124:127], v[144:147], v[194:197], v[124:127]
	v_mfma_f32_16x16x32_bf16 v[120:123], v[136:139], v[222:225], v[120:123]
	v_mfma_f32_16x16x32_bf16 v[112:115], v[144:147], v[222:225], v[112:115]
	v_mfma_f32_16x16x32_bf16 v[104:107], v[136:139], v[230:233], v[104:107]
	v_mfma_f32_16x16x32_bf16 v[94:97], v[144:147], v[230:233], v[94:97]
	v_mfma_f32_16x16x32_bf16 v[86:89], v[136:139], v[238:241], v[86:89]
	v_mfma_f32_16x16x32_bf16 v[78:81], v[144:147], v[238:241], v[78:81]
	s_setprio 2
	v_mfma_f32_16x16x32_bf16 v[128:131], v[140:143], v[198:201], v[128:131]
	v_mfma_f32_16x16x32_bf16 v[124:127], v[148:151], v[198:201], v[124:127]
	v_mfma_f32_16x16x32_bf16 v[120:123], v[140:143], v[226:229], v[120:123]
	v_mfma_f32_16x16x32_bf16 v[112:115], v[148:151], v[226:229], v[112:115]
	v_mfma_f32_16x16x32_bf16 v[104:107], v[140:143], v[234:237], v[104:107]
	v_mfma_f32_16x16x32_bf16 v[94:97], v[148:151], v[234:237], v[94:97]
	v_mfma_f32_16x16x32_bf16 v[86:89], v[140:143], v[242:245], v[86:89]
	v_mfma_f32_16x16x32_bf16 v[78:81], v[148:151], v[242:245], v[78:81]
	v_mfma_f32_16x16x32_bf16 v[116:119], v[152:155], v[194:197], v[116:119]
	v_mfma_f32_16x16x32_bf16 v[108:111], v[184:187], v[194:197], v[108:111]
	v_mfma_f32_16x16x32_bf16 v[100:103], v[152:155], v[222:225], v[100:103]
	v_mfma_f32_16x16x32_bf16 v[90:93], v[184:187], v[222:225], v[90:93]
	s_setprio 3
	v_mfma_f32_16x16x32_bf16 v[82:85], v[152:155], v[230:233], v[82:85]
	v_mfma_f32_16x16x32_bf16 v[74:77], v[184:187], v[230:233], v[74:77]
	v_mfma_f32_16x16x32_bf16 v[70:73], v[152:155], v[238:241], v[70:73]
	v_mfma_f32_16x16x32_bf16 v[66:69], v[184:187], v[238:241], v[66:69]
	v_mfma_f32_16x16x32_bf16 v[116:119], v[180:183], v[198:201], v[116:119]
	v_mfma_f32_16x16x32_bf16 v[108:111], v[190:193], v[198:201], v[108:111]
	v_mfma_f32_16x16x32_bf16 v[100:103], v[180:183], v[226:229], v[100:103]
	v_mfma_f32_16x16x32_bf16 v[90:93], v[190:193], v[226:229], v[90:93]
	v_mfma_f32_16x16x32_bf16 v[82:85], v[180:183], v[234:237], v[82:85]
	v_mfma_f32_16x16x32_bf16 v[74:77], v[190:193], v[234:237], v[74:77]
	v_mfma_f32_16x16x32_bf16 v[70:73], v[180:183], v[242:245], v[70:73]
	v_mfma_f32_16x16x32_bf16 v[66:69], v[190:193], v[242:245], v[66:69]
	s_setprio 0
	s_cmp_eq_u64 s[12:13], 0
	s_cbranch_scc1 .Lhb_53
	s_barrier
; #define PG8_STAGE(bufoff, gbase, voff) do { _Pragma("unroll") for (int _i = 0; _i < 2; ++_i) \
;         __builtin_amdgcn_global_load_lds((const unsigned*)((const char*)(gbase) + (voff)[_i]), (PG8_LAS unsigned*)(lds + (bufoff) + ldsw + _i * 8192), 16, 0, AUX_A); } while (0)
; #define PG8_STAGEB(bufoff, gbase, voff) do { _Pragma("unroll") for (int _i = 0; _i < 2; ++_i) \
;         __builtin_amdgcn_global_load_lds((const unsigned*)((const char*)(gbase) + (voff)[_i]), (PG8_LAS unsigned*)(lds + (bufoff) + ldsw + _i * 8192), 16, 0, AUX_B); } while (0)
; #define PG8_LDA(dst, b, h) do { _Pragma("unroll") for (int m = 0; m < 4; ++m) _Pragma("unroll") for (int k = 0; k < 2; ++k) dst[m][k] = *(const PG8_LAS bf16x8*)(lds + PG8_SA(b, h) + aoff + m * 2048 + k * 1024); } while (0)
; #define PG8_LDB(dst, b, h) do { _Pragma("unroll") for (int n = 0; n < 2; ++n) _Pragma("unroll") for (int k = 0; k < 2; ++k) dst[n][k] = *(const PG8_LAS bf16x8*)(lds + PG8_SB(b, h) + boff + n * 2048 + k * 1024); } while (0)
; #define PG8_MMA(ai, bj, At, Bt) do { __builtin_amdgcn_s_setprio(1); _Pragma("unroll") for (int m = 0; m < 4; ++m) _Pragma("unroll") for (int n = 0; n < 2; ++n) _Pragma("unroll") for (int k = 0; k < 2; ++k) \
;         acc[ai][bj][m][n] = __builtin_amdgcn_mfma_f32_16x16x32_bf16(Bt[n][k], At[m][k], acc[ai][bj][m][n], 0, 0, 0); __builtin_amdgcn_s_setprio(0); } while (0)
; #define PG8_WAIT_V(n) asm volatile("s_waitcnt vmcnt(" #n ")" ::: "memory")
; #define PG8_WAIT_L(n) asm volatile("s_waitcnt lgkmcnt(" #n ")" ::: "memory")
; #define PG8_BAR __builtin_amdgcn_s_barrier()
; #define PG8_SCHED __builtin_amdgcn_sched_barrier(0)
; template <class Epi, class Sched, bool ALIGN_EPI = false, bool SP2 = false>
; __device__ __forceinline__ void gemm_phase(PG8_LAS unsigned char* lds, const Gemm g, const Sched& S, const Epi& E) {
;     ...
;             PG8_LDA(At, 0, 1); PG8_STAGEB(PG8_SB(0, 0), b2, voffB); PG8_STAGEB(PG8_SB(0, 1), b2 + hstep, voffB); PG8_STAGE(PG8_SA(0, 0), a2, voffA);
;             PG8_WAIT_V(8); PG8_WAIT_L(0); PG8_BAR; PG8_MMA(1, 0, At, B0); PG8_MMA(1, 1, At, B1); PG8_BAR; PG8_SCHED;
;             PG8_LDB(B0, 1, 0); PG8_LDB(B1, 1, 1); PG8_SCHED; PG8_LDA(At, 1, 0); PG8_STAGE(PG8_SA(0, 1), a2 + hstep, voffA);
;             PG8_WAIT_V(8); PG8_WAIT_L(0); PG8_BAR; PG8_MMA(0, 0, At, B0); PG8_MMA(0, 1, At, B1); PG8_BAR; PG8_SCHED;
.Lhb_53:
	s_add_i32 s0, s29, s49
	v_lshl_add_u64 v[168:169], s[42:43], 0, v[160:161]
	s_mov_b32 m0, s0
	ds_read_b128 v[194:197], v189 offset:16384
	ds_read_b128 v[198:201], v189 offset:17408
	ds_read_b128 v[222:225], v189 offset:18432
	ds_read_b128 v[226:229], v189 offset:19456
	ds_read_b128 v[230:233], v189 offset:20480
	ds_read_b128 v[234:237], v189 offset:21504
	ds_read_b128 v[238:241], v189 offset:22528
	ds_read_b128 v[242:245], v189 offset:23552
	global_load_lds_dwordx4 v[168:169], off
	s_add_i32 m0, s0, 0x2000
	s_add_u32 s0, s42, 0x160000
	v_lshl_add_u64 v[172:173], s[42:43], 0, v[156:157]
	s_addc_u32 s1, s43, 0
	s_add_i32 s2, s46, s49
	global_load_lds_dwordx4 v[172:173], off
	v_lshl_add_u64 v[202:203], s[0:1], 0, v[160:161]
	s_mov_b32 m0, s2
	v_lshl_add_u64 v[212:213], s[44:45], 0, v[158:159]
	global_load_lds_dwordx4 v[202:203], off
	v_lshl_add_u64 v[202:203], s[0:1], 0, v[156:157]
	s_add_i32 m0, s2, 0x2000
	s_nop 0
	global_load_lds_dwordx4 v[202:203], off
	v_lshl_add_u64 v[202:203], s[44:45], 0, v[162:163]
	s_mov_b32 m0, s50
	s_nop 0
	global_load_lds_dwordx4 v[202:203], off
	s_mov_b32 m0, s51
	s_nop 0
	global_load_lds_dwordx4 v[212:213], off
	s_waitcnt vmcnt(8)
	s_waitcnt lgkmcnt(0)
	s_cmp_lg_u64 s[12:13], 0
	s_cbranch_scc1 .Lhb_50
	s_barrier
.Lhb_50:
	s_setprio 1
	s_waitcnt lgkmcnt(0)
	v_mfma_f32_16x16x32_bf16 v[62:65], v[136:139], v[194:197], v[62:65]
	v_mfma_f32_16x16x32_bf16 v[58:61], v[144:147], v[194:197], v[58:61]
	v_mfma_f32_16x16x32_bf16 v[54:57], v[136:139], v[222:225], v[54:57]
	v_mfma_f32_16x16x32_bf16 v[46:49], v[144:147], v[222:225], v[46:49]
	v_mfma_f32_16x16x32_bf16 v[38:41], v[136:139], v[230:233], v[38:41]
	v_mfma_f32_16x16x32_bf16 v[30:33], v[144:147], v[230:233], v[30:33]
	v_mfma_f32_16x16x32_bf16 v[22:25], v[136:139], v[238:241], v[22:25]
	v_mfma_f32_16x16x32_bf16 v[14:17], v[144:147], v[238:241], v[14:17]
	s_setprio 2
	v_mfma_f32_16x16x32_bf16 v[62:65], v[140:143], v[198:201], v[62:65]
	v_mfma_f32_16x16x32_bf16 v[58:61], v[148:151], v[198:201], v[58:61]
	v_mfma_f32_16x16x32_bf16 v[54:57], v[140:143], v[226:229], v[54:57]
	v_mfma_f32_16x16x32_bf16 v[46:49], v[148:151], v[226:229], v[46:49]
	v_mfma_f32_16x16x32_bf16 v[38:41], v[140:143], v[234:237], v[38:41]
	v_mfma_f32_16x16x32_bf16 v[30:33], v[148:151], v[234:237], v[30:33]
	v_mfma_f32_16x16x32_bf16 v[22:25], v[140:143], v[242:245], v[22:25]
	v_mfma_f32_16x16x32_bf16 v[14:17], v[148:151], v[242:245], v[14:17]
	v_mfma_f32_16x16x32_bf16 v[50:53], v[152:155], v[194:197], v[50:53]
	v_mfma_f32_16x16x32_bf16 v[42:45], v[184:187], v[194:197], v[42:45]
	v_mfma_f32_16x16x32_bf16 v[34:37], v[152:155], v[222:225], v[34:37]
	v_mfma_f32_16x16x32_bf16 v[26:29], v[184:187], v[222:225], v[26:29]
	s_setprio 3
	v_mfma_f32_16x16x32_bf16 v[18:21], v[152:155], v[230:233], v[18:21]
	v_mfma_f32_16x16x32_bf16 v[10:13], v[184:187], v[230:233], v[10:13]
	v_mfma_f32_16x16x32_bf16 v[6:9], v[152:155], v[238:241], v[6:9]
	v_mfma_f32_16x16x32_bf16 v[2:5], v[184:187], v[238:241], v[2:5]
	v_mfma_f32_16x16x32_bf16 v[50:53], v[180:183], v[198:201], v[50:53]
	v_mfma_f32_16x16x32_bf16 v[42:45], v[190:193], v[198:201], v[42:45]
	v_mfma_f32_16x16x32_bf16 v[34:37], v[180:183], v[226:229], v[34:37]
	v_mfma_f32_16x16x32_bf16 v[26:29], v[190:193], v[226:229], v[26:29]
	v_mfma_f32_16x16x32_bf16 v[18:21], v[180:183], v[234:237], v[18:21]
	v_mfma_f32_16x16x32_bf16 v[10:13], v[190:193], v[234:237], v[10:13]
	v_mfma_f32_16x16x32_bf16 v[6:9], v[180:183], v[242:245], v[6:9]
	v_mfma_f32_16x16x32_bf16 v[2:5], v[190:193], v[242:245], v[2:5]
	s_setprio 0
	s_cmp_eq_u64 s[12:13], 0
	s_cbranch_scc1 .Lhb_54
	s_barrier
.Lhb_54:
	s_add_i32 s2, 0, 0x18000
	s_add_i32 s29, 0, 0x1c000
	v_add_u32_e32 v148, s2, v99
	v_add_u32_e32 v190, s29, v99
	ds_read_b128 v[136:139], v148
	ds_read_b128 v[140:143], v148 offset:1024
	ds_read_b128 v[144:147], v148 offset:2048
	ds_read_b128 v[148:151], v148 offset:3072
	ds_read_b128 v[152:155], v190
	ds_read_b128 v[180:183], v190 offset:1024
	ds_read_b128 v[184:187], v190 offset:2048
	ds_read_b128 v[190:193], v190 offset:3072
	s_add_u32 s0, s44, 0x160000
	s_addc_u32 s1, s45, 0
	s_mov_b32 m0, s52
	v_lshl_add_u64 v[246:247], s[0:1], 0, v[162:163]
	ds_read_b128 v[194:197], v189 offset:32768
	ds_read_b128 v[198:201], v189 offset:33792
	ds_read_b128 v[222:225], v189 offset:34816
	ds_read_b128 v[226:229], v189 offset:35840
	ds_read_b128 v[230:233], v189 offset:36864
	ds_read_b128 v[234:237], v189 offset:37888
	ds_read_b128 v[238:241], v189 offset:38912
	ds_read_b128 v[242:245], v189 offset:39936
	global_load_lds_dwordx4 v[246:247], off
	v_lshl_add_u64 v[246:247], s[0:1], 0, v[158:159]
	s_mov_b32 m0, s53
	s_nop 0
	global_load_lds_dwordx4 v[246:247], off
	s_waitcnt vmcnt(8)
	s_waitcnt lgkmcnt(0)
	s_cmp_lg_u64 s[12:13], 0
	s_cbranch_scc1 .Lhb_51
	s_barrier

; #define PG8_STAGE(bufoff, gbase, voff) do { _Pragma("unroll") for (int _i = 0; _i < 2; ++_i) \
;         __builtin_amdgcn_global_load_lds((const unsigned*)((const char*)(gbase) + (voff)[_i]), (PG8_LAS unsigned*)(lds + (bufoff) + ldsw + _i * 8192), 16, 0, AUX_A); } while (0)
; #define PG8_STAGEB(bufoff, gbase, voff) do { _Pragma("unroll") for (int _i = 0; _i < 2; ++_i) \
;         __builtin_amdgcn_global_load_lds((const unsigned*)((const char*)(gbase) + (voff)[_i]), (PG8_LAS unsigned*)(lds + (bufoff) + ldsw + _i * 8192), 16, 0, AUX_B); } while (0)
; #define PG8_LDA(dst, b, h) do { _Pragma("unroll") for (int m = 0; m < 4; ++m) _Pragma("unroll") for (int k = 0; k < 2; ++k) dst[m][k] = *(const PG8_LAS bf16x8*)(lds + PG8_SA(b, h) + aoff + m * 2048 + k * 1024); } while (0)
; #define PG8_MMA(ai, bj, At, Bt) do { __builtin_amdgcn_s_setprio(1); _Pragma("unroll") for (int m = 0; m < 4; ++m) _Pragma("unroll") for (int n = 0; n < 2; ++n) _Pragma("unroll") for (int k = 0; k < 2; ++k) \
;         acc[ai][bj][m][n] = __builtin_amdgcn_mfma_f32_16x16x32_bf16(Bt[n][k], At[m][k], acc[ai][bj][m][n], 0, 0, 0); __builtin_amdgcn_s_setprio(0); } while (0)
; #define PG8_WAIT_V(n) asm volatile("s_waitcnt vmcnt(" #n ")" ::: "memory")
; #define PG8_WAIT_L(n) asm volatile("s_waitcnt lgkmcnt(" #n ")" ::: "memory")
; #define PG8_BAR __builtin_amdgcn_s_barrier()
; #define PG8_SCHED __builtin_amdgcn_sched_barrier(0)
; template <class Epi, class Sched, bool ALIGN_EPI = false, bool SP2 = false>
; __device__ __forceinline__ void gemm_phase(PG8_LAS unsigned char* lds, const Gemm g, const Sched& S, const Epi& E) {
;     ...
;             PG8_LDA(At, 1, 1); PG8_STAGEB(PG8_SB(1, 0), b3, voffB); PG8_STAGEB(PG8_SB(1, 1), b3 + hstep, voffB); PG8_STAGE(PG8_SA(1, 0), a3, voffA);
;             PG8_WAIT_V(8); PG8_WAIT_L(0); PG8_BAR; PG8_MMA(1, 0, At, B0); PG8_MMA(1, 1, At, B1); PG8_BAR; PG8_SCHED;
.Lhb_55:
	s_add_i32 s0, s2, s49
	v_lshl_add_u64 v[168:169], v[168:169], 0, s[76:77]
	s_mov_b32 m0, s0
	ds_read_b128 v[194:197], v189 offset:49152
	ds_read_b128 v[198:201], v189 offset:50176
	ds_read_b128 v[222:225], v189 offset:51200
	ds_read_b128 v[226:229], v189 offset:52224
	ds_read_b128 v[230:233], v189 offset:53248
	ds_read_b128 v[234:237], v189 offset:54272
	ds_read_b128 v[238:241], v189 offset:55296
	ds_read_b128 v[242:245], v189 offset:56320
	global_load_lds_dwordx4 v[168:169], off
	s_add_i32 m0, s0, 0x2000
	s_add_u32 s0, s42, 0x160080
	v_lshl_add_u64 v[168:169], v[172:173], 0, s[76:77]
	s_addc_u32 s1, s43, 0
	s_add_i32 s2, s29, s49
	global_load_lds_dwordx4 v[168:169], off
	v_lshl_add_u64 v[168:169], s[0:1], 0, v[160:161]
	s_mov_b32 m0, s2
	s_nop 0
	global_load_lds_dwordx4 v[168:169], off
	v_lshl_add_u64 v[168:169], s[0:1], 0, v[156:157]
	s_add_i32 m0, s2, 0x2000
	s_nop 0
	global_load_lds_dwordx4 v[168:169], off
	v_lshl_add_u64 v[168:169], v[202:203], 0, s[76:77]
	s_mov_b32 m0, s60
	s_nop 0
	global_load_lds_dwordx4 v[168:169], off
	v_lshl_add_u64 v[168:169], v[212:213], 0, s[76:77]
	s_mov_b32 m0, s61
	s_nop 0
	global_load_lds_dwordx4 v[168:169], off
	s_waitcnt vmcnt(8)
	s_waitcnt lgkmcnt(0)
	s_cmp_lg_u64 s[12:13], 0
	s_cbranch_scc1 .Lhb_52
	s_barrier

; #define PG8_BAR __builtin_amdgcn_s_barrier()
; template <class Epi, class Sched, bool ALIGN_EPI = false, bool SP2 = false>
; __device__ __forceinline__ void gemm_phase(PG8_LAS unsigned char* lds, const Gemm g, const Sched& S, const Epi& E) {
;     ...
;         for (int t = 0; t < nt; t += 2) {
;             const bool last = (t == nt - 2);
;             const char* a1 = PG8_KP(cA, t + 1, rot, nt);
;             const char* a2 = last ? nAr : PG8_KP(cA, t + 2, rot, nt); const char* b2 = last ? nBr : PG8_KP(cB, t + 2, rot, nt);
;             const char* a3 = a2 + kstep; const char* b3 = b2 + kstep;
;     ...
;         if constexpr (ALIGN_EPI) { if (wr == 0) PG8_BAR; }
.Lhb_56:
	s_add_i32 s0, s83, 2
	v_lshl_add_u64 v[132:133], v[132:133], 0, s[86:87]
	v_lshl_add_u64 v[134:135], v[134:135], 0, s[86:87]
	s_cmp_ge_i32 s83, s82
	s_mov_b32 s83, s0
	s_cbranch_scc0 .LBB0_1654
	s_and_b64 vcc, exec, s[12:13]
	s_cbranch_vccz .LBB0_1657
